# GEMM main loops: dropped the compiler's second lgkmcnt(0) behind each phase barrier (counter already drained before the barrier); gates epilogue xc loads issued together; scan2 main loop hand-written
# speedup vs baseline: 1.0054x; 1.0054x over previous
; #define PG8_STAGE(bufoff, gbase, voff) do { _Pragma("unroll") for (int _i = 0; _i < 2; ++_i) \
;         __builtin_amdgcn_global_load_lds((const unsigned*)((const char*)(gbase) + (voff)[_i]), (PG8_LAS unsigned*)(lds + (bufoff) + ldsw + _i * 8192), 16, 0, 0); } while (0)
; #define PG8_LDA(dst, b, h) do { _Pragma("unroll") for (int m = 0; m < 4; ++m) _Pragma("unroll") for (int k = 0; k < 2; ++k) dst[m][k] = *(const PG8_LAS bf16x8*)(lds + PG8_SA(b, h) + aoff + m * 2048 + k * 1024); } while (0)
; #define PG8_LDB(dst, b, h) do { _Pragma("unroll") for (int n = 0; n < 2; ++n) _Pragma("unroll") for (int k = 0; k < 2; ++k) dst[n][k] = *(const PG8_LAS bf16x8*)(lds + PG8_SB(b, h) + boff + n * 2048 + k * 1024); } while (0)
; #define PG8_MMA(ai, bj, At, Bt) do { __builtin_amdgcn_s_setprio(1); _Pragma("unroll") for (int m = 0; m < 4; ++m) _Pragma("unroll") for (int n = 0; n < 2; ++n) _Pragma("unroll") for (int k = 0; k < 2; ++k) \
;         acc[ai][bj][m][n] = __builtin_amdgcn_mfma_f32_16x16x32_bf16(Bt[n][k], At[m][k], acc[ai][bj][m][n], 0, 0, 0); __builtin_amdgcn_s_setprio(0); } while (0)
; #define PG8_WAIT_V(n) asm volatile("s_waitcnt vmcnt(" #n ")" ::: "memory")
; #define PG8_WAIT_L(n) asm volatile("s_waitcnt lgkmcnt(" #n ")" ::: "memory")
; #define PG8_BAR __builtin_amdgcn_s_barrier()
; #define PG8_SCHED __builtin_amdgcn_sched_barrier(0)
; template <class Epi, class Sched, bool ALIGN_EPI = false, bool SP2 = false>
; __device__ __forceinline__ void gemm_phase(PG8_LAS unsigned char* lds, const Gemm g, const Sched& S, const Epi& E, const int wid) {
;     ...
;             PG8_LDB(B0, 0, 0); PG8_LDB(B1, 0, 1); PG8_SCHED; PG8_LDA(At, 0, 0); PG8_STAGE(PG8_SA(1, 1), a1 + hstepA, voffA);
;             PG8_WAIT_V(8); PG8_WAIT_L(0); PG8_BAR; PG8_MMA(0, 0, At, B0); PG8_MMA(0, 1, At, B1); PG8_BAR; PG8_SCHED;
;             PG8_LDA(At, 0, 1); PG8_STAGE(PG8_SB(0, 0), b2, voffB); PG8_STAGE(PG8_SB(0, 1), b2 + hstepB, voffB); PG8_STAGE(PG8_SA(0, 0), a2, voffA);
.LBB0_119:
	ds_read_b128 v[144:147], v155
	ds_read_b128 v[148:151], v155 offset:1024
	ds_read_b128 v[158:161], v155 offset:2048
	ds_read_b128 v[162:165], v155 offset:3072
	ds_read_b128 v[166:169], v156
	ds_read_b128 v[170:173], v156 offset:1024
	ds_read_b128 v[174:177], v156 offset:2048
	ds_read_b128 v[180:183], v156 offset:3072
	s_add_i32 s41, s35, 2
	s_add_u32 s46, s44, 0xfffc0080
	s_addc_u32 s47, s45, -1
	s_cmp_eq_u32 s65, s35
	s_cselect_b32 s49, s37, s47
	s_cselect_b32 s48, s36, s46
	s_cselect_b32 s47, s39, s31
	s_cselect_b32 s46, s38, s7
	v_lshl_add_u64 v[216:217], s[44:45], 0, v[136:137]
	s_add_i32 m0, s58, 0xc000
	ds_read_b128 v[184:187], v157
	ds_read_b128 v[188:191], v157 offset:1024
	ds_read_b128 v[192:195], v157 offset:2048
	ds_read_b128 v[196:199], v157 offset:3072
	ds_read_b128 v[200:203], v157 offset:4096
	ds_read_b128 v[204:207], v157 offset:5120
	ds_read_b128 v[208:211], v157 offset:6144
	ds_read_b128 v[212:215], v157 offset:7168
	global_load_lds_dwordx4 v[216:217], off
	v_lshl_add_u64 v[216:217], s[44:45], 0, v[138:139]
	s_add_i32 m0, s58, 0xe000
	s_nop 0
	global_load_lds_dwordx4 v[216:217], off
	s_waitcnt vmcnt(8)
	s_waitcnt lgkmcnt(0)
	s_barrier
	s_setprio 1
	v_mfma_f32_16x16x32_bf16 v[124:127], v[144:147], v[184:187], v[124:127]
	v_mfma_f32_16x16x32_bf16 v[120:123], v[158:161], v[184:187], v[120:123]
	v_mfma_f32_16x16x32_bf16 v[108:111], v[144:147], v[192:195], v[108:111]
	v_mfma_f32_16x16x32_bf16 v[104:107], v[158:161], v[192:195], v[104:107]
	v_mfma_f32_16x16x32_bf16 v[92:95], v[144:147], v[200:203], v[92:95]
	v_mfma_f32_16x16x32_bf16 v[88:91], v[158:161], v[200:203], v[88:91]
	v_mfma_f32_16x16x32_bf16 v[76:79], v[144:147], v[208:211], v[76:79]
	v_mfma_f32_16x16x32_bf16 v[72:75], v[158:161], v[208:211], v[72:75]
	v_mfma_f32_16x16x32_bf16 v[124:127], v[148:151], v[188:191], v[124:127]
	v_mfma_f32_16x16x32_bf16 v[120:123], v[162:165], v[188:191], v[120:123]
	v_mfma_f32_16x16x32_bf16 v[108:111], v[148:151], v[196:199], v[108:111]
	v_mfma_f32_16x16x32_bf16 v[104:107], v[162:165], v[196:199], v[104:107]
	v_mfma_f32_16x16x32_bf16 v[92:95], v[148:151], v[204:207], v[92:95]
	v_mfma_f32_16x16x32_bf16 v[88:91], v[162:165], v[204:207], v[88:91]
	v_mfma_f32_16x16x32_bf16 v[76:79], v[148:151], v[212:215], v[76:79]
	v_mfma_f32_16x16x32_bf16 v[72:75], v[162:165], v[212:215], v[72:75]
	s_setprio 0
	s_setprio 1
	v_mfma_f32_16x16x32_bf16 v[116:119], v[166:169], v[184:187], v[116:119]
	v_mfma_f32_16x16x32_bf16 v[112:115], v[174:177], v[184:187], v[112:115]
	v_mfma_f32_16x16x32_bf16 v[100:103], v[166:169], v[192:195], v[100:103]
	v_mfma_f32_16x16x32_bf16 v[96:99], v[174:177], v[192:195], v[96:99]
	v_mfma_f32_16x16x32_bf16 v[84:87], v[166:169], v[200:203], v[84:87]
	v_mfma_f32_16x16x32_bf16 v[80:83], v[174:177], v[200:203], v[80:83]
	v_mfma_f32_16x16x32_bf16 v[68:71], v[166:169], v[208:211], v[68:71]
	v_mfma_f32_16x16x32_bf16 v[64:67], v[174:177], v[208:211], v[64:67]
	v_mfma_f32_16x16x32_bf16 v[116:119], v[170:173], v[188:191], v[116:119]
	v_mfma_f32_16x16x32_bf16 v[112:115], v[180:183], v[188:191], v[112:115]
	v_mfma_f32_16x16x32_bf16 v[100:103], v[170:173], v[196:199], v[100:103]
	v_mfma_f32_16x16x32_bf16 v[96:99], v[180:183], v[196:199], v[96:99]
	v_mfma_f32_16x16x32_bf16 v[84:87], v[170:173], v[204:207], v[84:87]
	v_mfma_f32_16x16x32_bf16 v[80:83], v[180:183], v[204:207], v[80:83]
	v_mfma_f32_16x16x32_bf16 v[68:71], v[170:173], v[212:215], v[68:71]
	v_mfma_f32_16x16x32_bf16 v[64:67], v[180:183], v[212:215], v[64:67]
	s_setprio 0
	s_barrier
	s_add_i32 s35, s69, s0
	v_lshl_add_u64 v[216:217], s[46:47], 0, v[130:131]
	s_mov_b32 m0, s35
	ds_read_b128 v[184:187], v157 offset:16384
	ds_read_b128 v[188:191], v157 offset:17408
	ds_read_b128 v[192:195], v157 offset:18432
	ds_read_b128 v[196:199], v157 offset:19456
	ds_read_b128 v[200:203], v157 offset:20480
	ds_read_b128 v[204:207], v157 offset:21504
	ds_read_b128 v[208:211], v157 offset:22528
	ds_read_b128 v[212:215], v157 offset:23552
	global_load_lds_dwordx4 v[216:217], off
	s_add_i32 m0, s35, 0x2000
	s_add_u32 s72, s46, 0x40000
	v_lshl_add_u64 v[218:219], s[46:47], 0, v[134:135]
	s_addc_u32 s73, s47, 0
	s_add_i32 s35, s70, s0
	global_load_lds_dwordx4 v[218:219], off
	v_lshl_add_u64 v[220:221], s[72:73], 0, v[130:131]
	s_mov_b32 m0, s35
	v_lshl_add_u64 v[222:223], s[48:49], 0, v[132:133]
	global_load_lds_dwordx4 v[220:221], off
	v_lshl_add_u64 v[220:221], s[72:73], 0, v[134:135]
	s_add_i32 m0, s35, 0x2000
	s_nop 0
	global_load_lds_dwordx4 v[220:221], off
	v_lshl_add_u64 v[220:221], s[48:49], 0, v[128:129]
	s_mov_b32 m0, s58
	s_nop 0
	global_load_lds_dwordx4 v[220:221], off
	s_mov_b32 m0, s59
	s_nop 0
	global_load_lds_dwordx4 v[222:223], off
	s_waitcnt vmcnt(8)
	s_waitcnt lgkmcnt(0)
	s_barrier
; #define PG8_STAGE(bufoff, gbase, voff) do { _Pragma("unroll") for (int _i = 0; _i < 2; ++_i) \
;         __builtin_amdgcn_global_load_lds((const unsigned*)((const char*)(gbase) + (voff)[_i]), (PG8_LAS unsigned*)(lds + (bufoff) + ldsw + _i * 8192), 16, 0, 0); } while (0)
; #define PG8_LDA(dst, b, h) do { _Pragma("unroll") for (int m = 0; m < 4; ++m) _Pragma("unroll") for (int k = 0; k < 2; ++k) dst[m][k] = *(const PG8_LAS bf16x8*)(lds + PG8_SA(b, h) + aoff + m * 2048 + k * 1024); } while (0)
; #define PG8_LDB(dst, b, h) do { _Pragma("unroll") for (int n = 0; n < 2; ++n) _Pragma("unroll") for (int k = 0; k < 2; ++k) dst[n][k] = *(const PG8_LAS bf16x8*)(lds + PG8_SB(b, h) + boff + n * 2048 + k * 1024); } while (0)
; #define PG8_MMA(ai, bj, At, Bt) do { __builtin_amdgcn_s_setprio(1); _Pragma("unroll") for (int m = 0; m < 4; ++m) _Pragma("unroll") for (int n = 0; n < 2; ++n) _Pragma("unroll") for (int k = 0; k < 2; ++k) \
;         acc[ai][bj][m][n] = __builtin_amdgcn_mfma_f32_16x16x32_bf16(Bt[n][k], At[m][k], acc[ai][bj][m][n], 0, 0, 0); __builtin_amdgcn_s_setprio(0); } while (0)
; #define PG8_WAIT_V(n) asm volatile("s_waitcnt vmcnt(" #n ")" ::: "memory")
; #define PG8_WAIT_L(n) asm volatile("s_waitcnt lgkmcnt(" #n ")" ::: "memory")
; #define PG8_BAR __builtin_amdgcn_s_barrier()
; #define PG8_SCHED __builtin_amdgcn_sched_barrier(0)
; template <class Epi, class Sched, bool ALIGN_EPI = false, bool SP2 = false>
; __device__ __forceinline__ void gemm_phase(PG8_LAS unsigned char* lds, const Gemm g, const Sched& S, const Epi& E, const int wid) {
;     ...
;             PG8_WAIT_V(8); PG8_WAIT_L(0); PG8_BAR; PG8_MMA(1, 0, At, B0); PG8_MMA(1, 1, At, B1); PG8_BAR; PG8_SCHED;
;             PG8_LDB(B0, 1, 0); PG8_LDB(B1, 1, 1); PG8_SCHED; PG8_LDA(At, 1, 0); PG8_STAGE(PG8_SA(0, 1), a2 + hstepA, voffA);
;             PG8_WAIT_V(8); PG8_WAIT_L(0); PG8_BAR; PG8_MMA(0, 0, At, B0); PG8_MMA(0, 1, At, B1); PG8_BAR; PG8_SCHED;
	s_setprio 1
	v_mfma_f32_16x16x32_bf16 v[60:63], v[144:147], v[184:187], v[60:63]
	v_mfma_f32_16x16x32_bf16 v[56:59], v[158:161], v[184:187], v[56:59]
	v_mfma_f32_16x16x32_bf16 v[44:47], v[144:147], v[192:195], v[44:47]
	v_mfma_f32_16x16x32_bf16 v[40:43], v[158:161], v[192:195], v[40:43]
	v_mfma_f32_16x16x32_bf16 v[28:31], v[144:147], v[200:203], v[28:31]
	v_mfma_f32_16x16x32_bf16 v[24:27], v[158:161], v[200:203], v[24:27]
	v_mfma_f32_16x16x32_bf16 v[12:15], v[144:147], v[208:211], v[12:15]
	v_mfma_f32_16x16x32_bf16 v[8:11], v[158:161], v[208:211], v[8:11]
	v_mfma_f32_16x16x32_bf16 v[60:63], v[148:151], v[188:191], v[60:63]
	v_mfma_f32_16x16x32_bf16 v[56:59], v[162:165], v[188:191], v[56:59]
	v_mfma_f32_16x16x32_bf16 v[44:47], v[148:151], v[196:199], v[44:47]
	v_mfma_f32_16x16x32_bf16 v[40:43], v[162:165], v[196:199], v[40:43]
	v_mfma_f32_16x16x32_bf16 v[28:31], v[148:151], v[204:207], v[28:31]
	v_mfma_f32_16x16x32_bf16 v[24:27], v[162:165], v[204:207], v[24:27]
	v_mfma_f32_16x16x32_bf16 v[12:15], v[148:151], v[212:215], v[12:15]
	v_mfma_f32_16x16x32_bf16 v[8:11], v[162:165], v[212:215], v[8:11]
	s_setprio 0
	s_setprio 1
	v_mfma_f32_16x16x32_bf16 v[52:55], v[166:169], v[184:187], v[52:55]
	v_mfma_f32_16x16x32_bf16 v[48:51], v[174:177], v[184:187], v[48:51]
	v_mfma_f32_16x16x32_bf16 v[36:39], v[166:169], v[192:195], v[36:39]
	v_mfma_f32_16x16x32_bf16 v[32:35], v[174:177], v[192:195], v[32:35]
	v_mfma_f32_16x16x32_bf16 v[20:23], v[166:169], v[200:203], v[20:23]
	v_mfma_f32_16x16x32_bf16 v[16:19], v[174:177], v[200:203], v[16:19]
	v_mfma_f32_16x16x32_bf16 v[4:7], v[166:169], v[208:211], v[4:7]
	v_mfma_f32_16x16x32_bf16 v[0:3], v[174:177], v[208:211], v[0:3]
	v_mfma_f32_16x16x32_bf16 v[52:55], v[170:173], v[188:191], v[52:55]
	v_mfma_f32_16x16x32_bf16 v[48:51], v[180:183], v[188:191], v[48:51]
	v_mfma_f32_16x16x32_bf16 v[36:39], v[170:173], v[196:199], v[36:39]
	v_mfma_f32_16x16x32_bf16 v[32:35], v[180:183], v[196:199], v[32:35]
	v_mfma_f32_16x16x32_bf16 v[20:23], v[170:173], v[204:207], v[20:23]
	v_mfma_f32_16x16x32_bf16 v[16:19], v[180:183], v[204:207], v[16:19]
	v_mfma_f32_16x16x32_bf16 v[4:7], v[170:173], v[212:215], v[4:7]
	v_mfma_f32_16x16x32_bf16 v[0:3], v[180:183], v[212:215], v[0:3]
	s_setprio 0
	s_barrier
	s_add_i32 s35, 0, 0x18000
	s_add_i32 s71, 0, 0x1c000
	v_add_u32_e32 v162, s35, v153
	v_add_u32_e32 v179, s71, v153
	ds_read_b128 v[144:147], v162
	ds_read_b128 v[148:151], v162 offset:1024
	ds_read_b128 v[158:161], v162 offset:2048
	ds_read_b128 v[162:165], v162 offset:3072
	ds_read_b128 v[166:169], v179
	ds_read_b128 v[170:173], v179 offset:1024
	ds_read_b128 v[174:177], v179 offset:2048
	ds_read_b128 v[180:183], v179 offset:3072
	s_add_u32 s48, s48, 0x40000
	s_addc_u32 s49, s49, 0
	s_mov_b32 m0, s60
	v_lshl_add_u64 v[224:225], s[48:49], 0, v[128:129]
	ds_read_b128 v[184:187], v157 offset:32768
	ds_read_b128 v[188:191], v157 offset:33792
	ds_read_b128 v[192:195], v157 offset:34816
	ds_read_b128 v[196:199], v157 offset:35840
	ds_read_b128 v[200:203], v157 offset:36864
	ds_read_b128 v[204:207], v157 offset:37888
	ds_read_b128 v[208:211], v157 offset:38912
	ds_read_b128 v[212:215], v157 offset:39936
	global_load_lds_dwordx4 v[224:225], off
	v_lshl_add_u64 v[224:225], s[48:49], 0, v[132:133]
	s_mov_b32 m0, s61
	s_nop 0
	global_load_lds_dwordx4 v[224:225], off
	s_waitcnt vmcnt(8)
	s_waitcnt lgkmcnt(0)
	s_barrier
	s_setprio 1
	v_mfma_f32_16x16x32_bf16 v[124:127], v[144:147], v[184:187], v[124:127]
	v_mfma_f32_16x16x32_bf16 v[120:123], v[158:161], v[184:187], v[120:123]
	v_mfma_f32_16x16x32_bf16 v[108:111], v[144:147], v[192:195], v[108:111]
	v_mfma_f32_16x16x32_bf16 v[104:107], v[158:161], v[192:195], v[104:107]
	v_mfma_f32_16x16x32_bf16 v[92:95], v[144:147], v[200:203], v[92:95]
	v_mfma_f32_16x16x32_bf16 v[88:91], v[158:161], v[200:203], v[88:91]
	v_mfma_f32_16x16x32_bf16 v[76:79], v[144:147], v[208:211], v[76:79]
	v_mfma_f32_16x16x32_bf16 v[72:75], v[158:161], v[208:211], v[72:75]
	v_mfma_f32_16x16x32_bf16 v[124:127], v[148:151], v[188:191], v[124:127]
	v_mfma_f32_16x16x32_bf16 v[120:123], v[162:165], v[188:191], v[120:123]
	v_mfma_f32_16x16x32_bf16 v[108:111], v[148:151], v[196:199], v[108:111]
	v_mfma_f32_16x16x32_bf16 v[104:107], v[162:165], v[196:199], v[104:107]
	v_mfma_f32_16x16x32_bf16 v[92:95], v[148:151], v[204:207], v[92:95]
	v_mfma_f32_16x16x32_bf16 v[88:91], v[162:165], v[204:207], v[88:91]
	v_mfma_f32_16x16x32_bf16 v[76:79], v[148:151], v[212:215], v[76:79]
	v_mfma_f32_16x16x32_bf16 v[72:75], v[162:165], v[212:215], v[72:75]
	s_setprio 0
	s_setprio 1
	v_mfma_f32_16x16x32_bf16 v[116:119], v[166:169], v[184:187], v[116:119]
	v_mfma_f32_16x16x32_bf16 v[112:115], v[174:177], v[184:187], v[112:115]
	v_mfma_f32_16x16x32_bf16 v[100:103], v[166:169], v[192:195], v[100:103]
	v_mfma_f32_16x16x32_bf16 v[96:99], v[174:177], v[192:195], v[96:99]
	v_mfma_f32_16x16x32_bf16 v[84:87], v[166:169], v[200:203], v[84:87]
	v_mfma_f32_16x16x32_bf16 v[80:83], v[174:177], v[200:203], v[80:83]
	v_mfma_f32_16x16x32_bf16 v[68:71], v[166:169], v[208:211], v[68:71]
	v_mfma_f32_16x16x32_bf16 v[64:67], v[174:177], v[208:211], v[64:67]
	v_mfma_f32_16x16x32_bf16 v[116:119], v[170:173], v[188:191], v[116:119]
	v_mfma_f32_16x16x32_bf16 v[112:115], v[180:183], v[188:191], v[112:115]
	v_mfma_f32_16x16x32_bf16 v[100:103], v[170:173], v[196:199], v[100:103]
	v_mfma_f32_16x16x32_bf16 v[96:99], v[180:183], v[196:199], v[96:99]
	v_mfma_f32_16x16x32_bf16 v[84:87], v[170:173], v[204:207], v[84:87]
	v_mfma_f32_16x16x32_bf16 v[80:83], v[180:183], v[204:207], v[80:83]
	v_mfma_f32_16x16x32_bf16 v[68:71], v[170:173], v[212:215], v[68:71]
	v_mfma_f32_16x16x32_bf16 v[64:67], v[180:183], v[212:215], v[64:67]
	s_setprio 0
	s_barrier
; #define PG8_STAGE(bufoff, gbase, voff) do { _Pragma("unroll") for (int _i = 0; _i < 2; ++_i) \
;         __builtin_amdgcn_global_load_lds((const unsigned*)((const char*)(gbase) + (voff)[_i]), (PG8_LAS unsigned*)(lds + (bufoff) + ldsw + _i * 8192), 16, 0, 0); } while (0)
; #define PG8_LDA(dst, b, h) do { _Pragma("unroll") for (int m = 0; m < 4; ++m) _Pragma("unroll") for (int k = 0; k < 2; ++k) dst[m][k] = *(const PG8_LAS bf16x8*)(lds + PG8_SA(b, h) + aoff + m * 2048 + k * 1024); } while (0)
; #define PG8_MMA(ai, bj, At, Bt) do { __builtin_amdgcn_s_setprio(1); _Pragma("unroll") for (int m = 0; m < 4; ++m) _Pragma("unroll") for (int n = 0; n < 2; ++n) _Pragma("unroll") for (int k = 0; k < 2; ++k) \
;         acc[ai][bj][m][n] = __builtin_amdgcn_mfma_f32_16x16x32_bf16(Bt[n][k], At[m][k], acc[ai][bj][m][n], 0, 0, 0); __builtin_amdgcn_s_setprio(0); } while (0)
; #define PG8_WAIT_V(n) asm volatile("s_waitcnt vmcnt(" #n ")" ::: "memory")
; #define PG8_WAIT_L(n) asm volatile("s_waitcnt lgkmcnt(" #n ")" ::: "memory")
; #define PG8_BAR __builtin_amdgcn_s_barrier()
; #define PG8_SCHED __builtin_amdgcn_sched_barrier(0)
; template <class Epi, class Sched, bool ALIGN_EPI = false, bool SP2 = false>
; __device__ __forceinline__ void gemm_phase(PG8_LAS unsigned char* lds, const Gemm g, const Sched& S, const Epi& E, const int wid) {
;     ...
;         for (int t = 0; t < nt; t += 2) {
;     ...
;             PG8_LDA(At, 1, 1); PG8_STAGE(PG8_SB(1, 0), b3, voffB); PG8_STAGE(PG8_SB(1, 1), b3 + hstepB, voffB); PG8_STAGE(PG8_SA(1, 0), a3, voffA);
;             PG8_WAIT_V(8); PG8_WAIT_L(0); PG8_BAR; PG8_MMA(1, 0, At, B0); PG8_MMA(1, 1, At, B1); PG8_BAR; PG8_SCHED;
	s_add_i32 s35, s35, s0
	v_lshl_add_u64 v[216:217], v[216:217], 0, s[12:13]
	s_mov_b32 m0, s35
	ds_read_b128 v[184:187], v157 offset:49152
	ds_read_b128 v[188:191], v157 offset:50176
	ds_read_b128 v[192:195], v157 offset:51200
	ds_read_b128 v[196:199], v157 offset:52224
	ds_read_b128 v[200:203], v157 offset:53248
	ds_read_b128 v[204:207], v157 offset:54272
	ds_read_b128 v[208:211], v157 offset:55296
	ds_read_b128 v[212:215], v157 offset:56320
	global_load_lds_dwordx4 v[216:217], off
	s_add_i32 m0, s35, 0x2000
	s_add_u32 s46, s46, 0x40080
	v_lshl_add_u64 v[216:217], v[218:219], 0, s[12:13]
	s_addc_u32 s47, s47, 0
	s_add_i32 s35, s71, s0
	global_load_lds_dwordx4 v[216:217], off
	v_lshl_add_u64 v[216:217], s[46:47], 0, v[130:131]
	s_mov_b32 m0, s35
	s_nop 0
	global_load_lds_dwordx4 v[216:217], off
	v_lshl_add_u64 v[216:217], s[46:47], 0, v[134:135]
	s_add_i32 m0, s35, 0x2000
	s_nop 0
	global_load_lds_dwordx4 v[216:217], off
	v_lshl_add_u64 v[216:217], v[220:221], 0, s[12:13]
	s_mov_b32 m0, s63
	s_nop 0
	global_load_lds_dwordx4 v[216:217], off
	v_lshl_add_u64 v[216:217], v[222:223], 0, s[12:13]
	s_mov_b32 m0, s64
	s_nop 0
	global_load_lds_dwordx4 v[216:217], off
	s_waitcnt vmcnt(8)
	s_waitcnt lgkmcnt(0)
	s_barrier
	s_setprio 1
	v_mfma_f32_16x16x32_bf16 v[60:63], v[144:147], v[184:187], v[60:63]
	v_mfma_f32_16x16x32_bf16 v[56:59], v[158:161], v[184:187], v[56:59]
	v_mfma_f32_16x16x32_bf16 v[44:47], v[144:147], v[192:195], v[44:47]
	v_mfma_f32_16x16x32_bf16 v[40:43], v[158:161], v[192:195], v[40:43]
	v_mfma_f32_16x16x32_bf16 v[28:31], v[144:147], v[200:203], v[28:31]
	v_mfma_f32_16x16x32_bf16 v[24:27], v[158:161], v[200:203], v[24:27]
	v_mfma_f32_16x16x32_bf16 v[12:15], v[144:147], v[208:211], v[12:15]
	v_mfma_f32_16x16x32_bf16 v[8:11], v[158:161], v[208:211], v[8:11]
	v_mfma_f32_16x16x32_bf16 v[60:63], v[148:151], v[188:191], v[60:63]
	v_mfma_f32_16x16x32_bf16 v[56:59], v[162:165], v[188:191], v[56:59]
	v_mfma_f32_16x16x32_bf16 v[44:47], v[148:151], v[196:199], v[44:47]
	v_mfma_f32_16x16x32_bf16 v[40:43], v[162:165], v[196:199], v[40:43]
	v_mfma_f32_16x16x32_bf16 v[28:31], v[148:151], v[204:207], v[28:31]
	v_mfma_f32_16x16x32_bf16 v[24:27], v[162:165], v[204:207], v[24:27]
	v_mfma_f32_16x16x32_bf16 v[12:15], v[148:151], v[212:215], v[12:15]
	v_mfma_f32_16x16x32_bf16 v[8:11], v[162:165], v[212:215], v[8:11]
	s_setprio 0
	s_setprio 1
	v_mfma_f32_16x16x32_bf16 v[52:55], v[166:169], v[184:187], v[52:55]
	v_mfma_f32_16x16x32_bf16 v[48:51], v[174:177], v[184:187], v[48:51]
	v_mfma_f32_16x16x32_bf16 v[36:39], v[166:169], v[192:195], v[36:39]
	v_mfma_f32_16x16x32_bf16 v[32:35], v[174:177], v[192:195], v[32:35]
	v_mfma_f32_16x16x32_bf16 v[20:23], v[166:169], v[200:203], v[20:23]
	v_mfma_f32_16x16x32_bf16 v[16:19], v[174:177], v[200:203], v[16:19]
	v_mfma_f32_16x16x32_bf16 v[4:7], v[166:169], v[208:211], v[4:7]
	v_mfma_f32_16x16x32_bf16 v[0:3], v[174:177], v[208:211], v[0:3]
	v_mfma_f32_16x16x32_bf16 v[52:55], v[170:173], v[188:191], v[52:55]
	v_mfma_f32_16x16x32_bf16 v[48:51], v[180:183], v[188:191], v[48:51]
	v_mfma_f32_16x16x32_bf16 v[36:39], v[170:173], v[196:199], v[36:39]
	v_mfma_f32_16x16x32_bf16 v[32:35], v[180:183], v[196:199], v[32:35]
	v_mfma_f32_16x16x32_bf16 v[20:23], v[170:173], v[204:207], v[20:23]
	v_mfma_f32_16x16x32_bf16 v[16:19], v[180:183], v[204:207], v[16:19]
	v_mfma_f32_16x16x32_bf16 v[4:7], v[170:173], v[212:215], v[4:7]
	v_mfma_f32_16x16x32_bf16 v[0:3], v[180:183], v[212:215], v[0:3]
	s_setprio 0
	s_barrier
	s_add_u32 s44, s44, 0x100
	s_addc_u32 s45, s45, 0
	s_add_u32 s7, s7, 0x100
	s_addc_u32 s31, s31, 0
	s_cmp_ge_i32 s41, s55
	s_mov_b32 s35, s41
	s_cbranch_scc0 .LBB0_119
	v_readlane_b32 s72, v250, 29
	s_and_b64 vcc, exec, s[24:25]
	s_cbranch_vccz .LBB0_122

; #define PG8_STAGE(bufoff, gbase, voff) do { _Pragma("unroll") for (int _i = 0; _i < 2; ++_i) \
;         __builtin_amdgcn_global_load_lds((const unsigned*)((const char*)(gbase) + (voff)[_i]), (PG8_LAS unsigned*)(lds + (bufoff) + ldsw + _i * 8192), 16, 0, 0); } while (0)
; #define PG8_LDA(dst, b, h) do { _Pragma("unroll") for (int m = 0; m < 4; ++m) _Pragma("unroll") for (int k = 0; k < 2; ++k) dst[m][k] = *(const PG8_LAS bf16x8*)(lds + PG8_SA(b, h) + aoff + m * 2048 + k * 1024); } while (0)
; #define PG8_LDB(dst, b, h) do { _Pragma("unroll") for (int n = 0; n < 2; ++n) _Pragma("unroll") for (int k = 0; k < 2; ++k) dst[n][k] = *(const PG8_LAS bf16x8*)(lds + PG8_SB(b, h) + boff + n * 2048 + k * 1024); } while (0)
; #define PG8_MMA(ai, bj, At, Bt) do { __builtin_amdgcn_s_setprio(1); _Pragma("unroll") for (int m = 0; m < 4; ++m) _Pragma("unroll") for (int n = 0; n < 2; ++n) _Pragma("unroll") for (int k = 0; k < 2; ++k) \
;         acc[ai][bj][m][n] = __builtin_amdgcn_mfma_f32_16x16x32_bf16(Bt[n][k], At[m][k], acc[ai][bj][m][n], 0, 0, 0); __builtin_amdgcn_s_setprio(0); } while (0)
; #define PG8_WAIT_V(n) asm volatile("s_waitcnt vmcnt(" #n ")" ::: "memory")
; #define PG8_WAIT_L(n) asm volatile("s_waitcnt lgkmcnt(" #n ")" ::: "memory")
; #define PG8_BAR __builtin_amdgcn_s_barrier()
; #define PG8_SCHED __builtin_amdgcn_sched_barrier(0)
; template <class Epi, class Sched, bool ALIGN_EPI = false, bool SP2 = false>
; __device__ __forceinline__ void gemm_phase(PG8_LAS unsigned char* lds, const Gemm g, const Sched& S, const Epi& E, const int wid) {
;     ...
;             PG8_LDB(B0, 0, 0); PG8_LDB(B1, 0, 1); PG8_SCHED; PG8_LDA(At, 0, 0); PG8_STAGE(PG8_SA(1, 1), a1 + hstepA, voffA);
;             PG8_WAIT_V(8); PG8_WAIT_L(0); PG8_BAR; PG8_MMA(0, 0, At, B0); PG8_MMA(0, 1, At, B1); PG8_BAR; PG8_SCHED;
;             PG8_LDA(At, 0, 1); PG8_STAGE(PG8_SB(0, 0), b2, voffB); PG8_STAGE(PG8_SB(0, 1), b2 + hstepB, voffB); PG8_STAGE(PG8_SA(0, 0), a2, voffA);
.LBB0_270:
	ds_read_b128 v[60:63], v182
	ds_read_b128 v[68:71], v182 offset:1024
	ds_read_b128 v[72:75], v182 offset:2048
	ds_read_b128 v[76:79], v182 offset:3072
	ds_read_b128 v[80:83], v183
	ds_read_b128 v[84:87], v183 offset:1024
	ds_read_b128 v[172:175], v183 offset:2048
	ds_read_b128 v[186:189], v183 offset:3072
	s_add_i32 s68, s46, 2
	s_add_u32 s47, s44, 0xfffc0080
	s_addc_u32 s48, s45, -1
	s_cmp_eq_u32 s63, s46
	s_cselect_b32 s46, s6, s35
	s_cselect_b32 s49, s39, s48
	s_cselect_b32 s48, s38, s47
	s_cselect_b32 s47, s7, s37
	v_lshl_add_u64 v[176:177], s[44:45], 0, v[162:163]
	s_add_i32 m0, s41, 0xc000
	ds_read_b128 v[190:193], v184
	ds_read_b128 v[194:197], v184 offset:1024
	ds_read_b128 v[198:201], v184 offset:2048
	ds_read_b128 v[202:205], v184 offset:3072
	ds_read_b128 v[206:209], v184 offset:4096
	ds_read_b128 v[210:213], v184 offset:5120
	ds_read_b128 v[214:217], v184 offset:6144
	ds_read_b128 v[218:221], v184 offset:7168
	global_load_lds_dwordx4 v[176:177], off
	v_lshl_add_u64 v[176:177], s[44:45], 0, v[164:165]
	s_add_i32 m0, s41, 0xe000
	s_nop 0
	global_load_lds_dwordx4 v[176:177], off
	s_waitcnt vmcnt(8)
	s_waitcnt lgkmcnt(0)
	s_barrier
	s_setprio 1
	v_mfma_f32_16x16x32_bf16 v[148:151], v[60:63], v[190:193], v[148:151]
	v_mfma_f32_16x16x32_bf16 v[140:143], v[72:75], v[190:193], v[140:143]
	v_mfma_f32_16x16x32_bf16 v[132:135], v[60:63], v[198:201], v[132:135]
	v_mfma_f32_16x16x32_bf16 v[124:127], v[72:75], v[198:201], v[124:127]
	v_mfma_f32_16x16x32_bf16 v[116:119], v[60:63], v[206:209], v[116:119]
	v_mfma_f32_16x16x32_bf16 v[108:111], v[72:75], v[206:209], v[108:111]
	v_mfma_f32_16x16x32_bf16 v[100:103], v[60:63], v[214:217], v[100:103]
	v_mfma_f32_16x16x32_bf16 v[92:95], v[72:75], v[214:217], v[92:95]
	v_mfma_f32_16x16x32_bf16 v[148:151], v[68:71], v[194:197], v[148:151]
	v_mfma_f32_16x16x32_bf16 v[140:143], v[76:79], v[194:197], v[140:143]
	v_mfma_f32_16x16x32_bf16 v[132:135], v[68:71], v[202:205], v[132:135]
	v_mfma_f32_16x16x32_bf16 v[124:127], v[76:79], v[202:205], v[124:127]
	v_mfma_f32_16x16x32_bf16 v[116:119], v[68:71], v[210:213], v[116:119]
	v_mfma_f32_16x16x32_bf16 v[108:111], v[76:79], v[210:213], v[108:111]
	v_mfma_f32_16x16x32_bf16 v[100:103], v[68:71], v[218:221], v[100:103]
	v_mfma_f32_16x16x32_bf16 v[92:95], v[76:79], v[218:221], v[92:95]
	s_setprio 0
	s_setprio 1
	v_mfma_f32_16x16x32_bf16 v[144:147], v[80:83], v[190:193], v[144:147]
	v_mfma_f32_16x16x32_bf16 v[136:139], v[172:175], v[190:193], v[136:139]
	v_mfma_f32_16x16x32_bf16 v[128:131], v[80:83], v[198:201], v[128:131]
	v_mfma_f32_16x16x32_bf16 v[120:123], v[172:175], v[198:201], v[120:123]
	v_mfma_f32_16x16x32_bf16 v[112:115], v[80:83], v[206:209], v[112:115]
	v_mfma_f32_16x16x32_bf16 v[104:107], v[172:175], v[206:209], v[104:107]
	v_mfma_f32_16x16x32_bf16 v[96:99], v[80:83], v[214:217], v[96:99]
	v_mfma_f32_16x16x32_bf16 v[88:91], v[172:175], v[214:217], v[88:91]
	v_mfma_f32_16x16x32_bf16 v[144:147], v[84:87], v[194:197], v[144:147]
	v_mfma_f32_16x16x32_bf16 v[136:139], v[186:189], v[194:197], v[136:139]
	v_mfma_f32_16x16x32_bf16 v[128:131], v[84:87], v[202:205], v[128:131]
	v_mfma_f32_16x16x32_bf16 v[120:123], v[186:189], v[202:205], v[120:123]
	v_mfma_f32_16x16x32_bf16 v[112:115], v[84:87], v[210:213], v[112:115]
	v_mfma_f32_16x16x32_bf16 v[104:107], v[186:189], v[210:213], v[104:107]
	v_mfma_f32_16x16x32_bf16 v[96:99], v[84:87], v[218:221], v[96:99]
	v_mfma_f32_16x16x32_bf16 v[88:91], v[186:189], v[218:221], v[88:91]
	s_setprio 0
	s_barrier
	s_add_i32 s69, s64, s0
	v_lshl_add_u64 v[176:177], s[46:47], 0, v[154:155]
	s_mov_b32 m0, s69
	ds_read_b128 v[190:193], v184 offset:16384
	ds_read_b128 v[194:197], v184 offset:17408
	ds_read_b128 v[198:201], v184 offset:18432
	ds_read_b128 v[202:205], v184 offset:19456
	ds_read_b128 v[206:209], v184 offset:20480
	ds_read_b128 v[210:213], v184 offset:21504
	ds_read_b128 v[214:217], v184 offset:22528
	ds_read_b128 v[218:221], v184 offset:23552
	global_load_lds_dwordx4 v[176:177], off
	s_add_i32 m0, s69, 0x2000
	s_add_u32 s70, s46, 0x10000
	v_lshl_add_u64 v[222:223], s[46:47], 0, v[158:159]
	s_addc_u32 s71, s47, 0
	s_add_i32 s69, s65, s0
	global_load_lds_dwordx4 v[222:223], off
	v_lshl_add_u64 v[224:225], s[70:71], 0, v[154:155]
	s_mov_b32 m0, s69
	v_lshl_add_u64 v[226:227], s[48:49], 0, v[156:157]
	global_load_lds_dwordx4 v[224:225], off
	v_lshl_add_u64 v[224:225], s[70:71], 0, v[158:159]
	s_add_i32 m0, s69, 0x2000
	s_nop 0
	global_load_lds_dwordx4 v[224:225], off
	v_lshl_add_u64 v[224:225], s[48:49], 0, v[152:153]
	s_mov_b32 m0, s41
	s_nop 0
	global_load_lds_dwordx4 v[224:225], off
	s_mov_b32 m0, s57
	s_nop 0
	global_load_lds_dwordx4 v[226:227], off
	s_waitcnt vmcnt(8)
	s_waitcnt lgkmcnt(0)
	s_barrier
; #define PG8_STAGE(bufoff, gbase, voff) do { _Pragma("unroll") for (int _i = 0; _i < 2; ++_i) \
;         __builtin_amdgcn_global_load_lds((const unsigned*)((const char*)(gbase) + (voff)[_i]), (PG8_LAS unsigned*)(lds + (bufoff) + ldsw + _i * 8192), 16, 0, 0); } while (0)
; #define PG8_LDA(dst, b, h) do { _Pragma("unroll") for (int m = 0; m < 4; ++m) _Pragma("unroll") for (int k = 0; k < 2; ++k) dst[m][k] = *(const PG8_LAS bf16x8*)(lds + PG8_SA(b, h) + aoff + m * 2048 + k * 1024); } while (0)
; #define PG8_LDB(dst, b, h) do { _Pragma("unroll") for (int n = 0; n < 2; ++n) _Pragma("unroll") for (int k = 0; k < 2; ++k) dst[n][k] = *(const PG8_LAS bf16x8*)(lds + PG8_SB(b, h) + boff + n * 2048 + k * 1024); } while (0)
; #define PG8_MMA(ai, bj, At, Bt) do { __builtin_amdgcn_s_setprio(1); _Pragma("unroll") for (int m = 0; m < 4; ++m) _Pragma("unroll") for (int n = 0; n < 2; ++n) _Pragma("unroll") for (int k = 0; k < 2; ++k) \
;         acc[ai][bj][m][n] = __builtin_amdgcn_mfma_f32_16x16x32_bf16(Bt[n][k], At[m][k], acc[ai][bj][m][n], 0, 0, 0); __builtin_amdgcn_s_setprio(0); } while (0)
; #define PG8_WAIT_V(n) asm volatile("s_waitcnt vmcnt(" #n ")" ::: "memory")
; #define PG8_WAIT_L(n) asm volatile("s_waitcnt lgkmcnt(" #n ")" ::: "memory")
; #define PG8_BAR __builtin_amdgcn_s_barrier()
; #define PG8_SCHED __builtin_amdgcn_sched_barrier(0)
; template <class Epi, class Sched, bool ALIGN_EPI = false, bool SP2 = false>
; __device__ __forceinline__ void gemm_phase(PG8_LAS unsigned char* lds, const Gemm g, const Sched& S, const Epi& E, const int wid) {
;     ...
;             PG8_WAIT_V(8); PG8_WAIT_L(0); PG8_BAR; PG8_MMA(1, 0, At, B0); PG8_MMA(1, 1, At, B1); PG8_BAR; PG8_SCHED;
;             PG8_LDB(B0, 1, 0); PG8_LDB(B1, 1, 1); PG8_SCHED; PG8_LDA(At, 1, 0); PG8_STAGE(PG8_SA(0, 1), a2 + hstepA, voffA);
;             PG8_WAIT_V(8); PG8_WAIT_L(0); PG8_BAR; PG8_MMA(0, 0, At, B0); PG8_MMA(0, 1, At, B1); PG8_BAR; PG8_SCHED;
	s_setprio 1
	v_mfma_f32_16x16x32_bf16 v[64:67], v[60:63], v[190:193], v[64:67]
	v_mfma_f32_16x16x32_bf16 v[52:55], v[72:75], v[190:193], v[52:55]
	v_mfma_f32_16x16x32_bf16 v[44:47], v[60:63], v[198:201], v[44:47]
	v_mfma_f32_16x16x32_bf16 v[36:39], v[72:75], v[198:201], v[36:39]
	v_mfma_f32_16x16x32_bf16 v[28:31], v[60:63], v[206:209], v[28:31]
	v_mfma_f32_16x16x32_bf16 v[20:23], v[72:75], v[206:209], v[20:23]
	v_mfma_f32_16x16x32_bf16 v[12:15], v[60:63], v[214:217], v[12:15]
	v_mfma_f32_16x16x32_bf16 v[4:7], v[72:75], v[214:217], v[4:7]
	v_mfma_f32_16x16x32_bf16 v[64:67], v[68:71], v[194:197], v[64:67]
	v_mfma_f32_16x16x32_bf16 v[52:55], v[76:79], v[194:197], v[52:55]
	v_mfma_f32_16x16x32_bf16 v[44:47], v[68:71], v[202:205], v[44:47]
	v_mfma_f32_16x16x32_bf16 v[36:39], v[76:79], v[202:205], v[36:39]
	v_mfma_f32_16x16x32_bf16 v[28:31], v[68:71], v[210:213], v[28:31]
	v_mfma_f32_16x16x32_bf16 v[20:23], v[76:79], v[210:213], v[20:23]
	v_mfma_f32_16x16x32_bf16 v[12:15], v[68:71], v[218:221], v[12:15]
	v_mfma_f32_16x16x32_bf16 v[4:7], v[76:79], v[218:221], v[4:7]
	s_setprio 0
	s_setprio 1
	v_mfma_f32_16x16x32_bf16 v[56:59], v[80:83], v[190:193], v[56:59]
	v_mfma_f32_16x16x32_bf16 v[48:51], v[172:175], v[190:193], v[48:51]
	v_mfma_f32_16x16x32_bf16 v[40:43], v[80:83], v[198:201], v[40:43]
	v_mfma_f32_16x16x32_bf16 v[32:35], v[172:175], v[198:201], v[32:35]
	v_mfma_f32_16x16x32_bf16 v[24:27], v[80:83], v[206:209], v[24:27]
	v_mfma_f32_16x16x32_bf16 v[16:19], v[172:175], v[206:209], v[16:19]
	v_mfma_f32_16x16x32_bf16 v[8:11], v[80:83], v[214:217], v[8:11]
	v_mfma_f32_16x16x32_bf16 v[0:3], v[172:175], v[214:217], v[0:3]
	v_mfma_f32_16x16x32_bf16 v[56:59], v[84:87], v[194:197], v[56:59]
	v_mfma_f32_16x16x32_bf16 v[48:51], v[186:189], v[194:197], v[48:51]
	v_mfma_f32_16x16x32_bf16 v[40:43], v[84:87], v[202:205], v[40:43]
	v_mfma_f32_16x16x32_bf16 v[32:35], v[186:189], v[202:205], v[32:35]
	v_mfma_f32_16x16x32_bf16 v[24:27], v[84:87], v[210:213], v[24:27]
	v_mfma_f32_16x16x32_bf16 v[16:19], v[186:189], v[210:213], v[16:19]
	v_mfma_f32_16x16x32_bf16 v[8:11], v[84:87], v[218:221], v[8:11]
	v_mfma_f32_16x16x32_bf16 v[0:3], v[186:189], v[218:221], v[0:3]
	s_setprio 0
	s_barrier
	s_add_i32 s69, 0, 0x18000
	s_add_i32 s70, 0, 0x1c000
	v_add_u32_e32 v76, s69, v179
	v_add_u32_e32 v160, s70, v179
	ds_read_b128 v[60:63], v76
	ds_read_b128 v[68:71], v76 offset:1024
	ds_read_b128 v[72:75], v76 offset:2048
	ds_read_b128 v[76:79], v76 offset:3072
	ds_read_b128 v[80:83], v160
	ds_read_b128 v[84:87], v160 offset:1024
	ds_read_b128 v[172:175], v160 offset:2048
	ds_read_b128 v[186:189], v160 offset:3072
	s_add_u32 s48, s48, 0x40000
	s_addc_u32 s49, s49, 0
	s_mov_b32 m0, s58
	v_lshl_add_u64 v[228:229], s[48:49], 0, v[152:153]
	ds_read_b128 v[190:193], v184 offset:32768
	ds_read_b128 v[194:197], v184 offset:33792
	ds_read_b128 v[198:201], v184 offset:34816
	ds_read_b128 v[202:205], v184 offset:35840
	ds_read_b128 v[206:209], v184 offset:36864
	ds_read_b128 v[210:213], v184 offset:37888
	ds_read_b128 v[214:217], v184 offset:38912
	ds_read_b128 v[218:221], v184 offset:39936
	global_load_lds_dwordx4 v[228:229], off
	v_lshl_add_u64 v[228:229], s[48:49], 0, v[156:157]
	s_mov_b32 m0, s59
	s_nop 0
	global_load_lds_dwordx4 v[228:229], off
	s_waitcnt vmcnt(8)
	s_waitcnt lgkmcnt(0)
	s_barrier
	s_setprio 1
	v_mfma_f32_16x16x32_bf16 v[148:151], v[60:63], v[190:193], v[148:151]
	v_mfma_f32_16x16x32_bf16 v[140:143], v[72:75], v[190:193], v[140:143]
	v_mfma_f32_16x16x32_bf16 v[132:135], v[60:63], v[198:201], v[132:135]
	v_mfma_f32_16x16x32_bf16 v[124:127], v[72:75], v[198:201], v[124:127]
	v_mfma_f32_16x16x32_bf16 v[116:119], v[60:63], v[206:209], v[116:119]
	v_mfma_f32_16x16x32_bf16 v[108:111], v[72:75], v[206:209], v[108:111]
	v_mfma_f32_16x16x32_bf16 v[100:103], v[60:63], v[214:217], v[100:103]
	v_mfma_f32_16x16x32_bf16 v[92:95], v[72:75], v[214:217], v[92:95]
	v_mfma_f32_16x16x32_bf16 v[148:151], v[68:71], v[194:197], v[148:151]
	v_mfma_f32_16x16x32_bf16 v[140:143], v[76:79], v[194:197], v[140:143]
	v_mfma_f32_16x16x32_bf16 v[132:135], v[68:71], v[202:205], v[132:135]
	v_mfma_f32_16x16x32_bf16 v[124:127], v[76:79], v[202:205], v[124:127]
	v_mfma_f32_16x16x32_bf16 v[116:119], v[68:71], v[210:213], v[116:119]
	v_mfma_f32_16x16x32_bf16 v[108:111], v[76:79], v[210:213], v[108:111]
	v_mfma_f32_16x16x32_bf16 v[100:103], v[68:71], v[218:221], v[100:103]
	v_mfma_f32_16x16x32_bf16 v[92:95], v[76:79], v[218:221], v[92:95]
	s_setprio 0
	s_setprio 1
	v_mfma_f32_16x16x32_bf16 v[144:147], v[80:83], v[190:193], v[144:147]
	v_mfma_f32_16x16x32_bf16 v[136:139], v[172:175], v[190:193], v[136:139]
	v_mfma_f32_16x16x32_bf16 v[128:131], v[80:83], v[198:201], v[128:131]
	v_mfma_f32_16x16x32_bf16 v[120:123], v[172:175], v[198:201], v[120:123]
	v_mfma_f32_16x16x32_bf16 v[112:115], v[80:83], v[206:209], v[112:115]
	v_mfma_f32_16x16x32_bf16 v[104:107], v[172:175], v[206:209], v[104:107]
	v_mfma_f32_16x16x32_bf16 v[96:99], v[80:83], v[214:217], v[96:99]
	v_mfma_f32_16x16x32_bf16 v[88:91], v[172:175], v[214:217], v[88:91]
	v_mfma_f32_16x16x32_bf16 v[144:147], v[84:87], v[194:197], v[144:147]
	v_mfma_f32_16x16x32_bf16 v[136:139], v[186:189], v[194:197], v[136:139]
	v_mfma_f32_16x16x32_bf16 v[128:131], v[84:87], v[202:205], v[128:131]
	v_mfma_f32_16x16x32_bf16 v[120:123], v[186:189], v[202:205], v[120:123]
	v_mfma_f32_16x16x32_bf16 v[112:115], v[84:87], v[210:213], v[112:115]
	v_mfma_f32_16x16x32_bf16 v[104:107], v[186:189], v[210:213], v[104:107]
	v_mfma_f32_16x16x32_bf16 v[96:99], v[84:87], v[218:221], v[96:99]
	v_mfma_f32_16x16x32_bf16 v[88:91], v[186:189], v[218:221], v[88:91]
	s_setprio 0
	s_barrier
; #define PG8_STAGE(bufoff, gbase, voff) do { _Pragma("unroll") for (int _i = 0; _i < 2; ++_i) \
;         __builtin_amdgcn_global_load_lds((const unsigned*)((const char*)(gbase) + (voff)[_i]), (PG8_LAS unsigned*)(lds + (bufoff) + ldsw + _i * 8192), 16, 0, 0); } while (0)
; #define PG8_LDA(dst, b, h) do { _Pragma("unroll") for (int m = 0; m < 4; ++m) _Pragma("unroll") for (int k = 0; k < 2; ++k) dst[m][k] = *(const PG8_LAS bf16x8*)(lds + PG8_SA(b, h) + aoff + m * 2048 + k * 1024); } while (0)
; #define PG8_MMA(ai, bj, At, Bt) do { __builtin_amdgcn_s_setprio(1); _Pragma("unroll") for (int m = 0; m < 4; ++m) _Pragma("unroll") for (int n = 0; n < 2; ++n) _Pragma("unroll") for (int k = 0; k < 2; ++k) \
;         acc[ai][bj][m][n] = __builtin_amdgcn_mfma_f32_16x16x32_bf16(Bt[n][k], At[m][k], acc[ai][bj][m][n], 0, 0, 0); __builtin_amdgcn_s_setprio(0); } while (0)
; #define PG8_WAIT_V(n) asm volatile("s_waitcnt vmcnt(" #n ")" ::: "memory")
; #define PG8_WAIT_L(n) asm volatile("s_waitcnt lgkmcnt(" #n ")" ::: "memory")
; #define PG8_BAR __builtin_amdgcn_s_barrier()
; #define PG8_SCHED __builtin_amdgcn_sched_barrier(0)
; template <class Epi, class Sched, bool ALIGN_EPI = false, bool SP2 = false>
; __device__ __forceinline__ void gemm_phase(PG8_LAS unsigned char* lds, const Gemm g, const Sched& S, const Epi& E, const int wid) {
;     ...
;         for (int t = 0; t < nt; t += 2) {
;     ...
;             PG8_LDA(At, 1, 1); PG8_STAGE(PG8_SB(1, 0), b3, voffB); PG8_STAGE(PG8_SB(1, 1), b3 + hstepB, voffB); PG8_STAGE(PG8_SA(1, 0), a3, voffA);
;             PG8_WAIT_V(8); PG8_WAIT_L(0); PG8_BAR; PG8_MMA(1, 0, At, B0); PG8_MMA(1, 1, At, B1); PG8_BAR; PG8_SCHED;
	s_add_i32 s48, s69, s0
	v_lshl_add_u64 v[176:177], v[176:177], 0, s[22:23]
	s_mov_b32 m0, s48
	ds_read_b128 v[190:193], v184 offset:49152
	ds_read_b128 v[194:197], v184 offset:50176
	ds_read_b128 v[198:201], v184 offset:51200
	ds_read_b128 v[202:205], v184 offset:52224
	ds_read_b128 v[206:209], v184 offset:53248
	ds_read_b128 v[210:213], v184 offset:54272
	ds_read_b128 v[214:217], v184 offset:55296
	ds_read_b128 v[218:221], v184 offset:56320
	global_load_lds_dwordx4 v[176:177], off
	s_add_i32 m0, s48, 0x2000
	s_add_u32 s46, s46, 0x10080
	v_lshl_add_u64 v[176:177], v[222:223], 0, s[22:23]
	s_addc_u32 s47, s47, 0
	s_add_i32 s48, s70, s0
	global_load_lds_dwordx4 v[176:177], off
	v_lshl_add_u64 v[176:177], s[46:47], 0, v[154:155]
	s_mov_b32 m0, s48
	s_nop 0
	global_load_lds_dwordx4 v[176:177], off
	v_lshl_add_u64 v[176:177], s[46:47], 0, v[158:159]
	s_add_i32 m0, s48, 0x2000
	s_nop 0
	global_load_lds_dwordx4 v[176:177], off
	v_lshl_add_u64 v[176:177], v[224:225], 0, s[22:23]
	s_mov_b32 m0, s61
	s_nop 0
	global_load_lds_dwordx4 v[176:177], off
	v_lshl_add_u64 v[176:177], v[226:227], 0, s[22:23]
	s_mov_b32 m0, s62
	s_nop 0
	global_load_lds_dwordx4 v[176:177], off
	s_waitcnt vmcnt(8)
	s_waitcnt lgkmcnt(0)
	s_barrier
	s_setprio 1
	v_mfma_f32_16x16x32_bf16 v[64:67], v[60:63], v[190:193], v[64:67]
	v_mfma_f32_16x16x32_bf16 v[52:55], v[72:75], v[190:193], v[52:55]
	v_mfma_f32_16x16x32_bf16 v[44:47], v[60:63], v[198:201], v[44:47]
	v_mfma_f32_16x16x32_bf16 v[36:39], v[72:75], v[198:201], v[36:39]
	v_mfma_f32_16x16x32_bf16 v[28:31], v[60:63], v[206:209], v[28:31]
	v_mfma_f32_16x16x32_bf16 v[20:23], v[72:75], v[206:209], v[20:23]
	v_mfma_f32_16x16x32_bf16 v[12:15], v[60:63], v[214:217], v[12:15]
	v_mfma_f32_16x16x32_bf16 v[4:7], v[72:75], v[214:217], v[4:7]
	v_mfma_f32_16x16x32_bf16 v[64:67], v[68:71], v[194:197], v[64:67]
	v_mfma_f32_16x16x32_bf16 v[52:55], v[76:79], v[194:197], v[52:55]
	v_mfma_f32_16x16x32_bf16 v[44:47], v[68:71], v[202:205], v[44:47]
	v_mfma_f32_16x16x32_bf16 v[36:39], v[76:79], v[202:205], v[36:39]
	v_mfma_f32_16x16x32_bf16 v[28:31], v[68:71], v[210:213], v[28:31]
	v_mfma_f32_16x16x32_bf16 v[20:23], v[76:79], v[210:213], v[20:23]
	v_mfma_f32_16x16x32_bf16 v[12:15], v[68:71], v[218:221], v[12:15]
	v_mfma_f32_16x16x32_bf16 v[4:7], v[76:79], v[218:221], v[4:7]
	s_setprio 0
	s_setprio 1
	v_mfma_f32_16x16x32_bf16 v[56:59], v[80:83], v[190:193], v[56:59]
	v_mfma_f32_16x16x32_bf16 v[48:51], v[172:175], v[190:193], v[48:51]
	v_mfma_f32_16x16x32_bf16 v[40:43], v[80:83], v[198:201], v[40:43]
	v_mfma_f32_16x16x32_bf16 v[32:35], v[172:175], v[198:201], v[32:35]
	v_mfma_f32_16x16x32_bf16 v[24:27], v[80:83], v[206:209], v[24:27]
	v_mfma_f32_16x16x32_bf16 v[16:19], v[172:175], v[206:209], v[16:19]
	v_mfma_f32_16x16x32_bf16 v[8:11], v[80:83], v[214:217], v[8:11]
	v_mfma_f32_16x16x32_bf16 v[0:3], v[172:175], v[214:217], v[0:3]
	v_mfma_f32_16x16x32_bf16 v[56:59], v[84:87], v[194:197], v[56:59]
	v_mfma_f32_16x16x32_bf16 v[48:51], v[186:189], v[194:197], v[48:51]
	v_mfma_f32_16x16x32_bf16 v[40:43], v[84:87], v[202:205], v[40:43]
	v_mfma_f32_16x16x32_bf16 v[32:35], v[186:189], v[202:205], v[32:35]
	v_mfma_f32_16x16x32_bf16 v[24:27], v[84:87], v[210:213], v[24:27]
	v_mfma_f32_16x16x32_bf16 v[16:19], v[186:189], v[210:213], v[16:19]
	v_mfma_f32_16x16x32_bf16 v[8:11], v[84:87], v[218:221], v[8:11]
	v_mfma_f32_16x16x32_bf16 v[0:3], v[186:189], v[218:221], v[0:3]
	s_setprio 0
	s_barrier
	s_add_u32 s44, s44, 0x100
	s_addc_u32 s45, s45, 0
	s_add_u32 s35, s35, 0x100
	s_addc_u32 s37, s37, 0
	s_cmp_ge_i32 s68, s54
	s_mov_b32 s46, s68
	s_cbranch_scc0 .LBB0_270
	s_and_b64 vcc, exec, s[30:31]
	s_cbranch_vccz .LBB0_273

; __device__ __forceinline__ unsigned pk_f16(float lo, float hi) { f32x2 v = {lo, hi}; return __builtin_bit_cast(unsigned, __builtin_convertvector(v, f16v2)); }
; __device__ __forceinline__ float bf_lo(unsigned w) { return __uint_as_float(w << 16); }
; __device__ __forceinline__ float bf_hi(unsigned w) { return __uint_as_float(w & 0xffff0000u); }
; __device__ __forceinline__ float fast_sigmoid(float v) { return __builtin_amdgcn_rcpf(1.0f + __builtin_amdgcn_exp2f(-v * LOG2E)); }
;     __device__ __forceinline__ void operator()(const AccT& acc, const Unit& u, int wr, int wc, int fr, int fq) const {
;         const int ch0 = (u.pn >> 1) * 256 + (u.pn & 1) * 128 + wc * 32 + 8 * fq, row0 = u.pm * BM + wr * 64 + fr;
;         f32x4 br[2], bi[2], c8[2];
; #pragma unroll
;         for (int n = 0; n < 2; ++n) { br[n] = *(const f32x4*)(b_r + ch0 + 4 * n); bi[n] = *(const f32x4*)(b_i + ch0 + 4 * n); c8[n] = *(const f32x4*)(c8t + ch0 + 4 * n); }
; #pragma unroll
;         for (int ai = 0; ai < 2; ++ai)
; #pragma unroll
;             for (int m = 0; m < 4; ++m) { const unsigned off = (unsigned)(row0 + ai * HALF + m * 16) * DM + ch0;
;                 const u32x4 xw = *(const u32x4*)(xc + off);
;                 const float xv[8] = {bf_lo(xw.x), bf_hi(xw.x), bf_lo(xw.y), bf_hi(xw.y), bf_lo(xw.z), bf_hi(xw.z), bf_lo(xw.w), bf_hi(xw.w)};
;                 u32x4 pk[2];
; #pragma unroll
;                 for (int n = 0; n < 2; ++n)
; #pragma unroll
;                     for (int e = 0; e < 4; ++e) {
;                         const float rr = fast_sigmoid(acc[ai][0][m][n][e] + br[n][e]), ii = fast_sigmoid(acc[ai][1][m][n][e] + bi[n][e]);
;                         const float la = c8[n][e] * rr, a = __builtin_amdgcn_exp2f(la * LOG2E), x2 = 2.0f * la;
;                         const float ser = -x2 * (1.0f + x2 * (0.5f + x2 * (0.16666667f + x2 * 0.041666668f)));
;                         const float m2 = x2 > -0.06f ? ser : 1.0f - a * a;
;                         pk[n][e] = pk_f16(la * (LOG2E * 1024.0f), __builtin_amdgcn_sqrtf(fmaxf(m2, 0.f)) * (ii * xv[4 * n + e])); }
.LBB0_273:
	v_lshl_add_u32 v60, s67, 7, v180
	s_lshl_b32 s35, s40, 18
	v_add3_u32 v160, s35, v181, v60
	v_ashrrev_i32_e32 v61, 31, v60
	v_readlane_b32 s68, v250, 2
	v_lshl_add_u64 v[62:63], v[160:161], 1, s[12:13]
	v_lshlrev_b64 v[60:61], 2, v[60:61]
	v_readlane_b32 s70, v250, 4
	v_readlane_b32 s71, v250, 5
	global_load_dwordx4 v[186:189], v[62:63], off
	s_mov_b64 s[98:99], 0x8000
	v_lshl_add_u64 v[228:229], v[62:63], 0, s[98:99]
	global_load_dwordx4 v[200:203], v[228:229], off
	s_mov_b64 s[98:99], 0x10000
	v_lshl_add_u64 v[228:229], v[62:63], 0, s[98:99]
	global_load_dwordx4 v[204:207], v[228:229], off
	s_mov_b64 s[98:99], 0x18000
	v_lshl_add_u64 v[228:229], v[62:63], 0, s[98:99]
	global_load_dwordx4 v[208:211], v[228:229], off
	s_mov_b64 s[98:99], 0x40000
	v_lshl_add_u64 v[228:229], v[62:63], 0, s[98:99]
	global_load_dwordx4 v[212:215], v[228:229], off
	s_mov_b64 s[98:99], 0x48000
	v_lshl_add_u64 v[228:229], v[62:63], 0, s[98:99]
	global_load_dwordx4 v[216:219], v[228:229], off
	s_mov_b64 s[98:99], 0x50000
	v_lshl_add_u64 v[228:229], v[62:63], 0, s[98:99]
	global_load_dwordx4 v[220:223], v[228:229], off
	s_mov_b64 s[98:99], 0x58000
	v_lshl_add_u64 v[228:229], v[62:63], 0, s[98:99]
	global_load_dwordx4 v[224:227], v[228:229], off
	v_lshl_add_u64 v[62:63], s[26:27], 0, v[60:61]
	v_lshl_add_u64 v[68:69], s[70:71], 0, v[60:61]
	v_lshl_add_u64 v[60:61], s[10:11], 0, v[60:61]
	global_load_dwordx4 v[84:87], v[62:63], off
	global_load_dwordx4 v[80:83], v[68:69], off
	global_load_dwordx4 v[76:79], v[60:61], off
	global_load_dwordx4 v[72:75], v[62:63], off offset:16
	s_nop 0
	global_load_dwordx4 v[68:71], v[68:69], off offset:16
	s_nop 0
	global_load_dwordx4 v[60:63], v[60:61], off offset:16
	v_readlane_b32 s69, v250, 3
	v_readlane_b32 s72, v250, 6
	v_readlane_b32 s73, v250, 7
	v_readlane_b32 s74, v250, 8
	v_readlane_b32 s75, v250, 9
	v_readlane_b32 s76, v250, 10
	v_readlane_b32 s77, v250, 11
	v_readlane_b32 s78, v250, 12
	v_readlane_b32 s79, v250, 13
	v_readlane_b32 s80, v250, 14
	v_readlane_b32 s81, v250, 15
	v_readlane_b32 s82, v250, 16
	v_readlane_b32 s83, v250, 17
	s_waitcnt vmcnt(0)
	v_add_f32_e32 v171, v148, v84
	v_add_f32_e32 v172, v144, v80
	v_add_f32_e32 v145, v145, v81
	v_mul_f32_e32 v171, 0xbfb8aa3b, v171
	v_mul_f32_e32 v172, 0xbfb8aa3b, v172
	v_mul_f32_e32 v145, 0xbfb8aa3b, v145
	v_exp_f32_e32 v171, v171
	v_exp_f32_e32 v172, v172
	v_exp_f32_e32 v145, v145
	v_add_f32_e32 v149, v149, v85
	v_mul_f32_e32 v149, 0xbfb8aa3b, v149
	v_exp_f32_e32 v149, v149
	v_add_f32_e32 v171, 1.0, v171
	v_add_f32_e32 v172, 1.0, v172
	v_lshlrev_b32_e32 v191, 16, v186
	v_and_b32_e32 v193, 0xffff0000, v186
	v_add_f32_e32 v186, 1.0, v145
	v_rcp_f32_e32 v190, v171
	v_rcp_f32_e32 v145, v172
	v_add_f32_e32 v174, v150, v86
	v_add_f32_e32 v176, v146, v82
	v_add_f32_e32 v151, v151, v87
	v_add_f32_e32 v147, v147, v83
	v_mul_f32_e32 v174, 0xbfb8aa3b, v174
	v_mul_f32_e32 v176, 0xbfb8aa3b, v176
	v_mov_b32_e32 v144, v76
	v_mul_f32_e32 v151, 0xbfb8aa3b, v151
	v_mul_f32_e32 v147, 0xbfb8aa3b, v147
	v_exp_f32_e32 v174, v174
	v_exp_f32_e32 v176, v176
	v_add_f32_e32 v149, 1.0, v149
	v_exp_f32_e32 v151, v151
	v_exp_f32_e32 v147, v147
	v_rcp_f32_e32 v192, v149
	v_rcp_f32_e32 v149, v186
	v_pk_mul_f32 v[144:145], v[144:145], v[190:191]
	v_mov_b32_e32 v148, v77
	v_mul_f32_e32 v171, 0x3fb8aa3b, v144
	v_add_f32_e32 v172, v144, v144
	v_exp_f32_e32 v171, v171
	v_add_f32_e32 v174, 1.0, v174
	v_add_f32_e32 v176, 1.0, v176
	v_fmamk_f32 v190, v172, 0x3d2aaaab, v185
	v_lshlrev_b32_e32 v197, 16, v188
	v_and_b32_e32 v177, 0xffff0000, v188
	v_add_f32_e32 v151, 1.0, v151
	v_add_f32_e32 v188, 1.0, v147
	v_rcp_f32_e32 v194, v174
	v_rcp_f32_e32 v147, v176
	v_pk_mul_f32 v[148:149], v[148:149], v[192:193]
	v_fma_f32 v190, v172, v190, 0.5
	v_rcp_f32_e32 v186, v151
	v_rcp_f32_e32 v151, v188
	v_mul_f32_e32 v174, 0x3fb8aa3b, v148
	v_fma_f32 v190, v172, v190, 1.0
	v_add_f32_e32 v176, v148, v148
	v_exp_f32_e32 v174, v174
	v_mul_f32_e64 v190, v190, -v172
	v_fma_f32 v171, -v171, v171, 1.0
	v_cmp_lt_f32_e32 vcc, s66, v172
	v_lshlrev_b32_e32 v195, 16, v187
	v_mov_b32_e32 v146, v78
	v_fmamk_f32 v191, v176, 0x3d2aaaab, v185
	v_cndmask_b32_e32 v171, v171, v190, vcc
	v_and_b32_e32 v187, 0xffff0000, v187
	v_mov_b32_e32 v150, v79
	v_pk_mul_f32 v[146:147], v[146:147], v[194:195]
	v_fma_f32 v191, v176, v191, 0.5
	v_max_f32_e32 v171, 0, v171
	v_pk_mul_f32 v[150:151], v[150:151], v[186:187]
	v_mul_f32_e32 v186, 0x3fb8aa3b, v146
	v_fma_f32 v191, v176, v191, 1.0
	v_sqrt_f32_e32 v171, v171
	v_add_f32_e32 v187, v146, v146
	v_exp_f32_e32 v186, v186
	v_mul_f32_e64 v191, v191, -v176
	v_fma_f32 v174, -v174, v174, 1.0
	v_cmp_lt_f32_e32 vcc, s66, v176
	v_fmamk_f32 v192, v187, 0x3d2aaaab, v185
	v_fma_f32 v192, v187, v192, 0.5
	v_cndmask_b32_e32 v172, v174, v191, vcc
	v_max_f32_e32 v172, 0, v172
	v_fma_f32 v192, v187, v192, 1.0
	v_pk_mul_f32 v[144:145], v[144:145], v[170:171]
	v_sqrt_f32_e32 v171, v172
	v_mul_f32_e64 v192, v192, -v187
	v_fma_f32 v186, -v186, v186, 1.0
	v_cmp_lt_f32_e32 vcc, s66, v187
	v_mul_f32_e32 v188, 0x3fb8aa3b, v150
	v_lshlrev_b32_e32 v175, 16, v189
	v_cndmask_b32_e32 v172, v186, v192, vcc
	v_max_f32_e32 v172, 0, v172
	v_and_b32_e32 v173, 0xffff0000, v189
	v_add_f32_e32 v189, v150, v150
	v_exp_f32_e32 v188, v188
	v_pk_mul_f32 v[148:149], v[148:149], v[170:171]
	v_sqrt_f32_e32 v171, v172
	v_add_f32_e32 v140, v140, v72
	v_add_f32_e32 v136, v136, v68
	v_fmamk_f32 v172, v189, 0x3d2aaaab, v185
	v_mul_f32_e32 v140, 0xbfb8aa3b, v140
	v_mul_f32_e32 v136, 0xbfb8aa3b, v136
	v_fma_f32 v172, v189, v172, 0.5
	v_exp_f32_e32 v140, v140
	v_exp_f32_e32 v136, v136
	v_fma_f32 v172, v189, v172, 1.0
	v_pk_mul_f32 v[146:147], v[146:147], v[170:171]
; __device__ __forceinline__ unsigned pk_f16(float lo, float hi) { f32x2 v = {lo, hi}; return __builtin_bit_cast(unsigned, __builtin_convertvector(v, f16v2)); }
; __device__ __forceinline__ float bf_lo(unsigned w) { return __uint_as_float(w << 16); }
; __device__ __forceinline__ float bf_hi(unsigned w) { return __uint_as_float(w & 0xffff0000u); }
; __device__ __forceinline__ float fast_sigmoid(float v) { return __builtin_amdgcn_rcpf(1.0f + __builtin_amdgcn_exp2f(-v * LOG2E)); }
;     __device__ __forceinline__ void operator()(const AccT& acc, const Unit& u, int wr, int wc, int fr, int fq) const {
;     ...
;             for (int m = 0; m < 4; ++m) { const unsigned off = (unsigned)(row0 + ai * HALF + m * 16) * DM + ch0;
;                 const u32x4 xw = *(const u32x4*)(xc + off);
;                 const float xv[8] = {bf_lo(xw.x), bf_hi(xw.x), bf_lo(xw.y), bf_hi(xw.y), bf_lo(xw.z), bf_hi(xw.z), bf_lo(xw.w), bf_hi(xw.w)};
;                 u32x4 pk[2];
; #pragma unroll
;                 for (int n = 0; n < 2; ++n)
; #pragma unroll
;                     for (int e = 0; e < 4; ++e) {
;                         const float rr = fast_sigmoid(acc[ai][0][m][n][e] + br[n][e]), ii = fast_sigmoid(acc[ai][1][m][n][e] + bi[n][e]);
;                         const float la = c8[n][e] * rr, a = __builtin_amdgcn_exp2f(la * LOG2E), x2 = 2.0f * la;
;                         const float ser = -x2 * (1.0f + x2 * (0.5f + x2 * (0.16666667f + x2 * 0.041666668f)));
;                         const float m2 = x2 > -0.06f ? ser : 1.0f - a * a;
;                         pk[n][e] = pk_f16(la * (LOG2E * 1024.0f), __builtin_amdgcn_sqrtf(fmaxf(m2, 0.f)) * (ii * xv[4 * n + e])); }
;                 *(u32x4*)(au_out + off) = pk[0]; *(u32x4*)(au_out + off + 4) = pk[1];
	v_mul_f32_e64 v171, v172, -v189
	v_fma_f32 v172, -v188, v188, 1.0
	v_cmp_lt_f32_e32 vcc, s66, v189
	v_add_f32_e32 v140, 1.0, v140
	v_add_f32_e32 v136, 1.0, v136
	v_cndmask_b32_e32 v171, v172, v171, vcc
	v_max_f32_e32 v171, 0, v171
	v_sqrt_f32_e32 v171, v171
	v_rcp_f32_e32 v196, v140
	v_rcp_f32_e32 v187, v136
	v_mov_b32_e32 v186, v60
	v_cvt_pk_f16_f32 v136, v144, v145
	v_pk_mul_f32 v[144:145], v[150:151], v[170:171]
	v_pk_mul_f32 v[150:151], v[186:187], v[196:197]
	v_add_f32_e32 v141, v141, v73
	v_mul_f32_e32 v140, 0x3fb8aa3b, v150
	v_exp_f32_e32 v140, v140
	v_add_f32_e32 v171, v150, v150
	v_fmamk_f32 v172, v171, 0x3d2aaaab, v185
	v_add_f32_e32 v137, v137, v69
	v_fma_f32 v172, v171, v172, 0.5
	v_mul_f32_e32 v141, 0xbfb8aa3b, v141
	v_mul_f32_e32 v137, 0xbfb8aa3b, v137
	v_fma_f32 v172, v171, v172, 1.0
	v_exp_f32_e32 v141, v141
	v_exp_f32_e32 v137, v137
	v_mul_f32_e64 v172, v172, -v171
	v_fma_f32 v140, -v140, v140, 1.0
	v_cmp_lt_f32_e32 vcc, s66, v171
	v_add_f32_e32 v137, 1.0, v137
	v_add_f32_e32 v142, v142, v74
	v_cndmask_b32_e32 v140, v140, v172, vcc
	v_max_f32_e32 v140, 0, v140
	v_sqrt_f32_e32 v171, v140
	v_add_f32_e32 v140, 1.0, v141
	v_rcp_f32_e32 v176, v140
	v_rcp_f32_e32 v141, v137
	v_mov_b32_e32 v140, v61
	v_cvt_pk_f16_f32 v137, v148, v149
	v_pk_mul_f32 v[148:149], v[150:151], v[170:171]
	v_pk_mul_f32 v[140:141], v[140:141], v[176:177]
	v_add_f32_e32 v138, v138, v70
	v_mul_f32_e32 v150, 0x3fb8aa3b, v140
	v_exp_f32_e32 v150, v150
	v_add_f32_e32 v151, v140, v140
	v_fmamk_f32 v171, v151, 0x3d2aaaab, v185
	v_mul_f32_e32 v142, 0xbfb8aa3b, v142
	v_mul_f32_e32 v138, 0xbfb8aa3b, v138
	v_fma_f32 v171, v151, v171, 0.5
	v_exp_f32_e32 v142, v142
	v_exp_f32_e32 v138, v138
	v_fma_f32 v171, v151, v171, 1.0
	v_mul_f32_e64 v171, v171, -v151
	v_fma_f32 v150, -v150, v150, 1.0
	v_cmp_lt_f32_e32 vcc, s66, v151
	v_add_f32_e32 v142, 1.0, v142
	v_add_f32_e32 v138, 1.0, v138
	v_cndmask_b32_e32 v150, v150, v171, vcc
	v_max_f32_e32 v150, 0, v150
	v_sqrt_f32_e32 v171, v150
	v_rcp_f32_e32 v174, v142
	v_rcp_f32_e32 v151, v138
	v_mov_b32_e32 v150, v62
	v_cvt_pk_f16_f32 v138, v146, v147
	v_pk_mul_f32 v[146:147], v[140:141], v[170:171]
	v_pk_mul_f32 v[140:141], v[150:151], v[174:175]
	v_add_f32_e32 v143, v143, v75
	v_mul_f32_e32 v142, 0x3fb8aa3b, v140
	v_exp_f32_e32 v142, v142
	v_add_f32_e32 v150, v140, v140
	v_fmamk_f32 v151, v150, 0x3d2aaaab, v185
	v_add_f32_e32 v139, v139, v71
	v_fma_f32 v151, v150, v151, 0.5
	v_mul_f32_e32 v143, 0xbfb8aa3b, v143
	v_mul_f32_e32 v139, 0xbfb8aa3b, v139
	v_fma_f32 v151, v150, v151, 1.0
	v_exp_f32_e32 v143, v143
	v_exp_f32_e32 v139, v139
	v_mul_f32_e64 v151, v151, -v150
	v_fma_f32 v142, -v142, v142, 1.0
	v_cmp_lt_f32_e32 vcc, s66, v150
	v_add_f32_e32 v139, 1.0, v139
	v_add_f32_e32 v132, v132, v84
	v_cndmask_b32_e32 v142, v142, v151, vcc
	v_max_f32_e32 v142, 0, v142
	v_sqrt_f32_e32 v171, v142
	v_add_f32_e32 v142, 1.0, v143
	v_rcp_f32_e32 v172, v142
	v_rcp_f32_e32 v143, v139
	v_mov_b32_e32 v142, v63
	v_cvt_pk_f16_f32 v139, v144, v145
	v_pk_mul_f32 v[144:145], v[140:141], v[170:171]
	v_pk_mul_f32 v[150:151], v[142:143], v[172:173]
	v_add_f32_e32 v128, v128, v80
	v_mul_f32_e32 v140, 0x3fb8aa3b, v150
	v_exp_f32_e32 v140, v140
	v_add_f32_e32 v141, v150, v150
	v_fmamk_f32 v142, v141, 0x3d2aaaab, v185
	v_fma_f32 v142, v141, v142, 0.5
	v_fma_f32 v142, v141, v142, 1.0
	v_mul_f32_e64 v142, v142, -v141
	v_fma_f32 v140, -v140, v140, 1.0
	v_cmp_lt_f32_e32 vcc, s66, v141
	v_cvt_pk_f16_f32 v141, v146, v147
	v_mul_f32_e32 v132, 0xbfb8aa3b, v132
	v_cndmask_b32_e32 v140, v140, v142, vcc
	v_max_f32_e32 v140, 0, v140
	v_sqrt_f32_e32 v171, v140
	v_cvt_pk_f16_f32 v142, v144, v145
	v_cvt_pk_f16_f32 v140, v148, v149
	v_mul_f32_e32 v128, 0xbfb8aa3b, v128
	v_pk_mul_f32 v[144:145], v[150:151], v[170:171]
	v_exp_f32_e32 v132, v132
	v_cvt_pk_f16_f32 v143, v144, v145
	v_lshl_add_u64 v[144:145], v[160:161], 2, s[18:19]
	global_store_dwordx4 v[144:145], v[136:139], off
	global_store_dwordx4 v[144:145], v[140:143], off offset:16
	v_exp_f32_e32 v128, v128
	v_add_u32_e32 v136, 0x4000, v160
	v_mov_b32_e32 v137, v161
	v_lshl_add_u64 v[138:139], v[136:137], 1, s[12:13]
	v_mov_b32_e32 v138, v200
	v_mov_b32_e32 v139, v201
	v_mov_b32_e32 v140, v202
	v_mov_b32_e32 v141, v203
	v_add_f32_e32 v132, 1.0, v132
	v_add_f32_e32 v128, 1.0, v128
	v_rcp_f32_e32 v142, v132
	v_rcp_f32_e32 v149, v128
	v_mov_b32_e32 v148, v76
	v_add_f32_e32 v129, v129, v81
	v_mul_f32_e32 v129, 0xbfb8aa3b, v129
	v_exp_f32_e32 v129, v129
	v_add_f32_e32 v134, v134, v86
	v_add_f32_e32 v130, v130, v82
	v_mul_f32_e32 v134, 0xbfb8aa3b, v134
	v_mul_f32_e32 v130, 0xbfb8aa3b, v130
	v_exp_f32_e32 v134, v134
	v_exp_f32_e32 v130, v130
	v_add_f32_e32 v131, v131, v83
	v_mul_f32_e32 v131, 0xbfb8aa3b, v131
	v_exp_f32_e32 v131, v131
	v_add_f32_e32 v130, 1.0, v130
	v_add_f32_e32 v124, v124, v72
	v_add_f32_e32 v120, v120, v68
	v_mul_f32_e32 v124, 0xbfb8aa3b, v124
	v_mul_f32_e32 v120, 0xbfb8aa3b, v120
	v_exp_f32_e32 v124, v124
	v_exp_f32_e32 v120, v120
	v_add_f32_e32 v125, v125, v73
	v_add_f32_e32 v121, v121, v69
	v_add_f32_e32 v124, 1.0, v124
	v_add_f32_e32 v120, 1.0, v120
	v_rcp_f32_e32 v150, v124
	v_mul_f32_e32 v125, 0xbfb8aa3b, v125
	v_mul_f32_e32 v121, 0xbfb8aa3b, v121
	v_exp_f32_e32 v125, v125
	v_exp_f32_e32 v121, v121
	v_add_f32_e32 v126, v126, v74
	v_add_f32_e32 v122, v122, v70
	v_mul_f32_e32 v126, 0xbfb8aa3b, v126
	v_add_f32_e32 v121, 1.0, v121
	v_mul_f32_e32 v122, 0xbfb8aa3b, v122
	v_exp_f32_e32 v126, v126
	v_exp_f32_e32 v122, v122
	v_add_f32_e32 v127, v127, v75
	v_add_f32_e32 v123, v123, v71
	v_add_f32_e32 v126, 1.0, v126
	v_add_f32_e32 v122, 1.0, v122
	v_mul_f32_e32 v127, 0xbfb8aa3b, v127
	v_mul_f32_e32 v123, 0xbfb8aa3b, v123
; __device__ __forceinline__ unsigned pk_f16(float lo, float hi) { f32x2 v = {lo, hi}; return __builtin_bit_cast(unsigned, __builtin_convertvector(v, f16v2)); }
; __device__ __forceinline__ float bf_lo(unsigned w) { return __uint_as_float(w << 16); }
; __device__ __forceinline__ float bf_hi(unsigned w) { return __uint_as_float(w & 0xffff0000u); }
; __device__ __forceinline__ float fast_sigmoid(float v) { return __builtin_amdgcn_rcpf(1.0f + __builtin_amdgcn_exp2f(-v * LOG2E)); }
;     __device__ __forceinline__ void operator()(const AccT& acc, const Unit& u, int wr, int wc, int fr, int fq) const {
;     ...
;             for (int m = 0; m < 4; ++m) { const unsigned off = (unsigned)(row0 + ai * HALF + m * 16) * DM + ch0;
;                 const u32x4 xw = *(const u32x4*)(xc + off);
;                 const float xv[8] = {bf_lo(xw.x), bf_hi(xw.x), bf_lo(xw.y), bf_hi(xw.y), bf_lo(xw.z), bf_hi(xw.z), bf_lo(xw.w), bf_hi(xw.w)};
;                 u32x4 pk[2];
; #pragma unroll
;                 for (int n = 0; n < 2; ++n)
; #pragma unroll
;                     for (int e = 0; e < 4; ++e) {
;                         const float rr = fast_sigmoid(acc[ai][0][m][n][e] + br[n][e]), ii = fast_sigmoid(acc[ai][1][m][n][e] + bi[n][e]);
;                         const float la = c8[n][e] * rr, a = __builtin_amdgcn_exp2f(la * LOG2E), x2 = 2.0f * la;
;                         const float ser = -x2 * (1.0f + x2 * (0.5f + x2 * (0.16666667f + x2 * 0.041666668f)));
;                         const float m2 = x2 > -0.06f ? ser : 1.0f - a * a;
;                         pk[n][e] = pk_f16(la * (LOG2E * 1024.0f), __builtin_amdgcn_sqrtf(fmaxf(m2, 0.f)) * (ii * xv[4 * n + e])); }
;                 *(u32x4*)(au_out + off) = pk[0]; *(u32x4*)(au_out + off + 4) = pk[1];
	v_exp_f32_e32 v127, v127
	v_exp_f32_e32 v123, v123
	v_add_f32_e32 v116, v116, v84
	v_add_f32_e32 v112, v112, v80
	v_mul_f32_e32 v116, 0xbfb8aa3b, v116
	v_add_f32_e32 v123, 1.0, v123
	v_mul_f32_e32 v112, 0xbfb8aa3b, v112
	v_exp_f32_e32 v116, v116
	v_exp_f32_e32 v112, v112
	v_add_f32_e32 v113, v113, v81
	v_mul_f32_e32 v113, 0xbfb8aa3b, v113
	v_add_f32_e32 v116, 1.0, v116
	v_add_f32_e32 v112, 1.0, v112
	v_exp_f32_e32 v113, v113
	v_add_f32_e32 v118, v118, v86
	v_add_f32_e32 v114, v114, v82
	v_mul_f32_e32 v118, 0xbfb8aa3b, v118
	v_mul_f32_e32 v114, 0xbfb8aa3b, v114
	v_exp_f32_e32 v118, v118
	v_exp_f32_e32 v114, v114
	v_add_f32_e32 v115, v115, v83
	v_mul_f32_e32 v115, 0xbfb8aa3b, v115
	v_exp_f32_e32 v115, v115
	v_add_f32_e32 v114, 1.0, v114
	v_add_f32_e32 v108, v108, v72
	v_add_f32_e32 v104, v104, v68
	v_mul_f32_e32 v108, 0xbfb8aa3b, v108
	v_mul_f32_e32 v104, 0xbfb8aa3b, v104
	v_exp_f32_e32 v108, v108
	v_exp_f32_e32 v104, v104
	v_add_f32_e32 v109, v109, v73
	v_add_f32_e32 v105, v105, v69
	v_add_f32_e32 v108, 1.0, v108
	s_nop 0
	v_lshlrev_b32_e32 v143, 16, v138
	v_pk_mul_f32 v[142:143], v[148:149], v[142:143]
	v_and_b32_e32 v145, 0xffff0000, v138
	v_add_f32_e32 v132, v142, v142
	v_fmamk_f32 v138, v132, 0x3d2aaaab, v185
	v_mul_f32_e32 v128, 0x3fb8aa3b, v142
	v_fma_f32 v138, v132, v138, 0.5
	v_exp_f32_e32 v128, v128
	v_fma_f32 v138, v132, v138, 1.0
	v_mul_f32_e64 v138, v138, -v132
	v_cmp_lt_f32_e32 vcc, s66, v132
	v_add_f32_e32 v132, v133, v85
	v_mul_f32_e32 v132, 0xbfb8aa3b, v132
	v_exp_f32_e32 v132, v132
	v_fma_f32 v128, -v128, v128, 1.0
	v_cndmask_b32_e32 v128, v128, v138, vcc
	v_max_f32_e32 v128, 0, v128
	v_sqrt_f32_e32 v171, v128
	v_add_f32_e32 v128, 1.0, v132
	v_rcp_f32_e32 v144, v128
	v_add_f32_e32 v128, 1.0, v129
	v_rcp_f32_e32 v129, v128
	v_mov_b32_e32 v128, v77
	v_lshlrev_b32_e32 v151, 16, v140
	v_and_b32_e32 v133, 0xffff0000, v140
	v_pk_mul_f32 v[128:129], v[128:129], v[144:145]
	v_pk_mul_f32 v[142:143], v[142:143], v[170:171]
	v_mul_f32_e32 v132, 0x3fb8aa3b, v128
	v_exp_f32_e32 v132, v132
	v_add_f32_e32 v138, v128, v128
	v_fmamk_f32 v140, v138, 0x3d2aaaab, v185
	v_fma_f32 v140, v138, v140, 0.5
	v_fma_f32 v140, v138, v140, 1.0
	v_mul_f32_e64 v140, v140, -v138
	v_fma_f32 v132, -v132, v132, 1.0
	v_cmp_lt_f32_e32 vcc, s66, v138
	v_rcp_f32_e32 v145, v130
	v_lshlrev_b32_e32 v147, 16, v139
	v_cndmask_b32_e32 v132, v132, v140, vcc
	v_max_f32_e32 v132, 0, v132
	v_sqrt_f32_e32 v171, v132
	v_add_f32_e32 v132, 1.0, v134
	v_rcp_f32_e32 v146, v132
	v_mov_b32_e32 v144, v78
	v_pk_mul_f32 v[128:129], v[128:129], v[170:171]
	v_and_b32_e32 v139, 0xffff0000, v139
	v_pk_mul_f32 v[144:145], v[144:145], v[146:147]
	v_lshlrev_b32_e32 v149, 16, v141
	v_add_f32_e32 v132, v144, v144
	v_fmamk_f32 v134, v132, 0x3d2aaaab, v185
	v_mul_f32_e32 v130, 0x3fb8aa3b, v144
	v_fma_f32 v134, v132, v134, 0.5
	v_exp_f32_e32 v130, v130
	v_fma_f32 v134, v132, v134, 1.0
	v_mul_f32_e64 v134, v134, -v132
	v_cmp_lt_f32_e32 vcc, s66, v132
	v_add_f32_e32 v132, v135, v87
	v_mul_f32_e32 v132, 0xbfb8aa3b, v132
	v_exp_f32_e32 v132, v132
	v_fma_f32 v130, -v130, v130, 1.0
	v_cndmask_b32_e32 v130, v130, v134, vcc
	v_max_f32_e32 v130, 0, v130
	v_sqrt_f32_e32 v171, v130
	v_add_f32_e32 v130, 1.0, v132
	v_rcp_f32_e32 v138, v130
	v_add_f32_e32 v130, 1.0, v131
	v_rcp_f32_e32 v131, v130
	v_mov_b32_e32 v130, v79
	v_and_b32_e32 v135, 0xffff0000, v141
	v_pk_mul_f32 v[140:141], v[144:145], v[170:171]
	v_pk_mul_f32 v[130:131], v[130:131], v[138:139]
	v_rcp_f32_e32 v139, v120
	v_mul_f32_e32 v132, 0x3fb8aa3b, v130
	v_exp_f32_e32 v132, v132
	v_add_f32_e32 v134, v130, v130
	v_fmamk_f32 v138, v134, 0x3d2aaaab, v185
	v_fma_f32 v138, v134, v138, 0.5
	v_fma_f32 v138, v134, v138, 1.0
	v_mul_f32_e64 v138, v138, -v134
	v_fma_f32 v132, -v132, v132, 1.0
	v_cmp_lt_f32_e32 vcc, s66, v134
	v_rcp_f32_e32 v148, v126
	v_cvt_pk_f16_f32 v120, v142, v143
	v_cndmask_b32_e32 v132, v132, v138, vcc
	v_mov_b32_e32 v138, v60
	v_pk_mul_f32 v[138:139], v[138:139], v[150:151]
	v_max_f32_e32 v132, 0, v132
	v_mul_f32_e32 v124, 0x3fb8aa3b, v138
	v_sqrt_f32_e32 v171, v132
	v_exp_f32_e32 v124, v124
	v_add_f32_e32 v132, v138, v138
	v_fmamk_f32 v134, v132, 0x3d2aaaab, v185
	v_fma_f32 v134, v132, v134, 0.5
	v_fma_f32 v134, v132, v134, 1.0
	v_mul_f32_e64 v134, v134, -v132
	v_fma_f32 v124, -v124, v124, 1.0
	v_cmp_lt_f32_e32 vcc, s66, v132
	v_pk_mul_f32 v[130:131], v[130:131], v[170:171]
	v_add_f32_e32 v104, 1.0, v104
	v_cndmask_b32_e32 v124, v124, v134, vcc
	v_max_f32_e32 v124, 0, v124
	v_sqrt_f32_e32 v171, v124
	v_add_f32_e32 v124, 1.0, v125
	v_rcp_f32_e32 v132, v124
	v_rcp_f32_e32 v125, v121
	v_mov_b32_e32 v124, v61
	v_cvt_pk_f16_f32 v121, v128, v129
	v_pk_mul_f32 v[128:129], v[138:139], v[170:171]
	v_pk_mul_f32 v[124:125], v[124:125], v[132:133]
	v_mul_f32_e32 v109, 0xbfb8aa3b, v109
	v_mul_f32_e32 v132, 0x3fb8aa3b, v124
	v_exp_f32_e32 v132, v132
	v_add_f32_e32 v133, v124, v124
	v_fmamk_f32 v134, v133, 0x3d2aaaab, v185
	v_fma_f32 v134, v133, v134, 0.5
	v_fma_f32 v134, v133, v134, 1.0
	v_mul_f32_e64 v134, v134, -v133
	v_fma_f32 v132, -v132, v132, 1.0
	v_cmp_lt_f32_e32 vcc, s66, v133
	v_rcp_f32_e32 v133, v122
	v_cvt_pk_f16_f32 v122, v140, v141
	v_cndmask_b32_e32 v132, v132, v134, vcc
	v_max_f32_e32 v132, 0, v132
	v_sqrt_f32_e32 v171, v132
	v_mov_b32_e32 v132, v62
	v_mul_f32_e32 v105, 0xbfb8aa3b, v105
	v_exp_f32_e32 v109, v109
	v_pk_mul_f32 v[138:139], v[124:125], v[170:171]
	v_pk_mul_f32 v[124:125], v[132:133], v[148:149]
	v_exp_f32_e32 v105, v105
	v_mul_f32_e32 v126, 0x3fb8aa3b, v124
	v_exp_f32_e32 v126, v126
	v_add_f32_e32 v132, v124, v124
	v_fmamk_f32 v133, v132, 0x3d2aaaab, v185
	v_fma_f32 v133, v132, v133, 0.5
	v_fma_f32 v133, v132, v133, 1.0
; __device__ __forceinline__ unsigned pk_f16(float lo, float hi) { f32x2 v = {lo, hi}; return __builtin_bit_cast(unsigned, __builtin_convertvector(v, f16v2)); }
; __device__ __forceinline__ float bf_lo(unsigned w) { return __uint_as_float(w << 16); }
; __device__ __forceinline__ float bf_hi(unsigned w) { return __uint_as_float(w & 0xffff0000u); }
; __device__ __forceinline__ float fast_sigmoid(float v) { return __builtin_amdgcn_rcpf(1.0f + __builtin_amdgcn_exp2f(-v * LOG2E)); }
;     __device__ __forceinline__ void operator()(const AccT& acc, const Unit& u, int wr, int wc, int fr, int fq) const {
;     ...
;             for (int m = 0; m < 4; ++m) { const unsigned off = (unsigned)(row0 + ai * HALF + m * 16) * DM + ch0;
;                 const u32x4 xw = *(const u32x4*)(xc + off);
;                 const float xv[8] = {bf_lo(xw.x), bf_hi(xw.x), bf_lo(xw.y), bf_hi(xw.y), bf_lo(xw.z), bf_hi(xw.z), bf_lo(xw.w), bf_hi(xw.w)};
;                 u32x4 pk[2];
; #pragma unroll
;                 for (int n = 0; n < 2; ++n)
; #pragma unroll
;                     for (int e = 0; e < 4; ++e) {
;                         const float rr = fast_sigmoid(acc[ai][0][m][n][e] + br[n][e]), ii = fast_sigmoid(acc[ai][1][m][n][e] + bi[n][e]);
;                         const float la = c8[n][e] * rr, a = __builtin_amdgcn_exp2f(la * LOG2E), x2 = 2.0f * la;
;                         const float ser = -x2 * (1.0f + x2 * (0.5f + x2 * (0.16666667f + x2 * 0.041666668f)));
;                         const float m2 = x2 > -0.06f ? ser : 1.0f - a * a;
;                         pk[n][e] = pk_f16(la * (LOG2E * 1024.0f), __builtin_amdgcn_sqrtf(fmaxf(m2, 0.f)) * (ii * xv[4 * n + e])); }
;                 *(u32x4*)(au_out + off) = pk[0]; *(u32x4*)(au_out + off + 4) = pk[1];
	v_mul_f32_e64 v133, v133, -v132
	v_fma_f32 v126, -v126, v126, 1.0
	v_cmp_lt_f32_e32 vcc, s66, v132
	v_add_f32_e32 v105, 1.0, v105
	v_add_f32_e32 v110, v110, v74
	v_cndmask_b32_e32 v126, v126, v133, vcc
	v_max_f32_e32 v126, 0, v126
	v_sqrt_f32_e32 v171, v126
	v_add_f32_e32 v126, 1.0, v127
	v_rcp_f32_e32 v134, v126
	v_rcp_f32_e32 v127, v123
	v_mov_b32_e32 v126, v63
	v_cvt_pk_f16_f32 v123, v130, v131
	v_pk_mul_f32 v[130:131], v[124:125], v[170:171]
	v_pk_mul_f32 v[132:133], v[126:127], v[134:135]
	v_rcp_f32_e32 v134, v108
	v_mul_f32_e32 v124, 0x3fb8aa3b, v132
	v_exp_f32_e32 v124, v124
	v_add_f32_e32 v125, v132, v132
	v_fmamk_f32 v126, v125, 0x3d2aaaab, v185
	v_fma_f32 v126, v125, v126, 0.5
	v_fma_f32 v126, v125, v126, 1.0
	v_mul_f32_e64 v126, v126, -v125
	v_fma_f32 v124, -v124, v124, 1.0
	v_cmp_lt_f32_e32 vcc, s66, v125
	v_cvt_pk_f16_f32 v125, v138, v139
	v_add_f32_e32 v106, v106, v70
	v_cndmask_b32_e32 v124, v124, v126, vcc
	v_max_f32_e32 v124, 0, v124
	v_sqrt_f32_e32 v171, v124
	v_cvt_pk_f16_f32 v124, v128, v129
	v_cvt_pk_f16_f32 v126, v130, v131
	v_mul_f32_e32 v110, 0xbfb8aa3b, v110
	v_pk_mul_f32 v[128:129], v[132:133], v[170:171]
	v_rcp_f32_e32 v133, v112
	v_cvt_pk_f16_f32 v127, v128, v129
	v_lshl_add_u64 v[128:129], v[136:137], 2, s[18:19]
	global_store_dwordx4 v[128:129], v[120:123], off
	global_store_dwordx4 v[128:129], v[124:127], off offset:16
	v_mov_b32_e32 v132, v76
	v_add_u32_e32 v120, 0x8000, v160
	v_mov_b32_e32 v121, v161
	v_lshl_add_u64 v[122:123], v[120:121], 1, s[12:13]
	v_mov_b32_e32 v122, v204
	v_mov_b32_e32 v123, v205
	v_mov_b32_e32 v124, v206
	v_mov_b32_e32 v125, v207
	v_rcp_f32_e32 v126, v116
	v_mul_f32_e32 v106, 0xbfb8aa3b, v106
	v_exp_f32_e32 v110, v110
	v_exp_f32_e32 v106, v106
	v_add_f32_e32 v111, v111, v75
	v_add_f32_e32 v107, v107, v71
	v_add_f32_e32 v110, 1.0, v110
	v_add_f32_e32 v106, 1.0, v106
	v_mul_f32_e32 v111, 0xbfb8aa3b, v111
	v_mul_f32_e32 v107, 0xbfb8aa3b, v107
	v_exp_f32_e32 v111, v111
	v_exp_f32_e32 v107, v107
	v_add_f32_e32 v100, v100, v84
	v_add_f32_e32 v96, v96, v80
	v_mul_f32_e32 v100, 0xbfb8aa3b, v100
	v_add_f32_e32 v107, 1.0, v107
	v_mul_f32_e32 v96, 0xbfb8aa3b, v96
	v_exp_f32_e32 v100, v100
	v_exp_f32_e32 v96, v96
	v_add_f32_e32 v97, v97, v81
	v_mul_f32_e32 v97, 0xbfb8aa3b, v97
	v_add_f32_e32 v100, 1.0, v100
	v_add_f32_e32 v96, 1.0, v96
	v_exp_f32_e32 v97, v97
	v_add_f32_e32 v102, v102, v86
	v_add_f32_e32 v98, v98, v82
	v_mul_f32_e32 v102, 0xbfb8aa3b, v102
	v_mul_f32_e32 v98, 0xbfb8aa3b, v98
	v_exp_f32_e32 v102, v102
	v_exp_f32_e32 v98, v98
	v_add_f32_e32 v99, v99, v83
	v_mul_f32_e32 v99, 0xbfb8aa3b, v99
	v_exp_f32_e32 v99, v99
	v_add_f32_e32 v98, 1.0, v98
	v_add_f32_e32 v92, v92, v72
	v_add_f32_e32 v88, v88, v68
	v_mul_f32_e32 v92, 0xbfb8aa3b, v92
	v_mul_f32_e32 v88, 0xbfb8aa3b, v88
	v_exp_f32_e32 v92, v92
	v_exp_f32_e32 v88, v88
	v_add_f32_e32 v93, v93, v73
	v_add_f32_e32 v89, v89, v69
	v_add_f32_e32 v92, 1.0, v92
	v_add_f32_e32 v88, 1.0, v88
	v_mul_f32_e32 v93, 0xbfb8aa3b, v93
	v_mul_f32_e32 v89, 0xbfb8aa3b, v89
	v_exp_f32_e32 v93, v93
	v_exp_f32_e32 v89, v89
	v_add_f32_e32 v94, v94, v74
	v_add_f32_e32 v90, v90, v70
	v_mul_f32_e32 v94, 0xbfb8aa3b, v94
	v_add_f32_e32 v89, 1.0, v89
	v_mul_f32_e32 v90, 0xbfb8aa3b, v90
	v_exp_f32_e32 v94, v94
	v_exp_f32_e32 v90, v90
	v_add_f32_e32 v95, v95, v75
	v_add_f32_e32 v91, v91, v71
	v_add_f32_e32 v94, 1.0, v94
	v_add_f32_e32 v90, 1.0, v90
	v_mul_f32_e32 v95, 0xbfb8aa3b, v95
	v_mul_f32_e32 v91, 0xbfb8aa3b, v91
	v_exp_f32_e32 v95, v95
	v_exp_f32_e32 v91, v91
	v_add_f32_e32 v64, v64, v84
	v_add_f32_e32 v56, v56, v80
	v_mul_f32_e32 v64, 0xbfb8aa3b, v64
	v_add_f32_e32 v91, 1.0, v91
	v_mul_f32_e32 v56, 0xbfb8aa3b, v56
	v_exp_f32_e32 v64, v64
	v_exp_f32_e32 v56, v56
	v_add_f32_e32 v57, v57, v81
	v_mul_f32_e32 v57, 0xbfb8aa3b, v57
	v_add_f32_e32 v64, 1.0, v64
	v_add_f32_e32 v56, 1.0, v56
	v_exp_f32_e32 v57, v57
	v_add_f32_e32 v66, v66, v86
	v_add_f32_e32 v58, v58, v82
	v_mul_f32_e32 v66, 0xbfb8aa3b, v66
	v_mul_f32_e32 v58, 0xbfb8aa3b, v58
	s_nop 0
	v_lshlrev_b32_e32 v127, 16, v122
	v_pk_mul_f32 v[126:127], v[132:133], v[126:127]
	v_and_b32_e32 v129, 0xffff0000, v122
	v_add_f32_e32 v116, v126, v126
	v_fmamk_f32 v122, v116, 0x3d2aaaab, v185
	v_mul_f32_e32 v112, 0x3fb8aa3b, v126
	v_fma_f32 v122, v116, v122, 0.5
	v_exp_f32_e32 v112, v112
	v_fma_f32 v122, v116, v122, 1.0
	v_mul_f32_e64 v122, v122, -v116
	v_cmp_lt_f32_e32 vcc, s66, v116
	v_add_f32_e32 v116, v117, v85
	v_mul_f32_e32 v116, 0xbfb8aa3b, v116
	v_exp_f32_e32 v116, v116
	v_fma_f32 v112, -v112, v112, 1.0
	v_cndmask_b32_e32 v112, v112, v122, vcc
	v_max_f32_e32 v112, 0, v112
	v_sqrt_f32_e32 v171, v112
	v_add_f32_e32 v112, 1.0, v116
	v_rcp_f32_e32 v128, v112
	v_add_f32_e32 v112, 1.0, v113
	v_rcp_f32_e32 v113, v112
	v_mov_b32_e32 v112, v77
	v_lshlrev_b32_e32 v135, 16, v124
	v_and_b32_e32 v117, 0xffff0000, v124
	v_pk_mul_f32 v[112:113], v[112:113], v[128:129]
	v_pk_mul_f32 v[126:127], v[126:127], v[170:171]
	v_mul_f32_e32 v116, 0x3fb8aa3b, v112
	v_exp_f32_e32 v116, v116
	v_add_f32_e32 v122, v112, v112
	v_fmamk_f32 v124, v122, 0x3d2aaaab, v185
	v_fma_f32 v124, v122, v124, 0.5
	v_fma_f32 v124, v122, v124, 1.0
	v_mul_f32_e64 v124, v124, -v122
	v_fma_f32 v116, -v116, v116, 1.0
	v_cmp_lt_f32_e32 vcc, s66, v122
	v_rcp_f32_e32 v129, v114
	v_lshlrev_b32_e32 v131, 16, v123
	v_cndmask_b32_e32 v116, v116, v124, vcc
	v_max_f32_e32 v116, 0, v116
	v_sqrt_f32_e32 v171, v116
	v_add_f32_e32 v116, 1.0, v118
	v_rcp_f32_e32 v130, v116
	v_mov_b32_e32 v128, v78
	v_pk_mul_f32 v[112:113], v[112:113], v[170:171]
	v_and_b32_e32 v123, 0xffff0000, v123
	v_pk_mul_f32 v[128:129], v[128:129], v[130:131]
	v_lshlrev_b32_e32 v133, 16, v125
; __device__ __forceinline__ unsigned pk_f16(float lo, float hi) { f32x2 v = {lo, hi}; return __builtin_bit_cast(unsigned, __builtin_convertvector(v, f16v2)); }
; __device__ __forceinline__ float bf_lo(unsigned w) { return __uint_as_float(w << 16); }
; __device__ __forceinline__ float bf_hi(unsigned w) { return __uint_as_float(w & 0xffff0000u); }
; __device__ __forceinline__ float fast_sigmoid(float v) { return __builtin_amdgcn_rcpf(1.0f + __builtin_amdgcn_exp2f(-v * LOG2E)); }
;     __device__ __forceinline__ void operator()(const AccT& acc, const Unit& u, int wr, int wc, int fr, int fq) const {
;     ...
;             for (int m = 0; m < 4; ++m) { const unsigned off = (unsigned)(row0 + ai * HALF + m * 16) * DM + ch0;
;                 const u32x4 xw = *(const u32x4*)(xc + off);
;                 const float xv[8] = {bf_lo(xw.x), bf_hi(xw.x), bf_lo(xw.y), bf_hi(xw.y), bf_lo(xw.z), bf_hi(xw.z), bf_lo(xw.w), bf_hi(xw.w)};
;                 u32x4 pk[2];
; #pragma unroll
;                 for (int n = 0; n < 2; ++n)
; #pragma unroll
;                     for (int e = 0; e < 4; ++e) {
;                         const float rr = fast_sigmoid(acc[ai][0][m][n][e] + br[n][e]), ii = fast_sigmoid(acc[ai][1][m][n][e] + bi[n][e]);
;                         const float la = c8[n][e] * rr, a = __builtin_amdgcn_exp2f(la * LOG2E), x2 = 2.0f * la;
;                         const float ser = -x2 * (1.0f + x2 * (0.5f + x2 * (0.16666667f + x2 * 0.041666668f)));
;                         const float m2 = x2 > -0.06f ? ser : 1.0f - a * a;
;                         pk[n][e] = pk_f16(la * (LOG2E * 1024.0f), __builtin_amdgcn_sqrtf(fmaxf(m2, 0.f)) * (ii * xv[4 * n + e])); }
;                 *(u32x4*)(au_out + off) = pk[0]; *(u32x4*)(au_out + off + 4) = pk[1];
	v_add_f32_e32 v116, v128, v128
	v_fmamk_f32 v118, v116, 0x3d2aaaab, v185
	v_mul_f32_e32 v114, 0x3fb8aa3b, v128
	v_fma_f32 v118, v116, v118, 0.5
	v_exp_f32_e32 v114, v114
	v_fma_f32 v118, v116, v118, 1.0
	v_mul_f32_e64 v118, v118, -v116
	v_cmp_lt_f32_e32 vcc, s66, v116
	v_add_f32_e32 v116, v119, v87
	v_mul_f32_e32 v116, 0xbfb8aa3b, v116
	v_exp_f32_e32 v116, v116
	v_fma_f32 v114, -v114, v114, 1.0
	v_cndmask_b32_e32 v114, v114, v118, vcc
	v_max_f32_e32 v114, 0, v114
	v_sqrt_f32_e32 v171, v114
	v_add_f32_e32 v114, 1.0, v116
	v_rcp_f32_e32 v122, v114
	v_add_f32_e32 v114, 1.0, v115
	v_rcp_f32_e32 v115, v114
	v_mov_b32_e32 v114, v79
	v_and_b32_e32 v119, 0xffff0000, v125
	v_pk_mul_f32 v[124:125], v[128:129], v[170:171]
	v_pk_mul_f32 v[114:115], v[114:115], v[122:123]
	v_rcp_f32_e32 v123, v104
	v_mul_f32_e32 v116, 0x3fb8aa3b, v114
	v_exp_f32_e32 v116, v116
	v_add_f32_e32 v118, v114, v114
	v_fmamk_f32 v122, v118, 0x3d2aaaab, v185
	v_fma_f32 v122, v118, v122, 0.5
	v_fma_f32 v122, v118, v122, 1.0
	v_mul_f32_e64 v122, v122, -v118
	v_fma_f32 v116, -v116, v116, 1.0
	v_cmp_lt_f32_e32 vcc, s66, v118
	v_rcp_f32_e32 v132, v110
	v_cvt_pk_f16_f32 v104, v126, v127
	v_cndmask_b32_e32 v116, v116, v122, vcc
	v_mov_b32_e32 v122, v60
	v_pk_mul_f32 v[122:123], v[122:123], v[134:135]
	v_max_f32_e32 v116, 0, v116
	v_mul_f32_e32 v108, 0x3fb8aa3b, v122
	v_sqrt_f32_e32 v171, v116
	v_exp_f32_e32 v108, v108
	v_add_f32_e32 v116, v122, v122
	v_fmamk_f32 v118, v116, 0x3d2aaaab, v185
	v_fma_f32 v118, v116, v118, 0.5
	v_fma_f32 v118, v116, v118, 1.0
	v_mul_f32_e64 v118, v118, -v116
	v_fma_f32 v108, -v108, v108, 1.0
	v_cmp_lt_f32_e32 vcc, s66, v116
	v_pk_mul_f32 v[114:115], v[114:115], v[170:171]
	v_exp_f32_e32 v66, v66
	v_cndmask_b32_e32 v108, v108, v118, vcc
	v_max_f32_e32 v108, 0, v108
	v_sqrt_f32_e32 v171, v108
	v_add_f32_e32 v108, 1.0, v109
	v_rcp_f32_e32 v116, v108
	v_rcp_f32_e32 v109, v105
	v_mov_b32_e32 v108, v61
	v_cvt_pk_f16_f32 v105, v112, v113
	v_pk_mul_f32 v[112:113], v[122:123], v[170:171]
	v_pk_mul_f32 v[108:109], v[108:109], v[116:117]
	v_exp_f32_e32 v58, v58
	v_mul_f32_e32 v116, 0x3fb8aa3b, v108
	v_exp_f32_e32 v116, v116
	v_add_f32_e32 v117, v108, v108
	v_fmamk_f32 v118, v117, 0x3d2aaaab, v185
	v_fma_f32 v118, v117, v118, 0.5
	v_fma_f32 v118, v117, v118, 1.0
	v_mul_f32_e64 v118, v118, -v117
	v_fma_f32 v116, -v116, v116, 1.0
	v_cmp_lt_f32_e32 vcc, s66, v117
	v_rcp_f32_e32 v117, v106
	v_cvt_pk_f16_f32 v106, v124, v125
	v_cndmask_b32_e32 v116, v116, v118, vcc
	v_max_f32_e32 v116, 0, v116
	v_sqrt_f32_e32 v171, v116
	v_mov_b32_e32 v116, v62
	v_add_f32_e32 v58, 1.0, v58
	v_add_f32_e32 v59, v59, v83
	v_pk_mul_f32 v[122:123], v[108:109], v[170:171]
	v_pk_mul_f32 v[108:109], v[116:117], v[132:133]
	v_mul_f32_e32 v59, 0xbfb8aa3b, v59
	v_mul_f32_e32 v110, 0x3fb8aa3b, v108
	v_exp_f32_e32 v110, v110
	v_add_f32_e32 v116, v108, v108
	v_fmamk_f32 v117, v116, 0x3d2aaaab, v185
	v_fma_f32 v117, v116, v117, 0.5
	v_fma_f32 v117, v116, v117, 1.0
	v_mul_f32_e64 v117, v117, -v116
	v_fma_f32 v110, -v110, v110, 1.0
	v_cmp_lt_f32_e32 vcc, s66, v116
	v_exp_f32_e32 v59, v59
	v_add_f32_e32 v52, v52, v72
	v_cndmask_b32_e32 v110, v110, v117, vcc
	v_max_f32_e32 v110, 0, v110
	v_sqrt_f32_e32 v171, v110
	v_add_f32_e32 v110, 1.0, v111
	v_rcp_f32_e32 v118, v110
	v_rcp_f32_e32 v111, v107
	v_mov_b32_e32 v110, v63
	v_cvt_pk_f16_f32 v107, v114, v115
	v_pk_mul_f32 v[114:115], v[108:109], v[170:171]
	v_pk_mul_f32 v[116:117], v[110:111], v[118:119]
	v_rcp_f32_e32 v118, v92
	v_mul_f32_e32 v108, 0x3fb8aa3b, v116
	v_exp_f32_e32 v108, v108
	v_add_f32_e32 v109, v116, v116
	v_fmamk_f32 v110, v109, 0x3d2aaaab, v185
	v_fma_f32 v110, v109, v110, 0.5
	v_fma_f32 v110, v109, v110, 1.0
	v_mul_f32_e64 v110, v110, -v109
	v_fma_f32 v108, -v108, v108, 1.0
	v_cmp_lt_f32_e32 vcc, s66, v109
	v_cvt_pk_f16_f32 v109, v122, v123
	v_add_f32_e32 v48, v48, v68
	v_cndmask_b32_e32 v108, v108, v110, vcc
	v_max_f32_e32 v108, 0, v108
	v_sqrt_f32_e32 v171, v108
	v_cvt_pk_f16_f32 v108, v112, v113
	v_cvt_pk_f16_f32 v110, v114, v115
	v_mul_f32_e32 v52, 0xbfb8aa3b, v52
	v_pk_mul_f32 v[112:113], v[116:117], v[170:171]
	v_rcp_f32_e32 v117, v96
	v_cvt_pk_f16_f32 v111, v112, v113
	v_lshl_add_u64 v[112:113], v[120:121], 2, s[18:19]
	global_store_dwordx4 v[112:113], v[104:107], off
	global_store_dwordx4 v[112:113], v[108:111], off offset:16
	v_mov_b32_e32 v116, v76
	v_add_u32_e32 v104, 0xc000, v160
	v_mov_b32_e32 v105, v161
	v_lshl_add_u64 v[106:107], v[104:105], 1, s[12:13]
	v_mov_b32_e32 v106, v208
	v_mov_b32_e32 v107, v209
	v_mov_b32_e32 v108, v210
	v_mov_b32_e32 v109, v211
	v_rcp_f32_e32 v110, v100
	v_mul_f32_e32 v48, 0xbfb8aa3b, v48
	v_exp_f32_e32 v52, v52
	v_exp_f32_e32 v48, v48
	v_add_f32_e32 v53, v53, v73
	v_add_f32_e32 v49, v49, v69
	v_add_f32_e32 v52, 1.0, v52
	v_add_f32_e32 v48, 1.0, v48
	v_mul_f32_e32 v53, 0xbfb8aa3b, v53
	v_mul_f32_e32 v49, 0xbfb8aa3b, v49
	v_exp_f32_e32 v53, v53
	v_exp_f32_e32 v49, v49
	v_add_f32_e32 v54, v54, v74
	v_add_f32_e32 v50, v50, v70
	v_mul_f32_e32 v54, 0xbfb8aa3b, v54
	v_add_f32_e32 v49, 1.0, v49
	v_mul_f32_e32 v50, 0xbfb8aa3b, v50
	v_exp_f32_e32 v54, v54
	v_exp_f32_e32 v50, v50
	v_add_f32_e32 v55, v55, v75
	v_add_f32_e32 v51, v51, v71
	v_add_f32_e32 v54, 1.0, v54
	v_add_f32_e32 v50, 1.0, v50
	v_mul_f32_e32 v55, 0xbfb8aa3b, v55
	v_mul_f32_e32 v51, 0xbfb8aa3b, v51
	v_exp_f32_e32 v55, v55
	v_exp_f32_e32 v51, v51
	v_add_f32_e32 v44, v44, v84
	v_add_f32_e32 v40, v40, v80
	v_mul_f32_e32 v44, 0xbfb8aa3b, v44
	v_add_f32_e32 v51, 1.0, v51
	v_mul_f32_e32 v40, 0xbfb8aa3b, v40
	v_exp_f32_e32 v44, v44
	v_exp_f32_e32 v40, v40
	v_add_f32_e32 v41, v41, v81
	v_mul_f32_e32 v41, 0xbfb8aa3b, v41
	v_add_f32_e32 v44, 1.0, v44
; __device__ __forceinline__ unsigned pk_f16(float lo, float hi) { f32x2 v = {lo, hi}; return __builtin_bit_cast(unsigned, __builtin_convertvector(v, f16v2)); }
; __device__ __forceinline__ float bf_lo(unsigned w) { return __uint_as_float(w << 16); }
; __device__ __forceinline__ float bf_hi(unsigned w) { return __uint_as_float(w & 0xffff0000u); }
; __device__ __forceinline__ float fast_sigmoid(float v) { return __builtin_amdgcn_rcpf(1.0f + __builtin_amdgcn_exp2f(-v * LOG2E)); }
;     __device__ __forceinline__ void operator()(const AccT& acc, const Unit& u, int wr, int wc, int fr, int fq) const {
;     ...
;             for (int m = 0; m < 4; ++m) { const unsigned off = (unsigned)(row0 + ai * HALF + m * 16) * DM + ch0;
;                 const u32x4 xw = *(const u32x4*)(xc + off);
;                 const float xv[8] = {bf_lo(xw.x), bf_hi(xw.x), bf_lo(xw.y), bf_hi(xw.y), bf_lo(xw.z), bf_hi(xw.z), bf_lo(xw.w), bf_hi(xw.w)};
;                 u32x4 pk[2];
; #pragma unroll
;                 for (int n = 0; n < 2; ++n)
; #pragma unroll
;                     for (int e = 0; e < 4; ++e) {
;                         const float rr = fast_sigmoid(acc[ai][0][m][n][e] + br[n][e]), ii = fast_sigmoid(acc[ai][1][m][n][e] + bi[n][e]);
;                         const float la = c8[n][e] * rr, a = __builtin_amdgcn_exp2f(la * LOG2E), x2 = 2.0f * la;
;                         const float ser = -x2 * (1.0f + x2 * (0.5f + x2 * (0.16666667f + x2 * 0.041666668f)));
;                         const float m2 = x2 > -0.06f ? ser : 1.0f - a * a;
;                         pk[n][e] = pk_f16(la * (LOG2E * 1024.0f), __builtin_amdgcn_sqrtf(fmaxf(m2, 0.f)) * (ii * xv[4 * n + e])); }
;                 *(u32x4*)(au_out + off) = pk[0]; *(u32x4*)(au_out + off + 4) = pk[1];
	v_add_f32_e32 v40, 1.0, v40
	v_exp_f32_e32 v41, v41
	v_add_f32_e32 v46, v46, v86
	v_add_f32_e32 v42, v42, v82
	v_mul_f32_e32 v46, 0xbfb8aa3b, v46
	v_mul_f32_e32 v42, 0xbfb8aa3b, v42
	v_exp_f32_e32 v46, v46
	v_exp_f32_e32 v42, v42
	v_add_f32_e32 v43, v43, v83
	v_mul_f32_e32 v43, 0xbfb8aa3b, v43
	v_exp_f32_e32 v43, v43
	v_add_f32_e32 v42, 1.0, v42
	v_add_f32_e32 v36, v36, v72
	v_add_f32_e32 v32, v32, v68
	v_mul_f32_e32 v36, 0xbfb8aa3b, v36
	v_mul_f32_e32 v32, 0xbfb8aa3b, v32
	v_exp_f32_e32 v36, v36
	v_exp_f32_e32 v32, v32
	v_add_f32_e32 v37, v37, v73
	v_add_f32_e32 v33, v33, v69
	v_add_f32_e32 v36, 1.0, v36
	v_add_f32_e32 v32, 1.0, v32
	v_mul_f32_e32 v37, 0xbfb8aa3b, v37
	v_mul_f32_e32 v33, 0xbfb8aa3b, v33
	v_exp_f32_e32 v37, v37
	v_exp_f32_e32 v33, v33
	v_add_f32_e32 v38, v38, v74
	v_add_f32_e32 v34, v34, v70
	v_mul_f32_e32 v38, 0xbfb8aa3b, v38
	v_add_f32_e32 v33, 1.0, v33
	v_mul_f32_e32 v34, 0xbfb8aa3b, v34
	v_exp_f32_e32 v38, v38
	v_exp_f32_e32 v34, v34
	v_add_f32_e32 v39, v39, v75
	v_add_f32_e32 v35, v35, v71
	v_add_f32_e32 v38, 1.0, v38
	v_add_f32_e32 v34, 1.0, v34
	v_mul_f32_e32 v39, 0xbfb8aa3b, v39
	v_mul_f32_e32 v35, 0xbfb8aa3b, v35
	v_exp_f32_e32 v39, v39
	v_exp_f32_e32 v35, v35
	v_add_f32_e32 v28, v28, v84
	s_nop 0
	v_lshlrev_b32_e32 v111, 16, v106
	v_pk_mul_f32 v[110:111], v[116:117], v[110:111]
	v_and_b32_e32 v113, 0xffff0000, v106
	v_add_f32_e32 v100, v110, v110
	v_fmamk_f32 v106, v100, 0x3d2aaaab, v185
	v_mul_f32_e32 v96, 0x3fb8aa3b, v110
	v_fma_f32 v106, v100, v106, 0.5
	v_exp_f32_e32 v96, v96
	v_fma_f32 v106, v100, v106, 1.0
	v_mul_f32_e64 v106, v106, -v100
	v_cmp_lt_f32_e32 vcc, s66, v100
	v_add_f32_e32 v100, v101, v85
	v_mul_f32_e32 v100, 0xbfb8aa3b, v100
	v_exp_f32_e32 v100, v100
	v_fma_f32 v96, -v96, v96, 1.0
	v_cndmask_b32_e32 v96, v96, v106, vcc
	v_max_f32_e32 v96, 0, v96
	v_sqrt_f32_e32 v171, v96
	v_add_f32_e32 v96, 1.0, v100
	v_rcp_f32_e32 v112, v96
	v_add_f32_e32 v96, 1.0, v97
	v_rcp_f32_e32 v97, v96
	v_mov_b32_e32 v96, v77
	v_lshlrev_b32_e32 v119, 16, v108
	v_and_b32_e32 v101, 0xffff0000, v108
	v_pk_mul_f32 v[96:97], v[96:97], v[112:113]
	v_pk_mul_f32 v[110:111], v[170:171], v[110:111]
	v_mul_f32_e32 v100, 0x3fb8aa3b, v96
	v_exp_f32_e32 v100, v100
	v_add_f32_e32 v106, v96, v96
	v_fmamk_f32 v108, v106, 0x3d2aaaab, v185
	v_fma_f32 v108, v106, v108, 0.5
	v_fma_f32 v108, v106, v108, 1.0
	v_mul_f32_e64 v108, v108, -v106
	v_fma_f32 v100, -v100, v100, 1.0
	v_cmp_lt_f32_e32 vcc, s66, v106
	v_rcp_f32_e32 v113, v98
	v_lshlrev_b32_e32 v115, 16, v107
	v_cndmask_b32_e32 v100, v100, v108, vcc
	v_max_f32_e32 v100, 0, v100
	v_sqrt_f32_e32 v171, v100
	v_add_f32_e32 v100, 1.0, v102
	v_rcp_f32_e32 v114, v100
	v_mov_b32_e32 v112, v78
	v_pk_mul_f32 v[96:97], v[170:171], v[96:97]
	v_and_b32_e32 v107, 0xffff0000, v107
	v_pk_mul_f32 v[112:113], v[112:113], v[114:115]
	v_lshlrev_b32_e32 v117, 16, v109
	v_add_f32_e32 v100, v112, v112
	v_fmamk_f32 v102, v100, 0x3d2aaaab, v185
	v_mul_f32_e32 v98, 0x3fb8aa3b, v112
	v_fma_f32 v102, v100, v102, 0.5
	v_exp_f32_e32 v98, v98
	v_fma_f32 v102, v100, v102, 1.0
	v_mul_f32_e64 v102, v102, -v100
	v_cmp_lt_f32_e32 vcc, s66, v100
	v_add_f32_e32 v100, v103, v87
	v_mul_f32_e32 v100, 0xbfb8aa3b, v100
	v_exp_f32_e32 v100, v100
	v_fma_f32 v98, -v98, v98, 1.0
	v_cndmask_b32_e32 v98, v98, v102, vcc
	v_max_f32_e32 v98, 0, v98
	v_sqrt_f32_e32 v171, v98
	v_add_f32_e32 v98, 1.0, v100
	v_rcp_f32_e32 v106, v98
	v_add_f32_e32 v98, 1.0, v99
	v_rcp_f32_e32 v99, v98
	v_mov_b32_e32 v98, v79
	v_and_b32_e32 v103, 0xffff0000, v109
	v_pk_mul_f32 v[108:109], v[170:171], v[112:113]
	v_pk_mul_f32 v[98:99], v[98:99], v[106:107]
	v_rcp_f32_e32 v107, v88
	v_mul_f32_e32 v100, 0x3fb8aa3b, v98
	v_exp_f32_e32 v100, v100
	v_add_f32_e32 v102, v98, v98
	v_fmamk_f32 v106, v102, 0x3d2aaaab, v185
	v_fma_f32 v106, v102, v106, 0.5
	v_fma_f32 v106, v102, v106, 1.0
	v_mul_f32_e64 v106, v106, -v102
	v_fma_f32 v100, -v100, v100, 1.0
	v_cmp_lt_f32_e32 vcc, s66, v102
	v_rcp_f32_e32 v116, v94
	v_cvt_pk_f16_f32 v88, v110, v111
	v_cndmask_b32_e32 v100, v100, v106, vcc
	v_mov_b32_e32 v106, v60
	v_pk_mul_f32 v[106:107], v[106:107], v[118:119]
	v_max_f32_e32 v100, 0, v100
	v_mul_f32_e32 v92, 0x3fb8aa3b, v106
	v_sqrt_f32_e32 v171, v100
	v_exp_f32_e32 v92, v92
	v_add_f32_e32 v100, v106, v106
	v_fmamk_f32 v102, v100, 0x3d2aaaab, v185
	v_fma_f32 v102, v100, v102, 0.5
	v_fma_f32 v102, v100, v102, 1.0
	v_mul_f32_e64 v102, v102, -v100
	v_fma_f32 v92, -v92, v92, 1.0
	v_cmp_lt_f32_e32 vcc, s66, v100
	v_pk_mul_f32 v[98:99], v[170:171], v[98:99]
	v_add_f32_e32 v35, 1.0, v35
	v_cndmask_b32_e32 v92, v92, v102, vcc
	v_max_f32_e32 v92, 0, v92
	v_sqrt_f32_e32 v171, v92
	v_add_f32_e32 v92, 1.0, v93
	v_rcp_f32_e32 v100, v92
	v_rcp_f32_e32 v93, v89
	v_mov_b32_e32 v92, v61
	v_cvt_pk_f16_f32 v89, v96, v97
	v_pk_mul_f32 v[96:97], v[170:171], v[106:107]
	v_pk_mul_f32 v[92:93], v[92:93], v[100:101]
	v_add_f32_e32 v24, v24, v80
	v_mul_f32_e32 v100, 0x3fb8aa3b, v92
	v_exp_f32_e32 v100, v100
	v_add_f32_e32 v101, v92, v92
	v_fmamk_f32 v102, v101, 0x3d2aaaab, v185
	v_fma_f32 v102, v101, v102, 0.5
	v_fma_f32 v102, v101, v102, 1.0
	v_mul_f32_e64 v102, v102, -v101
	v_fma_f32 v100, -v100, v100, 1.0
	v_cmp_lt_f32_e32 vcc, s66, v101
	v_rcp_f32_e32 v101, v90
	v_cvt_pk_f16_f32 v90, v108, v109
	v_cndmask_b32_e32 v100, v100, v102, vcc
	v_max_f32_e32 v100, 0, v100
	v_sqrt_f32_e32 v171, v100
	v_mov_b32_e32 v100, v62
	v_mul_f32_e32 v28, 0xbfb8aa3b, v28
	v_mul_f32_e32 v24, 0xbfb8aa3b, v24
	v_pk_mul_f32 v[106:107], v[170:171], v[92:93]
	v_pk_mul_f32 v[92:93], v[100:101], v[116:117]
	v_exp_f32_e32 v28, v28
	v_mul_f32_e32 v94, 0x3fb8aa3b, v92
	v_exp_f32_e32 v94, v94
	v_add_f32_e32 v100, v92, v92
; __device__ __forceinline__ unsigned pk_f16(float lo, float hi) { f32x2 v = {lo, hi}; return __builtin_bit_cast(unsigned, __builtin_convertvector(v, f16v2)); }
; __device__ __forceinline__ float bf_lo(unsigned w) { return __uint_as_float(w << 16); }
; __device__ __forceinline__ float bf_hi(unsigned w) { return __uint_as_float(w & 0xffff0000u); }
; __device__ __forceinline__ float fast_sigmoid(float v) { return __builtin_amdgcn_rcpf(1.0f + __builtin_amdgcn_exp2f(-v * LOG2E)); }
;     __device__ __forceinline__ void operator()(const AccT& acc, const Unit& u, int wr, int wc, int fr, int fq) const {
;     ...
;             for (int m = 0; m < 4; ++m) { const unsigned off = (unsigned)(row0 + ai * HALF + m * 16) * DM + ch0;
;                 const u32x4 xw = *(const u32x4*)(xc + off);
;                 const float xv[8] = {bf_lo(xw.x), bf_hi(xw.x), bf_lo(xw.y), bf_hi(xw.y), bf_lo(xw.z), bf_hi(xw.z), bf_lo(xw.w), bf_hi(xw.w)};
;                 u32x4 pk[2];
; #pragma unroll
;                 for (int n = 0; n < 2; ++n)
; #pragma unroll
;                     for (int e = 0; e < 4; ++e) {
;                         const float rr = fast_sigmoid(acc[ai][0][m][n][e] + br[n][e]), ii = fast_sigmoid(acc[ai][1][m][n][e] + bi[n][e]);
;                         const float la = c8[n][e] * rr, a = __builtin_amdgcn_exp2f(la * LOG2E), x2 = 2.0f * la;
;                         const float ser = -x2 * (1.0f + x2 * (0.5f + x2 * (0.16666667f + x2 * 0.041666668f)));
;                         const float m2 = x2 > -0.06f ? ser : 1.0f - a * a;
;                         pk[n][e] = pk_f16(la * (LOG2E * 1024.0f), __builtin_amdgcn_sqrtf(fmaxf(m2, 0.f)) * (ii * xv[4 * n + e])); }
;                 *(u32x4*)(au_out + off) = pk[0]; *(u32x4*)(au_out + off + 4) = pk[1];
	v_fmamk_f32 v101, v100, 0x3d2aaaab, v185
	v_fma_f32 v101, v100, v101, 0.5
	v_fma_f32 v101, v100, v101, 1.0
	v_mul_f32_e64 v101, v101, -v100
	v_fma_f32 v94, -v94, v94, 1.0
	v_cmp_lt_f32_e32 vcc, s66, v100
	v_exp_f32_e32 v24, v24
	v_add_f32_e32 v28, 1.0, v28
	v_cndmask_b32_e32 v94, v94, v101, vcc
	v_max_f32_e32 v94, 0, v94
	v_sqrt_f32_e32 v171, v94
	v_add_f32_e32 v94, 1.0, v95
	v_rcp_f32_e32 v102, v94
	v_rcp_f32_e32 v95, v91
	v_mov_b32_e32 v94, v63
	v_cvt_pk_f16_f32 v91, v98, v99
	v_pk_mul_f32 v[98:99], v[170:171], v[92:93]
	v_pk_mul_f32 v[100:101], v[94:95], v[102:103]
	v_rcp_f32_e32 v102, v52
	v_mul_f32_e32 v92, 0x3fb8aa3b, v100
	v_exp_f32_e32 v92, v92
	v_add_f32_e32 v93, v100, v100
	v_fmamk_f32 v94, v93, 0x3d2aaaab, v185
	v_fma_f32 v94, v93, v94, 0.5
	v_fma_f32 v94, v93, v94, 1.0
	v_mul_f32_e64 v94, v94, -v93
	v_fma_f32 v92, -v92, v92, 1.0
	v_cmp_lt_f32_e32 vcc, s66, v93
	v_cvt_pk_f16_f32 v93, v106, v107
	v_add_f32_e32 v24, 1.0, v24
	v_cndmask_b32_e32 v92, v92, v94, vcc
	v_max_f32_e32 v92, 0, v92
	v_sqrt_f32_e32 v171, v92
	v_cvt_pk_f16_f32 v92, v96, v97
	v_cvt_pk_f16_f32 v94, v98, v99
	v_add_f32_e32 v25, v25, v81
	v_pk_mul_f32 v[96:97], v[170:171], v[100:101]
	v_rcp_f32_e32 v101, v56
	v_cvt_pk_f16_f32 v95, v96, v97
	v_lshl_add_u64 v[96:97], v[104:105], 2, s[18:19]
	global_store_dwordx4 v[96:97], v[88:91], off
	global_store_dwordx4 v[96:97], v[92:95], off offset:16
	v_mov_b32_e32 v100, v76
	v_add_u32_e32 v88, 0x20000, v160
	v_mov_b32_e32 v89, v161
	v_lshl_add_u64 v[90:91], v[88:89], 1, s[12:13]
	v_mov_b32_e32 v90, v212
	v_mov_b32_e32 v91, v213
	v_mov_b32_e32 v92, v214
	v_mov_b32_e32 v93, v215
	v_rcp_f32_e32 v94, v64
	v_mul_f32_e32 v25, 0xbfb8aa3b, v25
	v_exp_f32_e32 v25, v25
	v_add_f32_e32 v30, v30, v86
	v_add_f32_e32 v26, v26, v82
	v_mul_f32_e32 v30, 0xbfb8aa3b, v30
	v_mul_f32_e32 v26, 0xbfb8aa3b, v26
	v_exp_f32_e32 v30, v30
	v_exp_f32_e32 v26, v26
	v_add_f32_e32 v27, v27, v83
	v_mul_f32_e32 v27, 0xbfb8aa3b, v27
	v_exp_f32_e32 v27, v27
	v_add_f32_e32 v26, 1.0, v26
	v_add_f32_e32 v20, v20, v72
	v_add_f32_e32 v16, v16, v68
	v_mul_f32_e32 v20, 0xbfb8aa3b, v20
	v_mul_f32_e32 v16, 0xbfb8aa3b, v16
	v_exp_f32_e32 v20, v20
	v_exp_f32_e32 v16, v16
	v_add_f32_e32 v21, v21, v73
	v_add_f32_e32 v17, v17, v69
	v_add_f32_e32 v20, 1.0, v20
	v_add_f32_e32 v16, 1.0, v16
	v_mul_f32_e32 v21, 0xbfb8aa3b, v21
	v_mul_f32_e32 v17, 0xbfb8aa3b, v17
	v_exp_f32_e32 v21, v21
	v_exp_f32_e32 v17, v17
	v_add_f32_e32 v22, v22, v74
	v_add_f32_e32 v18, v18, v70
	v_mul_f32_e32 v22, 0xbfb8aa3b, v22
	v_add_f32_e32 v17, 1.0, v17
	v_mul_f32_e32 v18, 0xbfb8aa3b, v18
	v_exp_f32_e32 v22, v22
	v_exp_f32_e32 v18, v18
	v_add_f32_e32 v23, v23, v75
	v_add_f32_e32 v19, v19, v71
	v_add_f32_e32 v22, 1.0, v22
	v_add_f32_e32 v18, 1.0, v18
	v_mul_f32_e32 v23, 0xbfb8aa3b, v23
	v_mul_f32_e32 v19, 0xbfb8aa3b, v19
	v_exp_f32_e32 v23, v23
	v_exp_f32_e32 v19, v19
	v_add_f32_e32 v12, v12, v84
	v_add_f32_e32 v8, v8, v80
	v_mul_f32_e32 v12, 0xbfb8aa3b, v12
	v_add_f32_e32 v19, 1.0, v19
	v_mul_f32_e32 v8, 0xbfb8aa3b, v8
	v_exp_f32_e32 v12, v12
	v_exp_f32_e32 v8, v8
	v_add_f32_e32 v9, v9, v81
	v_mul_f32_e32 v9, 0xbfb8aa3b, v9
	v_add_f32_e32 v12, 1.0, v12
	v_add_f32_e32 v8, 1.0, v8
	v_exp_f32_e32 v9, v9
	v_add_f32_e32 v14, v14, v86
	v_add_f32_e32 v10, v10, v82
	v_mul_f32_e32 v14, 0xbfb8aa3b, v14
	v_mul_f32_e32 v10, 0xbfb8aa3b, v10
	v_exp_f32_e32 v14, v14
	v_exp_f32_e32 v10, v10
	v_add_f32_e32 v11, v11, v83
	v_mul_f32_e32 v11, 0xbfb8aa3b, v11
	v_exp_f32_e32 v11, v11
	v_add_f32_e32 v10, 1.0, v10
	v_add_f32_e32 v4, v4, v72
	v_add_f32_e32 v0, v0, v68
	v_mul_f32_e32 v4, 0xbfb8aa3b, v4
	v_mul_f32_e32 v0, 0xbfb8aa3b, v0
	v_exp_f32_e32 v4, v4
	v_exp_f32_e32 v0, v0
	v_add_f32_e32 v5, v5, v73
	v_add_f32_e32 v1, v1, v69
	v_add_f32_e32 v4, 1.0, v4
	v_add_f32_e32 v0, 1.0, v0
	v_mul_f32_e32 v5, 0xbfb8aa3b, v5
	v_mul_f32_e32 v1, 0xbfb8aa3b, v1
	v_exp_f32_e32 v5, v5
	v_exp_f32_e32 v1, v1
	v_add_f32_e32 v6, v6, v74
	s_nop 0
	v_lshlrev_b32_e32 v95, 16, v90
	v_pk_mul_f32 v[94:95], v[100:101], v[94:95]
	v_and_b32_e32 v97, 0xffff0000, v90
	v_add_f32_e32 v64, v94, v94
	v_fmamk_f32 v90, v64, 0x3d2aaaab, v185
	v_mul_f32_e32 v56, 0x3fb8aa3b, v94
	v_fma_f32 v90, v64, v90, 0.5
	v_exp_f32_e32 v56, v56
	v_fma_f32 v90, v64, v90, 1.0
	v_mul_f32_e64 v90, v90, -v64
	v_cmp_lt_f32_e32 vcc, s66, v64
	v_add_f32_e32 v64, v65, v85
	v_mul_f32_e32 v64, 0xbfb8aa3b, v64
	v_exp_f32_e32 v64, v64
	v_fma_f32 v56, -v56, v56, 1.0
	v_cndmask_b32_e32 v56, v56, v90, vcc
	v_max_f32_e32 v56, 0, v56
	v_sqrt_f32_e32 v171, v56
	v_add_f32_e32 v56, 1.0, v64
	v_rcp_f32_e32 v96, v56
	v_add_f32_e32 v56, 1.0, v57
	v_rcp_f32_e32 v57, v56
	v_mov_b32_e32 v56, v77
	v_lshlrev_b32_e32 v103, 16, v92
	v_and_b32_e32 v65, 0xffff0000, v92
	v_pk_mul_f32 v[56:57], v[56:57], v[96:97]
	v_pk_mul_f32 v[94:95], v[170:171], v[94:95]
	v_mul_f32_e32 v64, 0x3fb8aa3b, v56
	v_exp_f32_e32 v64, v64
	v_add_f32_e32 v90, v56, v56
	v_fmamk_f32 v92, v90, 0x3d2aaaab, v185
	v_fma_f32 v92, v90, v92, 0.5
	v_fma_f32 v92, v90, v92, 1.0
	v_mul_f32_e64 v92, v92, -v90
	v_fma_f32 v64, -v64, v64, 1.0
	v_cmp_lt_f32_e32 vcc, s66, v90
	v_rcp_f32_e32 v97, v58
	v_lshlrev_b32_e32 v99, 16, v91
	v_cndmask_b32_e32 v64, v64, v92, vcc
	v_max_f32_e32 v64, 0, v64
	v_sqrt_f32_e32 v171, v64
	v_add_f32_e32 v64, 1.0, v66
	v_rcp_f32_e32 v98, v64
	v_mov_b32_e32 v96, v78
	v_pk_mul_f32 v[56:57], v[170:171], v[56:57]
	v_and_b32_e32 v91, 0xffff0000, v91
	v_pk_mul_f32 v[96:97], v[96:97], v[98:99]
	v_lshlrev_b32_e32 v101, 16, v93
	v_add_f32_e32 v64, v96, v96
	v_fmamk_f32 v66, v64, 0x3d2aaaab, v185
	v_mul_f32_e32 v58, 0x3fb8aa3b, v96
	v_fma_f32 v66, v64, v66, 0.5
	v_exp_f32_e32 v58, v58
	v_fma_f32 v66, v64, v66, 1.0
; __device__ __forceinline__ unsigned pk_f16(float lo, float hi) { f32x2 v = {lo, hi}; return __builtin_bit_cast(unsigned, __builtin_convertvector(v, f16v2)); }
; __device__ __forceinline__ float bf_lo(unsigned w) { return __uint_as_float(w << 16); }
; __device__ __forceinline__ float bf_hi(unsigned w) { return __uint_as_float(w & 0xffff0000u); }
; __device__ __forceinline__ float fast_sigmoid(float v) { return __builtin_amdgcn_rcpf(1.0f + __builtin_amdgcn_exp2f(-v * LOG2E)); }
;     __device__ __forceinline__ void operator()(const AccT& acc, const Unit& u, int wr, int wc, int fr, int fq) const {
;     ...
;             for (int m = 0; m < 4; ++m) { const unsigned off = (unsigned)(row0 + ai * HALF + m * 16) * DM + ch0;
;                 const u32x4 xw = *(const u32x4*)(xc + off);
;                 const float xv[8] = {bf_lo(xw.x), bf_hi(xw.x), bf_lo(xw.y), bf_hi(xw.y), bf_lo(xw.z), bf_hi(xw.z), bf_lo(xw.w), bf_hi(xw.w)};
;                 u32x4 pk[2];
; #pragma unroll
;                 for (int n = 0; n < 2; ++n)
; #pragma unroll
;                     for (int e = 0; e < 4; ++e) {
;                         const float rr = fast_sigmoid(acc[ai][0][m][n][e] + br[n][e]), ii = fast_sigmoid(acc[ai][1][m][n][e] + bi[n][e]);
;                         const float la = c8[n][e] * rr, a = __builtin_amdgcn_exp2f(la * LOG2E), x2 = 2.0f * la;
;                         const float ser = -x2 * (1.0f + x2 * (0.5f + x2 * (0.16666667f + x2 * 0.041666668f)));
;                         const float m2 = x2 > -0.06f ? ser : 1.0f - a * a;
;                         pk[n][e] = pk_f16(la * (LOG2E * 1024.0f), __builtin_amdgcn_sqrtf(fmaxf(m2, 0.f)) * (ii * xv[4 * n + e])); }
;                 *(u32x4*)(au_out + off) = pk[0]; *(u32x4*)(au_out + off + 4) = pk[1];
	v_mul_f32_e64 v66, v66, -v64
	v_cmp_lt_f32_e32 vcc, s66, v64
	v_add_f32_e32 v64, v67, v87
	v_mul_f32_e32 v64, 0xbfb8aa3b, v64
	v_exp_f32_e32 v64, v64
	v_fma_f32 v58, -v58, v58, 1.0
	v_cndmask_b32_e32 v58, v58, v66, vcc
	v_max_f32_e32 v58, 0, v58
	v_sqrt_f32_e32 v171, v58
	v_add_f32_e32 v58, 1.0, v64
	v_rcp_f32_e32 v90, v58
	v_add_f32_e32 v58, 1.0, v59
	v_rcp_f32_e32 v59, v58
	v_mov_b32_e32 v58, v79
	v_and_b32_e32 v67, 0xffff0000, v93
	v_pk_mul_f32 v[92:93], v[170:171], v[96:97]
	v_pk_mul_f32 v[58:59], v[58:59], v[90:91]
	v_rcp_f32_e32 v91, v48
	v_mul_f32_e32 v64, 0x3fb8aa3b, v58
	v_exp_f32_e32 v64, v64
	v_add_f32_e32 v66, v58, v58
	v_fmamk_f32 v90, v66, 0x3d2aaaab, v185
	v_fma_f32 v90, v66, v90, 0.5
	v_fma_f32 v90, v66, v90, 1.0
	v_mul_f32_e64 v90, v90, -v66
	v_fma_f32 v64, -v64, v64, 1.0
	v_cmp_lt_f32_e32 vcc, s66, v66
	v_rcp_f32_e32 v100, v54
	v_cvt_pk_f16_f32 v48, v94, v95
	v_cndmask_b32_e32 v64, v64, v90, vcc
	v_mov_b32_e32 v90, v60
	v_pk_mul_f32 v[90:91], v[90:91], v[102:103]
	v_max_f32_e32 v64, 0, v64
	v_mul_f32_e32 v52, 0x3fb8aa3b, v90
	v_sqrt_f32_e32 v171, v64
	v_exp_f32_e32 v52, v52
	v_add_f32_e32 v64, v90, v90
	v_fmamk_f32 v66, v64, 0x3d2aaaab, v185
	v_fma_f32 v66, v64, v66, 0.5
	v_fma_f32 v66, v64, v66, 1.0
	v_mul_f32_e64 v66, v66, -v64
	v_fma_f32 v52, -v52, v52, 1.0
	v_cmp_lt_f32_e32 vcc, s66, v64
	v_pk_mul_f32 v[58:59], v[170:171], v[58:59]
	v_add_f32_e32 v1, 1.0, v1
	v_cndmask_b32_e32 v52, v52, v66, vcc
	v_max_f32_e32 v52, 0, v52
	v_sqrt_f32_e32 v171, v52
	v_add_f32_e32 v52, 1.0, v53
	v_rcp_f32_e32 v64, v52
	v_rcp_f32_e32 v53, v49
	v_mov_b32_e32 v52, v61
	v_cvt_pk_f16_f32 v49, v56, v57
	v_pk_mul_f32 v[56:57], v[170:171], v[90:91]
	v_pk_mul_f32 v[52:53], v[52:53], v[64:65]
	v_add_f32_e32 v2, v2, v70
	v_mul_f32_e32 v64, 0x3fb8aa3b, v52
	v_exp_f32_e32 v64, v64
	v_add_f32_e32 v65, v52, v52
	v_fmamk_f32 v66, v65, 0x3d2aaaab, v185
	v_fma_f32 v66, v65, v66, 0.5
	v_fma_f32 v66, v65, v66, 1.0
	v_mul_f32_e64 v66, v66, -v65
	v_fma_f32 v64, -v64, v64, 1.0
	v_cmp_lt_f32_e32 vcc, s66, v65
	v_rcp_f32_e32 v65, v50
	v_cvt_pk_f16_f32 v50, v92, v93
	v_cndmask_b32_e32 v64, v64, v66, vcc
	v_max_f32_e32 v64, 0, v64
	v_sqrt_f32_e32 v171, v64
	v_mov_b32_e32 v64, v62
	v_mul_f32_e32 v6, 0xbfb8aa3b, v6
	v_mul_f32_e32 v2, 0xbfb8aa3b, v2
	v_pk_mul_f32 v[90:91], v[170:171], v[52:53]
	v_pk_mul_f32 v[52:53], v[64:65], v[100:101]
	v_exp_f32_e32 v6, v6
	v_mul_f32_e32 v54, 0x3fb8aa3b, v52
	v_exp_f32_e32 v54, v54
	v_add_f32_e32 v64, v52, v52
	v_fmamk_f32 v65, v64, 0x3d2aaaab, v185
	v_fma_f32 v65, v64, v65, 0.5
	v_fma_f32 v65, v64, v65, 1.0
	v_mul_f32_e64 v65, v65, -v64
	v_fma_f32 v54, -v54, v54, 1.0
	v_cmp_lt_f32_e32 vcc, s66, v64
	v_exp_f32_e32 v2, v2
	v_add_f32_e32 v6, 1.0, v6
	v_cndmask_b32_e32 v54, v54, v65, vcc
	v_max_f32_e32 v54, 0, v54
	v_sqrt_f32_e32 v171, v54
	v_add_f32_e32 v54, 1.0, v55
	v_rcp_f32_e32 v66, v54
	v_rcp_f32_e32 v55, v51
	v_mov_b32_e32 v54, v63
	v_cvt_pk_f16_f32 v51, v58, v59
	v_pk_mul_f32 v[58:59], v[170:171], v[52:53]
	v_pk_mul_f32 v[64:65], v[54:55], v[66:67]
	v_rcp_f32_e32 v66, v36
	v_mul_f32_e32 v52, 0x3fb8aa3b, v64
	v_exp_f32_e32 v52, v52
	v_add_f32_e32 v53, v64, v64
	v_fmamk_f32 v54, v53, 0x3d2aaaab, v185
	v_fma_f32 v54, v53, v54, 0.5
	v_fma_f32 v54, v53, v54, 1.0
	v_mul_f32_e64 v54, v54, -v53
	v_fma_f32 v52, -v52, v52, 1.0
	v_cmp_lt_f32_e32 vcc, s66, v53
	v_cvt_pk_f16_f32 v53, v90, v91
	v_add_f32_e32 v2, 1.0, v2
	v_cndmask_b32_e32 v52, v52, v54, vcc
	v_max_f32_e32 v52, 0, v52
	v_sqrt_f32_e32 v171, v52
	v_cvt_pk_f16_f32 v52, v56, v57
	v_cvt_pk_f16_f32 v54, v58, v59
	v_add_f32_e32 v7, v7, v75
	v_pk_mul_f32 v[56:57], v[170:171], v[64:65]
	v_rcp_f32_e32 v65, v40
	v_cvt_pk_f16_f32 v55, v56, v57
	v_lshl_add_u64 v[56:57], v[88:89], 2, s[18:19]
	global_store_dwordx4 v[56:57], v[48:51], off
	global_store_dwordx4 v[56:57], v[52:55], off offset:16
	v_mov_b32_e32 v64, v76
	v_add_u32_e32 v48, 0x24000, v160
	v_mov_b32_e32 v49, v161
	v_lshl_add_u64 v[50:51], v[48:49], 1, s[12:13]
	v_mov_b32_e32 v50, v216
	v_mov_b32_e32 v51, v217
	v_mov_b32_e32 v52, v218
	v_mov_b32_e32 v53, v219
	v_rcp_f32_e32 v54, v44
	v_add_f32_e32 v3, v3, v71
	v_mul_f32_e32 v7, 0xbfb8aa3b, v7
	v_mul_f32_e32 v3, 0xbfb8aa3b, v3
	v_exp_f32_e32 v7, v7
	v_exp_f32_e32 v3, v3
	s_nop 0
	v_lshlrev_b32_e32 v55, 16, v50
	v_pk_mul_f32 v[54:55], v[64:65], v[54:55]
	v_and_b32_e32 v57, 0xffff0000, v50
	v_add_f32_e32 v44, v54, v54
	v_fmamk_f32 v50, v44, 0x3d2aaaab, v185
	v_mul_f32_e32 v40, 0x3fb8aa3b, v54
	v_fma_f32 v50, v44, v50, 0.5
	v_exp_f32_e32 v40, v40
	v_fma_f32 v50, v44, v50, 1.0
	v_mul_f32_e64 v50, v50, -v44
	v_cmp_lt_f32_e32 vcc, s66, v44
	v_add_f32_e32 v44, v45, v85
	v_mul_f32_e32 v44, 0xbfb8aa3b, v44
	v_exp_f32_e32 v44, v44
	v_fma_f32 v40, -v40, v40, 1.0
	v_cndmask_b32_e32 v40, v40, v50, vcc
	v_max_f32_e32 v40, 0, v40
	v_sqrt_f32_e32 v171, v40
	v_add_f32_e32 v40, 1.0, v44
	v_rcp_f32_e32 v56, v40
	v_add_f32_e32 v40, 1.0, v41
	v_rcp_f32_e32 v41, v40
	v_mov_b32_e32 v40, v77
	v_lshlrev_b32_e32 v67, 16, v52
	v_and_b32_e32 v45, 0xffff0000, v52
	v_pk_mul_f32 v[40:41], v[40:41], v[56:57]
	v_pk_mul_f32 v[54:55], v[170:171], v[54:55]
	v_mul_f32_e32 v44, 0x3fb8aa3b, v40
	v_exp_f32_e32 v44, v44
	v_add_f32_e32 v50, v40, v40
	v_fmamk_f32 v52, v50, 0x3d2aaaab, v185
	v_fma_f32 v52, v50, v52, 0.5
	v_fma_f32 v52, v50, v52, 1.0
	v_mul_f32_e64 v52, v52, -v50
	v_fma_f32 v44, -v44, v44, 1.0
	v_cmp_lt_f32_e32 vcc, s66, v50
	v_rcp_f32_e32 v57, v42
	v_lshlrev_b32_e32 v59, 16, v51
	v_cndmask_b32_e32 v44, v44, v52, vcc
	v_max_f32_e32 v44, 0, v44
	v_sqrt_f32_e32 v171, v44
	v_add_f32_e32 v44, 1.0, v46
	v_rcp_f32_e32 v58, v44
	v_mov_b32_e32 v56, v78
	v_pk_mul_f32 v[40:41], v[170:171], v[40:41]
; __device__ __forceinline__ unsigned pk_f16(float lo, float hi) { f32x2 v = {lo, hi}; return __builtin_bit_cast(unsigned, __builtin_convertvector(v, f16v2)); }
; __device__ __forceinline__ float bf_lo(unsigned w) { return __uint_as_float(w << 16); }
; __device__ __forceinline__ float bf_hi(unsigned w) { return __uint_as_float(w & 0xffff0000u); }
; __device__ __forceinline__ float fast_sigmoid(float v) { return __builtin_amdgcn_rcpf(1.0f + __builtin_amdgcn_exp2f(-v * LOG2E)); }
;     __device__ __forceinline__ void operator()(const AccT& acc, const Unit& u, int wr, int wc, int fr, int fq) const {
;     ...
;             for (int m = 0; m < 4; ++m) { const unsigned off = (unsigned)(row0 + ai * HALF + m * 16) * DM + ch0;
;                 const u32x4 xw = *(const u32x4*)(xc + off);
;                 const float xv[8] = {bf_lo(xw.x), bf_hi(xw.x), bf_lo(xw.y), bf_hi(xw.y), bf_lo(xw.z), bf_hi(xw.z), bf_lo(xw.w), bf_hi(xw.w)};
;                 u32x4 pk[2];
; #pragma unroll
;                 for (int n = 0; n < 2; ++n)
; #pragma unroll
;                     for (int e = 0; e < 4; ++e) {
;                         const float rr = fast_sigmoid(acc[ai][0][m][n][e] + br[n][e]), ii = fast_sigmoid(acc[ai][1][m][n][e] + bi[n][e]);
;                         const float la = c8[n][e] * rr, a = __builtin_amdgcn_exp2f(la * LOG2E), x2 = 2.0f * la;
;                         const float ser = -x2 * (1.0f + x2 * (0.5f + x2 * (0.16666667f + x2 * 0.041666668f)));
;                         const float m2 = x2 > -0.06f ? ser : 1.0f - a * a;
;                         pk[n][e] = pk_f16(la * (LOG2E * 1024.0f), __builtin_amdgcn_sqrtf(fmaxf(m2, 0.f)) * (ii * xv[4 * n + e])); }
;                 *(u32x4*)(au_out + off) = pk[0]; *(u32x4*)(au_out + off + 4) = pk[1];
	v_and_b32_e32 v51, 0xffff0000, v51
	v_pk_mul_f32 v[56:57], v[56:57], v[58:59]
	v_lshlrev_b32_e32 v65, 16, v53
	v_add_f32_e32 v44, v56, v56
	v_fmamk_f32 v46, v44, 0x3d2aaaab, v185
	v_mul_f32_e32 v42, 0x3fb8aa3b, v56
	v_fma_f32 v46, v44, v46, 0.5
	v_exp_f32_e32 v42, v42
	v_fma_f32 v46, v44, v46, 1.0
	v_mul_f32_e64 v46, v46, -v44
	v_cmp_lt_f32_e32 vcc, s66, v44
	v_add_f32_e32 v44, v47, v87
	v_mul_f32_e32 v44, 0xbfb8aa3b, v44
	v_exp_f32_e32 v44, v44
	v_fma_f32 v42, -v42, v42, 1.0
	v_cndmask_b32_e32 v42, v42, v46, vcc
	v_max_f32_e32 v42, 0, v42
	v_sqrt_f32_e32 v171, v42
	v_add_f32_e32 v42, 1.0, v44
	v_rcp_f32_e32 v50, v42
	v_add_f32_e32 v42, 1.0, v43
	v_rcp_f32_e32 v43, v42
	v_mov_b32_e32 v42, v79
	v_and_b32_e32 v47, 0xffff0000, v53
	v_pk_mul_f32 v[52:53], v[170:171], v[56:57]
	v_pk_mul_f32 v[42:43], v[42:43], v[50:51]
	v_rcp_f32_e32 v51, v32
	v_mul_f32_e32 v44, 0x3fb8aa3b, v42
	v_exp_f32_e32 v44, v44
	v_add_f32_e32 v46, v42, v42
	v_fmamk_f32 v50, v46, 0x3d2aaaab, v185
	v_fma_f32 v50, v46, v50, 0.5
	v_fma_f32 v50, v46, v50, 1.0
	v_mul_f32_e64 v50, v50, -v46
	v_fma_f32 v44, -v44, v44, 1.0
	v_cmp_lt_f32_e32 vcc, s66, v46
	v_rcp_f32_e32 v64, v38
	v_cvt_pk_f16_f32 v32, v54, v55
	v_cndmask_b32_e32 v44, v44, v50, vcc
	v_mov_b32_e32 v50, v60
	v_pk_mul_f32 v[50:51], v[50:51], v[66:67]
	v_max_f32_e32 v44, 0, v44
	v_mul_f32_e32 v36, 0x3fb8aa3b, v50
	v_sqrt_f32_e32 v171, v44
	v_exp_f32_e32 v36, v36
	v_add_f32_e32 v44, v50, v50
	v_fmamk_f32 v46, v44, 0x3d2aaaab, v185
	v_fma_f32 v46, v44, v46, 0.5
	v_fma_f32 v46, v44, v46, 1.0
	v_mul_f32_e64 v46, v46, -v44
	v_fma_f32 v36, -v36, v36, 1.0
	v_cmp_lt_f32_e32 vcc, s66, v44
	v_pk_mul_f32 v[42:43], v[170:171], v[42:43]
	v_add_f32_e32 v3, 1.0, v3
	v_cndmask_b32_e32 v36, v36, v46, vcc
	v_max_f32_e32 v36, 0, v36
	v_sqrt_f32_e32 v171, v36
	v_add_f32_e32 v36, 1.0, v37
	v_rcp_f32_e32 v44, v36
	v_rcp_f32_e32 v37, v33
	v_mov_b32_e32 v36, v61
	v_cvt_pk_f16_f32 v33, v40, v41
	v_pk_mul_f32 v[40:41], v[170:171], v[50:51]
	v_pk_mul_f32 v[36:37], v[36:37], v[44:45]
	s_nop 0
	v_mul_f32_e32 v44, 0x3fb8aa3b, v36
	v_exp_f32_e32 v44, v44
	v_add_f32_e32 v45, v36, v36
	v_fmamk_f32 v46, v45, 0x3d2aaaab, v185
	v_fma_f32 v46, v45, v46, 0.5
	v_fma_f32 v46, v45, v46, 1.0
	v_mul_f32_e64 v46, v46, -v45
	v_fma_f32 v44, -v44, v44, 1.0
	v_cmp_lt_f32_e32 vcc, s66, v45
	v_rcp_f32_e32 v45, v34
	v_cvt_pk_f16_f32 v34, v52, v53
	v_cndmask_b32_e32 v44, v44, v46, vcc
	v_max_f32_e32 v44, 0, v44
	v_sqrt_f32_e32 v171, v44
	v_mov_b32_e32 v44, v62
	v_pk_mul_f32 v[50:51], v[170:171], v[36:37]
	v_pk_mul_f32 v[36:37], v[44:45], v[64:65]
	s_nop 0
	v_mul_f32_e32 v38, 0x3fb8aa3b, v36
	v_exp_f32_e32 v38, v38
	v_add_f32_e32 v44, v36, v36
	v_fmamk_f32 v45, v44, 0x3d2aaaab, v185
	v_fma_f32 v45, v44, v45, 0.5
	v_fma_f32 v45, v44, v45, 1.0
	v_mul_f32_e64 v45, v45, -v44
	v_fma_f32 v38, -v38, v38, 1.0
	v_cmp_lt_f32_e32 vcc, s66, v44
	s_nop 1
	v_cndmask_b32_e32 v38, v38, v45, vcc
	v_max_f32_e32 v38, 0, v38
	v_sqrt_f32_e32 v171, v38
	v_add_f32_e32 v38, 1.0, v39
	v_rcp_f32_e32 v46, v38
	v_rcp_f32_e32 v39, v35
	v_mov_b32_e32 v38, v63
	v_cvt_pk_f16_f32 v35, v42, v43
	v_pk_mul_f32 v[42:43], v[170:171], v[36:37]
	v_pk_mul_f32 v[44:45], v[38:39], v[46:47]
	v_rcp_f32_e32 v46, v20
	v_mul_f32_e32 v36, 0x3fb8aa3b, v44
	v_exp_f32_e32 v36, v36
	v_add_f32_e32 v37, v44, v44
	v_fmamk_f32 v38, v37, 0x3d2aaaab, v185
	v_fma_f32 v38, v37, v38, 0.5
	v_fma_f32 v38, v37, v38, 1.0
	v_mul_f32_e64 v38, v38, -v37
	v_fma_f32 v36, -v36, v36, 1.0
	v_cmp_lt_f32_e32 vcc, s66, v37
	v_cvt_pk_f16_f32 v37, v50, v51
	s_nop 0
	v_cndmask_b32_e32 v36, v36, v38, vcc
	v_max_f32_e32 v36, 0, v36
	v_sqrt_f32_e32 v171, v36
	v_cvt_pk_f16_f32 v36, v40, v41
	v_cvt_pk_f16_f32 v38, v42, v43
	v_pk_mul_f32 v[40:41], v[170:171], v[44:45]
	s_nop 0
	v_cvt_pk_f16_f32 v39, v40, v41
	v_lshl_add_u64 v[40:41], v[48:49], 2, s[18:19]
	global_store_dwordx4 v[40:41], v[32:35], off
	global_store_dwordx4 v[40:41], v[36:39], off offset:16
	v_rcp_f32_e32 v45, v24
	v_add_u32_e32 v32, 0x28000, v160
	v_mov_b32_e32 v33, v161
	v_lshl_add_u64 v[34:35], v[32:33], 1, s[12:13]
	v_mov_b32_e32 v34, v220
	v_mov_b32_e32 v35, v221
	v_mov_b32_e32 v36, v222
	v_mov_b32_e32 v37, v223
	v_rcp_f32_e32 v38, v28
	v_mov_b32_e32 v44, v76
	v_add_u32_e32 v160, 0x2c000, v160
	s_nop 0
	v_lshlrev_b32_e32 v39, 16, v34
	v_pk_mul_f32 v[38:39], v[44:45], v[38:39]
	v_and_b32_e32 v41, 0xffff0000, v34
	v_add_f32_e32 v28, v38, v38
	v_fmamk_f32 v34, v28, 0x3d2aaaab, v185
	v_mul_f32_e32 v24, 0x3fb8aa3b, v38
	v_fma_f32 v34, v28, v34, 0.5
	v_exp_f32_e32 v24, v24
	v_fma_f32 v34, v28, v34, 1.0
	v_mul_f32_e64 v34, v34, -v28
	v_cmp_lt_f32_e32 vcc, s66, v28
	v_add_f32_e32 v28, v29, v85
	v_mul_f32_e32 v28, 0xbfb8aa3b, v28
	v_exp_f32_e32 v28, v28
	v_fma_f32 v24, -v24, v24, 1.0
	v_cndmask_b32_e32 v24, v24, v34, vcc
	v_max_f32_e32 v24, 0, v24
	v_sqrt_f32_e32 v171, v24
	v_add_f32_e32 v24, 1.0, v28
	v_rcp_f32_e32 v40, v24
	v_add_f32_e32 v24, 1.0, v25
	v_rcp_f32_e32 v25, v24
	v_mov_b32_e32 v24, v77
	v_lshlrev_b32_e32 v47, 16, v36
	v_and_b32_e32 v29, 0xffff0000, v36
	v_pk_mul_f32 v[24:25], v[24:25], v[40:41]
	v_pk_mul_f32 v[38:39], v[170:171], v[38:39]
	v_mul_f32_e32 v28, 0x3fb8aa3b, v24
	v_exp_f32_e32 v28, v28
	v_add_f32_e32 v34, v24, v24
	v_fmamk_f32 v36, v34, 0x3d2aaaab, v185
	v_fma_f32 v36, v34, v36, 0.5
	v_fma_f32 v36, v34, v36, 1.0
	v_mul_f32_e64 v36, v36, -v34
	v_fma_f32 v28, -v28, v28, 1.0
	v_cmp_lt_f32_e32 vcc, s66, v34
	v_rcp_f32_e32 v41, v26
	v_lshlrev_b32_e32 v43, 16, v35
	v_cndmask_b32_e32 v28, v28, v36, vcc
	v_max_f32_e32 v28, 0, v28
	v_sqrt_f32_e32 v171, v28
	v_add_f32_e32 v28, 1.0, v30
	v_rcp_f32_e32 v42, v28
	v_mov_b32_e32 v40, v78
	v_pk_mul_f32 v[24:25], v[170:171], v[24:25]
; __device__ __forceinline__ unsigned pk_f16(float lo, float hi) { f32x2 v = {lo, hi}; return __builtin_bit_cast(unsigned, __builtin_convertvector(v, f16v2)); }
; __device__ __forceinline__ float bf_lo(unsigned w) { return __uint_as_float(w << 16); }
; __device__ __forceinline__ float bf_hi(unsigned w) { return __uint_as_float(w & 0xffff0000u); }
; __device__ __forceinline__ float fast_sigmoid(float v) { return __builtin_amdgcn_rcpf(1.0f + __builtin_amdgcn_exp2f(-v * LOG2E)); }
;     __device__ __forceinline__ void operator()(const AccT& acc, const Unit& u, int wr, int wc, int fr, int fq) const {
;     ...
;             for (int m = 0; m < 4; ++m) { const unsigned off = (unsigned)(row0 + ai * HALF + m * 16) * DM + ch0;
;                 const u32x4 xw = *(const u32x4*)(xc + off);
;                 const float xv[8] = {bf_lo(xw.x), bf_hi(xw.x), bf_lo(xw.y), bf_hi(xw.y), bf_lo(xw.z), bf_hi(xw.z), bf_lo(xw.w), bf_hi(xw.w)};
;                 u32x4 pk[2];
; #pragma unroll
;                 for (int n = 0; n < 2; ++n)
; #pragma unroll
;                     for (int e = 0; e < 4; ++e) {
;                         const float rr = fast_sigmoid(acc[ai][0][m][n][e] + br[n][e]), ii = fast_sigmoid(acc[ai][1][m][n][e] + bi[n][e]);
;                         const float la = c8[n][e] * rr, a = __builtin_amdgcn_exp2f(la * LOG2E), x2 = 2.0f * la;
;                         const float ser = -x2 * (1.0f + x2 * (0.5f + x2 * (0.16666667f + x2 * 0.041666668f)));
;                         const float m2 = x2 > -0.06f ? ser : 1.0f - a * a;
;                         pk[n][e] = pk_f16(la * (LOG2E * 1024.0f), __builtin_amdgcn_sqrtf(fmaxf(m2, 0.f)) * (ii * xv[4 * n + e])); }
;                 *(u32x4*)(au_out + off) = pk[0]; *(u32x4*)(au_out + off + 4) = pk[1];
	v_and_b32_e32 v35, 0xffff0000, v35
	v_pk_mul_f32 v[40:41], v[40:41], v[42:43]
	v_lshlrev_b32_e32 v45, 16, v37
	v_add_f32_e32 v28, v40, v40
	v_fmamk_f32 v30, v28, 0x3d2aaaab, v185
	v_mul_f32_e32 v26, 0x3fb8aa3b, v40
	v_fma_f32 v30, v28, v30, 0.5
	v_exp_f32_e32 v26, v26
	v_fma_f32 v30, v28, v30, 1.0
	v_mul_f32_e64 v30, v30, -v28
	v_cmp_lt_f32_e32 vcc, s66, v28
	v_add_f32_e32 v28, v31, v87
	v_mul_f32_e32 v28, 0xbfb8aa3b, v28
	v_exp_f32_e32 v28, v28
	v_fma_f32 v26, -v26, v26, 1.0
	v_cndmask_b32_e32 v26, v26, v30, vcc
	v_max_f32_e32 v26, 0, v26
	v_sqrt_f32_e32 v171, v26
	v_add_f32_e32 v26, 1.0, v28
	v_rcp_f32_e32 v34, v26
	v_add_f32_e32 v26, 1.0, v27
	v_rcp_f32_e32 v27, v26
	v_mov_b32_e32 v26, v79
	v_and_b32_e32 v31, 0xffff0000, v37
	v_pk_mul_f32 v[36:37], v[170:171], v[40:41]
	v_pk_mul_f32 v[26:27], v[26:27], v[34:35]
	v_rcp_f32_e32 v35, v16
	v_mul_f32_e32 v28, 0x3fb8aa3b, v26
	v_exp_f32_e32 v28, v28
	v_add_f32_e32 v30, v26, v26
	v_fmamk_f32 v34, v30, 0x3d2aaaab, v185
	v_fma_f32 v34, v30, v34, 0.5
	v_fma_f32 v34, v30, v34, 1.0
	v_mul_f32_e64 v34, v34, -v30
	v_fma_f32 v28, -v28, v28, 1.0
	v_cmp_lt_f32_e32 vcc, s66, v30
	v_rcp_f32_e32 v44, v22
	v_cvt_pk_f16_f32 v16, v38, v39
	v_cndmask_b32_e32 v28, v28, v34, vcc
	v_mov_b32_e32 v34, v60
	v_pk_mul_f32 v[34:35], v[34:35], v[46:47]
	v_max_f32_e32 v28, 0, v28
	v_mul_f32_e32 v20, 0x3fb8aa3b, v34
	v_sqrt_f32_e32 v171, v28
	v_exp_f32_e32 v20, v20
	v_add_f32_e32 v28, v34, v34
	v_fmamk_f32 v30, v28, 0x3d2aaaab, v185
	v_fma_f32 v30, v28, v30, 0.5
	v_fma_f32 v30, v28, v30, 1.0
	v_mul_f32_e64 v30, v30, -v28
	v_fma_f32 v20, -v20, v20, 1.0
	v_cmp_lt_f32_e32 vcc, s66, v28
	v_pk_mul_f32 v[26:27], v[170:171], v[26:27]
	s_nop 0
	v_cndmask_b32_e32 v20, v20, v30, vcc
	v_max_f32_e32 v20, 0, v20
	v_sqrt_f32_e32 v171, v20
	v_add_f32_e32 v20, 1.0, v21
	v_rcp_f32_e32 v28, v20
	v_rcp_f32_e32 v21, v17
	v_mov_b32_e32 v20, v61
	v_cvt_pk_f16_f32 v17, v24, v25
	v_pk_mul_f32 v[24:25], v[170:171], v[34:35]
	v_pk_mul_f32 v[20:21], v[20:21], v[28:29]
	s_nop 0
	v_mul_f32_e32 v28, 0x3fb8aa3b, v20
	v_exp_f32_e32 v28, v28
	v_add_f32_e32 v29, v20, v20
	v_fmamk_f32 v30, v29, 0x3d2aaaab, v185
	v_fma_f32 v30, v29, v30, 0.5
	v_fma_f32 v30, v29, v30, 1.0
	v_mul_f32_e64 v30, v30, -v29
	v_fma_f32 v28, -v28, v28, 1.0
	v_cmp_lt_f32_e32 vcc, s66, v29
	v_rcp_f32_e32 v29, v18
	v_cvt_pk_f16_f32 v18, v36, v37
	v_cndmask_b32_e32 v28, v28, v30, vcc
	v_max_f32_e32 v28, 0, v28
	v_sqrt_f32_e32 v171, v28
	v_mov_b32_e32 v28, v62
	v_pk_mul_f32 v[34:35], v[170:171], v[20:21]
	v_pk_mul_f32 v[20:21], v[28:29], v[44:45]
	s_nop 0
	v_mul_f32_e32 v22, 0x3fb8aa3b, v20
	v_exp_f32_e32 v22, v22
	v_add_f32_e32 v28, v20, v20
	v_fmamk_f32 v29, v28, 0x3d2aaaab, v185
	v_fma_f32 v29, v28, v29, 0.5
	v_fma_f32 v29, v28, v29, 1.0
	v_mul_f32_e64 v29, v29, -v28
	v_fma_f32 v22, -v22, v22, 1.0
	v_cmp_lt_f32_e32 vcc, s66, v28
	s_nop 1
	v_cndmask_b32_e32 v22, v22, v29, vcc
	v_max_f32_e32 v22, 0, v22
	v_sqrt_f32_e32 v171, v22
	v_add_f32_e32 v22, 1.0, v23
	v_rcp_f32_e32 v30, v22
	v_rcp_f32_e32 v23, v19
	v_mov_b32_e32 v22, v63
	v_cvt_pk_f16_f32 v19, v26, v27
	v_pk_mul_f32 v[26:27], v[170:171], v[20:21]
	v_pk_mul_f32 v[28:29], v[22:23], v[30:31]
	s_nop 0
	v_mul_f32_e32 v20, 0x3fb8aa3b, v28
	v_exp_f32_e32 v20, v20
	v_add_f32_e32 v21, v28, v28
	v_fmamk_f32 v22, v21, 0x3d2aaaab, v185
	v_fma_f32 v22, v21, v22, 0.5
	v_fma_f32 v22, v21, v22, 1.0
	v_mul_f32_e64 v22, v22, -v21
	v_fma_f32 v20, -v20, v20, 1.0
	v_cmp_lt_f32_e32 vcc, s66, v21
	v_cvt_pk_f16_f32 v21, v34, v35
	s_nop 0
	v_cndmask_b32_e32 v20, v20, v22, vcc
	v_max_f32_e32 v20, 0, v20
	v_sqrt_f32_e32 v171, v20
	v_cvt_pk_f16_f32 v20, v24, v25
	v_cvt_pk_f16_f32 v22, v26, v27
	v_rcp_f32_e32 v27, v8
	v_pk_mul_f32 v[24:25], v[170:171], v[28:29]
	v_mov_b32_e32 v26, v76
	v_cvt_pk_f16_f32 v23, v24, v25
	v_lshl_add_u64 v[24:25], v[32:33], 2, s[18:19]
	global_store_dwordx4 v[24:25], v[16:19], off
	global_store_dwordx4 v[24:25], v[20:23], off offset:16
	v_rcp_f32_e32 v28, v4
	v_lshl_add_u64 v[16:17], v[160:161], 1, s[12:13]
	v_mov_b32_e32 v16, v224
	v_mov_b32_e32 v17, v225
	v_mov_b32_e32 v18, v226
	v_mov_b32_e32 v19, v227
	v_rcp_f32_e32 v20, v12
	s_nop 0
	v_lshlrev_b32_e32 v21, 16, v16
	v_pk_mul_f32 v[20:21], v[26:27], v[20:21]
	v_and_b32_e32 v23, 0xffff0000, v16
	v_add_f32_e32 v12, v20, v20
	v_fmamk_f32 v16, v12, 0x3d2aaaab, v185
	v_mul_f32_e32 v8, 0x3fb8aa3b, v20
	v_fma_f32 v16, v12, v16, 0.5
	v_exp_f32_e32 v8, v8
	v_fma_f32 v16, v12, v16, 1.0
	v_mul_f32_e64 v16, v16, -v12
	v_cmp_lt_f32_e32 vcc, s66, v12
	v_add_f32_e32 v12, v13, v85
	v_mul_f32_e32 v12, 0xbfb8aa3b, v12
	v_exp_f32_e32 v12, v12
	v_fma_f32 v8, -v8, v8, 1.0
	v_cndmask_b32_e32 v8, v8, v16, vcc
	v_max_f32_e32 v8, 0, v8
	v_sqrt_f32_e32 v171, v8
	v_add_f32_e32 v8, 1.0, v12
; __device__ __forceinline__ unsigned pk_f16(float lo, float hi) { f32x2 v = {lo, hi}; return __builtin_bit_cast(unsigned, __builtin_convertvector(v, f16v2)); }
; __device__ __forceinline__ float fast_sigmoid(float v) { return __builtin_amdgcn_rcpf(1.0f + __builtin_amdgcn_exp2f(-v * LOG2E)); }
; #define PG8_BAR __builtin_amdgcn_s_barrier()
;     __device__ __forceinline__ void operator()(const AccT& acc, const Unit& u, int wr, int wc, int fr, int fq) const {
;     ...
;                 for (int n = 0; n < 2; ++n)
; #pragma unroll
;                     for (int e = 0; e < 4; ++e) {
;                         const float rr = fast_sigmoid(acc[ai][0][m][n][e] + br[n][e]), ii = fast_sigmoid(acc[ai][1][m][n][e] + bi[n][e]);
;                         const float la = c8[n][e] * rr, a = __builtin_amdgcn_exp2f(la * LOG2E), x2 = 2.0f * la;
;                         const float ser = -x2 * (1.0f + x2 * (0.5f + x2 * (0.16666667f + x2 * 0.041666668f)));
;                         const float m2 = x2 > -0.06f ? ser : 1.0f - a * a;
;                         pk[n][e] = pk_f16(la * (LOG2E * 1024.0f), __builtin_amdgcn_sqrtf(fmaxf(m2, 0.f)) * (ii * xv[4 * n + e])); }
;                 *(u32x4*)(au_out + off) = pk[0]; *(u32x4*)(au_out + off + 4) = pk[1];
;                 asm volatile("" ::: "memory"); }
; template <class Epi, class Sched, bool ALIGN_EPI = false, bool SP2 = false>
; __device__ __forceinline__ void gemm_phase(PG8_LAS unsigned char* lds, const Gemm g, const Sched& S, const Epi& E, const int wid) {
;     ...
;         if constexpr (ALIGN_EPI) { if (wr == 0) PG8_BAR; }
;         if constexpr (!Epi::AFTER_DRAIN) { E(acc, cur, wr, wc, fr, fq); S.done(cur); }
;         if (!has_next) break;
; #pragma unroll
;         for (int a = 0; a < 2; ++a)
; #pragma unroll
;             for (int b = 0; b < 2; ++b)
; #pragma unroll
;                 for (int m = 0; m < 4; ++m)
; #pragma unroll
;                     for (int n = 0; n < 2; ++n) acc[a][b][m][n] = (f32x4){0.f, 0.f, 0.f, 0.f};
;         cur = nxt; cA = nA; cB = nB; ++ui;
;         if constexpr (ALIGN_EPI) { if (wr == 1) PG8_BAR; }
	v_rcp_f32_e32 v22, v8
	v_add_f32_e32 v8, 1.0, v9
	v_rcp_f32_e32 v9, v8
	v_mov_b32_e32 v8, v77
	v_lshlrev_b32_e32 v29, 16, v18
	v_and_b32_e32 v13, 0xffff0000, v18
	v_pk_mul_f32 v[8:9], v[8:9], v[22:23]
	v_pk_mul_f32 v[20:21], v[170:171], v[20:21]
	v_mul_f32_e32 v12, 0x3fb8aa3b, v8
	v_exp_f32_e32 v12, v12
	v_add_f32_e32 v16, v8, v8
	v_fmamk_f32 v18, v16, 0x3d2aaaab, v185
	v_fma_f32 v18, v16, v18, 0.5
	v_fma_f32 v18, v16, v18, 1.0
	v_mul_f32_e64 v18, v18, -v16
	v_fma_f32 v12, -v12, v12, 1.0
	v_cmp_lt_f32_e32 vcc, s66, v16
	v_rcp_f32_e32 v23, v10
	v_lshlrev_b32_e32 v25, 16, v17
	v_cndmask_b32_e32 v12, v12, v18, vcc
	v_max_f32_e32 v12, 0, v12
	v_sqrt_f32_e32 v171, v12
	v_add_f32_e32 v12, 1.0, v14
	v_rcp_f32_e32 v24, v12
	v_mov_b32_e32 v22, v78
	v_pk_mul_f32 v[8:9], v[170:171], v[8:9]
	v_and_b32_e32 v17, 0xffff0000, v17
	v_pk_mul_f32 v[22:23], v[22:23], v[24:25]
	v_lshlrev_b32_e32 v27, 16, v19
	v_add_f32_e32 v12, v22, v22
	v_fmamk_f32 v14, v12, 0x3d2aaaab, v185
	v_mul_f32_e32 v10, 0x3fb8aa3b, v22
	v_fma_f32 v14, v12, v14, 0.5
	v_exp_f32_e32 v10, v10
	v_fma_f32 v14, v12, v14, 1.0
	v_mul_f32_e64 v14, v14, -v12
	v_cmp_lt_f32_e32 vcc, s66, v12
	v_add_f32_e32 v12, v15, v87
	v_mul_f32_e32 v12, 0xbfb8aa3b, v12
	v_exp_f32_e32 v12, v12
	v_fma_f32 v10, -v10, v10, 1.0
	v_cndmask_b32_e32 v10, v10, v14, vcc
	v_max_f32_e32 v10, 0, v10
	v_sqrt_f32_e32 v171, v10
	v_add_f32_e32 v10, 1.0, v12
	v_rcp_f32_e32 v16, v10
	v_add_f32_e32 v10, 1.0, v11
	v_rcp_f32_e32 v11, v10
	v_mov_b32_e32 v10, v79
	v_and_b32_e32 v15, 0xffff0000, v19
	v_pk_mul_f32 v[18:19], v[170:171], v[22:23]
	v_pk_mul_f32 v[10:11], v[10:11], v[16:17]
	v_rcp_f32_e32 v17, v0
	v_mul_f32_e32 v12, 0x3fb8aa3b, v10
	v_exp_f32_e32 v12, v12
	v_add_f32_e32 v14, v10, v10
	v_fmamk_f32 v16, v14, 0x3d2aaaab, v185
	v_fma_f32 v16, v14, v16, 0.5
	v_fma_f32 v16, v14, v16, 1.0
	v_mul_f32_e64 v16, v16, -v14
	v_fma_f32 v12, -v12, v12, 1.0
	v_cmp_lt_f32_e32 vcc, s66, v14
	v_rcp_f32_e32 v26, v6
	v_cvt_pk_f16_f32 v0, v20, v21
	v_cndmask_b32_e32 v12, v12, v16, vcc
	v_mov_b32_e32 v16, v60
	v_pk_mul_f32 v[16:17], v[16:17], v[28:29]
	v_max_f32_e32 v12, 0, v12
	v_mul_f32_e32 v4, 0x3fb8aa3b, v16
	v_sqrt_f32_e32 v171, v12
	v_exp_f32_e32 v4, v4
	v_add_f32_e32 v12, v16, v16
	v_fmamk_f32 v14, v12, 0x3d2aaaab, v185
	v_fma_f32 v14, v12, v14, 0.5
	v_fma_f32 v14, v12, v14, 1.0
	v_mul_f32_e64 v14, v14, -v12
	v_fma_f32 v4, -v4, v4, 1.0
	v_cmp_lt_f32_e32 vcc, s66, v12
	v_pk_mul_f32 v[10:11], v[170:171], v[10:11]
	s_nop 0
	v_cndmask_b32_e32 v4, v4, v14, vcc
	v_max_f32_e32 v4, 0, v4
	v_sqrt_f32_e32 v171, v4
	v_add_f32_e32 v4, 1.0, v5
	v_rcp_f32_e32 v12, v4
	v_rcp_f32_e32 v5, v1
	v_mov_b32_e32 v4, v61
	v_cvt_pk_f16_f32 v1, v8, v9
	v_pk_mul_f32 v[8:9], v[170:171], v[16:17]
	v_pk_mul_f32 v[4:5], v[4:5], v[12:13]
	s_nop 0
	v_mul_f32_e32 v12, 0x3fb8aa3b, v4
	v_exp_f32_e32 v12, v12
	v_add_f32_e32 v13, v4, v4
	v_fmamk_f32 v14, v13, 0x3d2aaaab, v185
	v_fma_f32 v14, v13, v14, 0.5
	v_fma_f32 v14, v13, v14, 1.0
	v_mul_f32_e64 v14, v14, -v13
	v_fma_f32 v12, -v12, v12, 1.0
	v_cmp_lt_f32_e32 vcc, s66, v13
	v_rcp_f32_e32 v13, v2
	v_cvt_pk_f16_f32 v2, v18, v19
	v_cndmask_b32_e32 v12, v12, v14, vcc
	v_max_f32_e32 v12, 0, v12
	v_sqrt_f32_e32 v171, v12
	v_mov_b32_e32 v12, v62
	v_pk_mul_f32 v[16:17], v[170:171], v[4:5]
	v_pk_mul_f32 v[4:5], v[12:13], v[26:27]
	s_nop 0
	v_mul_f32_e32 v6, 0x3fb8aa3b, v4
	v_exp_f32_e32 v6, v6
	v_add_f32_e32 v12, v4, v4
	v_fmamk_f32 v13, v12, 0x3d2aaaab, v185
	v_fma_f32 v13, v12, v13, 0.5
	v_fma_f32 v13, v12, v13, 1.0
	v_mul_f32_e64 v13, v13, -v12
	v_fma_f32 v6, -v6, v6, 1.0
	v_cmp_lt_f32_e32 vcc, s66, v12
	s_nop 1
	v_cndmask_b32_e32 v6, v6, v13, vcc
	v_max_f32_e32 v6, 0, v6
	v_sqrt_f32_e32 v171, v6
	v_add_f32_e32 v6, 1.0, v7
	v_rcp_f32_e32 v14, v6
	v_rcp_f32_e32 v7, v3
	v_mov_b32_e32 v6, v63
	v_cvt_pk_f16_f32 v3, v10, v11
	v_pk_mul_f32 v[10:11], v[170:171], v[4:5]
	v_pk_mul_f32 v[12:13], v[6:7], v[14:15]
	s_nop 0
	v_mul_f32_e32 v4, 0x3fb8aa3b, v12
	v_exp_f32_e32 v4, v4
	v_add_f32_e32 v5, v12, v12
	v_fmamk_f32 v6, v5, 0x3d2aaaab, v185
	v_fma_f32 v6, v5, v6, 0.5
	v_fma_f32 v6, v5, v6, 1.0
	v_mul_f32_e64 v6, v6, -v5
	v_fma_f32 v4, -v4, v4, 1.0
	v_cmp_lt_f32_e32 vcc, s66, v5
	v_cvt_pk_f16_f32 v5, v16, v17
	s_nop 0
	v_cndmask_b32_e32 v4, v4, v6, vcc
	v_max_f32_e32 v4, 0, v4
	v_sqrt_f32_e32 v171, v4
	v_cvt_pk_f16_f32 v4, v8, v9
	v_cvt_pk_f16_f32 v6, v10, v11
	s_and_b64 vcc, exec, s[4:5]
	v_pk_mul_f32 v[8:9], v[170:171], v[12:13]
	s_mov_b64 s[4:5], -1
	v_cvt_pk_f16_f32 v7, v8, v9
	v_lshl_add_u64 v[8:9], v[160:161], 2, s[18:19]
	global_store_dwordx4 v[8:9], v[0:3], off
	global_store_dwordx4 v[8:9], v[4:7], off offset:16
	s_cbranch_vccnz .LBB0_259
	s_andn2_b64 vcc, exec, s[8:9]
	s_cbranch_vccnz .LBB0_258
	s_barrier
	s_branch .LBB0_258

; __device__ __forceinline__ unsigned pk_bf16(float lo, float hi) { f32x2 v = {lo, hi}; return __builtin_bit_cast(unsigned, __builtin_convertvector(v, bf16v2)); }
; __device__ __forceinline__ float bf_lo(unsigned w) { return __uint_as_float(w << 16); }
; __device__ __forceinline__ float bf_hi(unsigned w) { return __uint_as_float(w & 0xffff0000u); }
; __device__ __forceinline__ void scan_pass2_tile(const unsigned* au, const f32x4* saggP, const f32x4* saggH, const f32x4* cpreP, const f32x4* cpreH, const bf16_t* gate, bf16_t* y, int pm, int blk, int tid) {
;     const int cl = tid >> 6, ql = tid & 63, b = pm / SCAN_NSC, c4 = blk * 64 + ql, ck = pm * SCAN_SC + cl;
;     f32x4 C = {0.f, 0.f, 0.f, 0.f};
;     for (int j = b * SCAN_NSC; j < pm; ++j) { const f32x4 p = saggP[(size_t)j * 256 + c4], h = saggH[(size_t)j * 256 + c4]; C = p * C + h; }
;     f32x4 Hh = cpreP[(size_t)ck * 256 + c4] * C + cpreH[(size_t)ck * 256 + c4];
;     const size_t off = (size_t)ck * SCAN_L * DM + 4 * c4;
; #pragma unroll 16
;     for (int t = 0; t < SCAN_L; ++t) { const size_t o = off + (size_t)t * DM; f32x4 a, u; au_unpack(*(const u32x4*)(au + o), a, u); const u32x2 gw2 = *(const u32x2*)(gate + o);
;         Hh = a * Hh + u;
;         u32x2 w; w.x = pk_bf16(Hh[0] * bf_lo(gw2.x), Hh[1] * bf_hi(gw2.x)); w.y = pk_bf16(Hh[2] * bf_lo(gw2.y), Hh[3] * bf_hi(gw2.y));
;         *(u32x2*)(y + o) = w; }
.LBB0_347:
	v_mov_b32_e32 v6, v14
	v_mov_b32_e32 v7, v15
	v_mov_b32_e32 v8, v12
	v_mov_b32_e32 v9, v13
	v_add_u32_e32 v10, 0xba00000, v4
	v_add_u32_e32 v11, 0x5a00000, v2
	v_add_u32_e32 v16, 0x7a00000, v2
	v_add_u32_e32 v17, 0x0, v10
	global_load_dwordx4 v[20:23], v17, s[90:91]
	v_add_u32_e32 v18, 0x0, v11
	global_load_dwordx2 v[84:85], v18, s[90:91]
	v_add_u32_e32 v17, 0x1000, v10
	global_load_dwordx4 v[24:27], v17, s[90:91]
	global_load_dwordx2 v[86:87], v18, s[90:91] offset:2048
	v_add_u32_e32 v17, 0x2000, v10
	global_load_dwordx4 v[28:31], v17, s[90:91]
	v_add_u32_e32 v18, 0x1000, v11
	global_load_dwordx2 v[88:89], v18, s[90:91]
	v_add_u32_e32 v17, 0x3000, v10
	global_load_dwordx4 v[32:35], v17, s[90:91]
	global_load_dwordx2 v[90:91], v18, s[90:91] offset:2048
	v_add_u32_e32 v17, 0x4000, v10
	global_load_dwordx4 v[36:39], v17, s[90:91]
	v_add_u32_e32 v18, 0x2000, v11
	global_load_dwordx2 v[92:93], v18, s[90:91]
	v_add_u32_e32 v17, 0x5000, v10
	global_load_dwordx4 v[40:43], v17, s[90:91]
	global_load_dwordx2 v[94:95], v18, s[90:91] offset:2048
	v_add_u32_e32 v17, 0x6000, v10
	global_load_dwordx4 v[44:47], v17, s[90:91]
	v_add_u32_e32 v18, 0x3000, v11
	global_load_dwordx2 v[96:97], v18, s[90:91]
	v_add_u32_e32 v17, 0x7000, v10
	global_load_dwordx4 v[48:51], v17, s[90:91]
	global_load_dwordx2 v[98:99], v18, s[90:91] offset:2048
	v_add_u32_e32 v17, 0x8000, v10
	global_load_dwordx4 v[52:55], v17, s[90:91]
	v_add_u32_e32 v18, 0x4000, v11
	global_load_dwordx2 v[100:101], v18, s[90:91]
	v_add_u32_e32 v17, 0x9000, v10
	global_load_dwordx4 v[56:59], v17, s[90:91]
	global_load_dwordx2 v[102:103], v18, s[90:91] offset:2048
	v_add_u32_e32 v17, 0xa000, v10
	global_load_dwordx4 v[60:63], v17, s[90:91]
	v_add_u32_e32 v18, 0x5000, v11
	global_load_dwordx2 v[104:105], v18, s[90:91]
	v_add_u32_e32 v17, 0xb000, v10
	global_load_dwordx4 v[64:67], v17, s[90:91]
	global_load_dwordx2 v[106:107], v18, s[90:91] offset:2048
	v_add_u32_e32 v17, 0xc000, v10
	global_load_dwordx4 v[68:71], v17, s[90:91]
	v_add_u32_e32 v18, 0x6000, v11
	global_load_dwordx2 v[108:109], v18, s[90:91]
	v_add_u32_e32 v17, 0xd000, v10
	global_load_dwordx4 v[72:75], v17, s[90:91]
	global_load_dwordx2 v[110:111], v18, s[90:91] offset:2048
	v_add_u32_e32 v17, 0xe000, v10
	global_load_dwordx4 v[76:79], v17, s[90:91]
	v_add_u32_e32 v18, 0x7000, v11
	global_load_dwordx2 v[112:113], v18, s[90:91]
	v_add_u32_e32 v17, 0xf000, v10
	global_load_dwordx4 v[80:83], v17, s[90:91]
	global_load_dwordx2 v[114:115], v18, s[90:91] offset:2048
	s_waitcnt vmcnt(30)
	v_cvt_f32_f16_e32 v216, v20
	v_cvt_f32_f16_e32 v217, v21
	v_cvt_f32_f16_e32 v218, v22
	v_cvt_f32_f16_e32 v219, v23
	v_cvt_f32_f16_sdwa v220, v20 dst_sel:DWORD dst_unused:UNUSED_PAD src0_sel:WORD_1
	v_cvt_f32_f16_sdwa v221, v21 dst_sel:DWORD dst_unused:UNUSED_PAD src0_sel:WORD_1
	v_cvt_f32_f16_sdwa v222, v22 dst_sel:DWORD dst_unused:UNUSED_PAD src0_sel:WORD_1
	v_cvt_f32_f16_sdwa v223, v23 dst_sel:DWORD dst_unused:UNUSED_PAD src0_sel:WORD_1
	v_mul_f32_e32 v216, 0x3a800000, v216
	v_mul_f32_e32 v217, 0x3a800000, v217
	v_mul_f32_e32 v218, 0x3a800000, v218
	v_mul_f32_e32 v219, 0x3a800000, v219
	v_exp_f32_e32 v224, v216
	v_exp_f32_e32 v225, v217
	v_exp_f32_e32 v226, v218
	v_exp_f32_e32 v227, v219
	v_lshlrev_b32_e32 v228, 16, v84
	v_and_b32_e32 v229, 0xffff0000, v84
	v_lshlrev_b32_e32 v230, 16, v85
	v_and_b32_e32 v231, 0xffff0000, v85
	v_pk_fma_f32 v[8:9], v[8:9], v[226:227], v[222:223]
	v_pk_fma_f32 v[6:7], v[6:7], v[224:225], v[220:221]
	v_pk_mul_f32 v[234:235], v[8:9], v[230:231]
	v_pk_mul_f32 v[232:233], v[6:7], v[228:229]
	v_add_u32_e32 v19, 0x0, v16
	v_cvt_pk_bf16_f32 v236, v232, v233
	v_cvt_pk_bf16_f32 v237, v234, v235
	global_store_dwordx2 v19, v[236:237], s[90:91]
	s_waitcnt vmcnt(29)
	v_cvt_f32_f16_e32 v216, v24
	v_cvt_f32_f16_e32 v217, v25
	v_cvt_f32_f16_e32 v218, v26
	v_cvt_f32_f16_e32 v219, v27
	v_cvt_f32_f16_sdwa v220, v24 dst_sel:DWORD dst_unused:UNUSED_PAD src0_sel:WORD_1
	v_cvt_f32_f16_sdwa v221, v25 dst_sel:DWORD dst_unused:UNUSED_PAD src0_sel:WORD_1
	v_cvt_f32_f16_sdwa v222, v26 dst_sel:DWORD dst_unused:UNUSED_PAD src0_sel:WORD_1
	v_cvt_f32_f16_sdwa v223, v27 dst_sel:DWORD dst_unused:UNUSED_PAD src0_sel:WORD_1
	v_mul_f32_e32 v216, 0x3a800000, v216
	v_mul_f32_e32 v217, 0x3a800000, v217
	v_mul_f32_e32 v218, 0x3a800000, v218
	v_mul_f32_e32 v219, 0x3a800000, v219
	v_exp_f32_e32 v224, v216
	v_exp_f32_e32 v225, v217
	v_exp_f32_e32 v226, v218
	v_exp_f32_e32 v227, v219
	v_lshlrev_b32_e32 v228, 16, v86
	v_and_b32_e32 v229, 0xffff0000, v86
	v_lshlrev_b32_e32 v230, 16, v87
	v_and_b32_e32 v231, 0xffff0000, v87
	v_pk_fma_f32 v[8:9], v[8:9], v[226:227], v[222:223]
	v_pk_fma_f32 v[6:7], v[6:7], v[224:225], v[220:221]
	v_pk_mul_f32 v[234:235], v[8:9], v[230:231]
	v_pk_mul_f32 v[232:233], v[6:7], v[228:229]
	v_cvt_pk_bf16_f32 v236, v232, v233
	v_cvt_pk_bf16_f32 v237, v234, v235
	global_store_dwordx2 v19, v[236:237], s[90:91] offset:2048
	s_waitcnt vmcnt(28)
	v_cvt_f32_f16_e32 v216, v28
	v_cvt_f32_f16_e32 v217, v29
	v_cvt_f32_f16_e32 v218, v30
	v_cvt_f32_f16_e32 v219, v31
	v_cvt_f32_f16_sdwa v220, v28 dst_sel:DWORD dst_unused:UNUSED_PAD src0_sel:WORD_1
	v_cvt_f32_f16_sdwa v221, v29 dst_sel:DWORD dst_unused:UNUSED_PAD src0_sel:WORD_1
	v_cvt_f32_f16_sdwa v222, v30 dst_sel:DWORD dst_unused:UNUSED_PAD src0_sel:WORD_1
	v_cvt_f32_f16_sdwa v223, v31 dst_sel:DWORD dst_unused:UNUSED_PAD src0_sel:WORD_1
	v_mul_f32_e32 v216, 0x3a800000, v216
	v_mul_f32_e32 v217, 0x3a800000, v217
	v_mul_f32_e32 v218, 0x3a800000, v218
	v_mul_f32_e32 v219, 0x3a800000, v219
	v_exp_f32_e32 v224, v216
	v_exp_f32_e32 v225, v217
	v_exp_f32_e32 v226, v218
	v_exp_f32_e32 v227, v219
	v_lshlrev_b32_e32 v228, 16, v88
	v_and_b32_e32 v229, 0xffff0000, v88
	v_lshlrev_b32_e32 v230, 16, v89
	v_and_b32_e32 v231, 0xffff0000, v89
	v_pk_fma_f32 v[8:9], v[8:9], v[226:227], v[222:223]
	v_pk_fma_f32 v[6:7], v[6:7], v[224:225], v[220:221]
	v_pk_mul_f32 v[234:235], v[8:9], v[230:231]
	v_pk_mul_f32 v[232:233], v[6:7], v[228:229]
	v_add_u32_e32 v19, 0x1000, v16
	v_cvt_pk_bf16_f32 v236, v232, v233
	v_cvt_pk_bf16_f32 v237, v234, v235
	global_store_dwordx2 v19, v[236:237], s[90:91]
	s_waitcnt vmcnt(27)
; __device__ __forceinline__ unsigned pk_bf16(float lo, float hi) { f32x2 v = {lo, hi}; return __builtin_bit_cast(unsigned, __builtin_convertvector(v, bf16v2)); }
; __device__ __forceinline__ float bf_lo(unsigned w) { return __uint_as_float(w << 16); }
; __device__ __forceinline__ float bf_hi(unsigned w) { return __uint_as_float(w & 0xffff0000u); }
; __device__ __forceinline__ void scan_pass2_tile(const unsigned* au, const f32x4* saggP, const f32x4* saggH, const f32x4* cpreP, const f32x4* cpreH, const bf16_t* gate, bf16_t* y, int pm, int blk, int tid) {
;     ...
;     for (int t = 0; t < SCAN_L; ++t) { const size_t o = off + (size_t)t * DM; f32x4 a, u; au_unpack(*(const u32x4*)(au + o), a, u); const u32x2 gw2 = *(const u32x2*)(gate + o);
;         Hh = a * Hh + u;
;         u32x2 w; w.x = pk_bf16(Hh[0] * bf_lo(gw2.x), Hh[1] * bf_hi(gw2.x)); w.y = pk_bf16(Hh[2] * bf_lo(gw2.y), Hh[3] * bf_hi(gw2.y));
;         *(u32x2*)(y + o) = w; }
	v_cvt_f32_f16_e32 v216, v32
	v_cvt_f32_f16_e32 v217, v33
	v_cvt_f32_f16_e32 v218, v34
	v_cvt_f32_f16_e32 v219, v35
	v_cvt_f32_f16_sdwa v220, v32 dst_sel:DWORD dst_unused:UNUSED_PAD src0_sel:WORD_1
	v_cvt_f32_f16_sdwa v221, v33 dst_sel:DWORD dst_unused:UNUSED_PAD src0_sel:WORD_1
	v_cvt_f32_f16_sdwa v222, v34 dst_sel:DWORD dst_unused:UNUSED_PAD src0_sel:WORD_1
	v_cvt_f32_f16_sdwa v223, v35 dst_sel:DWORD dst_unused:UNUSED_PAD src0_sel:WORD_1
	v_mul_f32_e32 v216, 0x3a800000, v216
	v_mul_f32_e32 v217, 0x3a800000, v217
	v_mul_f32_e32 v218, 0x3a800000, v218
	v_mul_f32_e32 v219, 0x3a800000, v219
	v_exp_f32_e32 v224, v216
	v_exp_f32_e32 v225, v217
	v_exp_f32_e32 v226, v218
	v_exp_f32_e32 v227, v219
	v_lshlrev_b32_e32 v228, 16, v90
	v_and_b32_e32 v229, 0xffff0000, v90
	v_lshlrev_b32_e32 v230, 16, v91
	v_and_b32_e32 v231, 0xffff0000, v91
	v_pk_fma_f32 v[8:9], v[8:9], v[226:227], v[222:223]
	v_pk_fma_f32 v[6:7], v[6:7], v[224:225], v[220:221]
	v_pk_mul_f32 v[234:235], v[8:9], v[230:231]
	v_pk_mul_f32 v[232:233], v[6:7], v[228:229]
	v_cvt_pk_bf16_f32 v236, v232, v233
	v_cvt_pk_bf16_f32 v237, v234, v235
	global_store_dwordx2 v19, v[236:237], s[90:91] offset:2048
	s_waitcnt vmcnt(26)
	v_cvt_f32_f16_e32 v216, v36
	v_cvt_f32_f16_e32 v217, v37
	v_cvt_f32_f16_e32 v218, v38
	v_cvt_f32_f16_e32 v219, v39
	v_cvt_f32_f16_sdwa v220, v36 dst_sel:DWORD dst_unused:UNUSED_PAD src0_sel:WORD_1
	v_cvt_f32_f16_sdwa v221, v37 dst_sel:DWORD dst_unused:UNUSED_PAD src0_sel:WORD_1
	v_cvt_f32_f16_sdwa v222, v38 dst_sel:DWORD dst_unused:UNUSED_PAD src0_sel:WORD_1
	v_cvt_f32_f16_sdwa v223, v39 dst_sel:DWORD dst_unused:UNUSED_PAD src0_sel:WORD_1
	v_mul_f32_e32 v216, 0x3a800000, v216
	v_mul_f32_e32 v217, 0x3a800000, v217
	v_mul_f32_e32 v218, 0x3a800000, v218
	v_mul_f32_e32 v219, 0x3a800000, v219
	v_exp_f32_e32 v224, v216
	v_exp_f32_e32 v225, v217
	v_exp_f32_e32 v226, v218
	v_exp_f32_e32 v227, v219
	v_lshlrev_b32_e32 v228, 16, v92
	v_and_b32_e32 v229, 0xffff0000, v92
	v_lshlrev_b32_e32 v230, 16, v93
	v_and_b32_e32 v231, 0xffff0000, v93
	v_pk_fma_f32 v[8:9], v[8:9], v[226:227], v[222:223]
	v_pk_fma_f32 v[6:7], v[6:7], v[224:225], v[220:221]
	v_pk_mul_f32 v[234:235], v[8:9], v[230:231]
	v_pk_mul_f32 v[232:233], v[6:7], v[228:229]
	v_add_u32_e32 v19, 0x2000, v16
	v_cvt_pk_bf16_f32 v236, v232, v233
	v_cvt_pk_bf16_f32 v237, v234, v235
	global_store_dwordx2 v19, v[236:237], s[90:91]
	s_waitcnt vmcnt(25)
	v_cvt_f32_f16_e32 v216, v40
	v_cvt_f32_f16_e32 v217, v41
	v_cvt_f32_f16_e32 v218, v42
	v_cvt_f32_f16_e32 v219, v43
	v_cvt_f32_f16_sdwa v220, v40 dst_sel:DWORD dst_unused:UNUSED_PAD src0_sel:WORD_1
	v_cvt_f32_f16_sdwa v221, v41 dst_sel:DWORD dst_unused:UNUSED_PAD src0_sel:WORD_1
	v_cvt_f32_f16_sdwa v222, v42 dst_sel:DWORD dst_unused:UNUSED_PAD src0_sel:WORD_1
	v_cvt_f32_f16_sdwa v223, v43 dst_sel:DWORD dst_unused:UNUSED_PAD src0_sel:WORD_1
	v_mul_f32_e32 v216, 0x3a800000, v216
	v_mul_f32_e32 v217, 0x3a800000, v217
	v_mul_f32_e32 v218, 0x3a800000, v218
	v_mul_f32_e32 v219, 0x3a800000, v219
	v_exp_f32_e32 v224, v216
	v_exp_f32_e32 v225, v217
	v_exp_f32_e32 v226, v218
	v_exp_f32_e32 v227, v219
	v_lshlrev_b32_e32 v228, 16, v94
	v_and_b32_e32 v229, 0xffff0000, v94
	v_lshlrev_b32_e32 v230, 16, v95
	v_and_b32_e32 v231, 0xffff0000, v95
	v_pk_fma_f32 v[8:9], v[8:9], v[226:227], v[222:223]
	v_pk_fma_f32 v[6:7], v[6:7], v[224:225], v[220:221]
	v_pk_mul_f32 v[234:235], v[8:9], v[230:231]
	v_pk_mul_f32 v[232:233], v[6:7], v[228:229]
	v_cvt_pk_bf16_f32 v236, v232, v233
	v_cvt_pk_bf16_f32 v237, v234, v235
	global_store_dwordx2 v19, v[236:237], s[90:91] offset:2048
	s_waitcnt vmcnt(24)
	v_cvt_f32_f16_e32 v216, v44
	v_cvt_f32_f16_e32 v217, v45
	v_cvt_f32_f16_e32 v218, v46
	v_cvt_f32_f16_e32 v219, v47
	v_cvt_f32_f16_sdwa v220, v44 dst_sel:DWORD dst_unused:UNUSED_PAD src0_sel:WORD_1
	v_cvt_f32_f16_sdwa v221, v45 dst_sel:DWORD dst_unused:UNUSED_PAD src0_sel:WORD_1
	v_cvt_f32_f16_sdwa v222, v46 dst_sel:DWORD dst_unused:UNUSED_PAD src0_sel:WORD_1
	v_cvt_f32_f16_sdwa v223, v47 dst_sel:DWORD dst_unused:UNUSED_PAD src0_sel:WORD_1
	v_mul_f32_e32 v216, 0x3a800000, v216
	v_mul_f32_e32 v217, 0x3a800000, v217
	v_mul_f32_e32 v218, 0x3a800000, v218
	v_mul_f32_e32 v219, 0x3a800000, v219
	v_exp_f32_e32 v224, v216
	v_exp_f32_e32 v225, v217
	v_exp_f32_e32 v226, v218
	v_exp_f32_e32 v227, v219
	v_lshlrev_b32_e32 v228, 16, v96
	v_and_b32_e32 v229, 0xffff0000, v96
	v_lshlrev_b32_e32 v230, 16, v97
	v_and_b32_e32 v231, 0xffff0000, v97
	v_pk_fma_f32 v[8:9], v[8:9], v[226:227], v[222:223]
	v_pk_fma_f32 v[6:7], v[6:7], v[224:225], v[220:221]
	v_pk_mul_f32 v[234:235], v[8:9], v[230:231]
	v_pk_mul_f32 v[232:233], v[6:7], v[228:229]
	v_add_u32_e32 v19, 0x3000, v16
	v_cvt_pk_bf16_f32 v236, v232, v233
	v_cvt_pk_bf16_f32 v237, v234, v235
	global_store_dwordx2 v19, v[236:237], s[90:91]
	s_waitcnt vmcnt(23)
; __device__ __forceinline__ unsigned pk_bf16(float lo, float hi) { f32x2 v = {lo, hi}; return __builtin_bit_cast(unsigned, __builtin_convertvector(v, bf16v2)); }
; __device__ __forceinline__ float bf_lo(unsigned w) { return __uint_as_float(w << 16); }
; __device__ __forceinline__ float bf_hi(unsigned w) { return __uint_as_float(w & 0xffff0000u); }
; __device__ __forceinline__ void scan_pass2_tile(const unsigned* au, const f32x4* saggP, const f32x4* saggH, const f32x4* cpreP, const f32x4* cpreH, const bf16_t* gate, bf16_t* y, int pm, int blk, int tid) {
;     ...
;     for (int t = 0; t < SCAN_L; ++t) { const size_t o = off + (size_t)t * DM; f32x4 a, u; au_unpack(*(const u32x4*)(au + o), a, u); const u32x2 gw2 = *(const u32x2*)(gate + o);
;         Hh = a * Hh + u;
;         u32x2 w; w.x = pk_bf16(Hh[0] * bf_lo(gw2.x), Hh[1] * bf_hi(gw2.x)); w.y = pk_bf16(Hh[2] * bf_lo(gw2.y), Hh[3] * bf_hi(gw2.y));
;         *(u32x2*)(y + o) = w; }
	v_cvt_f32_f16_e32 v216, v48
	v_cvt_f32_f16_e32 v217, v49
	v_cvt_f32_f16_e32 v218, v50
	v_cvt_f32_f16_e32 v219, v51
	v_cvt_f32_f16_sdwa v220, v48 dst_sel:DWORD dst_unused:UNUSED_PAD src0_sel:WORD_1
	v_cvt_f32_f16_sdwa v221, v49 dst_sel:DWORD dst_unused:UNUSED_PAD src0_sel:WORD_1
	v_cvt_f32_f16_sdwa v222, v50 dst_sel:DWORD dst_unused:UNUSED_PAD src0_sel:WORD_1
	v_cvt_f32_f16_sdwa v223, v51 dst_sel:DWORD dst_unused:UNUSED_PAD src0_sel:WORD_1
	v_mul_f32_e32 v216, 0x3a800000, v216
	v_mul_f32_e32 v217, 0x3a800000, v217
	v_mul_f32_e32 v218, 0x3a800000, v218
	v_mul_f32_e32 v219, 0x3a800000, v219
	v_exp_f32_e32 v224, v216
	v_exp_f32_e32 v225, v217
	v_exp_f32_e32 v226, v218
	v_exp_f32_e32 v227, v219
	v_lshlrev_b32_e32 v228, 16, v98
	v_and_b32_e32 v229, 0xffff0000, v98
	v_lshlrev_b32_e32 v230, 16, v99
	v_and_b32_e32 v231, 0xffff0000, v99
	v_pk_fma_f32 v[8:9], v[8:9], v[226:227], v[222:223]
	v_pk_fma_f32 v[6:7], v[6:7], v[224:225], v[220:221]
	v_pk_mul_f32 v[234:235], v[8:9], v[230:231]
	v_pk_mul_f32 v[232:233], v[6:7], v[228:229]
	v_cvt_pk_bf16_f32 v236, v232, v233
	v_cvt_pk_bf16_f32 v237, v234, v235
	global_store_dwordx2 v19, v[236:237], s[90:91] offset:2048
	v_add_u32_e32 v17, 0x10000, v10
	global_load_dwordx4 v[116:119], v17, s[90:91]
	v_add_u32_e32 v18, 0x8000, v11
	global_load_dwordx2 v[184:185], v18, s[90:91]
	v_add_u32_e32 v17, 0x11000, v10
	global_load_dwordx4 v[120:123], v17, s[90:91]
	global_load_dwordx2 v[186:187], v18, s[90:91] offset:2048
	v_add_u32_e32 v17, 0x12000, v10
	global_load_dwordx4 v[124:127], v17, s[90:91]
	v_add_u32_e32 v18, 0x9000, v11
	global_load_dwordx2 v[188:189], v18, s[90:91]
	v_add_u32_e32 v17, 0x13000, v10
	global_load_dwordx4 v[128:131], v17, s[90:91]
	global_load_dwordx2 v[190:191], v18, s[90:91] offset:2048
	v_add_u32_e32 v17, 0x14000, v10
	global_load_dwordx4 v[132:135], v17, s[90:91]
	v_add_u32_e32 v18, 0xa000, v11
	global_load_dwordx2 v[192:193], v18, s[90:91]
	v_add_u32_e32 v17, 0x15000, v10
	global_load_dwordx4 v[136:139], v17, s[90:91]
	global_load_dwordx2 v[194:195], v18, s[90:91] offset:2048
	v_add_u32_e32 v17, 0x16000, v10
	global_load_dwordx4 v[140:143], v17, s[90:91]
	v_add_u32_e32 v18, 0xb000, v11
	global_load_dwordx2 v[196:197], v18, s[90:91]
	v_add_u32_e32 v17, 0x17000, v10
	global_load_dwordx4 v[144:147], v17, s[90:91]
	global_load_dwordx2 v[198:199], v18, s[90:91] offset:2048
	v_add_u32_e32 v17, 0x18000, v10
	global_load_dwordx4 v[148:151], v17, s[90:91]
	v_add_u32_e32 v18, 0xc000, v11
	global_load_dwordx2 v[200:201], v18, s[90:91]
	v_add_u32_e32 v17, 0x19000, v10
	global_load_dwordx4 v[152:155], v17, s[90:91]
	global_load_dwordx2 v[202:203], v18, s[90:91] offset:2048
	v_add_u32_e32 v17, 0x1a000, v10
	global_load_dwordx4 v[156:159], v17, s[90:91]
	v_add_u32_e32 v18, 0xd000, v11
	global_load_dwordx2 v[204:205], v18, s[90:91]
	v_add_u32_e32 v17, 0x1b000, v10
	global_load_dwordx4 v[160:163], v17, s[90:91]
	global_load_dwordx2 v[206:207], v18, s[90:91] offset:2048
	v_add_u32_e32 v17, 0x1c000, v10
	global_load_dwordx4 v[164:167], v17, s[90:91]
	v_add_u32_e32 v18, 0xe000, v11
	global_load_dwordx2 v[208:209], v18, s[90:91]
	v_add_u32_e32 v17, 0x1d000, v10
	global_load_dwordx4 v[168:171], v17, s[90:91]
	global_load_dwordx2 v[210:211], v18, s[90:91] offset:2048
	v_add_u32_e32 v17, 0x1e000, v10
	global_load_dwordx4 v[172:175], v17, s[90:91]
	v_add_u32_e32 v18, 0xf000, v11
	global_load_dwordx2 v[212:213], v18, s[90:91]
	v_add_u32_e32 v17, 0x1f000, v10
	global_load_dwordx4 v[180:183], v17, s[90:91]
	global_load_dwordx2 v[214:215], v18, s[90:91] offset:2048
	s_waitcnt vmcnt(54)
	v_cvt_f32_f16_e32 v216, v52
	v_cvt_f32_f16_e32 v217, v53
	v_cvt_f32_f16_e32 v218, v54
	v_cvt_f32_f16_e32 v219, v55
	v_cvt_f32_f16_sdwa v220, v52 dst_sel:DWORD dst_unused:UNUSED_PAD src0_sel:WORD_1
	v_cvt_f32_f16_sdwa v221, v53 dst_sel:DWORD dst_unused:UNUSED_PAD src0_sel:WORD_1
	v_cvt_f32_f16_sdwa v222, v54 dst_sel:DWORD dst_unused:UNUSED_PAD src0_sel:WORD_1
	v_cvt_f32_f16_sdwa v223, v55 dst_sel:DWORD dst_unused:UNUSED_PAD src0_sel:WORD_1
	v_mul_f32_e32 v216, 0x3a800000, v216
	v_mul_f32_e32 v217, 0x3a800000, v217
	v_mul_f32_e32 v218, 0x3a800000, v218
	v_mul_f32_e32 v219, 0x3a800000, v219
	v_exp_f32_e32 v224, v216
	v_exp_f32_e32 v225, v217
	v_exp_f32_e32 v226, v218
	v_exp_f32_e32 v227, v219
	v_lshlrev_b32_e32 v228, 16, v100
	v_and_b32_e32 v229, 0xffff0000, v100
	v_lshlrev_b32_e32 v230, 16, v101
	v_and_b32_e32 v231, 0xffff0000, v101
	v_pk_fma_f32 v[8:9], v[8:9], v[226:227], v[222:223]
	v_pk_fma_f32 v[6:7], v[6:7], v[224:225], v[220:221]
	v_pk_mul_f32 v[234:235], v[8:9], v[230:231]
	v_pk_mul_f32 v[232:233], v[6:7], v[228:229]
	v_add_u32_e32 v19, 0x4000, v16
	v_cvt_pk_bf16_f32 v236, v232, v233
	v_cvt_pk_bf16_f32 v237, v234, v235
	global_store_dwordx2 v19, v[236:237], s[90:91]
	s_waitcnt vmcnt(53)
	v_cvt_f32_f16_e32 v216, v56
	v_cvt_f32_f16_e32 v217, v57
	v_cvt_f32_f16_e32 v218, v58
	v_cvt_f32_f16_e32 v219, v59
	v_cvt_f32_f16_sdwa v220, v56 dst_sel:DWORD dst_unused:UNUSED_PAD src0_sel:WORD_1
	v_cvt_f32_f16_sdwa v221, v57 dst_sel:DWORD dst_unused:UNUSED_PAD src0_sel:WORD_1
	v_cvt_f32_f16_sdwa v222, v58 dst_sel:DWORD dst_unused:UNUSED_PAD src0_sel:WORD_1
	v_cvt_f32_f16_sdwa v223, v59 dst_sel:DWORD dst_unused:UNUSED_PAD src0_sel:WORD_1
	v_mul_f32_e32 v216, 0x3a800000, v216
	v_mul_f32_e32 v217, 0x3a800000, v217
	v_mul_f32_e32 v218, 0x3a800000, v218
	v_mul_f32_e32 v219, 0x3a800000, v219
	v_exp_f32_e32 v224, v216
	v_exp_f32_e32 v225, v217
	v_exp_f32_e32 v226, v218
	v_exp_f32_e32 v227, v219
	v_lshlrev_b32_e32 v228, 16, v102
	v_and_b32_e32 v229, 0xffff0000, v102
	v_lshlrev_b32_e32 v230, 16, v103
	v_and_b32_e32 v231, 0xffff0000, v103
	v_pk_fma_f32 v[8:9], v[8:9], v[226:227], v[222:223]
	v_pk_fma_f32 v[6:7], v[6:7], v[224:225], v[220:221]
	v_pk_mul_f32 v[234:235], v[8:9], v[230:231]
	v_pk_mul_f32 v[232:233], v[6:7], v[228:229]
	v_cvt_pk_bf16_f32 v236, v232, v233
	v_cvt_pk_bf16_f32 v237, v234, v235
	global_store_dwordx2 v19, v[236:237], s[90:91] offset:2048
	s_waitcnt vmcnt(52)
; __device__ __forceinline__ unsigned pk_bf16(float lo, float hi) { f32x2 v = {lo, hi}; return __builtin_bit_cast(unsigned, __builtin_convertvector(v, bf16v2)); }
; __device__ __forceinline__ float bf_lo(unsigned w) { return __uint_as_float(w << 16); }
; __device__ __forceinline__ float bf_hi(unsigned w) { return __uint_as_float(w & 0xffff0000u); }
; __device__ __forceinline__ void scan_pass2_tile(const unsigned* au, const f32x4* saggP, const f32x4* saggH, const f32x4* cpreP, const f32x4* cpreH, const bf16_t* gate, bf16_t* y, int pm, int blk, int tid) {
;     ...
;     for (int t = 0; t < SCAN_L; ++t) { const size_t o = off + (size_t)t * DM; f32x4 a, u; au_unpack(*(const u32x4*)(au + o), a, u); const u32x2 gw2 = *(const u32x2*)(gate + o);
;         Hh = a * Hh + u;
;         u32x2 w; w.x = pk_bf16(Hh[0] * bf_lo(gw2.x), Hh[1] * bf_hi(gw2.x)); w.y = pk_bf16(Hh[2] * bf_lo(gw2.y), Hh[3] * bf_hi(gw2.y));
;         *(u32x2*)(y + o) = w; }
	v_cvt_f32_f16_e32 v216, v60
	v_cvt_f32_f16_e32 v217, v61
	v_cvt_f32_f16_e32 v218, v62
	v_cvt_f32_f16_e32 v219, v63
	v_cvt_f32_f16_sdwa v220, v60 dst_sel:DWORD dst_unused:UNUSED_PAD src0_sel:WORD_1
	v_cvt_f32_f16_sdwa v221, v61 dst_sel:DWORD dst_unused:UNUSED_PAD src0_sel:WORD_1
	v_cvt_f32_f16_sdwa v222, v62 dst_sel:DWORD dst_unused:UNUSED_PAD src0_sel:WORD_1
	v_cvt_f32_f16_sdwa v223, v63 dst_sel:DWORD dst_unused:UNUSED_PAD src0_sel:WORD_1
	v_mul_f32_e32 v216, 0x3a800000, v216
	v_mul_f32_e32 v217, 0x3a800000, v217
	v_mul_f32_e32 v218, 0x3a800000, v218
	v_mul_f32_e32 v219, 0x3a800000, v219
	v_exp_f32_e32 v224, v216
	v_exp_f32_e32 v225, v217
	v_exp_f32_e32 v226, v218
	v_exp_f32_e32 v227, v219
	v_lshlrev_b32_e32 v228, 16, v104
	v_and_b32_e32 v229, 0xffff0000, v104
	v_lshlrev_b32_e32 v230, 16, v105
	v_and_b32_e32 v231, 0xffff0000, v105
	v_pk_fma_f32 v[8:9], v[8:9], v[226:227], v[222:223]
	v_pk_fma_f32 v[6:7], v[6:7], v[224:225], v[220:221]
	v_pk_mul_f32 v[234:235], v[8:9], v[230:231]
	v_pk_mul_f32 v[232:233], v[6:7], v[228:229]
	v_add_u32_e32 v19, 0x5000, v16
	v_cvt_pk_bf16_f32 v236, v232, v233
	v_cvt_pk_bf16_f32 v237, v234, v235
	global_store_dwordx2 v19, v[236:237], s[90:91]
	s_waitcnt vmcnt(51)
	v_cvt_f32_f16_e32 v216, v64
	v_cvt_f32_f16_e32 v217, v65
	v_cvt_f32_f16_e32 v218, v66
	v_cvt_f32_f16_e32 v219, v67
	v_cvt_f32_f16_sdwa v220, v64 dst_sel:DWORD dst_unused:UNUSED_PAD src0_sel:WORD_1
	v_cvt_f32_f16_sdwa v221, v65 dst_sel:DWORD dst_unused:UNUSED_PAD src0_sel:WORD_1
	v_cvt_f32_f16_sdwa v222, v66 dst_sel:DWORD dst_unused:UNUSED_PAD src0_sel:WORD_1
	v_cvt_f32_f16_sdwa v223, v67 dst_sel:DWORD dst_unused:UNUSED_PAD src0_sel:WORD_1
	v_mul_f32_e32 v216, 0x3a800000, v216
	v_mul_f32_e32 v217, 0x3a800000, v217
	v_mul_f32_e32 v218, 0x3a800000, v218
	v_mul_f32_e32 v219, 0x3a800000, v219
	v_exp_f32_e32 v224, v216
	v_exp_f32_e32 v225, v217
	v_exp_f32_e32 v226, v218
	v_exp_f32_e32 v227, v219
	v_lshlrev_b32_e32 v228, 16, v106
	v_and_b32_e32 v229, 0xffff0000, v106
	v_lshlrev_b32_e32 v230, 16, v107
	v_and_b32_e32 v231, 0xffff0000, v107
	v_pk_fma_f32 v[8:9], v[8:9], v[226:227], v[222:223]
	v_pk_fma_f32 v[6:7], v[6:7], v[224:225], v[220:221]
	v_pk_mul_f32 v[234:235], v[8:9], v[230:231]
	v_pk_mul_f32 v[232:233], v[6:7], v[228:229]
	v_cvt_pk_bf16_f32 v236, v232, v233
	v_cvt_pk_bf16_f32 v237, v234, v235
	global_store_dwordx2 v19, v[236:237], s[90:91] offset:2048
	s_waitcnt vmcnt(50)
	v_cvt_f32_f16_e32 v216, v68
	v_cvt_f32_f16_e32 v217, v69
	v_cvt_f32_f16_e32 v218, v70
	v_cvt_f32_f16_e32 v219, v71
	v_cvt_f32_f16_sdwa v220, v68 dst_sel:DWORD dst_unused:UNUSED_PAD src0_sel:WORD_1
	v_cvt_f32_f16_sdwa v221, v69 dst_sel:DWORD dst_unused:UNUSED_PAD src0_sel:WORD_1
	v_cvt_f32_f16_sdwa v222, v70 dst_sel:DWORD dst_unused:UNUSED_PAD src0_sel:WORD_1
	v_cvt_f32_f16_sdwa v223, v71 dst_sel:DWORD dst_unused:UNUSED_PAD src0_sel:WORD_1
	v_mul_f32_e32 v216, 0x3a800000, v216
	v_mul_f32_e32 v217, 0x3a800000, v217
	v_mul_f32_e32 v218, 0x3a800000, v218
	v_mul_f32_e32 v219, 0x3a800000, v219
	v_exp_f32_e32 v224, v216
	v_exp_f32_e32 v225, v217
	v_exp_f32_e32 v226, v218
	v_exp_f32_e32 v227, v219
	v_lshlrev_b32_e32 v228, 16, v108
	v_and_b32_e32 v229, 0xffff0000, v108
	v_lshlrev_b32_e32 v230, 16, v109
	v_and_b32_e32 v231, 0xffff0000, v109
	v_pk_fma_f32 v[8:9], v[8:9], v[226:227], v[222:223]
	v_pk_fma_f32 v[6:7], v[6:7], v[224:225], v[220:221]
	v_pk_mul_f32 v[234:235], v[8:9], v[230:231]
	v_pk_mul_f32 v[232:233], v[6:7], v[228:229]
	v_add_u32_e32 v19, 0x6000, v16
	v_cvt_pk_bf16_f32 v236, v232, v233
	v_cvt_pk_bf16_f32 v237, v234, v235
	global_store_dwordx2 v19, v[236:237], s[90:91]
	s_waitcnt vmcnt(49)
	v_cvt_f32_f16_e32 v216, v72
	v_cvt_f32_f16_e32 v217, v73
	v_cvt_f32_f16_e32 v218, v74
	v_cvt_f32_f16_e32 v219, v75
	v_cvt_f32_f16_sdwa v220, v72 dst_sel:DWORD dst_unused:UNUSED_PAD src0_sel:WORD_1
	v_cvt_f32_f16_sdwa v221, v73 dst_sel:DWORD dst_unused:UNUSED_PAD src0_sel:WORD_1
	v_cvt_f32_f16_sdwa v222, v74 dst_sel:DWORD dst_unused:UNUSED_PAD src0_sel:WORD_1
	v_cvt_f32_f16_sdwa v223, v75 dst_sel:DWORD dst_unused:UNUSED_PAD src0_sel:WORD_1
	v_mul_f32_e32 v216, 0x3a800000, v216
	v_mul_f32_e32 v217, 0x3a800000, v217
	v_mul_f32_e32 v218, 0x3a800000, v218
	v_mul_f32_e32 v219, 0x3a800000, v219
	v_exp_f32_e32 v224, v216
	v_exp_f32_e32 v225, v217
	v_exp_f32_e32 v226, v218
	v_exp_f32_e32 v227, v219
	v_lshlrev_b32_e32 v228, 16, v110
	v_and_b32_e32 v229, 0xffff0000, v110
	v_lshlrev_b32_e32 v230, 16, v111
	v_and_b32_e32 v231, 0xffff0000, v111
	v_pk_fma_f32 v[8:9], v[8:9], v[226:227], v[222:223]
	v_pk_fma_f32 v[6:7], v[6:7], v[224:225], v[220:221]
	v_pk_mul_f32 v[234:235], v[8:9], v[230:231]
	v_pk_mul_f32 v[232:233], v[6:7], v[228:229]
	v_cvt_pk_bf16_f32 v236, v232, v233
	v_cvt_pk_bf16_f32 v237, v234, v235
	global_store_dwordx2 v19, v[236:237], s[90:91] offset:2048
	s_waitcnt vmcnt(48)
	v_cvt_f32_f16_e32 v216, v76
	v_cvt_f32_f16_e32 v217, v77
	v_cvt_f32_f16_e32 v218, v78
	v_cvt_f32_f16_e32 v219, v79
	v_cvt_f32_f16_sdwa v220, v76 dst_sel:DWORD dst_unused:UNUSED_PAD src0_sel:WORD_1
	v_cvt_f32_f16_sdwa v221, v77 dst_sel:DWORD dst_unused:UNUSED_PAD src0_sel:WORD_1
	v_cvt_f32_f16_sdwa v222, v78 dst_sel:DWORD dst_unused:UNUSED_PAD src0_sel:WORD_1
	v_cvt_f32_f16_sdwa v223, v79 dst_sel:DWORD dst_unused:UNUSED_PAD src0_sel:WORD_1
	v_mul_f32_e32 v216, 0x3a800000, v216
	v_mul_f32_e32 v217, 0x3a800000, v217
	v_mul_f32_e32 v218, 0x3a800000, v218
	v_mul_f32_e32 v219, 0x3a800000, v219
	v_exp_f32_e32 v224, v216
	v_exp_f32_e32 v225, v217
	v_exp_f32_e32 v226, v218
	v_exp_f32_e32 v227, v219
	v_lshlrev_b32_e32 v228, 16, v112
	v_and_b32_e32 v229, 0xffff0000, v112
	v_lshlrev_b32_e32 v230, 16, v113
	v_and_b32_e32 v231, 0xffff0000, v113
	v_pk_fma_f32 v[8:9], v[8:9], v[226:227], v[222:223]
	v_pk_fma_f32 v[6:7], v[6:7], v[224:225], v[220:221]
	v_pk_mul_f32 v[234:235], v[8:9], v[230:231]
	v_pk_mul_f32 v[232:233], v[6:7], v[228:229]
	v_add_u32_e32 v19, 0x7000, v16
	v_cvt_pk_bf16_f32 v236, v232, v233
	v_cvt_pk_bf16_f32 v237, v234, v235
	global_store_dwordx2 v19, v[236:237], s[90:91]
	s_waitcnt vmcnt(47)
; __device__ __forceinline__ unsigned pk_bf16(float lo, float hi) { f32x2 v = {lo, hi}; return __builtin_bit_cast(unsigned, __builtin_convertvector(v, bf16v2)); }
; __device__ __forceinline__ float bf_lo(unsigned w) { return __uint_as_float(w << 16); }
; __device__ __forceinline__ float bf_hi(unsigned w) { return __uint_as_float(w & 0xffff0000u); }
; __device__ __forceinline__ void scan_pass2_tile(const unsigned* au, const f32x4* saggP, const f32x4* saggH, const f32x4* cpreP, const f32x4* cpreH, const bf16_t* gate, bf16_t* y, int pm, int blk, int tid) {
;     ...
;     for (int t = 0; t < SCAN_L; ++t) { const size_t o = off + (size_t)t * DM; f32x4 a, u; au_unpack(*(const u32x4*)(au + o), a, u); const u32x2 gw2 = *(const u32x2*)(gate + o);
;         Hh = a * Hh + u;
;         u32x2 w; w.x = pk_bf16(Hh[0] * bf_lo(gw2.x), Hh[1] * bf_hi(gw2.x)); w.y = pk_bf16(Hh[2] * bf_lo(gw2.y), Hh[3] * bf_hi(gw2.y));
;         *(u32x2*)(y + o) = w; }
	v_cvt_f32_f16_e32 v216, v80
	v_cvt_f32_f16_e32 v217, v81
	v_cvt_f32_f16_e32 v218, v82
	v_cvt_f32_f16_e32 v219, v83
	v_cvt_f32_f16_sdwa v220, v80 dst_sel:DWORD dst_unused:UNUSED_PAD src0_sel:WORD_1
	v_cvt_f32_f16_sdwa v221, v81 dst_sel:DWORD dst_unused:UNUSED_PAD src0_sel:WORD_1
	v_cvt_f32_f16_sdwa v222, v82 dst_sel:DWORD dst_unused:UNUSED_PAD src0_sel:WORD_1
	v_cvt_f32_f16_sdwa v223, v83 dst_sel:DWORD dst_unused:UNUSED_PAD src0_sel:WORD_1
	v_mul_f32_e32 v216, 0x3a800000, v216
	v_mul_f32_e32 v217, 0x3a800000, v217
	v_mul_f32_e32 v218, 0x3a800000, v218
	v_mul_f32_e32 v219, 0x3a800000, v219
	v_exp_f32_e32 v224, v216
	v_exp_f32_e32 v225, v217
	v_exp_f32_e32 v226, v218
	v_exp_f32_e32 v227, v219
	v_lshlrev_b32_e32 v228, 16, v114
	v_and_b32_e32 v229, 0xffff0000, v114
	v_lshlrev_b32_e32 v230, 16, v115
	v_and_b32_e32 v231, 0xffff0000, v115
	v_pk_fma_f32 v[8:9], v[8:9], v[226:227], v[222:223]
	v_pk_fma_f32 v[6:7], v[6:7], v[224:225], v[220:221]
	v_pk_mul_f32 v[234:235], v[8:9], v[230:231]
	v_pk_mul_f32 v[232:233], v[6:7], v[228:229]
	v_cvt_pk_bf16_f32 v236, v232, v233
	v_cvt_pk_bf16_f32 v237, v234, v235
	global_store_dwordx2 v19, v[236:237], s[90:91] offset:2048
	s_waitcnt vmcnt(38)
	v_cvt_f32_f16_e32 v216, v116
	v_cvt_f32_f16_e32 v217, v117
	v_cvt_f32_f16_e32 v218, v118
	v_cvt_f32_f16_e32 v219, v119
	v_cvt_f32_f16_sdwa v220, v116 dst_sel:DWORD dst_unused:UNUSED_PAD src0_sel:WORD_1
	v_cvt_f32_f16_sdwa v221, v117 dst_sel:DWORD dst_unused:UNUSED_PAD src0_sel:WORD_1
	v_cvt_f32_f16_sdwa v222, v118 dst_sel:DWORD dst_unused:UNUSED_PAD src0_sel:WORD_1
	v_cvt_f32_f16_sdwa v223, v119 dst_sel:DWORD dst_unused:UNUSED_PAD src0_sel:WORD_1
	v_mul_f32_e32 v216, 0x3a800000, v216
	v_mul_f32_e32 v217, 0x3a800000, v217
	v_mul_f32_e32 v218, 0x3a800000, v218
	v_mul_f32_e32 v219, 0x3a800000, v219
	v_exp_f32_e32 v224, v216
	v_exp_f32_e32 v225, v217
	v_exp_f32_e32 v226, v218
	v_exp_f32_e32 v227, v219
	v_lshlrev_b32_e32 v228, 16, v184
	v_and_b32_e32 v229, 0xffff0000, v184
	v_lshlrev_b32_e32 v230, 16, v185
	v_and_b32_e32 v231, 0xffff0000, v185
	v_pk_fma_f32 v[8:9], v[8:9], v[226:227], v[222:223]
	v_pk_fma_f32 v[6:7], v[6:7], v[224:225], v[220:221]
	v_pk_mul_f32 v[234:235], v[8:9], v[230:231]
	v_pk_mul_f32 v[232:233], v[6:7], v[228:229]
	v_add_u32_e32 v19, 0x8000, v16
	v_cvt_pk_bf16_f32 v236, v232, v233
	v_cvt_pk_bf16_f32 v237, v234, v235
	global_store_dwordx2 v19, v[236:237], s[90:91]
	s_waitcnt vmcnt(37)
	v_cvt_f32_f16_e32 v216, v120
	v_cvt_f32_f16_e32 v217, v121
	v_cvt_f32_f16_e32 v218, v122
	v_cvt_f32_f16_e32 v219, v123
	v_cvt_f32_f16_sdwa v220, v120 dst_sel:DWORD dst_unused:UNUSED_PAD src0_sel:WORD_1
	v_cvt_f32_f16_sdwa v221, v121 dst_sel:DWORD dst_unused:UNUSED_PAD src0_sel:WORD_1
	v_cvt_f32_f16_sdwa v222, v122 dst_sel:DWORD dst_unused:UNUSED_PAD src0_sel:WORD_1
	v_cvt_f32_f16_sdwa v223, v123 dst_sel:DWORD dst_unused:UNUSED_PAD src0_sel:WORD_1
	v_mul_f32_e32 v216, 0x3a800000, v216
	v_mul_f32_e32 v217, 0x3a800000, v217
	v_mul_f32_e32 v218, 0x3a800000, v218
	v_mul_f32_e32 v219, 0x3a800000, v219
	v_exp_f32_e32 v224, v216
	v_exp_f32_e32 v225, v217
	v_exp_f32_e32 v226, v218
	v_exp_f32_e32 v227, v219
	v_lshlrev_b32_e32 v228, 16, v186
	v_and_b32_e32 v229, 0xffff0000, v186
	v_lshlrev_b32_e32 v230, 16, v187
	v_and_b32_e32 v231, 0xffff0000, v187
	v_pk_fma_f32 v[8:9], v[8:9], v[226:227], v[222:223]
	v_pk_fma_f32 v[6:7], v[6:7], v[224:225], v[220:221]
	v_pk_mul_f32 v[234:235], v[8:9], v[230:231]
	v_pk_mul_f32 v[232:233], v[6:7], v[228:229]
	v_cvt_pk_bf16_f32 v236, v232, v233
	v_cvt_pk_bf16_f32 v237, v234, v235
	global_store_dwordx2 v19, v[236:237], s[90:91] offset:2048
	s_waitcnt vmcnt(36)
	v_cvt_f32_f16_e32 v216, v124
	v_cvt_f32_f16_e32 v217, v125
	v_cvt_f32_f16_e32 v218, v126
	v_cvt_f32_f16_e32 v219, v127
	v_cvt_f32_f16_sdwa v220, v124 dst_sel:DWORD dst_unused:UNUSED_PAD src0_sel:WORD_1
	v_cvt_f32_f16_sdwa v221, v125 dst_sel:DWORD dst_unused:UNUSED_PAD src0_sel:WORD_1
	v_cvt_f32_f16_sdwa v222, v126 dst_sel:DWORD dst_unused:UNUSED_PAD src0_sel:WORD_1
	v_cvt_f32_f16_sdwa v223, v127 dst_sel:DWORD dst_unused:UNUSED_PAD src0_sel:WORD_1
	v_mul_f32_e32 v216, 0x3a800000, v216
	v_mul_f32_e32 v217, 0x3a800000, v217
	v_mul_f32_e32 v218, 0x3a800000, v218
	v_mul_f32_e32 v219, 0x3a800000, v219
	v_exp_f32_e32 v224, v216
	v_exp_f32_e32 v225, v217
	v_exp_f32_e32 v226, v218
	v_exp_f32_e32 v227, v219
	v_lshlrev_b32_e32 v228, 16, v188
	v_and_b32_e32 v229, 0xffff0000, v188
	v_lshlrev_b32_e32 v230, 16, v189
	v_and_b32_e32 v231, 0xffff0000, v189
	v_pk_fma_f32 v[8:9], v[8:9], v[226:227], v[222:223]
	v_pk_fma_f32 v[6:7], v[6:7], v[224:225], v[220:221]
	v_pk_mul_f32 v[234:235], v[8:9], v[230:231]
	v_pk_mul_f32 v[232:233], v[6:7], v[228:229]
	v_add_u32_e32 v19, 0x9000, v16
	v_cvt_pk_bf16_f32 v236, v232, v233
	v_cvt_pk_bf16_f32 v237, v234, v235
	global_store_dwordx2 v19, v[236:237], s[90:91]
	s_waitcnt vmcnt(35)
	v_cvt_f32_f16_e32 v216, v128
	v_cvt_f32_f16_e32 v217, v129
	v_cvt_f32_f16_e32 v218, v130
	v_cvt_f32_f16_e32 v219, v131
	v_cvt_f32_f16_sdwa v220, v128 dst_sel:DWORD dst_unused:UNUSED_PAD src0_sel:WORD_1
	v_cvt_f32_f16_sdwa v221, v129 dst_sel:DWORD dst_unused:UNUSED_PAD src0_sel:WORD_1
	v_cvt_f32_f16_sdwa v222, v130 dst_sel:DWORD dst_unused:UNUSED_PAD src0_sel:WORD_1
	v_cvt_f32_f16_sdwa v223, v131 dst_sel:DWORD dst_unused:UNUSED_PAD src0_sel:WORD_1
	v_mul_f32_e32 v216, 0x3a800000, v216
	v_mul_f32_e32 v217, 0x3a800000, v217
	v_mul_f32_e32 v218, 0x3a800000, v218
	v_mul_f32_e32 v219, 0x3a800000, v219
	v_exp_f32_e32 v224, v216
	v_exp_f32_e32 v225, v217
	v_exp_f32_e32 v226, v218
	v_exp_f32_e32 v227, v219
	v_lshlrev_b32_e32 v228, 16, v190
	v_and_b32_e32 v229, 0xffff0000, v190
	v_lshlrev_b32_e32 v230, 16, v191
	v_and_b32_e32 v231, 0xffff0000, v191
	v_pk_fma_f32 v[8:9], v[8:9], v[226:227], v[222:223]
	v_pk_fma_f32 v[6:7], v[6:7], v[224:225], v[220:221]
	v_pk_mul_f32 v[234:235], v[8:9], v[230:231]
	v_pk_mul_f32 v[232:233], v[6:7], v[228:229]
	v_cvt_pk_bf16_f32 v236, v232, v233
	v_cvt_pk_bf16_f32 v237, v234, v235
	global_store_dwordx2 v19, v[236:237], s[90:91] offset:2048
	s_waitcnt vmcnt(34)
; __device__ __forceinline__ unsigned pk_bf16(float lo, float hi) { f32x2 v = {lo, hi}; return __builtin_bit_cast(unsigned, __builtin_convertvector(v, bf16v2)); }
; __device__ __forceinline__ float bf_lo(unsigned w) { return __uint_as_float(w << 16); }
; __device__ __forceinline__ float bf_hi(unsigned w) { return __uint_as_float(w & 0xffff0000u); }
; __device__ __forceinline__ void scan_pass2_tile(const unsigned* au, const f32x4* saggP, const f32x4* saggH, const f32x4* cpreP, const f32x4* cpreH, const bf16_t* gate, bf16_t* y, int pm, int blk, int tid) {
;     ...
;     for (int t = 0; t < SCAN_L; ++t) { const size_t o = off + (size_t)t * DM; f32x4 a, u; au_unpack(*(const u32x4*)(au + o), a, u); const u32x2 gw2 = *(const u32x2*)(gate + o);
;         Hh = a * Hh + u;
;         u32x2 w; w.x = pk_bf16(Hh[0] * bf_lo(gw2.x), Hh[1] * bf_hi(gw2.x)); w.y = pk_bf16(Hh[2] * bf_lo(gw2.y), Hh[3] * bf_hi(gw2.y));
;         *(u32x2*)(y + o) = w; }
	v_cvt_f32_f16_e32 v216, v132
	v_cvt_f32_f16_e32 v217, v133
	v_cvt_f32_f16_e32 v218, v134
	v_cvt_f32_f16_e32 v219, v135
	v_cvt_f32_f16_sdwa v220, v132 dst_sel:DWORD dst_unused:UNUSED_PAD src0_sel:WORD_1
	v_cvt_f32_f16_sdwa v221, v133 dst_sel:DWORD dst_unused:UNUSED_PAD src0_sel:WORD_1
	v_cvt_f32_f16_sdwa v222, v134 dst_sel:DWORD dst_unused:UNUSED_PAD src0_sel:WORD_1
	v_cvt_f32_f16_sdwa v223, v135 dst_sel:DWORD dst_unused:UNUSED_PAD src0_sel:WORD_1
	v_mul_f32_e32 v216, 0x3a800000, v216
	v_mul_f32_e32 v217, 0x3a800000, v217
	v_mul_f32_e32 v218, 0x3a800000, v218
	v_mul_f32_e32 v219, 0x3a800000, v219
	v_exp_f32_e32 v224, v216
	v_exp_f32_e32 v225, v217
	v_exp_f32_e32 v226, v218
	v_exp_f32_e32 v227, v219
	v_lshlrev_b32_e32 v228, 16, v192
	v_and_b32_e32 v229, 0xffff0000, v192
	v_lshlrev_b32_e32 v230, 16, v193
	v_and_b32_e32 v231, 0xffff0000, v193
	v_pk_fma_f32 v[8:9], v[8:9], v[226:227], v[222:223]
	v_pk_fma_f32 v[6:7], v[6:7], v[224:225], v[220:221]
	v_pk_mul_f32 v[234:235], v[8:9], v[230:231]
	v_pk_mul_f32 v[232:233], v[6:7], v[228:229]
	v_add_u32_e32 v19, 0xa000, v16
	v_cvt_pk_bf16_f32 v236, v232, v233
	v_cvt_pk_bf16_f32 v237, v234, v235
	global_store_dwordx2 v19, v[236:237], s[90:91]
	s_waitcnt vmcnt(33)
	v_cvt_f32_f16_e32 v216, v136
	v_cvt_f32_f16_e32 v217, v137
	v_cvt_f32_f16_e32 v218, v138
	v_cvt_f32_f16_e32 v219, v139
	v_cvt_f32_f16_sdwa v220, v136 dst_sel:DWORD dst_unused:UNUSED_PAD src0_sel:WORD_1
	v_cvt_f32_f16_sdwa v221, v137 dst_sel:DWORD dst_unused:UNUSED_PAD src0_sel:WORD_1
	v_cvt_f32_f16_sdwa v222, v138 dst_sel:DWORD dst_unused:UNUSED_PAD src0_sel:WORD_1
	v_cvt_f32_f16_sdwa v223, v139 dst_sel:DWORD dst_unused:UNUSED_PAD src0_sel:WORD_1
	v_mul_f32_e32 v216, 0x3a800000, v216
	v_mul_f32_e32 v217, 0x3a800000, v217
	v_mul_f32_e32 v218, 0x3a800000, v218
	v_mul_f32_e32 v219, 0x3a800000, v219
	v_exp_f32_e32 v224, v216
	v_exp_f32_e32 v225, v217
	v_exp_f32_e32 v226, v218
	v_exp_f32_e32 v227, v219
	v_lshlrev_b32_e32 v228, 16, v194
	v_and_b32_e32 v229, 0xffff0000, v194
	v_lshlrev_b32_e32 v230, 16, v195
	v_and_b32_e32 v231, 0xffff0000, v195
	v_pk_fma_f32 v[8:9], v[8:9], v[226:227], v[222:223]
	v_pk_fma_f32 v[6:7], v[6:7], v[224:225], v[220:221]
	v_pk_mul_f32 v[234:235], v[8:9], v[230:231]
	v_pk_mul_f32 v[232:233], v[6:7], v[228:229]
	v_cvt_pk_bf16_f32 v236, v232, v233
	v_cvt_pk_bf16_f32 v237, v234, v235
	global_store_dwordx2 v19, v[236:237], s[90:91] offset:2048
	s_waitcnt vmcnt(32)
	v_cvt_f32_f16_e32 v216, v140
	v_cvt_f32_f16_e32 v217, v141
	v_cvt_f32_f16_e32 v218, v142
	v_cvt_f32_f16_e32 v219, v143
	v_cvt_f32_f16_sdwa v220, v140 dst_sel:DWORD dst_unused:UNUSED_PAD src0_sel:WORD_1
	v_cvt_f32_f16_sdwa v221, v141 dst_sel:DWORD dst_unused:UNUSED_PAD src0_sel:WORD_1
	v_cvt_f32_f16_sdwa v222, v142 dst_sel:DWORD dst_unused:UNUSED_PAD src0_sel:WORD_1
	v_cvt_f32_f16_sdwa v223, v143 dst_sel:DWORD dst_unused:UNUSED_PAD src0_sel:WORD_1
	v_mul_f32_e32 v216, 0x3a800000, v216
	v_mul_f32_e32 v217, 0x3a800000, v217
	v_mul_f32_e32 v218, 0x3a800000, v218
	v_mul_f32_e32 v219, 0x3a800000, v219
	v_exp_f32_e32 v224, v216
	v_exp_f32_e32 v225, v217
	v_exp_f32_e32 v226, v218
	v_exp_f32_e32 v227, v219
	v_lshlrev_b32_e32 v228, 16, v196
	v_and_b32_e32 v229, 0xffff0000, v196
	v_lshlrev_b32_e32 v230, 16, v197
	v_and_b32_e32 v231, 0xffff0000, v197
	v_pk_fma_f32 v[8:9], v[8:9], v[226:227], v[222:223]
	v_pk_fma_f32 v[6:7], v[6:7], v[224:225], v[220:221]
	v_pk_mul_f32 v[234:235], v[8:9], v[230:231]
	v_pk_mul_f32 v[232:233], v[6:7], v[228:229]
	v_add_u32_e32 v19, 0xb000, v16
	v_cvt_pk_bf16_f32 v236, v232, v233
	v_cvt_pk_bf16_f32 v237, v234, v235
	global_store_dwordx2 v19, v[236:237], s[90:91]
	s_waitcnt vmcnt(31)
	v_cvt_f32_f16_e32 v216, v144
	v_cvt_f32_f16_e32 v217, v145
	v_cvt_f32_f16_e32 v218, v146
	v_cvt_f32_f16_e32 v219, v147
	v_cvt_f32_f16_sdwa v220, v144 dst_sel:DWORD dst_unused:UNUSED_PAD src0_sel:WORD_1
	v_cvt_f32_f16_sdwa v221, v145 dst_sel:DWORD dst_unused:UNUSED_PAD src0_sel:WORD_1
	v_cvt_f32_f16_sdwa v222, v146 dst_sel:DWORD dst_unused:UNUSED_PAD src0_sel:WORD_1
	v_cvt_f32_f16_sdwa v223, v147 dst_sel:DWORD dst_unused:UNUSED_PAD src0_sel:WORD_1
	v_mul_f32_e32 v216, 0x3a800000, v216
	v_mul_f32_e32 v217, 0x3a800000, v217
	v_mul_f32_e32 v218, 0x3a800000, v218
	v_mul_f32_e32 v219, 0x3a800000, v219
	v_exp_f32_e32 v224, v216
	v_exp_f32_e32 v225, v217
	v_exp_f32_e32 v226, v218
	v_exp_f32_e32 v227, v219
	v_lshlrev_b32_e32 v228, 16, v198
	v_and_b32_e32 v229, 0xffff0000, v198
	v_lshlrev_b32_e32 v230, 16, v199
	v_and_b32_e32 v231, 0xffff0000, v199
	v_pk_fma_f32 v[8:9], v[8:9], v[226:227], v[222:223]
	v_pk_fma_f32 v[6:7], v[6:7], v[224:225], v[220:221]
	v_pk_mul_f32 v[234:235], v[8:9], v[230:231]
	v_pk_mul_f32 v[232:233], v[6:7], v[228:229]
	v_cvt_pk_bf16_f32 v236, v232, v233
	v_cvt_pk_bf16_f32 v237, v234, v235
	global_store_dwordx2 v19, v[236:237], s[90:91] offset:2048
	s_waitcnt vmcnt(30)
	v_cvt_f32_f16_e32 v216, v148
	v_cvt_f32_f16_e32 v217, v149
	v_cvt_f32_f16_e32 v218, v150
	v_cvt_f32_f16_e32 v219, v151
	v_cvt_f32_f16_sdwa v220, v148 dst_sel:DWORD dst_unused:UNUSED_PAD src0_sel:WORD_1
	v_cvt_f32_f16_sdwa v221, v149 dst_sel:DWORD dst_unused:UNUSED_PAD src0_sel:WORD_1
	v_cvt_f32_f16_sdwa v222, v150 dst_sel:DWORD dst_unused:UNUSED_PAD src0_sel:WORD_1
	v_cvt_f32_f16_sdwa v223, v151 dst_sel:DWORD dst_unused:UNUSED_PAD src0_sel:WORD_1
	v_mul_f32_e32 v216, 0x3a800000, v216
	v_mul_f32_e32 v217, 0x3a800000, v217
	v_mul_f32_e32 v218, 0x3a800000, v218
	v_mul_f32_e32 v219, 0x3a800000, v219
	v_exp_f32_e32 v224, v216
	v_exp_f32_e32 v225, v217
	v_exp_f32_e32 v226, v218
	v_exp_f32_e32 v227, v219
	v_lshlrev_b32_e32 v228, 16, v200
	v_and_b32_e32 v229, 0xffff0000, v200
	v_lshlrev_b32_e32 v230, 16, v201
	v_and_b32_e32 v231, 0xffff0000, v201
	v_pk_fma_f32 v[8:9], v[8:9], v[226:227], v[222:223]
	v_pk_fma_f32 v[6:7], v[6:7], v[224:225], v[220:221]
	v_pk_mul_f32 v[234:235], v[8:9], v[230:231]
	v_pk_mul_f32 v[232:233], v[6:7], v[228:229]
	v_add_u32_e32 v19, 0xc000, v16
	v_cvt_pk_bf16_f32 v236, v232, v233
	v_cvt_pk_bf16_f32 v237, v234, v235
	global_store_dwordx2 v19, v[236:237], s[90:91]
	s_waitcnt vmcnt(29)
; __device__ __forceinline__ unsigned pk_bf16(float lo, float hi) { f32x2 v = {lo, hi}; return __builtin_bit_cast(unsigned, __builtin_convertvector(v, bf16v2)); }
; __device__ __forceinline__ float bf_lo(unsigned w) { return __uint_as_float(w << 16); }
; __device__ __forceinline__ float bf_hi(unsigned w) { return __uint_as_float(w & 0xffff0000u); }
; __device__ __forceinline__ void scan_pass2_tile(const unsigned* au, const f32x4* saggP, const f32x4* saggH, const f32x4* cpreP, const f32x4* cpreH, const bf16_t* gate, bf16_t* y, int pm, int blk, int tid) {
;     ...
;     for (int t = 0; t < SCAN_L; ++t) { const size_t o = off + (size_t)t * DM; f32x4 a, u; au_unpack(*(const u32x4*)(au + o), a, u); const u32x2 gw2 = *(const u32x2*)(gate + o);
;         Hh = a * Hh + u;
;         u32x2 w; w.x = pk_bf16(Hh[0] * bf_lo(gw2.x), Hh[1] * bf_hi(gw2.x)); w.y = pk_bf16(Hh[2] * bf_lo(gw2.y), Hh[3] * bf_hi(gw2.y));
;         *(u32x2*)(y + o) = w; }
	v_cvt_f32_f16_e32 v216, v152
	v_cvt_f32_f16_e32 v217, v153
	v_cvt_f32_f16_e32 v218, v154
	v_cvt_f32_f16_e32 v219, v155
	v_cvt_f32_f16_sdwa v220, v152 dst_sel:DWORD dst_unused:UNUSED_PAD src0_sel:WORD_1
	v_cvt_f32_f16_sdwa v221, v153 dst_sel:DWORD dst_unused:UNUSED_PAD src0_sel:WORD_1
	v_cvt_f32_f16_sdwa v222, v154 dst_sel:DWORD dst_unused:UNUSED_PAD src0_sel:WORD_1
	v_cvt_f32_f16_sdwa v223, v155 dst_sel:DWORD dst_unused:UNUSED_PAD src0_sel:WORD_1
	v_mul_f32_e32 v216, 0x3a800000, v216
	v_mul_f32_e32 v217, 0x3a800000, v217
	v_mul_f32_e32 v218, 0x3a800000, v218
	v_mul_f32_e32 v219, 0x3a800000, v219
	v_exp_f32_e32 v224, v216
	v_exp_f32_e32 v225, v217
	v_exp_f32_e32 v226, v218
	v_exp_f32_e32 v227, v219
	v_lshlrev_b32_e32 v228, 16, v202
	v_and_b32_e32 v229, 0xffff0000, v202
	v_lshlrev_b32_e32 v230, 16, v203
	v_and_b32_e32 v231, 0xffff0000, v203
	v_pk_fma_f32 v[8:9], v[8:9], v[226:227], v[222:223]
	v_pk_fma_f32 v[6:7], v[6:7], v[224:225], v[220:221]
	v_pk_mul_f32 v[234:235], v[8:9], v[230:231]
	v_pk_mul_f32 v[232:233], v[6:7], v[228:229]
	v_cvt_pk_bf16_f32 v236, v232, v233
	v_cvt_pk_bf16_f32 v237, v234, v235
	global_store_dwordx2 v19, v[236:237], s[90:91] offset:2048
	s_waitcnt vmcnt(28)
	v_cvt_f32_f16_e32 v216, v156
	v_cvt_f32_f16_e32 v217, v157
	v_cvt_f32_f16_e32 v218, v158
	v_cvt_f32_f16_e32 v219, v159
	v_cvt_f32_f16_sdwa v220, v156 dst_sel:DWORD dst_unused:UNUSED_PAD src0_sel:WORD_1
	v_cvt_f32_f16_sdwa v221, v157 dst_sel:DWORD dst_unused:UNUSED_PAD src0_sel:WORD_1
	v_cvt_f32_f16_sdwa v222, v158 dst_sel:DWORD dst_unused:UNUSED_PAD src0_sel:WORD_1
	v_cvt_f32_f16_sdwa v223, v159 dst_sel:DWORD dst_unused:UNUSED_PAD src0_sel:WORD_1
	v_mul_f32_e32 v216, 0x3a800000, v216
	v_mul_f32_e32 v217, 0x3a800000, v217
	v_mul_f32_e32 v218, 0x3a800000, v218
	v_mul_f32_e32 v219, 0x3a800000, v219
	v_exp_f32_e32 v224, v216
	v_exp_f32_e32 v225, v217
	v_exp_f32_e32 v226, v218
	v_exp_f32_e32 v227, v219
	v_lshlrev_b32_e32 v228, 16, v204
	v_and_b32_e32 v229, 0xffff0000, v204
	v_lshlrev_b32_e32 v230, 16, v205
	v_and_b32_e32 v231, 0xffff0000, v205
	v_pk_fma_f32 v[8:9], v[8:9], v[226:227], v[222:223]
	v_pk_fma_f32 v[6:7], v[6:7], v[224:225], v[220:221]
	v_pk_mul_f32 v[234:235], v[8:9], v[230:231]
	v_pk_mul_f32 v[232:233], v[6:7], v[228:229]
	v_add_u32_e32 v19, 0xd000, v16
	v_cvt_pk_bf16_f32 v236, v232, v233
	v_cvt_pk_bf16_f32 v237, v234, v235
	global_store_dwordx2 v19, v[236:237], s[90:91]
	s_waitcnt vmcnt(27)
	v_cvt_f32_f16_e32 v216, v160
	v_cvt_f32_f16_e32 v217, v161
	v_cvt_f32_f16_e32 v218, v162
	v_cvt_f32_f16_e32 v219, v163
	v_cvt_f32_f16_sdwa v220, v160 dst_sel:DWORD dst_unused:UNUSED_PAD src0_sel:WORD_1
	v_cvt_f32_f16_sdwa v221, v161 dst_sel:DWORD dst_unused:UNUSED_PAD src0_sel:WORD_1
	v_cvt_f32_f16_sdwa v222, v162 dst_sel:DWORD dst_unused:UNUSED_PAD src0_sel:WORD_1
	v_cvt_f32_f16_sdwa v223, v163 dst_sel:DWORD dst_unused:UNUSED_PAD src0_sel:WORD_1
	v_mul_f32_e32 v216, 0x3a800000, v216
	v_mul_f32_e32 v217, 0x3a800000, v217
	v_mul_f32_e32 v218, 0x3a800000, v218
	v_mul_f32_e32 v219, 0x3a800000, v219
	v_exp_f32_e32 v224, v216
	v_exp_f32_e32 v225, v217
	v_exp_f32_e32 v226, v218
	v_exp_f32_e32 v227, v219
	v_lshlrev_b32_e32 v228, 16, v206
	v_and_b32_e32 v229, 0xffff0000, v206
	v_lshlrev_b32_e32 v230, 16, v207
	v_and_b32_e32 v231, 0xffff0000, v207
	v_pk_fma_f32 v[8:9], v[8:9], v[226:227], v[222:223]
	v_pk_fma_f32 v[6:7], v[6:7], v[224:225], v[220:221]
	v_pk_mul_f32 v[234:235], v[8:9], v[230:231]
	v_pk_mul_f32 v[232:233], v[6:7], v[228:229]
	v_cvt_pk_bf16_f32 v236, v232, v233
	v_cvt_pk_bf16_f32 v237, v234, v235
	global_store_dwordx2 v19, v[236:237], s[90:91] offset:2048
	s_waitcnt vmcnt(26)
	v_cvt_f32_f16_e32 v216, v164
	v_cvt_f32_f16_e32 v217, v165
	v_cvt_f32_f16_e32 v218, v166
	v_cvt_f32_f16_e32 v219, v167
	v_cvt_f32_f16_sdwa v220, v164 dst_sel:DWORD dst_unused:UNUSED_PAD src0_sel:WORD_1
	v_cvt_f32_f16_sdwa v221, v165 dst_sel:DWORD dst_unused:UNUSED_PAD src0_sel:WORD_1
	v_cvt_f32_f16_sdwa v222, v166 dst_sel:DWORD dst_unused:UNUSED_PAD src0_sel:WORD_1
	v_cvt_f32_f16_sdwa v223, v167 dst_sel:DWORD dst_unused:UNUSED_PAD src0_sel:WORD_1
	v_mul_f32_e32 v216, 0x3a800000, v216
	v_mul_f32_e32 v217, 0x3a800000, v217
	v_mul_f32_e32 v218, 0x3a800000, v218
	v_mul_f32_e32 v219, 0x3a800000, v219
	v_exp_f32_e32 v224, v216
	v_exp_f32_e32 v225, v217
	v_exp_f32_e32 v226, v218
	v_exp_f32_e32 v227, v219
	v_lshlrev_b32_e32 v228, 16, v208
	v_and_b32_e32 v229, 0xffff0000, v208
	v_lshlrev_b32_e32 v230, 16, v209
	v_and_b32_e32 v231, 0xffff0000, v209
	v_pk_fma_f32 v[8:9], v[8:9], v[226:227], v[222:223]
	v_pk_fma_f32 v[6:7], v[6:7], v[224:225], v[220:221]
	v_pk_mul_f32 v[234:235], v[8:9], v[230:231]
	v_pk_mul_f32 v[232:233], v[6:7], v[228:229]
	v_add_u32_e32 v19, 0xe000, v16
	v_cvt_pk_bf16_f32 v236, v232, v233
	v_cvt_pk_bf16_f32 v237, v234, v235
	global_store_dwordx2 v19, v[236:237], s[90:91]
	s_waitcnt vmcnt(25)
; __device__ __forceinline__ unsigned pk_bf16(float lo, float hi) { f32x2 v = {lo, hi}; return __builtin_bit_cast(unsigned, __builtin_convertvector(v, bf16v2)); }
; __device__ __forceinline__ float bf_lo(unsigned w) { return __uint_as_float(w << 16); }
; __device__ __forceinline__ float bf_hi(unsigned w) { return __uint_as_float(w & 0xffff0000u); }
; __device__ __forceinline__ int fresh_lane() { int l; asm volatile("v_mbcnt_lo_u32_b32 %0, -1, 0\n\tv_mbcnt_hi_u32_b32 %0, -1, %0" : "=v"(l)); return l; }
; __device__ __forceinline__ void scan_pass2_tile(const unsigned* au, const f32x4* saggP, const f32x4* saggH, const f32x4* cpreP, const f32x4* cpreH, const bf16_t* gate, bf16_t* y, int pm, int blk, int tid) {
;     ...
;     for (int t = 0; t < SCAN_L; ++t) { const size_t o = off + (size_t)t * DM; f32x4 a, u; au_unpack(*(const u32x4*)(au + o), a, u); const u32x2 gw2 = *(const u32x2*)(gate + o);
;         Hh = a * Hh + u;
;         u32x2 w; w.x = pk_bf16(Hh[0] * bf_lo(gw2.x), Hh[1] * bf_hi(gw2.x)); w.y = pk_bf16(Hh[2] * bf_lo(gw2.y), Hh[3] * bf_hi(gw2.y));
;         *(u32x2*)(y + o) = w; }
; __global__ void __launch_bounds__(NTHREADS, 2) fwd_megakernel(Params p) {
;     ...
;     for (int wi = bx; wi < (MTOK / 256) * 4; wi += G)
;         scan_pass2_tile(AU, (const f32x4*)(ws + WS_AGGP), (const f32x4*)(ws + WS_AGGP + 512 * 1024), (const f32x4*)(ws + WS_AGGH), (const f32x4*)(ws + WS_CARRY), R0, R1, wi >> 2, wi & 3, wave * 64 + fresh_lane());
	v_cvt_f32_f16_e32 v216, v168
	v_cvt_f32_f16_e32 v217, v169
	v_cvt_f32_f16_e32 v218, v170
	v_cvt_f32_f16_e32 v219, v171
	v_cvt_f32_f16_sdwa v220, v168 dst_sel:DWORD dst_unused:UNUSED_PAD src0_sel:WORD_1
	v_cvt_f32_f16_sdwa v221, v169 dst_sel:DWORD dst_unused:UNUSED_PAD src0_sel:WORD_1
	v_cvt_f32_f16_sdwa v222, v170 dst_sel:DWORD dst_unused:UNUSED_PAD src0_sel:WORD_1
	v_cvt_f32_f16_sdwa v223, v171 dst_sel:DWORD dst_unused:UNUSED_PAD src0_sel:WORD_1
	v_mul_f32_e32 v216, 0x3a800000, v216
	v_mul_f32_e32 v217, 0x3a800000, v217
	v_mul_f32_e32 v218, 0x3a800000, v218
	v_mul_f32_e32 v219, 0x3a800000, v219
	v_exp_f32_e32 v224, v216
	v_exp_f32_e32 v225, v217
	v_exp_f32_e32 v226, v218
	v_exp_f32_e32 v227, v219
	v_lshlrev_b32_e32 v228, 16, v210
	v_and_b32_e32 v229, 0xffff0000, v210
	v_lshlrev_b32_e32 v230, 16, v211
	v_and_b32_e32 v231, 0xffff0000, v211
	v_pk_fma_f32 v[8:9], v[8:9], v[226:227], v[222:223]
	v_pk_fma_f32 v[6:7], v[6:7], v[224:225], v[220:221]
	v_pk_mul_f32 v[234:235], v[8:9], v[230:231]
	v_pk_mul_f32 v[232:233], v[6:7], v[228:229]
	v_cvt_pk_bf16_f32 v236, v232, v233
	v_cvt_pk_bf16_f32 v237, v234, v235
	global_store_dwordx2 v19, v[236:237], s[90:91] offset:2048
	s_waitcnt vmcnt(24)
	v_cvt_f32_f16_e32 v216, v172
	v_cvt_f32_f16_e32 v217, v173
	v_cvt_f32_f16_e32 v218, v174
	v_cvt_f32_f16_e32 v219, v175
	v_cvt_f32_f16_sdwa v220, v172 dst_sel:DWORD dst_unused:UNUSED_PAD src0_sel:WORD_1
	v_cvt_f32_f16_sdwa v221, v173 dst_sel:DWORD dst_unused:UNUSED_PAD src0_sel:WORD_1
	v_cvt_f32_f16_sdwa v222, v174 dst_sel:DWORD dst_unused:UNUSED_PAD src0_sel:WORD_1
	v_cvt_f32_f16_sdwa v223, v175 dst_sel:DWORD dst_unused:UNUSED_PAD src0_sel:WORD_1
	v_mul_f32_e32 v216, 0x3a800000, v216
	v_mul_f32_e32 v217, 0x3a800000, v217
	v_mul_f32_e32 v218, 0x3a800000, v218
	v_mul_f32_e32 v219, 0x3a800000, v219
	v_exp_f32_e32 v224, v216
	v_exp_f32_e32 v225, v217
	v_exp_f32_e32 v226, v218
	v_exp_f32_e32 v227, v219
	v_lshlrev_b32_e32 v228, 16, v212
	v_and_b32_e32 v229, 0xffff0000, v212
	v_lshlrev_b32_e32 v230, 16, v213
	v_and_b32_e32 v231, 0xffff0000, v213
	v_pk_fma_f32 v[8:9], v[8:9], v[226:227], v[222:223]
	v_pk_fma_f32 v[6:7], v[6:7], v[224:225], v[220:221]
	v_pk_mul_f32 v[234:235], v[8:9], v[230:231]
	v_pk_mul_f32 v[232:233], v[6:7], v[228:229]
	v_add_u32_e32 v19, 0xf000, v16
	v_cvt_pk_bf16_f32 v236, v232, v233
	v_cvt_pk_bf16_f32 v237, v234, v235
	global_store_dwordx2 v19, v[236:237], s[90:91]
	s_waitcnt vmcnt(23)
	v_cvt_f32_f16_e32 v216, v180
	v_cvt_f32_f16_e32 v217, v181
	v_cvt_f32_f16_e32 v218, v182
	v_cvt_f32_f16_e32 v219, v183
	v_cvt_f32_f16_sdwa v220, v180 dst_sel:DWORD dst_unused:UNUSED_PAD src0_sel:WORD_1
	v_cvt_f32_f16_sdwa v221, v181 dst_sel:DWORD dst_unused:UNUSED_PAD src0_sel:WORD_1
	v_cvt_f32_f16_sdwa v222, v182 dst_sel:DWORD dst_unused:UNUSED_PAD src0_sel:WORD_1
	v_cvt_f32_f16_sdwa v223, v183 dst_sel:DWORD dst_unused:UNUSED_PAD src0_sel:WORD_1
	v_mul_f32_e32 v216, 0x3a800000, v216
	v_mul_f32_e32 v217, 0x3a800000, v217
	v_mul_f32_e32 v218, 0x3a800000, v218
	v_mul_f32_e32 v219, 0x3a800000, v219
	v_exp_f32_e32 v224, v216
	v_exp_f32_e32 v225, v217
	v_exp_f32_e32 v226, v218
	v_exp_f32_e32 v227, v219
	v_lshlrev_b32_e32 v228, 16, v214
	v_and_b32_e32 v229, 0xffff0000, v214
	v_lshlrev_b32_e32 v230, 16, v215
	v_and_b32_e32 v231, 0xffff0000, v215
	v_pk_fma_f32 v[8:9], v[8:9], v[226:227], v[222:223]
	v_pk_fma_f32 v[6:7], v[6:7], v[224:225], v[220:221]
	v_pk_mul_f32 v[234:235], v[8:9], v[230:231]
	v_pk_mul_f32 v[232:233], v[6:7], v[228:229]
	v_cvt_pk_bf16_f32 v236, v232, v233
	v_cvt_pk_bf16_f32 v237, v234, v235
	global_store_dwordx2 v19, v[236:237], s[90:91] offset:2048
	s_add_i32 s64, s64, s42
	s_add_i32 s30, s30, s31
	s_cmpk_gt_i32 s64, 0xff
	s_cbranch_scc0 .LBB0_343

; #define PG8_STAGE(bufoff, gbase, voff) do { _Pragma("unroll") for (int _i = 0; _i < 2; ++_i) \
;         __builtin_amdgcn_global_load_lds((const unsigned*)((const char*)(gbase) + (voff)[_i]), (PG8_LAS unsigned*)(lds + (bufoff) + ldsw + _i * 8192), 16, 0, 0); } while (0)
; #define PG8_LDA(dst, b, h) do { _Pragma("unroll") for (int m = 0; m < 4; ++m) _Pragma("unroll") for (int k = 0; k < 2; ++k) dst[m][k] = *(const PG8_LAS bf16x8*)(lds + PG8_SA(b, h) + aoff + m * 2048 + k * 1024); } while (0)
; #define PG8_LDB(dst, b, h) do { _Pragma("unroll") for (int n = 0; n < 2; ++n) _Pragma("unroll") for (int k = 0; k < 2; ++k) dst[n][k] = *(const PG8_LAS bf16x8*)(lds + PG8_SB(b, h) + boff + n * 2048 + k * 1024); } while (0)
; #define PG8_MMA(ai, bj, At, Bt) do { __builtin_amdgcn_s_setprio(1); _Pragma("unroll") for (int m = 0; m < 4; ++m) _Pragma("unroll") for (int n = 0; n < 2; ++n) _Pragma("unroll") for (int k = 0; k < 2; ++k) \
;         acc[ai][bj][m][n] = __builtin_amdgcn_mfma_f32_16x16x32_bf16(Bt[n][k], At[m][k], acc[ai][bj][m][n], 0, 0, 0); __builtin_amdgcn_s_setprio(0); } while (0)
; #define PG8_WAIT_V(n) asm volatile("s_waitcnt vmcnt(" #n ")" ::: "memory")
; #define PG8_WAIT_L(n) asm volatile("s_waitcnt lgkmcnt(" #n ")" ::: "memory")
; #define PG8_BAR __builtin_amdgcn_s_barrier()
; #define PG8_SCHED __builtin_amdgcn_sched_barrier(0)
; template <class Epi, class Sched, bool ALIGN_EPI = false, bool SP2 = false>
; __device__ __forceinline__ void gemm_phase(PG8_LAS unsigned char* lds, const Gemm g, const Sched& S, const Epi& E, const int wid) {
;     ...
;             if constexpr (SP2) {
;             PG8_LDB(B0, 0, 0); PG8_LDB(B1, 0, 1); PG8_SCHED; PG8_LDA(At, 0, 0); PG8_STAGE(PG8_SA(1, 1), a1 + hstepA, voffA);
;             PG8_WAIT_V(8); PG8_WAIT_L(0); PG8_BAR; PG8_MMA(0, 0, At, B0); PG8_MMA(0, 1, At, B1); PG8_BAR; PG8_SCHED;
;             PG8_LDA(At, 0, 1); PG8_STAGE(PG8_SB(0, 0), b2, voffB); PG8_STAGE(PG8_SB(0, 1), b2 + hstepB, voffB); PG8_STAGE(PG8_SA(0, 0), a2, voffA);
;             PG8_WAIT_V(8); PG8_WAIT_L(0); PG8_BAR; PG8_MMA(1, 0, At, B0); PG8_MMA(1, 1, At, B1); PG8_BAR; PG8_SCHED;
.LBB0_405:
	v_add_u32_e32 v162, s62, v148
	v_add_u32_e32 v179, s63, v148
	ds_read_b128 v[150:153], v162
	ds_read_b128 v[154:157], v162 offset:1024
	ds_read_b128 v[158:161], v162 offset:2048
	ds_read_b128 v[162:165], v162 offset:3072
	ds_read_b128 v[166:169], v179
	ds_read_b128 v[170:173], v179 offset:1024
	ds_read_b128 v[174:177], v179 offset:2048
	ds_read_b128 v[180:183], v179 offset:3072
	s_add_i32 s65, s44, 2
	s_add_u32 s45, s40, 0xfffc0080
	s_addc_u32 s46, s41, -1
	s_cmp_eq_u32 s61, s44
	s_cselect_b32 s44, s38, s31
	s_cselect_b32 s47, s37, s46
	s_cselect_b32 s46, s36, s45
	s_cselect_b32 s45, s39, s35
	v_lshl_add_u64 v[216:217], s[40:41], 0, v[136:137]
	s_add_i32 m0, s11, 0xc000
	ds_read_b128 v[184:187], v149
	ds_read_b128 v[188:191], v149 offset:1024
	ds_read_b128 v[192:195], v149 offset:2048
	ds_read_b128 v[196:199], v149 offset:3072
	ds_read_b128 v[200:203], v149 offset:4096
	ds_read_b128 v[204:207], v149 offset:5120
	ds_read_b128 v[208:211], v149 offset:6144
	ds_read_b128 v[212:215], v149 offset:7168
	global_load_lds_dwordx4 v[216:217], off
	v_lshl_add_u64 v[216:217], s[40:41], 0, v[138:139]
	s_add_i32 m0, s11, 0xe000
	s_nop 0
	global_load_lds_dwordx4 v[216:217], off
	s_waitcnt vmcnt(8)
	s_waitcnt lgkmcnt(0)
	s_barrier
	s_setprio 1
	v_mfma_f32_16x16x32_bf16 v[124:127], v[150:153], v[184:187], v[124:127]
	v_mfma_f32_16x16x32_bf16 v[120:123], v[158:161], v[184:187], v[120:123]
	v_mfma_f32_16x16x32_bf16 v[108:111], v[150:153], v[192:195], v[108:111]
	v_mfma_f32_16x16x32_bf16 v[104:107], v[158:161], v[192:195], v[104:107]
	v_mfma_f32_16x16x32_bf16 v[100:103], v[150:153], v[200:203], v[100:103]
	v_mfma_f32_16x16x32_bf16 v[92:95], v[158:161], v[200:203], v[92:95]
	v_mfma_f32_16x16x32_bf16 v[84:87], v[150:153], v[208:211], v[84:87]
	v_mfma_f32_16x16x32_bf16 v[76:79], v[158:161], v[208:211], v[76:79]
	v_mfma_f32_16x16x32_bf16 v[124:127], v[154:157], v[188:191], v[124:127]
	v_mfma_f32_16x16x32_bf16 v[120:123], v[162:165], v[188:191], v[120:123]
	v_mfma_f32_16x16x32_bf16 v[108:111], v[154:157], v[196:199], v[108:111]
	v_mfma_f32_16x16x32_bf16 v[104:107], v[162:165], v[196:199], v[104:107]
	v_mfma_f32_16x16x32_bf16 v[100:103], v[154:157], v[204:207], v[100:103]
	v_mfma_f32_16x16x32_bf16 v[92:95], v[162:165], v[204:207], v[92:95]
	v_mfma_f32_16x16x32_bf16 v[84:87], v[154:157], v[212:215], v[84:87]
	v_mfma_f32_16x16x32_bf16 v[76:79], v[162:165], v[212:215], v[76:79]
	s_setprio 0
	s_setprio 1
	v_mfma_f32_16x16x32_bf16 v[116:119], v[166:169], v[184:187], v[116:119]
	v_mfma_f32_16x16x32_bf16 v[112:115], v[174:177], v[184:187], v[112:115]
	v_mfma_f32_16x16x32_bf16 v[96:99], v[166:169], v[192:195], v[96:99]
	v_mfma_f32_16x16x32_bf16 v[88:91], v[174:177], v[192:195], v[88:91]
	v_mfma_f32_16x16x32_bf16 v[80:83], v[166:169], v[200:203], v[80:83]
	v_mfma_f32_16x16x32_bf16 v[72:75], v[174:177], v[200:203], v[72:75]
	v_mfma_f32_16x16x32_bf16 v[68:71], v[166:169], v[208:211], v[68:71]
	v_mfma_f32_16x16x32_bf16 v[64:67], v[174:177], v[208:211], v[64:67]
	v_mfma_f32_16x16x32_bf16 v[116:119], v[170:173], v[188:191], v[116:119]
	v_mfma_f32_16x16x32_bf16 v[112:115], v[180:183], v[188:191], v[112:115]
	v_mfma_f32_16x16x32_bf16 v[96:99], v[170:173], v[196:199], v[96:99]
	v_mfma_f32_16x16x32_bf16 v[88:91], v[180:183], v[196:199], v[88:91]
	v_mfma_f32_16x16x32_bf16 v[80:83], v[170:173], v[204:207], v[80:83]
	v_mfma_f32_16x16x32_bf16 v[72:75], v[180:183], v[204:207], v[72:75]
	v_mfma_f32_16x16x32_bf16 v[68:71], v[170:173], v[212:215], v[68:71]
	v_mfma_f32_16x16x32_bf16 v[64:67], v[180:183], v[212:215], v[64:67]
	s_setprio 0
	s_barrier
	s_add_i32 s66, s62, s0
	v_lshl_add_u64 v[216:217], s[44:45], 0, v[134:135]
	s_mov_b32 m0, s66
	ds_read_b128 v[184:187], v149 offset:16384
	ds_read_b128 v[188:191], v149 offset:17408
	ds_read_b128 v[192:195], v149 offset:18432
	ds_read_b128 v[196:199], v149 offset:19456
	ds_read_b128 v[200:203], v149 offset:20480
	ds_read_b128 v[204:207], v149 offset:21504
	ds_read_b128 v[208:211], v149 offset:22528
	ds_read_b128 v[212:215], v149 offset:23552
	global_load_lds_dwordx4 v[216:217], off
	s_add_i32 m0, s66, 0x2000
	s_add_u32 s66, s44, 0x40000
	v_lshl_add_u64 v[218:219], s[44:45], 0, v[132:133]
	s_addc_u32 s67, s45, 0
	s_add_i32 s68, s63, s0
	global_load_lds_dwordx4 v[218:219], off
	v_lshl_add_u64 v[220:221], s[66:67], 0, v[134:135]
	s_mov_b32 m0, s68
	v_lshl_add_u64 v[222:223], s[46:47], 0, v[130:131]
	global_load_lds_dwordx4 v[220:221], off
	v_lshl_add_u64 v[220:221], s[66:67], 0, v[132:133]
	s_add_i32 m0, s68, 0x2000
	s_nop 0
	global_load_lds_dwordx4 v[220:221], off
	v_lshl_add_u64 v[220:221], s[46:47], 0, v[128:129]
	s_mov_b32 m0, s11
	s_nop 0
	global_load_lds_dwordx4 v[220:221], off
	s_mov_b32 m0, s55
	s_nop 0
	global_load_lds_dwordx4 v[222:223], off
	s_waitcnt vmcnt(8)
	s_waitcnt lgkmcnt(0)
	s_barrier
; #define PG8_STAGE(bufoff, gbase, voff) do { _Pragma("unroll") for (int _i = 0; _i < 2; ++_i) \
;         __builtin_amdgcn_global_load_lds((const unsigned*)((const char*)(gbase) + (voff)[_i]), (PG8_LAS unsigned*)(lds + (bufoff) + ldsw + _i * 8192), 16, 0, 0); } while (0)
; #define PG8_LDA(dst, b, h) do { _Pragma("unroll") for (int m = 0; m < 4; ++m) _Pragma("unroll") for (int k = 0; k < 2; ++k) dst[m][k] = *(const PG8_LAS bf16x8*)(lds + PG8_SA(b, h) + aoff + m * 2048 + k * 1024); } while (0)
; #define PG8_LDB(dst, b, h) do { _Pragma("unroll") for (int n = 0; n < 2; ++n) _Pragma("unroll") for (int k = 0; k < 2; ++k) dst[n][k] = *(const PG8_LAS bf16x8*)(lds + PG8_SB(b, h) + boff + n * 2048 + k * 1024); } while (0)
; #define PG8_MMA(ai, bj, At, Bt) do { __builtin_amdgcn_s_setprio(1); _Pragma("unroll") for (int m = 0; m < 4; ++m) _Pragma("unroll") for (int n = 0; n < 2; ++n) _Pragma("unroll") for (int k = 0; k < 2; ++k) \
;         acc[ai][bj][m][n] = __builtin_amdgcn_mfma_f32_16x16x32_bf16(Bt[n][k], At[m][k], acc[ai][bj][m][n], 0, 0, 0); __builtin_amdgcn_s_setprio(0); } while (0)
; #define PG8_WAIT_V(n) asm volatile("s_waitcnt vmcnt(" #n ")" ::: "memory")
; #define PG8_WAIT_L(n) asm volatile("s_waitcnt lgkmcnt(" #n ")" ::: "memory")
; #define PG8_BAR __builtin_amdgcn_s_barrier()
; #define PG8_SCHED __builtin_amdgcn_sched_barrier(0)
; template <class Epi, class Sched, bool ALIGN_EPI = false, bool SP2 = false>
; __device__ __forceinline__ void gemm_phase(PG8_LAS unsigned char* lds, const Gemm g, const Sched& S, const Epi& E, const int wid) {
;     ...
;             PG8_WAIT_V(8); PG8_WAIT_L(0); PG8_BAR; PG8_MMA(1, 0, At, B0); PG8_MMA(1, 1, At, B1); PG8_BAR; PG8_SCHED;
;             PG8_LDB(B0, 1, 0); PG8_LDB(B1, 1, 1); PG8_SCHED; PG8_LDA(At, 1, 0); PG8_STAGE(PG8_SA(0, 1), a2 + hstepA, voffA);
;             PG8_WAIT_V(8); PG8_WAIT_L(0); PG8_BAR; PG8_MMA(0, 0, At, B0); PG8_MMA(0, 1, At, B1); PG8_BAR; PG8_SCHED;
	s_setprio 1
	v_mfma_f32_16x16x32_bf16 v[52:55], v[150:153], v[184:187], v[52:55]
	v_mfma_f32_16x16x32_bf16 v[40:43], v[158:161], v[184:187], v[40:43]
	v_mfma_f32_16x16x32_bf16 v[28:31], v[150:153], v[192:195], v[28:31]
	v_mfma_f32_16x16x32_bf16 v[12:15], v[158:161], v[192:195], v[12:15]
	v_mfma_f32_16x16x32_bf16 v[60:63], v[150:153], v[200:203], v[60:63]
	v_mfma_f32_16x16x32_bf16 v[48:51], v[158:161], v[200:203], v[48:51]
	v_mfma_f32_16x16x32_bf16 v[36:39], v[150:153], v[208:211], v[36:39]
	v_mfma_f32_16x16x32_bf16 v[24:27], v[158:161], v[208:211], v[24:27]
	v_mfma_f32_16x16x32_bf16 v[52:55], v[154:157], v[188:191], v[52:55]
	v_mfma_f32_16x16x32_bf16 v[40:43], v[162:165], v[188:191], v[40:43]
	v_mfma_f32_16x16x32_bf16 v[28:31], v[154:157], v[196:199], v[28:31]
	v_mfma_f32_16x16x32_bf16 v[12:15], v[162:165], v[196:199], v[12:15]
	v_mfma_f32_16x16x32_bf16 v[60:63], v[154:157], v[204:207], v[60:63]
	v_mfma_f32_16x16x32_bf16 v[48:51], v[162:165], v[204:207], v[48:51]
	v_mfma_f32_16x16x32_bf16 v[36:39], v[154:157], v[212:215], v[36:39]
	v_mfma_f32_16x16x32_bf16 v[24:27], v[162:165], v[212:215], v[24:27]
	s_setprio 0
	s_setprio 1
	v_mfma_f32_16x16x32_bf16 v[20:23], v[166:169], v[184:187], v[20:23]
	v_mfma_f32_16x16x32_bf16 v[8:11], v[174:177], v[184:187], v[8:11]
	v_mfma_f32_16x16x32_bf16 v[56:59], v[166:169], v[192:195], v[56:59]
	v_mfma_f32_16x16x32_bf16 v[44:47], v[174:177], v[192:195], v[44:47]
	v_mfma_f32_16x16x32_bf16 v[32:35], v[166:169], v[200:203], v[32:35]
	v_mfma_f32_16x16x32_bf16 v[16:19], v[174:177], v[200:203], v[16:19]
	v_mfma_f32_16x16x32_bf16 v[4:7], v[166:169], v[208:211], v[4:7]
	v_mfma_f32_16x16x32_bf16 v[0:3], v[174:177], v[208:211], v[0:3]
	v_mfma_f32_16x16x32_bf16 v[20:23], v[170:173], v[188:191], v[20:23]
	v_mfma_f32_16x16x32_bf16 v[8:11], v[180:183], v[188:191], v[8:11]
	v_mfma_f32_16x16x32_bf16 v[56:59], v[170:173], v[196:199], v[56:59]
	v_mfma_f32_16x16x32_bf16 v[44:47], v[180:183], v[196:199], v[44:47]
	v_mfma_f32_16x16x32_bf16 v[32:35], v[170:173], v[204:207], v[32:35]
	v_mfma_f32_16x16x32_bf16 v[16:19], v[180:183], v[204:207], v[16:19]
	v_mfma_f32_16x16x32_bf16 v[4:7], v[170:173], v[212:215], v[4:7]
	v_mfma_f32_16x16x32_bf16 v[0:3], v[180:183], v[212:215], v[0:3]
	s_setprio 0
	s_barrier
	s_add_i32 s66, 0, 0x18000
	s_add_i32 s67, 0, 0x1c000
	v_add_u32_e32 v162, s66, v148
	v_add_u32_e32 v179, s67, v148
	ds_read_b128 v[150:153], v162
	ds_read_b128 v[154:157], v162 offset:1024
	ds_read_b128 v[158:161], v162 offset:2048
	ds_read_b128 v[162:165], v162 offset:3072
	ds_read_b128 v[166:169], v179
	ds_read_b128 v[170:173], v179 offset:1024
	ds_read_b128 v[174:177], v179 offset:2048
	ds_read_b128 v[180:183], v179 offset:3072
	s_add_u32 s46, s46, 0x40000
	s_addc_u32 s47, s47, 0
	s_mov_b32 m0, s56
	v_lshl_add_u64 v[224:225], s[46:47], 0, v[128:129]
	ds_read_b128 v[184:187], v149 offset:32768
	ds_read_b128 v[188:191], v149 offset:33792
	ds_read_b128 v[192:195], v149 offset:34816
	ds_read_b128 v[196:199], v149 offset:35840
	ds_read_b128 v[200:203], v149 offset:36864
	ds_read_b128 v[204:207], v149 offset:37888
	ds_read_b128 v[208:211], v149 offset:38912
	ds_read_b128 v[212:215], v149 offset:39936
	global_load_lds_dwordx4 v[224:225], off
	v_lshl_add_u64 v[224:225], s[46:47], 0, v[130:131]
	s_mov_b32 m0, s57
	s_nop 0
	global_load_lds_dwordx4 v[224:225], off
	s_waitcnt vmcnt(8)
	s_waitcnt lgkmcnt(0)
	s_barrier
	s_setprio 1
	v_mfma_f32_16x16x32_bf16 v[124:127], v[150:153], v[184:187], v[124:127]
	v_mfma_f32_16x16x32_bf16 v[120:123], v[158:161], v[184:187], v[120:123]
	v_mfma_f32_16x16x32_bf16 v[108:111], v[150:153], v[192:195], v[108:111]
	v_mfma_f32_16x16x32_bf16 v[104:107], v[158:161], v[192:195], v[104:107]
	v_mfma_f32_16x16x32_bf16 v[100:103], v[150:153], v[200:203], v[100:103]
	v_mfma_f32_16x16x32_bf16 v[92:95], v[158:161], v[200:203], v[92:95]
	v_mfma_f32_16x16x32_bf16 v[84:87], v[150:153], v[208:211], v[84:87]
	v_mfma_f32_16x16x32_bf16 v[76:79], v[158:161], v[208:211], v[76:79]
	v_mfma_f32_16x16x32_bf16 v[124:127], v[154:157], v[188:191], v[124:127]
	v_mfma_f32_16x16x32_bf16 v[120:123], v[162:165], v[188:191], v[120:123]
	v_mfma_f32_16x16x32_bf16 v[108:111], v[154:157], v[196:199], v[108:111]
	v_mfma_f32_16x16x32_bf16 v[104:107], v[162:165], v[196:199], v[104:107]
	v_mfma_f32_16x16x32_bf16 v[100:103], v[154:157], v[204:207], v[100:103]
	v_mfma_f32_16x16x32_bf16 v[92:95], v[162:165], v[204:207], v[92:95]
	v_mfma_f32_16x16x32_bf16 v[84:87], v[154:157], v[212:215], v[84:87]
	v_mfma_f32_16x16x32_bf16 v[76:79], v[162:165], v[212:215], v[76:79]
	s_setprio 0
	s_setprio 1
	v_mfma_f32_16x16x32_bf16 v[116:119], v[166:169], v[184:187], v[116:119]
	v_mfma_f32_16x16x32_bf16 v[112:115], v[174:177], v[184:187], v[112:115]
	v_mfma_f32_16x16x32_bf16 v[96:99], v[166:169], v[192:195], v[96:99]
	v_mfma_f32_16x16x32_bf16 v[88:91], v[174:177], v[192:195], v[88:91]
	v_mfma_f32_16x16x32_bf16 v[80:83], v[166:169], v[200:203], v[80:83]
	v_mfma_f32_16x16x32_bf16 v[72:75], v[174:177], v[200:203], v[72:75]
	v_mfma_f32_16x16x32_bf16 v[68:71], v[166:169], v[208:211], v[68:71]
	v_mfma_f32_16x16x32_bf16 v[64:67], v[174:177], v[208:211], v[64:67]
	v_mfma_f32_16x16x32_bf16 v[116:119], v[170:173], v[188:191], v[116:119]
	v_mfma_f32_16x16x32_bf16 v[112:115], v[180:183], v[188:191], v[112:115]
	v_mfma_f32_16x16x32_bf16 v[96:99], v[170:173], v[196:199], v[96:99]
	v_mfma_f32_16x16x32_bf16 v[88:91], v[180:183], v[196:199], v[88:91]
	v_mfma_f32_16x16x32_bf16 v[80:83], v[170:173], v[204:207], v[80:83]
	v_mfma_f32_16x16x32_bf16 v[72:75], v[180:183], v[204:207], v[72:75]
	v_mfma_f32_16x16x32_bf16 v[68:71], v[170:173], v[212:215], v[68:71]
	v_mfma_f32_16x16x32_bf16 v[64:67], v[180:183], v[212:215], v[64:67]
	s_setprio 0
	s_barrier
; #define PG8_STAGE(bufoff, gbase, voff) do { _Pragma("unroll") for (int _i = 0; _i < 2; ++_i) \
;         __builtin_amdgcn_global_load_lds((const unsigned*)((const char*)(gbase) + (voff)[_i]), (PG8_LAS unsigned*)(lds + (bufoff) + ldsw + _i * 8192), 16, 0, 0); } while (0)
; #define PG8_LDA(dst, b, h) do { _Pragma("unroll") for (int m = 0; m < 4; ++m) _Pragma("unroll") for (int k = 0; k < 2; ++k) dst[m][k] = *(const PG8_LAS bf16x8*)(lds + PG8_SA(b, h) + aoff + m * 2048 + k * 1024); } while (0)
; #define PG8_MMA(ai, bj, At, Bt) do { __builtin_amdgcn_s_setprio(1); _Pragma("unroll") for (int m = 0; m < 4; ++m) _Pragma("unroll") for (int n = 0; n < 2; ++n) _Pragma("unroll") for (int k = 0; k < 2; ++k) \
;         acc[ai][bj][m][n] = __builtin_amdgcn_mfma_f32_16x16x32_bf16(Bt[n][k], At[m][k], acc[ai][bj][m][n], 0, 0, 0); __builtin_amdgcn_s_setprio(0); } while (0)
; #define PG8_WAIT_V(n) asm volatile("s_waitcnt vmcnt(" #n ")" ::: "memory")
; #define PG8_WAIT_L(n) asm volatile("s_waitcnt lgkmcnt(" #n ")" ::: "memory")
; #define PG8_BAR __builtin_amdgcn_s_barrier()
; #define PG8_SCHED __builtin_amdgcn_sched_barrier(0)
; template <class Epi, class Sched, bool ALIGN_EPI = false, bool SP2 = false>
; __device__ __forceinline__ void gemm_phase(PG8_LAS unsigned char* lds, const Gemm g, const Sched& S, const Epi& E, const int wid) {
;     ...
;             PG8_WAIT_V(8); PG8_WAIT_L(0); PG8_BAR; PG8_MMA(0, 0, At, B0); PG8_MMA(0, 1, At, B1); PG8_BAR; PG8_SCHED;
;             PG8_LDA(At, 1, 1); PG8_STAGE(PG8_SB(1, 0), b3, voffB); PG8_STAGE(PG8_SB(1, 1), b3 + hstepB, voffB); PG8_STAGE(PG8_SA(1, 0), a3, voffA);
;             PG8_WAIT_V(8); PG8_WAIT_L(0); PG8_BAR; PG8_MMA(1, 0, At, B0); PG8_MMA(1, 1, At, B1); PG8_BAR; PG8_SCHED;
	s_add_i32 s46, s66, s0
	v_lshl_add_u64 v[216:217], v[216:217], 0, s[26:27]
	s_mov_b32 m0, s46
	ds_read_b128 v[184:187], v149 offset:49152
	ds_read_b128 v[188:191], v149 offset:50176
	ds_read_b128 v[192:195], v149 offset:51200
	ds_read_b128 v[196:199], v149 offset:52224
	ds_read_b128 v[200:203], v149 offset:53248
	ds_read_b128 v[204:207], v149 offset:54272
	ds_read_b128 v[208:211], v149 offset:55296
	ds_read_b128 v[212:215], v149 offset:56320
	global_load_lds_dwordx4 v[216:217], off
	s_add_i32 m0, s46, 0x2000
	s_add_u32 s44, s44, 0x40080
	v_lshl_add_u64 v[216:217], v[218:219], 0, s[26:27]
	s_addc_u32 s45, s45, 0
	s_add_i32 s46, s67, s0
	global_load_lds_dwordx4 v[216:217], off
	v_lshl_add_u64 v[216:217], s[44:45], 0, v[134:135]
	s_mov_b32 m0, s46
	s_nop 0
	global_load_lds_dwordx4 v[216:217], off
	v_lshl_add_u64 v[216:217], s[44:45], 0, v[132:133]
	s_add_i32 m0, s46, 0x2000
	s_nop 0
	global_load_lds_dwordx4 v[216:217], off
	v_lshl_add_u64 v[216:217], v[220:221], 0, s[26:27]
	s_mov_b32 m0, s59
	s_nop 0
	global_load_lds_dwordx4 v[216:217], off
	v_lshl_add_u64 v[216:217], v[222:223], 0, s[26:27]
	s_mov_b32 m0, s60
	s_nop 0
	global_load_lds_dwordx4 v[216:217], off
	s_waitcnt vmcnt(8)
	s_waitcnt lgkmcnt(0)
	s_barrier
	s_setprio 1
	v_mfma_f32_16x16x32_bf16 v[52:55], v[150:153], v[184:187], v[52:55]
	v_mfma_f32_16x16x32_bf16 v[40:43], v[158:161], v[184:187], v[40:43]
	v_mfma_f32_16x16x32_bf16 v[28:31], v[150:153], v[192:195], v[28:31]
	v_mfma_f32_16x16x32_bf16 v[12:15], v[158:161], v[192:195], v[12:15]
	v_mfma_f32_16x16x32_bf16 v[60:63], v[150:153], v[200:203], v[60:63]
	v_mfma_f32_16x16x32_bf16 v[48:51], v[158:161], v[200:203], v[48:51]
	v_mfma_f32_16x16x32_bf16 v[36:39], v[150:153], v[208:211], v[36:39]
	v_mfma_f32_16x16x32_bf16 v[24:27], v[158:161], v[208:211], v[24:27]
	v_mfma_f32_16x16x32_bf16 v[52:55], v[154:157], v[188:191], v[52:55]
	v_mfma_f32_16x16x32_bf16 v[40:43], v[162:165], v[188:191], v[40:43]
	v_mfma_f32_16x16x32_bf16 v[28:31], v[154:157], v[196:199], v[28:31]
	v_mfma_f32_16x16x32_bf16 v[12:15], v[162:165], v[196:199], v[12:15]
	v_mfma_f32_16x16x32_bf16 v[60:63], v[154:157], v[204:207], v[60:63]
	v_mfma_f32_16x16x32_bf16 v[48:51], v[162:165], v[204:207], v[48:51]
	v_mfma_f32_16x16x32_bf16 v[36:39], v[154:157], v[212:215], v[36:39]
	v_mfma_f32_16x16x32_bf16 v[24:27], v[162:165], v[212:215], v[24:27]
	s_setprio 0
	s_setprio 1
	v_mfma_f32_16x16x32_bf16 v[20:23], v[166:169], v[184:187], v[20:23]
	v_mfma_f32_16x16x32_bf16 v[8:11], v[174:177], v[184:187], v[8:11]
	v_mfma_f32_16x16x32_bf16 v[56:59], v[166:169], v[192:195], v[56:59]
	v_mfma_f32_16x16x32_bf16 v[44:47], v[174:177], v[192:195], v[44:47]
	v_mfma_f32_16x16x32_bf16 v[32:35], v[166:169], v[200:203], v[32:35]
	v_mfma_f32_16x16x32_bf16 v[16:19], v[174:177], v[200:203], v[16:19]
	v_mfma_f32_16x16x32_bf16 v[4:7], v[166:169], v[208:211], v[4:7]
	v_mfma_f32_16x16x32_bf16 v[0:3], v[174:177], v[208:211], v[0:3]
	v_mfma_f32_16x16x32_bf16 v[20:23], v[170:173], v[188:191], v[20:23]
	v_mfma_f32_16x16x32_bf16 v[8:11], v[180:183], v[188:191], v[8:11]
	v_mfma_f32_16x16x32_bf16 v[56:59], v[170:173], v[196:199], v[56:59]
	v_mfma_f32_16x16x32_bf16 v[44:47], v[180:183], v[196:199], v[44:47]
	v_mfma_f32_16x16x32_bf16 v[32:35], v[170:173], v[204:207], v[32:35]
	v_mfma_f32_16x16x32_bf16 v[16:19], v[180:183], v[204:207], v[16:19]
	v_mfma_f32_16x16x32_bf16 v[4:7], v[170:173], v[212:215], v[4:7]
	v_mfma_f32_16x16x32_bf16 v[0:3], v[180:183], v[212:215], v[0:3]
	s_setprio 0
	s_barrier
	s_add_u32 s40, s40, 0x100
	s_addc_u32 s41, s41, 0
	s_add_u32 s31, s31, 0x100
	s_addc_u32 s35, s35, 0
	s_cmp_ge_i32 s65, s49
	s_mov_b32 s44, s65
	s_cbranch_scc0 .LBB0_405

; #define PG8_STAGE(bufoff, gbase, voff) do { _Pragma("unroll") for (int _i = 0; _i < 2; ++_i) \
;         __builtin_amdgcn_global_load_lds((const unsigned*)((const char*)(gbase) + (voff)[_i]), (PG8_LAS unsigned*)(lds + (bufoff) + ldsw + _i * 8192), 16, 0, 0); } while (0)
; #define PG8_LDA(dst, b, h) do { _Pragma("unroll") for (int m = 0; m < 4; ++m) _Pragma("unroll") for (int k = 0; k < 2; ++k) dst[m][k] = *(const PG8_LAS bf16x8*)(lds + PG8_SA(b, h) + aoff + m * 2048 + k * 1024); } while (0)
; #define PG8_LDB(dst, b, h) do { _Pragma("unroll") for (int n = 0; n < 2; ++n) _Pragma("unroll") for (int k = 0; k < 2; ++k) dst[n][k] = *(const PG8_LAS bf16x8*)(lds + PG8_SB(b, h) + boff + n * 2048 + k * 1024); } while (0)
; #define PG8_MMA(ai, bj, At, Bt) do { __builtin_amdgcn_s_setprio(1); _Pragma("unroll") for (int m = 0; m < 4; ++m) _Pragma("unroll") for (int n = 0; n < 2; ++n) _Pragma("unroll") for (int k = 0; k < 2; ++k) \
;         acc[ai][bj][m][n] = __builtin_amdgcn_mfma_f32_16x16x32_bf16(Bt[n][k], At[m][k], acc[ai][bj][m][n], 0, 0, 0); __builtin_amdgcn_s_setprio(0); } while (0)
; #define PG8_WAIT_V(n) asm volatile("s_waitcnt vmcnt(" #n ")" ::: "memory")
; #define PG8_WAIT_L(n) asm volatile("s_waitcnt lgkmcnt(" #n ")" ::: "memory")
; #define PG8_BAR __builtin_amdgcn_s_barrier()
; #define PG8_SCHED __builtin_amdgcn_sched_barrier(0)
; template <class Epi, class Sched, bool ALIGN_EPI = false, bool SP2 = false>
; __device__ __forceinline__ void gemm_phase(PG8_LAS unsigned char* lds, const Gemm g, const Sched& S, const Epi& E, const int wid) {
;     ...
;         for (int t = 0; t < nt; t += 2) {
;             const bool last = (t == nt - 2);
;             const char* a1 = cA + (size_t)(t + 1) * kstep;
;             const char* a2 = last ? nA : cA + (size_t)(t + 2) * kstep; const char* b2 = last ? nB : cB + (size_t)(t + 2) * kstep;
;             const char* a3 = a2 + kstep; const char* b3 = b2 + kstep;
;             if (last && has_next) S.a_ready(nxt);
;             if constexpr (SP2) {
;             PG8_LDB(B0, 0, 0); PG8_LDB(B1, 0, 1); PG8_SCHED; PG8_LDA(At, 0, 0); PG8_STAGE(PG8_SA(1, 1), a1 + hstepA, voffA);
;             PG8_WAIT_V(8); PG8_WAIT_L(0); PG8_BAR; PG8_MMA(0, 0, At, B0); PG8_MMA(0, 1, At, B1); PG8_BAR; PG8_SCHED;
.LBB0_487:
	s_add_i32 s74, s58, 2
	s_add_u32 s59, s56, 0xfffc0080
	s_addc_u32 s60, s57, -1
	s_add_i32 s75, 0, 0x10000
	s_cmp_eq_u32 s72, s58
	s_cselect_b32 s61, s53, s60
	s_cselect_b32 s60, s52, s59
	v_add_u32_e32 v138, s75, v143
	s_cselect_b32 s59, s55, s51
	s_cselect_b32 s58, s54, s11
	s_add_i32 s76, 0, 0x14000
	ds_read_b128 v[170:173], v138
	ds_read_b128 v[174:177], v138 offset:1024
	ds_read_b128 v[178:181], v138 offset:2048
	ds_read_b128 v[182:185], v138 offset:3072
	v_add_u32_e32 v138, s76, v143
	ds_read_b128 v[186:189], v138
	ds_read_b128 v[190:193], v138 offset:1024
	ds_read_b128 v[194:197], v138 offset:2048
	ds_read_b128 v[198:201], v138 offset:3072
	v_lshl_add_u64 v[138:139], s[56:57], 0, v[134:135]
	s_add_i32 m0, s65, 0xc000
	ds_read_b128 v[202:205], v163
	ds_read_b128 v[206:209], v163 offset:1024
	ds_read_b128 v[210:213], v163 offset:2048
	ds_read_b128 v[214:217], v163 offset:3072
	ds_read_b128 v[218:221], v163 offset:4096
	ds_read_b128 v[222:225], v163 offset:5120
	ds_read_b128 v[226:229], v163 offset:6144
	ds_read_b128 v[230:233], v163 offset:7168
	global_load_lds_dwordx4 v[138:139], off
	v_lshl_add_u64 v[138:139], s[56:57], 0, v[136:137]
	s_add_i32 m0, s65, 0xe000
	s_nop 0
	global_load_lds_dwordx4 v[138:139], off
	s_waitcnt vmcnt(8)
	s_waitcnt lgkmcnt(0)
	s_barrier
	s_setprio 1
	v_mfma_f32_16x16x32_bf16 v[124:127], v[170:173], v[202:205], v[124:127]
	v_mfma_f32_16x16x32_bf16 v[116:119], v[178:181], v[202:205], v[116:119]
	v_mfma_f32_16x16x32_bf16 v[108:111], v[170:173], v[210:213], v[108:111]
	v_mfma_f32_16x16x32_bf16 v[100:103], v[178:181], v[210:213], v[100:103]
	v_mfma_f32_16x16x32_bf16 v[92:95], v[170:173], v[218:221], v[92:95]
	v_mfma_f32_16x16x32_bf16 v[84:87], v[178:181], v[218:221], v[84:87]
	v_mfma_f32_16x16x32_bf16 v[76:79], v[170:173], v[226:229], v[76:79]
	v_mfma_f32_16x16x32_bf16 v[68:71], v[178:181], v[226:229], v[68:71]
	v_mfma_f32_16x16x32_bf16 v[124:127], v[174:177], v[206:209], v[124:127]
	v_mfma_f32_16x16x32_bf16 v[116:119], v[182:185], v[206:209], v[116:119]
	v_mfma_f32_16x16x32_bf16 v[108:111], v[174:177], v[214:217], v[108:111]
	v_mfma_f32_16x16x32_bf16 v[100:103], v[182:185], v[214:217], v[100:103]
	v_mfma_f32_16x16x32_bf16 v[92:95], v[174:177], v[222:225], v[92:95]
	v_mfma_f32_16x16x32_bf16 v[84:87], v[182:185], v[222:225], v[84:87]
	v_mfma_f32_16x16x32_bf16 v[76:79], v[174:177], v[230:233], v[76:79]
	v_mfma_f32_16x16x32_bf16 v[68:71], v[182:185], v[230:233], v[68:71]
	s_setprio 0
	s_setprio 1
	v_mfma_f32_16x16x32_bf16 v[120:123], v[186:189], v[202:205], v[120:123]
	v_mfma_f32_16x16x32_bf16 v[112:115], v[194:197], v[202:205], v[112:115]
	v_mfma_f32_16x16x32_bf16 v[104:107], v[186:189], v[210:213], v[104:107]
	v_mfma_f32_16x16x32_bf16 v[96:99], v[194:197], v[210:213], v[96:99]
	v_mfma_f32_16x16x32_bf16 v[88:91], v[186:189], v[218:221], v[88:91]
	v_mfma_f32_16x16x32_bf16 v[80:83], v[194:197], v[218:221], v[80:83]
	v_mfma_f32_16x16x32_bf16 v[72:75], v[186:189], v[226:229], v[72:75]
	v_mfma_f32_16x16x32_bf16 v[64:67], v[194:197], v[226:229], v[64:67]
	v_mfma_f32_16x16x32_bf16 v[120:123], v[190:193], v[206:209], v[120:123]
	v_mfma_f32_16x16x32_bf16 v[112:115], v[198:201], v[206:209], v[112:115]
	v_mfma_f32_16x16x32_bf16 v[104:107], v[190:193], v[214:217], v[104:107]
	v_mfma_f32_16x16x32_bf16 v[96:99], v[198:201], v[214:217], v[96:99]
	v_mfma_f32_16x16x32_bf16 v[88:91], v[190:193], v[222:225], v[88:91]
	v_mfma_f32_16x16x32_bf16 v[80:83], v[198:201], v[222:225], v[80:83]
	v_mfma_f32_16x16x32_bf16 v[72:75], v[190:193], v[230:233], v[72:75]
	v_mfma_f32_16x16x32_bf16 v[64:67], v[198:201], v[230:233], v[64:67]
	s_setprio 0
	s_barrier
	s_add_i32 s75, s75, s0
	v_lshl_add_u64 v[138:139], s[58:59], 0, v[146:147]
	s_mov_b32 m0, s75
	ds_read_b128 v[202:205], v163 offset:16384
	ds_read_b128 v[206:209], v163 offset:17408
	ds_read_b128 v[210:213], v163 offset:18432
	ds_read_b128 v[214:217], v163 offset:19456
	ds_read_b128 v[218:221], v163 offset:20480
	ds_read_b128 v[222:225], v163 offset:21504
	ds_read_b128 v[226:229], v163 offset:22528
	ds_read_b128 v[230:233], v163 offset:23552
	global_load_lds_dwordx4 v[138:139], off
	s_add_i32 m0, s75, 0x2000
	s_add_u32 s82, s58, 0x40000
	v_lshl_add_u64 v[234:235], s[58:59], 0, v[128:129]
	s_addc_u32 s83, s59, 0
	s_add_i32 s75, s76, s0
	global_load_lds_dwordx4 v[234:235], off
	v_lshl_add_u64 v[236:237], s[82:83], 0, v[146:147]
	s_mov_b32 m0, s75
	v_lshl_add_u64 v[238:239], s[60:61], 0, v[130:131]
	global_load_lds_dwordx4 v[236:237], off
	v_lshl_add_u64 v[236:237], s[82:83], 0, v[128:129]
	s_add_i32 m0, s75, 0x2000
	s_nop 0
	global_load_lds_dwordx4 v[236:237], off
	v_lshl_add_u64 v[236:237], s[60:61], 0, v[132:133]
	s_mov_b32 m0, s65
	s_nop 0
	global_load_lds_dwordx4 v[236:237], off
	s_mov_b32 m0, s66
	s_nop 0
	global_load_lds_dwordx4 v[238:239], off
	s_waitcnt vmcnt(8)
	s_waitcnt lgkmcnt(0)
	s_barrier
; #define PG8_STAGE(bufoff, gbase, voff) do { _Pragma("unroll") for (int _i = 0; _i < 2; ++_i) \
;         __builtin_amdgcn_global_load_lds((const unsigned*)((const char*)(gbase) + (voff)[_i]), (PG8_LAS unsigned*)(lds + (bufoff) + ldsw + _i * 8192), 16, 0, 0); } while (0)
; #define PG8_LDA(dst, b, h) do { _Pragma("unroll") for (int m = 0; m < 4; ++m) _Pragma("unroll") for (int k = 0; k < 2; ++k) dst[m][k] = *(const PG8_LAS bf16x8*)(lds + PG8_SA(b, h) + aoff + m * 2048 + k * 1024); } while (0)
; #define PG8_LDB(dst, b, h) do { _Pragma("unroll") for (int n = 0; n < 2; ++n) _Pragma("unroll") for (int k = 0; k < 2; ++k) dst[n][k] = *(const PG8_LAS bf16x8*)(lds + PG8_SB(b, h) + boff + n * 2048 + k * 1024); } while (0)
; #define PG8_MMA(ai, bj, At, Bt) do { __builtin_amdgcn_s_setprio(1); _Pragma("unroll") for (int m = 0; m < 4; ++m) _Pragma("unroll") for (int n = 0; n < 2; ++n) _Pragma("unroll") for (int k = 0; k < 2; ++k) \
;         acc[ai][bj][m][n] = __builtin_amdgcn_mfma_f32_16x16x32_bf16(Bt[n][k], At[m][k], acc[ai][bj][m][n], 0, 0, 0); __builtin_amdgcn_s_setprio(0); } while (0)
; #define PG8_WAIT_V(n) asm volatile("s_waitcnt vmcnt(" #n ")" ::: "memory")
; #define PG8_WAIT_L(n) asm volatile("s_waitcnt lgkmcnt(" #n ")" ::: "memory")
; #define PG8_BAR __builtin_amdgcn_s_barrier()
; #define PG8_SCHED __builtin_amdgcn_sched_barrier(0)
; template <class Epi, class Sched, bool ALIGN_EPI = false, bool SP2 = false>
; __device__ __forceinline__ void gemm_phase(PG8_LAS unsigned char* lds, const Gemm g, const Sched& S, const Epi& E, const int wid) {
;     ...
;             PG8_WAIT_V(8); PG8_WAIT_L(0); PG8_BAR; PG8_MMA(1, 0, At, B0); PG8_MMA(1, 1, At, B1); PG8_BAR; PG8_SCHED;
;             PG8_LDB(B0, 1, 0); PG8_LDB(B1, 1, 1); PG8_SCHED; PG8_LDA(At, 1, 0); PG8_STAGE(PG8_SA(0, 1), a2 + hstepA, voffA);
;             PG8_WAIT_V(8); PG8_WAIT_L(0); PG8_BAR; PG8_MMA(0, 0, At, B0); PG8_MMA(0, 1, At, B1); PG8_BAR; PG8_SCHED;
	s_setprio 1
	v_mfma_f32_16x16x32_bf16 v[60:63], v[170:173], v[202:205], v[60:63]
	v_mfma_f32_16x16x32_bf16 v[52:55], v[178:181], v[202:205], v[52:55]
	v_mfma_f32_16x16x32_bf16 v[44:47], v[170:173], v[210:213], v[44:47]
	v_mfma_f32_16x16x32_bf16 v[36:39], v[178:181], v[210:213], v[36:39]
	v_mfma_f32_16x16x32_bf16 v[28:31], v[170:173], v[218:221], v[28:31]
	v_mfma_f32_16x16x32_bf16 v[20:23], v[178:181], v[218:221], v[20:23]
	v_mfma_f32_16x16x32_bf16 v[12:15], v[170:173], v[226:229], v[12:15]
	v_mfma_f32_16x16x32_bf16 v[4:7], v[178:181], v[226:229], v[4:7]
	v_mfma_f32_16x16x32_bf16 v[60:63], v[174:177], v[206:209], v[60:63]
	v_mfma_f32_16x16x32_bf16 v[52:55], v[182:185], v[206:209], v[52:55]
	v_mfma_f32_16x16x32_bf16 v[44:47], v[174:177], v[214:217], v[44:47]
	v_mfma_f32_16x16x32_bf16 v[36:39], v[182:185], v[214:217], v[36:39]
	v_mfma_f32_16x16x32_bf16 v[28:31], v[174:177], v[222:225], v[28:31]
	v_mfma_f32_16x16x32_bf16 v[20:23], v[182:185], v[222:225], v[20:23]
	v_mfma_f32_16x16x32_bf16 v[12:15], v[174:177], v[230:233], v[12:15]
	v_mfma_f32_16x16x32_bf16 v[4:7], v[182:185], v[230:233], v[4:7]
	s_setprio 0
	s_setprio 1
	v_mfma_f32_16x16x32_bf16 v[56:59], v[186:189], v[202:205], v[56:59]
	v_mfma_f32_16x16x32_bf16 v[48:51], v[194:197], v[202:205], v[48:51]
	v_mfma_f32_16x16x32_bf16 v[40:43], v[186:189], v[210:213], v[40:43]
	v_mfma_f32_16x16x32_bf16 v[32:35], v[194:197], v[210:213], v[32:35]
	v_mfma_f32_16x16x32_bf16 v[24:27], v[186:189], v[218:221], v[24:27]
	v_mfma_f32_16x16x32_bf16 v[16:19], v[194:197], v[218:221], v[16:19]
	v_mfma_f32_16x16x32_bf16 v[8:11], v[186:189], v[226:229], v[8:11]
	v_mfma_f32_16x16x32_bf16 v[0:3], v[194:197], v[226:229], v[0:3]
	v_mfma_f32_16x16x32_bf16 v[56:59], v[190:193], v[206:209], v[56:59]
	v_mfma_f32_16x16x32_bf16 v[48:51], v[198:201], v[206:209], v[48:51]
	v_mfma_f32_16x16x32_bf16 v[40:43], v[190:193], v[214:217], v[40:43]
	v_mfma_f32_16x16x32_bf16 v[32:35], v[198:201], v[214:217], v[32:35]
	v_mfma_f32_16x16x32_bf16 v[24:27], v[190:193], v[222:225], v[24:27]
	v_mfma_f32_16x16x32_bf16 v[16:19], v[198:201], v[222:225], v[16:19]
	v_mfma_f32_16x16x32_bf16 v[8:11], v[190:193], v[230:233], v[8:11]
	v_mfma_f32_16x16x32_bf16 v[0:3], v[198:201], v[230:233], v[0:3]
	s_setprio 0
	s_barrier
	s_add_i32 s75, 0, 0x18000
	v_add_u32_e32 v140, s75, v143
	s_add_i32 s76, 0, 0x1c000
	ds_read_b128 v[170:173], v140
	ds_read_b128 v[174:177], v140 offset:1024
	ds_read_b128 v[178:181], v140 offset:2048
	ds_read_b128 v[182:185], v140 offset:3072
	v_add_u32_e32 v140, s76, v143
	ds_read_b128 v[186:189], v140
	ds_read_b128 v[190:193], v140 offset:1024
	ds_read_b128 v[194:197], v140 offset:2048
	ds_read_b128 v[198:201], v140 offset:3072
	s_add_u32 s60, s60, 0x40000
	s_addc_u32 s61, s61, 0
	s_mov_b32 m0, s67
	v_lshl_add_u64 v[240:241], s[60:61], 0, v[132:133]
	ds_read_b128 v[202:205], v163 offset:32768
	ds_read_b128 v[206:209], v163 offset:33792
	ds_read_b128 v[210:213], v163 offset:34816
	ds_read_b128 v[214:217], v163 offset:35840
	ds_read_b128 v[218:221], v163 offset:36864
	ds_read_b128 v[222:225], v163 offset:37888
	ds_read_b128 v[226:229], v163 offset:38912
	ds_read_b128 v[230:233], v163 offset:39936
	global_load_lds_dwordx4 v[240:241], off
	v_lshl_add_u64 v[240:241], s[60:61], 0, v[130:131]
	s_mov_b32 m0, s68
	s_nop 0
	global_load_lds_dwordx4 v[240:241], off
	s_waitcnt vmcnt(8)
	s_waitcnt lgkmcnt(0)
	s_barrier
	s_setprio 1
	v_mfma_f32_16x16x32_bf16 v[124:127], v[170:173], v[202:205], v[124:127]
	v_mfma_f32_16x16x32_bf16 v[116:119], v[178:181], v[202:205], v[116:119]
	v_mfma_f32_16x16x32_bf16 v[108:111], v[170:173], v[210:213], v[108:111]
	v_mfma_f32_16x16x32_bf16 v[100:103], v[178:181], v[210:213], v[100:103]
	v_mfma_f32_16x16x32_bf16 v[92:95], v[170:173], v[218:221], v[92:95]
	v_mfma_f32_16x16x32_bf16 v[84:87], v[178:181], v[218:221], v[84:87]
	v_mfma_f32_16x16x32_bf16 v[76:79], v[170:173], v[226:229], v[76:79]
	v_mfma_f32_16x16x32_bf16 v[68:71], v[178:181], v[226:229], v[68:71]
	v_mfma_f32_16x16x32_bf16 v[124:127], v[174:177], v[206:209], v[124:127]
	v_mfma_f32_16x16x32_bf16 v[116:119], v[182:185], v[206:209], v[116:119]
	v_mfma_f32_16x16x32_bf16 v[108:111], v[174:177], v[214:217], v[108:111]
	v_mfma_f32_16x16x32_bf16 v[100:103], v[182:185], v[214:217], v[100:103]
	v_mfma_f32_16x16x32_bf16 v[92:95], v[174:177], v[222:225], v[92:95]
	v_mfma_f32_16x16x32_bf16 v[84:87], v[182:185], v[222:225], v[84:87]
	v_mfma_f32_16x16x32_bf16 v[76:79], v[174:177], v[230:233], v[76:79]
	v_mfma_f32_16x16x32_bf16 v[68:71], v[182:185], v[230:233], v[68:71]
	s_setprio 0
	s_setprio 1
	v_mfma_f32_16x16x32_bf16 v[120:123], v[186:189], v[202:205], v[120:123]
	v_mfma_f32_16x16x32_bf16 v[112:115], v[194:197], v[202:205], v[112:115]
	v_mfma_f32_16x16x32_bf16 v[104:107], v[186:189], v[210:213], v[104:107]
	v_mfma_f32_16x16x32_bf16 v[96:99], v[194:197], v[210:213], v[96:99]
	v_mfma_f32_16x16x32_bf16 v[88:91], v[186:189], v[218:221], v[88:91]
	v_mfma_f32_16x16x32_bf16 v[80:83], v[194:197], v[218:221], v[80:83]
	v_mfma_f32_16x16x32_bf16 v[72:75], v[186:189], v[226:229], v[72:75]
	v_mfma_f32_16x16x32_bf16 v[64:67], v[194:197], v[226:229], v[64:67]
	v_mfma_f32_16x16x32_bf16 v[120:123], v[190:193], v[206:209], v[120:123]
	v_mfma_f32_16x16x32_bf16 v[112:115], v[198:201], v[206:209], v[112:115]
	v_mfma_f32_16x16x32_bf16 v[104:107], v[190:193], v[214:217], v[104:107]
	v_mfma_f32_16x16x32_bf16 v[96:99], v[198:201], v[214:217], v[96:99]
	v_mfma_f32_16x16x32_bf16 v[88:91], v[190:193], v[222:225], v[88:91]
	v_mfma_f32_16x16x32_bf16 v[80:83], v[198:201], v[222:225], v[80:83]
	v_mfma_f32_16x16x32_bf16 v[72:75], v[190:193], v[230:233], v[72:75]
	v_mfma_f32_16x16x32_bf16 v[64:67], v[198:201], v[230:233], v[64:67]
	s_setprio 0
	s_barrier
; #define PG8_STAGE(bufoff, gbase, voff) do { _Pragma("unroll") for (int _i = 0; _i < 2; ++_i) \
;         __builtin_amdgcn_global_load_lds((const unsigned*)((const char*)(gbase) + (voff)[_i]), (PG8_LAS unsigned*)(lds + (bufoff) + ldsw + _i * 8192), 16, 0, 0); } while (0)
; #define PG8_LDA(dst, b, h) do { _Pragma("unroll") for (int m = 0; m < 4; ++m) _Pragma("unroll") for (int k = 0; k < 2; ++k) dst[m][k] = *(const PG8_LAS bf16x8*)(lds + PG8_SA(b, h) + aoff + m * 2048 + k * 1024); } while (0)
; #define PG8_MMA(ai, bj, At, Bt) do { __builtin_amdgcn_s_setprio(1); _Pragma("unroll") for (int m = 0; m < 4; ++m) _Pragma("unroll") for (int n = 0; n < 2; ++n) _Pragma("unroll") for (int k = 0; k < 2; ++k) \
;         acc[ai][bj][m][n] = __builtin_amdgcn_mfma_f32_16x16x32_bf16(Bt[n][k], At[m][k], acc[ai][bj][m][n], 0, 0, 0); __builtin_amdgcn_s_setprio(0); } while (0)
; #define PG8_WAIT_V(n) asm volatile("s_waitcnt vmcnt(" #n ")" ::: "memory")
; #define PG8_WAIT_L(n) asm volatile("s_waitcnt lgkmcnt(" #n ")" ::: "memory")
; #define PG8_BAR __builtin_amdgcn_s_barrier()
; #define PG8_SCHED __builtin_amdgcn_sched_barrier(0)
; template <class Epi, class Sched, bool ALIGN_EPI = false, bool SP2 = false>
; __device__ __forceinline__ void gemm_phase(PG8_LAS unsigned char* lds, const Gemm g, const Sched& S, const Epi& E, const int wid) {
;     ...
;             PG8_LDA(At, 1, 1); PG8_STAGE(PG8_SB(1, 0), b3, voffB); PG8_STAGE(PG8_SB(1, 1), b3 + hstepB, voffB); PG8_STAGE(PG8_SA(1, 0), a3, voffA);
;             PG8_WAIT_V(8); PG8_WAIT_L(0); PG8_BAR; PG8_MMA(1, 0, At, B0); PG8_MMA(1, 1, At, B1); PG8_BAR; PG8_SCHED;
	s_add_i32 s60, s75, s0
	v_lshl_add_u64 v[138:139], v[138:139], 0, s[80:81]
	s_mov_b32 m0, s60
	ds_read_b128 v[202:205], v163 offset:49152
	ds_read_b128 v[206:209], v163 offset:50176
	ds_read_b128 v[210:213], v163 offset:51200
	ds_read_b128 v[214:217], v163 offset:52224
	ds_read_b128 v[218:221], v163 offset:53248
	ds_read_b128 v[222:225], v163 offset:54272
	ds_read_b128 v[226:229], v163 offset:55296
	ds_read_b128 v[230:233], v163 offset:56320
	global_load_lds_dwordx4 v[138:139], off
	s_add_i32 m0, s60, 0x2000
	s_add_u32 s58, s58, 0x40080
	v_lshl_add_u64 v[138:139], v[234:235], 0, s[80:81]
	s_addc_u32 s59, s59, 0
	s_add_i32 s60, s76, s0
	global_load_lds_dwordx4 v[138:139], off
	v_lshl_add_u64 v[138:139], s[58:59], 0, v[146:147]
	s_mov_b32 m0, s60
	s_nop 0
	global_load_lds_dwordx4 v[138:139], off
	v_lshl_add_u64 v[138:139], s[58:59], 0, v[128:129]
	s_add_i32 m0, s60, 0x2000
	s_nop 0
	global_load_lds_dwordx4 v[138:139], off
	v_lshl_add_u64 v[138:139], v[236:237], 0, s[80:81]
	s_mov_b32 m0, s69
	s_nop 0
	global_load_lds_dwordx4 v[138:139], off
	v_lshl_add_u64 v[138:139], v[238:239], 0, s[80:81]
	s_mov_b32 m0, s70
	s_nop 0
	global_load_lds_dwordx4 v[138:139], off
	s_waitcnt vmcnt(8)
	s_waitcnt lgkmcnt(0)
	s_barrier
	s_setprio 1
	v_mfma_f32_16x16x32_bf16 v[60:63], v[170:173], v[202:205], v[60:63]
	v_mfma_f32_16x16x32_bf16 v[52:55], v[178:181], v[202:205], v[52:55]
	v_mfma_f32_16x16x32_bf16 v[44:47], v[170:173], v[210:213], v[44:47]
	v_mfma_f32_16x16x32_bf16 v[36:39], v[178:181], v[210:213], v[36:39]
	v_mfma_f32_16x16x32_bf16 v[28:31], v[170:173], v[218:221], v[28:31]
	v_mfma_f32_16x16x32_bf16 v[20:23], v[178:181], v[218:221], v[20:23]
	v_mfma_f32_16x16x32_bf16 v[12:15], v[170:173], v[226:229], v[12:15]
	v_mfma_f32_16x16x32_bf16 v[4:7], v[178:181], v[226:229], v[4:7]
	v_mfma_f32_16x16x32_bf16 v[60:63], v[174:177], v[206:209], v[60:63]
	v_mfma_f32_16x16x32_bf16 v[52:55], v[182:185], v[206:209], v[52:55]
	v_mfma_f32_16x16x32_bf16 v[44:47], v[174:177], v[214:217], v[44:47]
	v_mfma_f32_16x16x32_bf16 v[36:39], v[182:185], v[214:217], v[36:39]
	v_mfma_f32_16x16x32_bf16 v[28:31], v[174:177], v[222:225], v[28:31]
	v_mfma_f32_16x16x32_bf16 v[20:23], v[182:185], v[222:225], v[20:23]
	v_mfma_f32_16x16x32_bf16 v[12:15], v[174:177], v[230:233], v[12:15]
	v_mfma_f32_16x16x32_bf16 v[4:7], v[182:185], v[230:233], v[4:7]
	s_setprio 0
	s_setprio 1
	v_mfma_f32_16x16x32_bf16 v[56:59], v[186:189], v[202:205], v[56:59]
	v_mfma_f32_16x16x32_bf16 v[48:51], v[194:197], v[202:205], v[48:51]
	v_mfma_f32_16x16x32_bf16 v[40:43], v[186:189], v[210:213], v[40:43]
	v_mfma_f32_16x16x32_bf16 v[32:35], v[194:197], v[210:213], v[32:35]
	v_mfma_f32_16x16x32_bf16 v[24:27], v[186:189], v[218:221], v[24:27]
	v_mfma_f32_16x16x32_bf16 v[16:19], v[194:197], v[218:221], v[16:19]
	v_mfma_f32_16x16x32_bf16 v[8:11], v[186:189], v[226:229], v[8:11]
	v_mfma_f32_16x16x32_bf16 v[0:3], v[194:197], v[226:229], v[0:3]
	v_mfma_f32_16x16x32_bf16 v[56:59], v[190:193], v[206:209], v[56:59]
	v_mfma_f32_16x16x32_bf16 v[48:51], v[198:201], v[206:209], v[48:51]
	v_mfma_f32_16x16x32_bf16 v[40:43], v[190:193], v[214:217], v[40:43]
	v_mfma_f32_16x16x32_bf16 v[32:35], v[198:201], v[214:217], v[32:35]
	v_mfma_f32_16x16x32_bf16 v[24:27], v[190:193], v[222:225], v[24:27]
	v_mfma_f32_16x16x32_bf16 v[16:19], v[198:201], v[222:225], v[16:19]
	v_mfma_f32_16x16x32_bf16 v[8:11], v[190:193], v[230:233], v[8:11]
	v_mfma_f32_16x16x32_bf16 v[0:3], v[198:201], v[230:233], v[0:3]
	s_setprio 0
	s_barrier
	s_add_u32 s56, s56, 0x100
	s_addc_u32 s57, s57, 0
	s_add_u32 s11, s11, 0x100
	s_addc_u32 s51, s51, 0
	s_cmp_ge_i32 s74, s62
	s_mov_b32 s58, s74
	s_cbranch_scc0 .LBB0_487
	s_mov_b32 s74, 0x1e000
	s_mov_b32 s75, 0xc000
	s_mov_b32 s82, 0x24000
	s_mov_b32 s83, 0x26000
	s_mov_b32 s61, 0x2c000
	s_mov_b32 s60, 0x32000
	s_mov_b32 s76, 0x38000
	s_mov_b32 s51, 0x2e000
	s_and_b64 vcc, exec, s[6:7]
	s_cbranch_vccz .LBB0_490

; #define PG8_STAGE(bufoff, gbase, voff) do { _Pragma("unroll") for (int _i = 0; _i < 2; ++_i) \
;         __builtin_amdgcn_global_load_lds((const unsigned*)((const char*)(gbase) + (voff)[_i]), (PG8_LAS unsigned*)(lds + (bufoff) + ldsw + _i * 8192), 16, 0, 0); } while (0)
; #define PG8_LDA(dst, b, h) do { _Pragma("unroll") for (int m = 0; m < 4; ++m) _Pragma("unroll") for (int k = 0; k < 2; ++k) dst[m][k] = *(const PG8_LAS bf16x8*)(lds + PG8_SA(b, h) + aoff + m * 2048 + k * 1024); } while (0)
; #define PG8_LDB(dst, b, h) do { _Pragma("unroll") for (int n = 0; n < 2; ++n) _Pragma("unroll") for (int k = 0; k < 2; ++k) dst[n][k] = *(const PG8_LAS bf16x8*)(lds + PG8_SB(b, h) + boff + n * 2048 + k * 1024); } while (0)
; #define PG8_MMA(ai, bj, At, Bt) do { __builtin_amdgcn_s_setprio(1); _Pragma("unroll") for (int m = 0; m < 4; ++m) _Pragma("unroll") for (int n = 0; n < 2; ++n) _Pragma("unroll") for (int k = 0; k < 2; ++k) \
;         acc[ai][bj][m][n] = __builtin_amdgcn_mfma_f32_16x16x32_bf16(Bt[n][k], At[m][k], acc[ai][bj][m][n], 0, 0, 0); __builtin_amdgcn_s_setprio(0); } while (0)
; #define PG8_WAIT_V(n) asm volatile("s_waitcnt vmcnt(" #n ")" ::: "memory")
; #define PG8_WAIT_L(n) asm volatile("s_waitcnt lgkmcnt(" #n ")" ::: "memory")
; template <class Epi, class Sched, bool ALIGN_EPI = false, bool SP2 = false>
; __device__ __forceinline__ void gemm_phase(PG8_LAS unsigned char* lds, const Gemm g, const Sched& S, const Epi& E, const int wid) {
;     ...
;             const bool last = (t == nt - 2);
;             const char* a1 = cA + (size_t)(t + 1) * kstep;
;             const char* a2 = last ? nA : cA + (size_t)(t + 2) * kstep; const char* b2 = last ? nB : cB + (size_t)(t + 2) * kstep;
;             const char* a3 = a2 + kstep; const char* b3 = b2 + kstep;
;             if (last && has_next) S.a_ready(nxt);
;             if constexpr (SP2) {
;             PG8_LDB(B0, 0, 0); PG8_LDB(B1, 0, 1); PG8_SCHED; PG8_LDA(At, 0, 0); PG8_STAGE(PG8_SA(1, 1), a1 + hstepA, voffA);
;             PG8_WAIT_V(8); PG8_WAIT_L(0); PG8_BAR; PG8_MMA(0, 0, At, B0); PG8_MMA(0, 1, At, B1); PG8_BAR; PG8_SCHED;
;             PG8_LDA(At, 0, 1); PG8_STAGE(PG8_SB(0, 0), b2, voffB); PG8_STAGE(PG8_SB(0, 1), b2 + hstepB, voffB); PG8_STAGE(PG8_SA(0, 0), a2, voffA);
;             PG8_WAIT_V(8); PG8_WAIT_L(0); PG8_BAR; PG8_MMA(1, 0, At, B0); PG8_MMA(1, 1, At, B1); PG8_BAR; PG8_SCHED;
.LBB0_575:
	s_add_i32 vcc_lo, s58, 2
	s_add_u32 s56, s62, 0x100
	s_addc_u32 s57, s63, 0
	s_add_i32 s9, 0, 0x10000
	s_cmp_eq_u32 s73, s58
	s_cselect_b32 s61, s47, s57
	s_cselect_b32 s60, s46, s56
	v_add_u32_e32 v143, s9, v141
	s_cselect_b32 s59, s55, s83
	s_cselect_b32 s58, s54, s82
	s_add_i32 vcc_hi, 0, 0x14000
	ds_read_b128 v[170:173], v143
	ds_read_b128 v[174:177], v143 offset:1024
	ds_read_b128 v[178:181], v143 offset:2048
	ds_read_b128 v[182:185], v143 offset:3072
	v_add_u32_e32 v143, vcc_hi, v141
	ds_read_b128 v[186:189], v143
	ds_read_b128 v[190:193], v143 offset:1024
	ds_read_b128 v[194:197], v143 offset:2048
	ds_read_b128 v[198:201], v143 offset:3072
	v_lshl_add_u64 v[160:161], s[62:63], 0, v[134:135]
	s_add_i32 m0, s67, 0xc000
	ds_read_b128 v[202:205], v142
	ds_read_b128 v[206:209], v142 offset:1024
	ds_read_b128 v[210:213], v142 offset:2048
	ds_read_b128 v[214:217], v142 offset:3072
	ds_read_b128 v[218:221], v142 offset:4096
	ds_read_b128 v[222:225], v142 offset:5120
	ds_read_b128 v[226:229], v142 offset:6144
	ds_read_b128 v[230:233], v142 offset:7168
	global_load_lds_dwordx4 v[160:161], off
	v_lshl_add_u64 v[160:161], s[62:63], 0, v[136:137]
	s_add_i32 m0, s67, 0xe000
	s_nop 0
	global_load_lds_dwordx4 v[160:161], off
	s_waitcnt vmcnt(8)
	s_waitcnt lgkmcnt(0)
	s_barrier
	s_setprio 1
	v_mfma_f32_16x16x32_bf16 v[124:127], v[170:173], v[202:205], v[124:127]
	v_mfma_f32_16x16x32_bf16 v[120:123], v[178:181], v[202:205], v[120:123]
	v_mfma_f32_16x16x32_bf16 v[108:111], v[170:173], v[210:213], v[108:111]
	v_mfma_f32_16x16x32_bf16 v[104:107], v[178:181], v[210:213], v[104:107]
	v_mfma_f32_16x16x32_bf16 v[92:95], v[170:173], v[218:221], v[92:95]
	v_mfma_f32_16x16x32_bf16 v[88:91], v[178:181], v[218:221], v[88:91]
	v_mfma_f32_16x16x32_bf16 v[80:83], v[170:173], v[226:229], v[80:83]
	v_mfma_f32_16x16x32_bf16 v[76:79], v[178:181], v[226:229], v[76:79]
	v_mfma_f32_16x16x32_bf16 v[124:127], v[174:177], v[206:209], v[124:127]
	v_mfma_f32_16x16x32_bf16 v[120:123], v[182:185], v[206:209], v[120:123]
	v_mfma_f32_16x16x32_bf16 v[108:111], v[174:177], v[214:217], v[108:111]
	v_mfma_f32_16x16x32_bf16 v[104:107], v[182:185], v[214:217], v[104:107]
	v_mfma_f32_16x16x32_bf16 v[92:95], v[174:177], v[222:225], v[92:95]
	v_mfma_f32_16x16x32_bf16 v[88:91], v[182:185], v[222:225], v[88:91]
	v_mfma_f32_16x16x32_bf16 v[80:83], v[174:177], v[230:233], v[80:83]
	v_mfma_f32_16x16x32_bf16 v[76:79], v[182:185], v[230:233], v[76:79]
	s_setprio 0
	s_setprio 1
	v_mfma_f32_16x16x32_bf16 v[116:119], v[186:189], v[202:205], v[116:119]
	v_mfma_f32_16x16x32_bf16 v[112:115], v[194:197], v[202:205], v[112:115]
	v_mfma_f32_16x16x32_bf16 v[100:103], v[186:189], v[210:213], v[100:103]
	v_mfma_f32_16x16x32_bf16 v[96:99], v[194:197], v[210:213], v[96:99]
	v_mfma_f32_16x16x32_bf16 v[84:87], v[186:189], v[218:221], v[84:87]
	v_mfma_f32_16x16x32_bf16 v[72:75], v[194:197], v[218:221], v[72:75]
	v_mfma_f32_16x16x32_bf16 v[68:71], v[186:189], v[226:229], v[68:71]
	v_mfma_f32_16x16x32_bf16 v[64:67], v[194:197], v[226:229], v[64:67]
	v_mfma_f32_16x16x32_bf16 v[116:119], v[190:193], v[206:209], v[116:119]
	v_mfma_f32_16x16x32_bf16 v[112:115], v[198:201], v[206:209], v[112:115]
	v_mfma_f32_16x16x32_bf16 v[100:103], v[190:193], v[214:217], v[100:103]
	v_mfma_f32_16x16x32_bf16 v[96:99], v[198:201], v[214:217], v[96:99]
	v_mfma_f32_16x16x32_bf16 v[84:87], v[190:193], v[222:225], v[84:87]
	v_mfma_f32_16x16x32_bf16 v[72:75], v[198:201], v[222:225], v[72:75]
	v_mfma_f32_16x16x32_bf16 v[68:71], v[190:193], v[230:233], v[68:71]
	v_mfma_f32_16x16x32_bf16 v[64:67], v[198:201], v[230:233], v[64:67]
	s_setprio 0
	s_barrier
	s_add_i32 s9, s9, s0
	v_lshl_add_u64 v[160:161], s[58:59], 0, v[146:147]
	s_mov_b32 m0, s9
	ds_read_b128 v[202:205], v142 offset:16384
	ds_read_b128 v[206:209], v142 offset:17408
	ds_read_b128 v[210:213], v142 offset:18432
	ds_read_b128 v[214:217], v142 offset:19456
	ds_read_b128 v[218:221], v142 offset:20480
	ds_read_b128 v[222:225], v142 offset:21504
	ds_read_b128 v[226:229], v142 offset:22528
	ds_read_b128 v[230:233], v142 offset:23552
	global_load_lds_dwordx4 v[160:161], off
	s_add_i32 m0, s9, 0x2000
	s_add_u32 s62, s58, 0xb0000
	v_lshl_add_u64 v[234:235], s[58:59], 0, v[128:129]
	s_addc_u32 s63, s59, 0
	s_add_i32 s9, vcc_hi, s0
	global_load_lds_dwordx4 v[234:235], off
	v_lshl_add_u64 v[236:237], s[62:63], 0, v[146:147]
	s_mov_b32 m0, s9
	v_lshl_add_u64 v[238:239], s[60:61], 0, v[130:131]
	global_load_lds_dwordx4 v[236:237], off
	v_lshl_add_u64 v[236:237], s[62:63], 0, v[128:129]
	s_add_i32 m0, s9, 0x2000
	s_nop 0
	global_load_lds_dwordx4 v[236:237], off
	v_lshl_add_u64 v[236:237], s[60:61], 0, v[132:133]
	s_mov_b32 m0, s67
	s_nop 0
	global_load_lds_dwordx4 v[236:237], off
	s_mov_b32 m0, s68
	s_nop 0
	global_load_lds_dwordx4 v[238:239], off
	s_waitcnt vmcnt(8)
	s_waitcnt lgkmcnt(0)
	s_barrier
; #define PG8_STAGE(bufoff, gbase, voff) do { _Pragma("unroll") for (int _i = 0; _i < 2; ++_i) \
;         __builtin_amdgcn_global_load_lds((const unsigned*)((const char*)(gbase) + (voff)[_i]), (PG8_LAS unsigned*)(lds + (bufoff) + ldsw + _i * 8192), 16, 0, 0); } while (0)
; #define PG8_LDA(dst, b, h) do { _Pragma("unroll") for (int m = 0; m < 4; ++m) _Pragma("unroll") for (int k = 0; k < 2; ++k) dst[m][k] = *(const PG8_LAS bf16x8*)(lds + PG8_SA(b, h) + aoff + m * 2048 + k * 1024); } while (0)
; #define PG8_LDB(dst, b, h) do { _Pragma("unroll") for (int n = 0; n < 2; ++n) _Pragma("unroll") for (int k = 0; k < 2; ++k) dst[n][k] = *(const PG8_LAS bf16x8*)(lds + PG8_SB(b, h) + boff + n * 2048 + k * 1024); } while (0)
; #define PG8_MMA(ai, bj, At, Bt) do { __builtin_amdgcn_s_setprio(1); _Pragma("unroll") for (int m = 0; m < 4; ++m) _Pragma("unroll") for (int n = 0; n < 2; ++n) _Pragma("unroll") for (int k = 0; k < 2; ++k) \
;         acc[ai][bj][m][n] = __builtin_amdgcn_mfma_f32_16x16x32_bf16(Bt[n][k], At[m][k], acc[ai][bj][m][n], 0, 0, 0); __builtin_amdgcn_s_setprio(0); } while (0)
; #define PG8_WAIT_V(n) asm volatile("s_waitcnt vmcnt(" #n ")" ::: "memory")
; #define PG8_WAIT_L(n) asm volatile("s_waitcnt lgkmcnt(" #n ")" ::: "memory")
; #define PG8_BAR __builtin_amdgcn_s_barrier()
; #define PG8_SCHED __builtin_amdgcn_sched_barrier(0)
; template <class Epi, class Sched, bool ALIGN_EPI = false, bool SP2 = false>
; __device__ __forceinline__ void gemm_phase(PG8_LAS unsigned char* lds, const Gemm g, const Sched& S, const Epi& E, const int wid) {
;     ...
;             PG8_WAIT_V(8); PG8_WAIT_L(0); PG8_BAR; PG8_MMA(1, 0, At, B0); PG8_MMA(1, 1, At, B1); PG8_BAR; PG8_SCHED;
;             PG8_LDB(B0, 1, 0); PG8_LDB(B1, 1, 1); PG8_SCHED; PG8_LDA(At, 1, 0); PG8_STAGE(PG8_SA(0, 1), a2 + hstepA, voffA);
;             PG8_WAIT_V(8); PG8_WAIT_L(0); PG8_BAR; PG8_MMA(0, 0, At, B0); PG8_MMA(0, 1, At, B1); PG8_BAR; PG8_SCHED;
	s_setprio 1
	v_mfma_f32_16x16x32_bf16 v[56:59], v[170:173], v[202:205], v[56:59]
	v_mfma_f32_16x16x32_bf16 v[44:47], v[178:181], v[202:205], v[44:47]
	v_mfma_f32_16x16x32_bf16 v[32:35], v[170:173], v[210:213], v[32:35]
	v_mfma_f32_16x16x32_bf16 v[16:19], v[178:181], v[210:213], v[16:19]
	v_mfma_f32_16x16x32_bf16 v[60:63], v[170:173], v[218:221], v[60:63]
	v_mfma_f32_16x16x32_bf16 v[48:51], v[178:181], v[218:221], v[48:51]
	v_mfma_f32_16x16x32_bf16 v[40:43], v[170:173], v[226:229], v[40:43]
	v_mfma_f32_16x16x32_bf16 v[24:27], v[178:181], v[226:229], v[24:27]
	v_mfma_f32_16x16x32_bf16 v[56:59], v[174:177], v[206:209], v[56:59]
	v_mfma_f32_16x16x32_bf16 v[44:47], v[182:185], v[206:209], v[44:47]
	v_mfma_f32_16x16x32_bf16 v[32:35], v[174:177], v[214:217], v[32:35]
	v_mfma_f32_16x16x32_bf16 v[16:19], v[182:185], v[214:217], v[16:19]
	v_mfma_f32_16x16x32_bf16 v[60:63], v[174:177], v[222:225], v[60:63]
	v_mfma_f32_16x16x32_bf16 v[48:51], v[182:185], v[222:225], v[48:51]
	v_mfma_f32_16x16x32_bf16 v[40:43], v[174:177], v[230:233], v[40:43]
	v_mfma_f32_16x16x32_bf16 v[24:27], v[182:185], v[230:233], v[24:27]
	s_setprio 0
	s_setprio 1
	v_mfma_f32_16x16x32_bf16 v[28:31], v[186:189], v[202:205], v[28:31]
	v_mfma_f32_16x16x32_bf16 v[12:15], v[194:197], v[202:205], v[12:15]
	v_mfma_f32_16x16x32_bf16 v[4:7], v[186:189], v[210:213], v[4:7]
	v_mfma_f32_16x16x32_bf16 v[52:55], v[194:197], v[210:213], v[52:55]
	v_mfma_f32_16x16x32_bf16 v[36:39], v[186:189], v[218:221], v[36:39]
	v_mfma_f32_16x16x32_bf16 v[20:23], v[194:197], v[218:221], v[20:23]
	v_mfma_f32_16x16x32_bf16 v[8:11], v[186:189], v[226:229], v[8:11]
	v_mfma_f32_16x16x32_bf16 v[0:3], v[194:197], v[226:229], v[0:3]
	v_mfma_f32_16x16x32_bf16 v[28:31], v[190:193], v[206:209], v[28:31]
	v_mfma_f32_16x16x32_bf16 v[12:15], v[198:201], v[206:209], v[12:15]
	v_mfma_f32_16x16x32_bf16 v[4:7], v[190:193], v[214:217], v[4:7]
	v_mfma_f32_16x16x32_bf16 v[52:55], v[198:201], v[214:217], v[52:55]
	v_mfma_f32_16x16x32_bf16 v[36:39], v[190:193], v[222:225], v[36:39]
	v_mfma_f32_16x16x32_bf16 v[20:23], v[198:201], v[222:225], v[20:23]
	v_mfma_f32_16x16x32_bf16 v[8:11], v[190:193], v[230:233], v[8:11]
	v_mfma_f32_16x16x32_bf16 v[0:3], v[198:201], v[230:233], v[0:3]
	s_setprio 0
	s_barrier
	s_add_i32 s9, 0, 0x18000
	v_add_u32_e32 v143, s9, v141
	s_add_i32 s62, 0, 0x1c000
	ds_read_b128 v[170:173], v143
	ds_read_b128 v[174:177], v143 offset:1024
	ds_read_b128 v[178:181], v143 offset:2048
	ds_read_b128 v[182:185], v143 offset:3072
	v_add_u32_e32 v143, s62, v141
	ds_read_b128 v[186:189], v143
	ds_read_b128 v[190:193], v143 offset:1024
	ds_read_b128 v[194:197], v143 offset:2048
	ds_read_b128 v[198:201], v143 offset:3072
	s_add_u32 s60, s60, 0xb0000
	s_addc_u32 s61, s61, 0
	s_mov_b32 m0, s69
	v_lshl_add_u64 v[240:241], s[60:61], 0, v[132:133]
	ds_read_b128 v[202:205], v142 offset:32768
	ds_read_b128 v[206:209], v142 offset:33792
	ds_read_b128 v[210:213], v142 offset:34816
	ds_read_b128 v[214:217], v142 offset:35840
	ds_read_b128 v[218:221], v142 offset:36864
	ds_read_b128 v[222:225], v142 offset:37888
	ds_read_b128 v[226:229], v142 offset:38912
	ds_read_b128 v[230:233], v142 offset:39936
	global_load_lds_dwordx4 v[240:241], off
	v_lshl_add_u64 v[240:241], s[60:61], 0, v[130:131]
	s_mov_b32 m0, s70
	s_nop 0
	global_load_lds_dwordx4 v[240:241], off
	s_waitcnt vmcnt(8)
	s_waitcnt lgkmcnt(0)
	s_barrier
	s_setprio 1
	v_mfma_f32_16x16x32_bf16 v[124:127], v[170:173], v[202:205], v[124:127]
	v_mfma_f32_16x16x32_bf16 v[120:123], v[178:181], v[202:205], v[120:123]
	v_mfma_f32_16x16x32_bf16 v[108:111], v[170:173], v[210:213], v[108:111]
	v_mfma_f32_16x16x32_bf16 v[104:107], v[178:181], v[210:213], v[104:107]
	v_mfma_f32_16x16x32_bf16 v[92:95], v[170:173], v[218:221], v[92:95]
	v_mfma_f32_16x16x32_bf16 v[88:91], v[178:181], v[218:221], v[88:91]
	v_mfma_f32_16x16x32_bf16 v[80:83], v[170:173], v[226:229], v[80:83]
	v_mfma_f32_16x16x32_bf16 v[76:79], v[178:181], v[226:229], v[76:79]
	v_mfma_f32_16x16x32_bf16 v[124:127], v[174:177], v[206:209], v[124:127]
	v_mfma_f32_16x16x32_bf16 v[120:123], v[182:185], v[206:209], v[120:123]
	v_mfma_f32_16x16x32_bf16 v[108:111], v[174:177], v[214:217], v[108:111]
	v_mfma_f32_16x16x32_bf16 v[104:107], v[182:185], v[214:217], v[104:107]
	v_mfma_f32_16x16x32_bf16 v[92:95], v[174:177], v[222:225], v[92:95]
	v_mfma_f32_16x16x32_bf16 v[88:91], v[182:185], v[222:225], v[88:91]
	v_mfma_f32_16x16x32_bf16 v[80:83], v[174:177], v[230:233], v[80:83]
	v_mfma_f32_16x16x32_bf16 v[76:79], v[182:185], v[230:233], v[76:79]
	s_setprio 0
	s_setprio 1
	v_mfma_f32_16x16x32_bf16 v[116:119], v[186:189], v[202:205], v[116:119]
	v_mfma_f32_16x16x32_bf16 v[112:115], v[194:197], v[202:205], v[112:115]
	v_mfma_f32_16x16x32_bf16 v[100:103], v[186:189], v[210:213], v[100:103]
	v_mfma_f32_16x16x32_bf16 v[96:99], v[194:197], v[210:213], v[96:99]
	v_mfma_f32_16x16x32_bf16 v[84:87], v[186:189], v[218:221], v[84:87]
	v_mfma_f32_16x16x32_bf16 v[72:75], v[194:197], v[218:221], v[72:75]
	v_mfma_f32_16x16x32_bf16 v[68:71], v[186:189], v[226:229], v[68:71]
	v_mfma_f32_16x16x32_bf16 v[64:67], v[194:197], v[226:229], v[64:67]
	v_mfma_f32_16x16x32_bf16 v[116:119], v[190:193], v[206:209], v[116:119]
	v_mfma_f32_16x16x32_bf16 v[112:115], v[198:201], v[206:209], v[112:115]
	v_mfma_f32_16x16x32_bf16 v[100:103], v[190:193], v[214:217], v[100:103]
	v_mfma_f32_16x16x32_bf16 v[96:99], v[198:201], v[214:217], v[96:99]
	v_mfma_f32_16x16x32_bf16 v[84:87], v[190:193], v[222:225], v[84:87]
	v_mfma_f32_16x16x32_bf16 v[72:75], v[198:201], v[222:225], v[72:75]
	v_mfma_f32_16x16x32_bf16 v[68:71], v[190:193], v[230:233], v[68:71]
	v_mfma_f32_16x16x32_bf16 v[64:67], v[198:201], v[230:233], v[64:67]
	s_setprio 0
	s_barrier
; #define PG8_STAGE(bufoff, gbase, voff) do { _Pragma("unroll") for (int _i = 0; _i < 2; ++_i) \
;         __builtin_amdgcn_global_load_lds((const unsigned*)((const char*)(gbase) + (voff)[_i]), (PG8_LAS unsigned*)(lds + (bufoff) + ldsw + _i * 8192), 16, 0, 0); } while (0)
; #define PG8_LDA(dst, b, h) do { _Pragma("unroll") for (int m = 0; m < 4; ++m) _Pragma("unroll") for (int k = 0; k < 2; ++k) dst[m][k] = *(const PG8_LAS bf16x8*)(lds + PG8_SA(b, h) + aoff + m * 2048 + k * 1024); } while (0)
; #define PG8_MMA(ai, bj, At, Bt) do { __builtin_amdgcn_s_setprio(1); _Pragma("unroll") for (int m = 0; m < 4; ++m) _Pragma("unroll") for (int n = 0; n < 2; ++n) _Pragma("unroll") for (int k = 0; k < 2; ++k) \
;         acc[ai][bj][m][n] = __builtin_amdgcn_mfma_f32_16x16x32_bf16(Bt[n][k], At[m][k], acc[ai][bj][m][n], 0, 0, 0); __builtin_amdgcn_s_setprio(0); } while (0)
; #define PG8_WAIT_V(n) asm volatile("s_waitcnt vmcnt(" #n ")" ::: "memory")
; #define PG8_WAIT_L(n) asm volatile("s_waitcnt lgkmcnt(" #n ")" ::: "memory")
; #define PG8_BAR __builtin_amdgcn_s_barrier()
; #define PG8_SCHED __builtin_amdgcn_sched_barrier(0)
; template <class Epi, class Sched, bool ALIGN_EPI = false, bool SP2 = false>
; __device__ __forceinline__ void gemm_phase(PG8_LAS unsigned char* lds, const Gemm g, const Sched& S, const Epi& E, const int wid) {
;     ...
;             PG8_LDA(At, 1, 1); PG8_STAGE(PG8_SB(1, 0), b3, voffB); PG8_STAGE(PG8_SB(1, 1), b3 + hstepB, voffB); PG8_STAGE(PG8_SA(1, 0), a3, voffA);
;             PG8_WAIT_V(8); PG8_WAIT_L(0); PG8_BAR; PG8_MMA(1, 0, At, B0); PG8_MMA(1, 1, At, B1); PG8_BAR; PG8_SCHED;
	s_add_i32 s9, s9, s0
	v_lshl_add_u64 v[160:161], v[160:161], 0, s[80:81]
	s_mov_b32 m0, s9
	ds_read_b128 v[202:205], v142 offset:49152
	ds_read_b128 v[206:209], v142 offset:50176
	ds_read_b128 v[210:213], v142 offset:51200
	ds_read_b128 v[214:217], v142 offset:52224
	ds_read_b128 v[218:221], v142 offset:53248
	ds_read_b128 v[222:225], v142 offset:54272
	ds_read_b128 v[226:229], v142 offset:55296
	ds_read_b128 v[230:233], v142 offset:56320
	global_load_lds_dwordx4 v[160:161], off
	s_add_i32 m0, s9, 0x2000
	s_add_u32 s58, s58, 0xb0080
	v_lshl_add_u64 v[160:161], v[234:235], 0, s[80:81]
	s_addc_u32 s59, s59, 0
	s_add_i32 s9, s62, s0
	global_load_lds_dwordx4 v[160:161], off
	v_lshl_add_u64 v[160:161], s[58:59], 0, v[146:147]
	s_mov_b32 m0, s9
	s_nop 0
	global_load_lds_dwordx4 v[160:161], off
	v_lshl_add_u64 v[160:161], s[58:59], 0, v[128:129]
	s_add_i32 m0, s9, 0x2000
	s_nop 0
	global_load_lds_dwordx4 v[160:161], off
	v_lshl_add_u64 v[160:161], v[236:237], 0, s[80:81]
	s_mov_b32 m0, s71
	s_nop 0
	global_load_lds_dwordx4 v[160:161], off
	v_lshl_add_u64 v[160:161], v[238:239], 0, s[80:81]
	s_mov_b32 m0, s72
	s_nop 0
	global_load_lds_dwordx4 v[160:161], off
	s_waitcnt vmcnt(8)
	s_waitcnt lgkmcnt(0)
	s_barrier
	s_setprio 1
	v_mfma_f32_16x16x32_bf16 v[56:59], v[170:173], v[202:205], v[56:59]
	v_mfma_f32_16x16x32_bf16 v[44:47], v[178:181], v[202:205], v[44:47]
	v_mfma_f32_16x16x32_bf16 v[32:35], v[170:173], v[210:213], v[32:35]
	v_mfma_f32_16x16x32_bf16 v[16:19], v[178:181], v[210:213], v[16:19]
	v_mfma_f32_16x16x32_bf16 v[60:63], v[170:173], v[218:221], v[60:63]
	v_mfma_f32_16x16x32_bf16 v[48:51], v[178:181], v[218:221], v[48:51]
	v_mfma_f32_16x16x32_bf16 v[40:43], v[170:173], v[226:229], v[40:43]
	v_mfma_f32_16x16x32_bf16 v[24:27], v[178:181], v[226:229], v[24:27]
	v_mfma_f32_16x16x32_bf16 v[56:59], v[174:177], v[206:209], v[56:59]
	v_mfma_f32_16x16x32_bf16 v[44:47], v[182:185], v[206:209], v[44:47]
	v_mfma_f32_16x16x32_bf16 v[32:35], v[174:177], v[214:217], v[32:35]
	v_mfma_f32_16x16x32_bf16 v[16:19], v[182:185], v[214:217], v[16:19]
	v_mfma_f32_16x16x32_bf16 v[60:63], v[174:177], v[222:225], v[60:63]
	v_mfma_f32_16x16x32_bf16 v[48:51], v[182:185], v[222:225], v[48:51]
	v_mfma_f32_16x16x32_bf16 v[40:43], v[174:177], v[230:233], v[40:43]
	v_mfma_f32_16x16x32_bf16 v[24:27], v[182:185], v[230:233], v[24:27]
	s_setprio 0
	s_setprio 1
	v_mfma_f32_16x16x32_bf16 v[28:31], v[186:189], v[202:205], v[28:31]
	v_mfma_f32_16x16x32_bf16 v[12:15], v[194:197], v[202:205], v[12:15]
	v_mfma_f32_16x16x32_bf16 v[4:7], v[186:189], v[210:213], v[4:7]
	v_mfma_f32_16x16x32_bf16 v[52:55], v[194:197], v[210:213], v[52:55]
	v_mfma_f32_16x16x32_bf16 v[36:39], v[186:189], v[218:221], v[36:39]
	v_mfma_f32_16x16x32_bf16 v[20:23], v[194:197], v[218:221], v[20:23]
	v_mfma_f32_16x16x32_bf16 v[8:11], v[186:189], v[226:229], v[8:11]
	v_mfma_f32_16x16x32_bf16 v[0:3], v[194:197], v[226:229], v[0:3]
	v_mfma_f32_16x16x32_bf16 v[28:31], v[190:193], v[206:209], v[28:31]
	v_mfma_f32_16x16x32_bf16 v[12:15], v[198:201], v[206:209], v[12:15]
	v_mfma_f32_16x16x32_bf16 v[4:7], v[190:193], v[214:217], v[4:7]
	v_mfma_f32_16x16x32_bf16 v[52:55], v[198:201], v[214:217], v[52:55]
	v_mfma_f32_16x16x32_bf16 v[36:39], v[190:193], v[222:225], v[36:39]
	v_mfma_f32_16x16x32_bf16 v[20:23], v[198:201], v[222:225], v[20:23]
	v_mfma_f32_16x16x32_bf16 v[8:11], v[190:193], v[230:233], v[8:11]
	v_mfma_f32_16x16x32_bf16 v[0:3], v[198:201], v[230:233], v[0:3]
	s_setprio 0
	s_barrier
	s_add_u32 s82, s82, 0x100
	s_addc_u32 s83, s83, 0
	s_cmp_ge_i32 vcc_lo, s5
	s_mov_b64 s[62:63], s[56:57]
	s_mov_b32 s58, vcc_lo
	s_cbranch_scc0 .LBB0_575
	s_mov_b32 s63, 0xe000
	s_mov_b32 s82, 0x24000
	s_mov_b32 s83, 0x26000
	s_mov_b32 s59, 0x28000
	s_mov_b32 s58, 0x2a000
	s_mov_b32 s61, 0x2c000
	s_mov_b32 s60, 0x32000
	s_mov_b32 s56, 0x34000
	s_mov_b32 s57, 0x36000
	s_and_b64 vcc, exec, s[44:45]
	s_cbranch_vccnz .LBB0_561

; #define PG8_STAGE(bufoff, gbase, voff) do { _Pragma("unroll") for (int _i = 0; _i < 2; ++_i) \
;         __builtin_amdgcn_global_load_lds((const unsigned*)((const char*)(gbase) + (voff)[_i]), (PG8_LAS unsigned*)(lds + (bufoff) + ldsw + _i * 8192), 16, 0, 0); } while (0)
; #define PG8_LDA(dst, b, h) do { _Pragma("unroll") for (int m = 0; m < 4; ++m) _Pragma("unroll") for (int k = 0; k < 2; ++k) dst[m][k] = *(const PG8_LAS bf16x8*)(lds + PG8_SA(b, h) + aoff + m * 2048 + k * 1024); } while (0)
; #define PG8_LDB(dst, b, h) do { _Pragma("unroll") for (int n = 0; n < 2; ++n) _Pragma("unroll") for (int k = 0; k < 2; ++k) dst[n][k] = *(const PG8_LAS bf16x8*)(lds + PG8_SB(b, h) + boff + n * 2048 + k * 1024); } while (0)
; #define PG8_MMA(ai, bj, At, Bt) do { __builtin_amdgcn_s_setprio(1); _Pragma("unroll") for (int m = 0; m < 4; ++m) _Pragma("unroll") for (int n = 0; n < 2; ++n) _Pragma("unroll") for (int k = 0; k < 2; ++k) \
;         acc[ai][bj][m][n] = __builtin_amdgcn_mfma_f32_16x16x32_bf16(Bt[n][k], At[m][k], acc[ai][bj][m][n], 0, 0, 0); __builtin_amdgcn_s_setprio(0); } while (0)
; #define PG8_WAIT_V(n) asm volatile("s_waitcnt vmcnt(" #n ")" ::: "memory")
; #define PG8_WAIT_L(n) asm volatile("s_waitcnt lgkmcnt(" #n ")" ::: "memory")
; template <class Epi, class Sched, bool ALIGN_EPI = false, bool SP2 = false>
; __device__ __forceinline__ void gemm_phase(PG8_LAS unsigned char* lds, const Gemm g, const Sched& S, const Epi& E, const int wid) {
;     ...
;             const bool last = (t == nt - 2);
;             const char* a1 = cA + (size_t)(t + 1) * kstep;
;             const char* a2 = last ? nA : cA + (size_t)(t + 2) * kstep; const char* b2 = last ? nB : cB + (size_t)(t + 2) * kstep;
;             const char* a3 = a2 + kstep; const char* b3 = b2 + kstep;
;             if (last && has_next) S.a_ready(nxt);
;             if constexpr (SP2) {
;             PG8_LDB(B0, 0, 0); PG8_LDB(B1, 0, 1); PG8_SCHED; PG8_LDA(At, 0, 0); PG8_STAGE(PG8_SA(1, 1), a1 + hstepA, voffA);
;             PG8_WAIT_V(8); PG8_WAIT_L(0); PG8_BAR; PG8_MMA(0, 0, At, B0); PG8_MMA(0, 1, At, B1); PG8_BAR; PG8_SCHED;
;             PG8_LDA(At, 0, 1); PG8_STAGE(PG8_SB(0, 0), b2, voffB); PG8_STAGE(PG8_SB(0, 1), b2 + hstepB, voffB); PG8_STAGE(PG8_SA(0, 0), a2, voffA);
;             PG8_WAIT_V(8); PG8_WAIT_L(0); PG8_BAR; PG8_MMA(1, 0, At, B0); PG8_MMA(1, 1, At, B1); PG8_BAR; PG8_SCHED;
.LBB0_630:
	s_add_i32 vcc_lo, s58, 2
	s_add_u32 s56, s62, 0x100
	s_addc_u32 s57, s63, 0
	s_add_i32 vcc_hi, 0, 0x10000
	s_cmp_eq_u32 s73, s58
	s_cselect_b32 s61, s47, s57
	s_cselect_b32 s60, s46, s56
	s_cselect_b32 s59, s55, s83
	s_cselect_b32 s58, s54, s82
	s_add_i32 s9, 0, 0x14000
	v_add_u32_e32 v178, vcc_hi, v142
	v_add_u32_e32 v194, s9, v142
	ds_read_b128 v[160:163], v178
	ds_read_b128 v[170:173], v178 offset:1024
	ds_read_b128 v[174:177], v178 offset:2048
	ds_read_b128 v[178:181], v178 offset:3072
	ds_read_b128 v[182:185], v194
	ds_read_b128 v[186:189], v194 offset:1024
	ds_read_b128 v[190:193], v194 offset:2048
	ds_read_b128 v[194:197], v194 offset:3072
	v_lshl_add_u64 v[230:231], s[62:63], 0, v[134:135]
	s_add_i32 m0, s66, 0xc000
	ds_read_b128 v[198:201], v143
	ds_read_b128 v[202:205], v143 offset:1024
	ds_read_b128 v[206:209], v143 offset:2048
	ds_read_b128 v[210:213], v143 offset:3072
	ds_read_b128 v[214:217], v143 offset:4096
	ds_read_b128 v[218:221], v143 offset:5120
	ds_read_b128 v[222:225], v143 offset:6144
	ds_read_b128 v[226:229], v143 offset:7168
	global_load_lds_dwordx4 v[230:231], off
	v_lshl_add_u64 v[230:231], s[62:63], 0, v[136:137]
	s_add_i32 m0, s66, 0xe000
	s_nop 0
	global_load_lds_dwordx4 v[230:231], off
	s_waitcnt vmcnt(8)
	s_waitcnt lgkmcnt(0)
	s_barrier
	s_setprio 1
	v_mfma_f32_16x16x32_bf16 v[124:127], v[160:163], v[198:201], v[124:127]
	v_mfma_f32_16x16x32_bf16 v[120:123], v[174:177], v[198:201], v[120:123]
	v_mfma_f32_16x16x32_bf16 v[108:111], v[160:163], v[206:209], v[108:111]
	v_mfma_f32_16x16x32_bf16 v[104:107], v[174:177], v[206:209], v[104:107]
	v_mfma_f32_16x16x32_bf16 v[100:103], v[160:163], v[214:217], v[100:103]
	v_mfma_f32_16x16x32_bf16 v[92:95], v[174:177], v[214:217], v[92:95]
	v_mfma_f32_16x16x32_bf16 v[84:87], v[160:163], v[222:225], v[84:87]
	v_mfma_f32_16x16x32_bf16 v[76:79], v[174:177], v[222:225], v[76:79]
	v_mfma_f32_16x16x32_bf16 v[124:127], v[170:173], v[202:205], v[124:127]
	v_mfma_f32_16x16x32_bf16 v[120:123], v[178:181], v[202:205], v[120:123]
	v_mfma_f32_16x16x32_bf16 v[108:111], v[170:173], v[210:213], v[108:111]
	v_mfma_f32_16x16x32_bf16 v[104:107], v[178:181], v[210:213], v[104:107]
	v_mfma_f32_16x16x32_bf16 v[100:103], v[170:173], v[218:221], v[100:103]
	v_mfma_f32_16x16x32_bf16 v[92:95], v[178:181], v[218:221], v[92:95]
	v_mfma_f32_16x16x32_bf16 v[84:87], v[170:173], v[226:229], v[84:87]
	v_mfma_f32_16x16x32_bf16 v[76:79], v[178:181], v[226:229], v[76:79]
	s_setprio 0
	s_setprio 1
	v_mfma_f32_16x16x32_bf16 v[116:119], v[182:185], v[198:201], v[116:119]
	v_mfma_f32_16x16x32_bf16 v[112:115], v[190:193], v[198:201], v[112:115]
	v_mfma_f32_16x16x32_bf16 v[96:99], v[182:185], v[206:209], v[96:99]
	v_mfma_f32_16x16x32_bf16 v[88:91], v[190:193], v[206:209], v[88:91]
	v_mfma_f32_16x16x32_bf16 v[80:83], v[182:185], v[214:217], v[80:83]
	v_mfma_f32_16x16x32_bf16 v[72:75], v[190:193], v[214:217], v[72:75]
	v_mfma_f32_16x16x32_bf16 v[68:71], v[182:185], v[222:225], v[68:71]
	v_mfma_f32_16x16x32_bf16 v[60:63], v[190:193], v[222:225], v[60:63]
	v_mfma_f32_16x16x32_bf16 v[116:119], v[186:189], v[202:205], v[116:119]
	v_mfma_f32_16x16x32_bf16 v[112:115], v[194:197], v[202:205], v[112:115]
	v_mfma_f32_16x16x32_bf16 v[96:99], v[186:189], v[210:213], v[96:99]
	v_mfma_f32_16x16x32_bf16 v[88:91], v[194:197], v[210:213], v[88:91]
	v_mfma_f32_16x16x32_bf16 v[80:83], v[186:189], v[218:221], v[80:83]
	v_mfma_f32_16x16x32_bf16 v[72:75], v[194:197], v[218:221], v[72:75]
	v_mfma_f32_16x16x32_bf16 v[68:71], v[186:189], v[226:229], v[68:71]
	v_mfma_f32_16x16x32_bf16 v[60:63], v[194:197], v[226:229], v[60:63]
	s_setprio 0
	s_barrier
	s_add_i32 s62, vcc_hi, s0
	v_lshl_add_u64 v[230:231], s[58:59], 0, v[146:147]
	s_mov_b32 m0, s62
	ds_read_b128 v[198:201], v143 offset:16384
	ds_read_b128 v[202:205], v143 offset:17408
	ds_read_b128 v[206:209], v143 offset:18432
	ds_read_b128 v[210:213], v143 offset:19456
	ds_read_b128 v[214:217], v143 offset:20480
	ds_read_b128 v[218:221], v143 offset:21504
	ds_read_b128 v[222:225], v143 offset:22528
	ds_read_b128 v[226:229], v143 offset:23552
	global_load_lds_dwordx4 v[230:231], off
	s_add_i32 m0, s62, 0x2000
	s_add_u32 s62, s58, 0xb0000
	v_lshl_add_u64 v[232:233], s[58:59], 0, v[128:129]
	s_addc_u32 s63, s59, 0
	s_add_i32 s9, s9, s0
	global_load_lds_dwordx4 v[232:233], off
	v_lshl_add_u64 v[234:235], s[62:63], 0, v[146:147]
	s_mov_b32 m0, s9
	v_lshl_add_u64 v[236:237], s[60:61], 0, v[130:131]
	global_load_lds_dwordx4 v[234:235], off
	v_lshl_add_u64 v[234:235], s[62:63], 0, v[128:129]
	s_add_i32 m0, s9, 0x2000
	s_nop 0
	global_load_lds_dwordx4 v[234:235], off
	v_lshl_add_u64 v[234:235], s[60:61], 0, v[132:133]
	s_mov_b32 m0, s66
	s_nop 0
	global_load_lds_dwordx4 v[234:235], off
	s_mov_b32 m0, s67
	s_nop 0
	global_load_lds_dwordx4 v[236:237], off
	s_waitcnt vmcnt(8)
	s_waitcnt lgkmcnt(0)
	s_barrier
; #define PG8_STAGE(bufoff, gbase, voff) do { _Pragma("unroll") for (int _i = 0; _i < 2; ++_i) \
;         __builtin_amdgcn_global_load_lds((const unsigned*)((const char*)(gbase) + (voff)[_i]), (PG8_LAS unsigned*)(lds + (bufoff) + ldsw + _i * 8192), 16, 0, 0); } while (0)
; #define PG8_LDA(dst, b, h) do { _Pragma("unroll") for (int m = 0; m < 4; ++m) _Pragma("unroll") for (int k = 0; k < 2; ++k) dst[m][k] = *(const PG8_LAS bf16x8*)(lds + PG8_SA(b, h) + aoff + m * 2048 + k * 1024); } while (0)
; #define PG8_LDB(dst, b, h) do { _Pragma("unroll") for (int n = 0; n < 2; ++n) _Pragma("unroll") for (int k = 0; k < 2; ++k) dst[n][k] = *(const PG8_LAS bf16x8*)(lds + PG8_SB(b, h) + boff + n * 2048 + k * 1024); } while (0)
; #define PG8_MMA(ai, bj, At, Bt) do { __builtin_amdgcn_s_setprio(1); _Pragma("unroll") for (int m = 0; m < 4; ++m) _Pragma("unroll") for (int n = 0; n < 2; ++n) _Pragma("unroll") for (int k = 0; k < 2; ++k) \
;         acc[ai][bj][m][n] = __builtin_amdgcn_mfma_f32_16x16x32_bf16(Bt[n][k], At[m][k], acc[ai][bj][m][n], 0, 0, 0); __builtin_amdgcn_s_setprio(0); } while (0)
; #define PG8_WAIT_V(n) asm volatile("s_waitcnt vmcnt(" #n ")" ::: "memory")
; #define PG8_WAIT_L(n) asm volatile("s_waitcnt lgkmcnt(" #n ")" ::: "memory")
; #define PG8_BAR __builtin_amdgcn_s_barrier()
; #define PG8_SCHED __builtin_amdgcn_sched_barrier(0)
; template <class Epi, class Sched, bool ALIGN_EPI = false, bool SP2 = false>
; __device__ __forceinline__ void gemm_phase(PG8_LAS unsigned char* lds, const Gemm g, const Sched& S, const Epi& E, const int wid) {
;     ...
;             PG8_WAIT_V(8); PG8_WAIT_L(0); PG8_BAR; PG8_MMA(1, 0, At, B0); PG8_MMA(1, 1, At, B1); PG8_BAR; PG8_SCHED;
;             PG8_LDB(B0, 1, 0); PG8_LDB(B1, 1, 1); PG8_SCHED; PG8_LDA(At, 1, 0); PG8_STAGE(PG8_SA(0, 1), a2 + hstepA, voffA);
;             PG8_WAIT_V(8); PG8_WAIT_L(0); PG8_BAR; PG8_MMA(0, 0, At, B0); PG8_MMA(0, 1, At, B1); PG8_BAR; PG8_SCHED;
	s_setprio 1
	v_mfma_f32_16x16x32_bf16 v[48:51], v[160:163], v[198:201], v[48:51]
	v_mfma_f32_16x16x32_bf16 v[44:47], v[174:177], v[198:201], v[44:47]
	v_mfma_f32_16x16x32_bf16 v[24:27], v[160:163], v[206:209], v[24:27]
	v_mfma_f32_16x16x32_bf16 v[16:19], v[174:177], v[206:209], v[16:19]
	v_mfma_f32_16x16x32_bf16 v[64:67], v[160:163], v[214:217], v[64:67]
	v_mfma_f32_16x16x32_bf16 v[56:59], v[174:177], v[214:217], v[56:59]
	v_mfma_f32_16x16x32_bf16 v[40:43], v[160:163], v[222:225], v[40:43]
	v_mfma_f32_16x16x32_bf16 v[32:35], v[174:177], v[222:225], v[32:35]
	v_mfma_f32_16x16x32_bf16 v[48:51], v[170:173], v[202:205], v[48:51]
	v_mfma_f32_16x16x32_bf16 v[44:47], v[178:181], v[202:205], v[44:47]
	v_mfma_f32_16x16x32_bf16 v[24:27], v[170:173], v[210:213], v[24:27]
	v_mfma_f32_16x16x32_bf16 v[16:19], v[178:181], v[210:213], v[16:19]
	v_mfma_f32_16x16x32_bf16 v[64:67], v[170:173], v[218:221], v[64:67]
	v_mfma_f32_16x16x32_bf16 v[56:59], v[178:181], v[218:221], v[56:59]
	v_mfma_f32_16x16x32_bf16 v[40:43], v[170:173], v[226:229], v[40:43]
	v_mfma_f32_16x16x32_bf16 v[32:35], v[178:181], v[226:229], v[32:35]
	s_setprio 0
	s_setprio 1
	v_mfma_f32_16x16x32_bf16 v[20:23], v[182:185], v[198:201], v[20:23]
	v_mfma_f32_16x16x32_bf16 v[12:15], v[190:193], v[198:201], v[12:15]
	v_mfma_f32_16x16x32_bf16 v[0:3], v[182:185], v[206:209], v[0:3]
	v_mfma_f32_16x16x32_bf16 v[52:55], v[190:193], v[206:209], v[52:55]
	v_mfma_f32_16x16x32_bf16 v[36:39], v[182:185], v[214:217], v[36:39]
	v_mfma_f32_16x16x32_bf16 v[28:31], v[190:193], v[214:217], v[28:31]
	v_mfma_f32_16x16x32_bf16 v[8:11], v[182:185], v[222:225], v[8:11]
	v_mfma_f32_16x16x32_bf16 v[4:7], v[190:193], v[222:225], v[4:7]
	v_mfma_f32_16x16x32_bf16 v[20:23], v[186:189], v[202:205], v[20:23]
	v_mfma_f32_16x16x32_bf16 v[12:15], v[194:197], v[202:205], v[12:15]
	v_mfma_f32_16x16x32_bf16 v[0:3], v[186:189], v[210:213], v[0:3]
	v_mfma_f32_16x16x32_bf16 v[52:55], v[194:197], v[210:213], v[52:55]
	v_mfma_f32_16x16x32_bf16 v[36:39], v[186:189], v[218:221], v[36:39]
	v_mfma_f32_16x16x32_bf16 v[28:31], v[194:197], v[218:221], v[28:31]
	v_mfma_f32_16x16x32_bf16 v[8:11], v[186:189], v[226:229], v[8:11]
	v_mfma_f32_16x16x32_bf16 v[4:7], v[194:197], v[226:229], v[4:7]
	s_setprio 0
	s_barrier
	s_add_i32 s9, 0, 0x18000
	s_add_i32 s62, 0, 0x1c000
	v_add_u32_e32 v178, s9, v142
	v_add_u32_e32 v194, s62, v142
	ds_read_b128 v[160:163], v178
	ds_read_b128 v[170:173], v178 offset:1024
	ds_read_b128 v[174:177], v178 offset:2048
	ds_read_b128 v[178:181], v178 offset:3072
	ds_read_b128 v[182:185], v194
	ds_read_b128 v[186:189], v194 offset:1024
	ds_read_b128 v[190:193], v194 offset:2048
	ds_read_b128 v[194:197], v194 offset:3072
	s_add_u32 s60, s60, 0xb0000
	s_addc_u32 s61, s61, 0
	s_mov_b32 m0, s68
	v_lshl_add_u64 v[238:239], s[60:61], 0, v[132:133]
	ds_read_b128 v[198:201], v143 offset:32768
	ds_read_b128 v[202:205], v143 offset:33792
	ds_read_b128 v[206:209], v143 offset:34816
	ds_read_b128 v[210:213], v143 offset:35840
	ds_read_b128 v[214:217], v143 offset:36864
	ds_read_b128 v[218:221], v143 offset:37888
	ds_read_b128 v[222:225], v143 offset:38912
	ds_read_b128 v[226:229], v143 offset:39936
	global_load_lds_dwordx4 v[238:239], off
	v_lshl_add_u64 v[238:239], s[60:61], 0, v[130:131]
	s_mov_b32 m0, s69
	s_nop 0
	global_load_lds_dwordx4 v[238:239], off
	s_waitcnt vmcnt(8)
	s_waitcnt lgkmcnt(0)
	s_barrier
	s_setprio 1
	v_mfma_f32_16x16x32_bf16 v[124:127], v[160:163], v[198:201], v[124:127]
	v_mfma_f32_16x16x32_bf16 v[120:123], v[174:177], v[198:201], v[120:123]
	v_mfma_f32_16x16x32_bf16 v[108:111], v[160:163], v[206:209], v[108:111]
	v_mfma_f32_16x16x32_bf16 v[104:107], v[174:177], v[206:209], v[104:107]
	v_mfma_f32_16x16x32_bf16 v[100:103], v[160:163], v[214:217], v[100:103]
	v_mfma_f32_16x16x32_bf16 v[92:95], v[174:177], v[214:217], v[92:95]
	v_mfma_f32_16x16x32_bf16 v[84:87], v[160:163], v[222:225], v[84:87]
	v_mfma_f32_16x16x32_bf16 v[76:79], v[174:177], v[222:225], v[76:79]
	v_mfma_f32_16x16x32_bf16 v[124:127], v[170:173], v[202:205], v[124:127]
	v_mfma_f32_16x16x32_bf16 v[120:123], v[178:181], v[202:205], v[120:123]
	v_mfma_f32_16x16x32_bf16 v[108:111], v[170:173], v[210:213], v[108:111]
	v_mfma_f32_16x16x32_bf16 v[104:107], v[178:181], v[210:213], v[104:107]
	v_mfma_f32_16x16x32_bf16 v[100:103], v[170:173], v[218:221], v[100:103]
	v_mfma_f32_16x16x32_bf16 v[92:95], v[178:181], v[218:221], v[92:95]
	v_mfma_f32_16x16x32_bf16 v[84:87], v[170:173], v[226:229], v[84:87]
	v_mfma_f32_16x16x32_bf16 v[76:79], v[178:181], v[226:229], v[76:79]
	s_setprio 0
	s_setprio 1
	v_mfma_f32_16x16x32_bf16 v[116:119], v[182:185], v[198:201], v[116:119]
	v_mfma_f32_16x16x32_bf16 v[112:115], v[190:193], v[198:201], v[112:115]
	v_mfma_f32_16x16x32_bf16 v[96:99], v[182:185], v[206:209], v[96:99]
	v_mfma_f32_16x16x32_bf16 v[88:91], v[190:193], v[206:209], v[88:91]
	v_mfma_f32_16x16x32_bf16 v[80:83], v[182:185], v[214:217], v[80:83]
	v_mfma_f32_16x16x32_bf16 v[72:75], v[190:193], v[214:217], v[72:75]
	v_mfma_f32_16x16x32_bf16 v[68:71], v[182:185], v[222:225], v[68:71]
	v_mfma_f32_16x16x32_bf16 v[60:63], v[190:193], v[222:225], v[60:63]
	v_mfma_f32_16x16x32_bf16 v[116:119], v[186:189], v[202:205], v[116:119]
	v_mfma_f32_16x16x32_bf16 v[112:115], v[194:197], v[202:205], v[112:115]
	v_mfma_f32_16x16x32_bf16 v[96:99], v[186:189], v[210:213], v[96:99]
	v_mfma_f32_16x16x32_bf16 v[88:91], v[194:197], v[210:213], v[88:91]
	v_mfma_f32_16x16x32_bf16 v[80:83], v[186:189], v[218:221], v[80:83]
	v_mfma_f32_16x16x32_bf16 v[72:75], v[194:197], v[218:221], v[72:75]
	v_mfma_f32_16x16x32_bf16 v[68:71], v[186:189], v[226:229], v[68:71]
	v_mfma_f32_16x16x32_bf16 v[60:63], v[194:197], v[226:229], v[60:63]
	s_setprio 0
	s_barrier
; #define PG8_STAGE(bufoff, gbase, voff) do { _Pragma("unroll") for (int _i = 0; _i < 2; ++_i) \
;         __builtin_amdgcn_global_load_lds((const unsigned*)((const char*)(gbase) + (voff)[_i]), (PG8_LAS unsigned*)(lds + (bufoff) + ldsw + _i * 8192), 16, 0, 0); } while (0)
; #define PG8_LDA(dst, b, h) do { _Pragma("unroll") for (int m = 0; m < 4; ++m) _Pragma("unroll") for (int k = 0; k < 2; ++k) dst[m][k] = *(const PG8_LAS bf16x8*)(lds + PG8_SA(b, h) + aoff + m * 2048 + k * 1024); } while (0)
; #define PG8_MMA(ai, bj, At, Bt) do { __builtin_amdgcn_s_setprio(1); _Pragma("unroll") for (int m = 0; m < 4; ++m) _Pragma("unroll") for (int n = 0; n < 2; ++n) _Pragma("unroll") for (int k = 0; k < 2; ++k) \
;         acc[ai][bj][m][n] = __builtin_amdgcn_mfma_f32_16x16x32_bf16(Bt[n][k], At[m][k], acc[ai][bj][m][n], 0, 0, 0); __builtin_amdgcn_s_setprio(0); } while (0)
; #define PG8_WAIT_V(n) asm volatile("s_waitcnt vmcnt(" #n ")" ::: "memory")
; #define PG8_WAIT_L(n) asm volatile("s_waitcnt lgkmcnt(" #n ")" ::: "memory")
; #define PG8_BAR __builtin_amdgcn_s_barrier()
; #define PG8_SCHED __builtin_amdgcn_sched_barrier(0)
; template <class Epi, class Sched, bool ALIGN_EPI = false, bool SP2 = false>
; __device__ __forceinline__ void gemm_phase(PG8_LAS unsigned char* lds, const Gemm g, const Sched& S, const Epi& E, const int wid) {
;     ...
;             PG8_LDA(At, 1, 1); PG8_STAGE(PG8_SB(1, 0), b3, voffB); PG8_STAGE(PG8_SB(1, 1), b3 + hstepB, voffB); PG8_STAGE(PG8_SA(1, 0), a3, voffA);
;             PG8_WAIT_V(8); PG8_WAIT_L(0); PG8_BAR; PG8_MMA(1, 0, At, B0); PG8_MMA(1, 1, At, B1); PG8_BAR; PG8_SCHED;
	s_add_i32 s9, s9, s0
	v_lshl_add_u64 v[230:231], v[230:231], 0, s[80:81]
	s_mov_b32 m0, s9
	ds_read_b128 v[198:201], v143 offset:49152
	ds_read_b128 v[202:205], v143 offset:50176
	ds_read_b128 v[206:209], v143 offset:51200
	ds_read_b128 v[210:213], v143 offset:52224
	ds_read_b128 v[214:217], v143 offset:53248
	ds_read_b128 v[218:221], v143 offset:54272
	ds_read_b128 v[222:225], v143 offset:55296
	ds_read_b128 v[226:229], v143 offset:56320
	global_load_lds_dwordx4 v[230:231], off
	s_add_i32 m0, s9, 0x2000
	s_add_u32 s58, s58, 0xb0080
	v_lshl_add_u64 v[230:231], v[232:233], 0, s[80:81]
	s_addc_u32 s59, s59, 0
	s_add_i32 s9, s62, s0
	global_load_lds_dwordx4 v[230:231], off
	v_lshl_add_u64 v[230:231], s[58:59], 0, v[146:147]
	s_mov_b32 m0, s9
	s_nop 0
	global_load_lds_dwordx4 v[230:231], off
	v_lshl_add_u64 v[230:231], s[58:59], 0, v[128:129]
	s_add_i32 m0, s9, 0x2000
	s_nop 0
	global_load_lds_dwordx4 v[230:231], off
	v_lshl_add_u64 v[230:231], v[234:235], 0, s[80:81]
	s_mov_b32 m0, s71
	s_nop 0
	global_load_lds_dwordx4 v[230:231], off
	v_lshl_add_u64 v[230:231], v[236:237], 0, s[80:81]
	s_mov_b32 m0, s72
	s_nop 0
	global_load_lds_dwordx4 v[230:231], off
	s_waitcnt vmcnt(8)
	s_waitcnt lgkmcnt(0)
	s_barrier
	s_setprio 1
	v_mfma_f32_16x16x32_bf16 v[48:51], v[160:163], v[198:201], v[48:51]
	v_mfma_f32_16x16x32_bf16 v[44:47], v[174:177], v[198:201], v[44:47]
	v_mfma_f32_16x16x32_bf16 v[24:27], v[160:163], v[206:209], v[24:27]
	v_mfma_f32_16x16x32_bf16 v[16:19], v[174:177], v[206:209], v[16:19]
	v_mfma_f32_16x16x32_bf16 v[64:67], v[160:163], v[214:217], v[64:67]
	v_mfma_f32_16x16x32_bf16 v[56:59], v[174:177], v[214:217], v[56:59]
	v_mfma_f32_16x16x32_bf16 v[40:43], v[160:163], v[222:225], v[40:43]
	v_mfma_f32_16x16x32_bf16 v[32:35], v[174:177], v[222:225], v[32:35]
	v_mfma_f32_16x16x32_bf16 v[48:51], v[170:173], v[202:205], v[48:51]
	v_mfma_f32_16x16x32_bf16 v[44:47], v[178:181], v[202:205], v[44:47]
	v_mfma_f32_16x16x32_bf16 v[24:27], v[170:173], v[210:213], v[24:27]
	v_mfma_f32_16x16x32_bf16 v[16:19], v[178:181], v[210:213], v[16:19]
	v_mfma_f32_16x16x32_bf16 v[64:67], v[170:173], v[218:221], v[64:67]
	v_mfma_f32_16x16x32_bf16 v[56:59], v[178:181], v[218:221], v[56:59]
	v_mfma_f32_16x16x32_bf16 v[40:43], v[170:173], v[226:229], v[40:43]
	v_mfma_f32_16x16x32_bf16 v[32:35], v[178:181], v[226:229], v[32:35]
	s_setprio 0
	s_setprio 1
	v_mfma_f32_16x16x32_bf16 v[20:23], v[182:185], v[198:201], v[20:23]
	v_mfma_f32_16x16x32_bf16 v[12:15], v[190:193], v[198:201], v[12:15]
	v_mfma_f32_16x16x32_bf16 v[0:3], v[182:185], v[206:209], v[0:3]
	v_mfma_f32_16x16x32_bf16 v[52:55], v[190:193], v[206:209], v[52:55]
	v_mfma_f32_16x16x32_bf16 v[36:39], v[182:185], v[214:217], v[36:39]
	v_mfma_f32_16x16x32_bf16 v[28:31], v[190:193], v[214:217], v[28:31]
	v_mfma_f32_16x16x32_bf16 v[8:11], v[182:185], v[222:225], v[8:11]
	v_mfma_f32_16x16x32_bf16 v[4:7], v[190:193], v[222:225], v[4:7]
	v_mfma_f32_16x16x32_bf16 v[20:23], v[186:189], v[202:205], v[20:23]
	v_mfma_f32_16x16x32_bf16 v[12:15], v[194:197], v[202:205], v[12:15]
	v_mfma_f32_16x16x32_bf16 v[0:3], v[186:189], v[210:213], v[0:3]
	v_mfma_f32_16x16x32_bf16 v[52:55], v[194:197], v[210:213], v[52:55]
	v_mfma_f32_16x16x32_bf16 v[36:39], v[186:189], v[218:221], v[36:39]
	v_mfma_f32_16x16x32_bf16 v[28:31], v[194:197], v[218:221], v[28:31]
	v_mfma_f32_16x16x32_bf16 v[8:11], v[186:189], v[226:229], v[8:11]
	v_mfma_f32_16x16x32_bf16 v[4:7], v[194:197], v[226:229], v[4:7]
	s_setprio 0
	s_barrier
	s_add_u32 s82, s82, 0x100
	s_addc_u32 s83, s83, 0
	s_cmp_ge_i32 vcc_lo, s5
	s_mov_b64 s[62:63], s[56:57]
	s_mov_b32 s58, vcc_lo
	s_cbranch_scc0 .LBB0_630
	s_mov_b32 s63, 0xe000
	s_mov_b32 s82, 0x24000
	s_mov_b32 s83, 0x26000
	s_mov_b32 s59, 0x28000
	s_mov_b32 s58, 0x2a000
	s_mov_b32 s61, 0x2c000
	s_mov_b32 s60, 0x32000
	s_mov_b32 s56, 0x34000
	s_mov_b32 s57, 0x36000
	s_and_b64 vcc, exec, s[44:45]
	s_cbranch_vccnz .LBB0_616

; #define PG8_STAGE(bufoff, gbase, voff) do { _Pragma("unroll") for (int _i = 0; _i < 2; ++_i) \
;         __builtin_amdgcn_global_load_lds((const unsigned*)((const char*)(gbase) + (voff)[_i]), (PG8_LAS unsigned*)(lds + (bufoff) + ldsw + _i * 8192), 16, 0, 0); } while (0)
; #define PG8_LDA(dst, b, h) do { _Pragma("unroll") for (int m = 0; m < 4; ++m) _Pragma("unroll") for (int k = 0; k < 2; ++k) dst[m][k] = *(const PG8_LAS bf16x8*)(lds + PG8_SA(b, h) + aoff + m * 2048 + k * 1024); } while (0)
; #define PG8_LDB(dst, b, h) do { _Pragma("unroll") for (int n = 0; n < 2; ++n) _Pragma("unroll") for (int k = 0; k < 2; ++k) dst[n][k] = *(const PG8_LAS bf16x8*)(lds + PG8_SB(b, h) + boff + n * 2048 + k * 1024); } while (0)
; #define PG8_MMA(ai, bj, At, Bt) do { __builtin_amdgcn_s_setprio(1); _Pragma("unroll") for (int m = 0; m < 4; ++m) _Pragma("unroll") for (int n = 0; n < 2; ++n) _Pragma("unroll") for (int k = 0; k < 2; ++k) \
;         acc[ai][bj][m][n] = __builtin_amdgcn_mfma_f32_16x16x32_bf16(Bt[n][k], At[m][k], acc[ai][bj][m][n], 0, 0, 0); __builtin_amdgcn_s_setprio(0); } while (0)
; #define PG8_WAIT_V(n) asm volatile("s_waitcnt vmcnt(" #n ")" ::: "memory")
; #define PG8_WAIT_L(n) asm volatile("s_waitcnt lgkmcnt(" #n ")" ::: "memory")
; template <class Epi, class Sched, bool ALIGN_EPI = false, bool SP2 = false>
; __device__ __forceinline__ void gemm_phase(PG8_LAS unsigned char* lds, const Gemm g, const Sched& S, const Epi& E, const int wid) {
;     ...
;             const bool last = (t == nt - 2);
;             const char* a1 = cA + (size_t)(t + 1) * kstep;
;             const char* a2 = last ? nA : cA + (size_t)(t + 2) * kstep; const char* b2 = last ? nB : cB + (size_t)(t + 2) * kstep;
;             const char* a3 = a2 + kstep; const char* b3 = b2 + kstep;
;             if (last && has_next) S.a_ready(nxt);
;             if constexpr (SP2) {
;             PG8_LDB(B0, 0, 0); PG8_LDB(B1, 0, 1); PG8_SCHED; PG8_LDA(At, 0, 0); PG8_STAGE(PG8_SA(1, 1), a1 + hstepA, voffA);
;             PG8_WAIT_V(8); PG8_WAIT_L(0); PG8_BAR; PG8_MMA(0, 0, At, B0); PG8_MMA(0, 1, At, B1); PG8_BAR; PG8_SCHED;
;             PG8_LDA(At, 0, 1); PG8_STAGE(PG8_SB(0, 0), b2, voffB); PG8_STAGE(PG8_SB(0, 1), b2 + hstepB, voffB); PG8_STAGE(PG8_SA(0, 0), a2, voffA);
;             PG8_WAIT_V(8); PG8_WAIT_L(0); PG8_BAR; PG8_MMA(1, 0, At, B0); PG8_MMA(1, 1, At, B1); PG8_BAR; PG8_SCHED;
.LBB0_716:
	s_add_i32 s69, s49, 2
	s_add_u32 s9, s52, 0xfffc0080
	s_addc_u32 s54, s53, -1
	s_add_i32 s70, 0, 0x10000
	s_cmp_eq_u32 s66, s49
	s_cselect_b32 s57, s47, s54
	s_cselect_b32 s56, s46, s9
	v_add_u32_e32 v146, s70, v162
	s_cselect_b32 s55, s51, s11
	s_cselect_b32 s54, s50, s8
	s_add_i32 s9, 0, 0x14000
	ds_read_b128 v[128:131], v146
	ds_read_b128 v[178:181], v146 offset:1024
	ds_read_b128 v[182:185], v146 offset:2048
	ds_read_b128 v[186:189], v146 offset:3072
	v_add_u32_e32 v146, s9, v162
	ds_read_b128 v[190:193], v146
	ds_read_b128 v[194:197], v146 offset:1024
	ds_read_b128 v[198:201], v146 offset:2048
	ds_read_b128 v[202:205], v146 offset:3072
	v_lshl_add_u64 v[238:239], s[52:53], 0, v[140:141]
	s_add_i32 m0, s59, 0xc000
	ds_read_b128 v[206:209], v176
	ds_read_b128 v[210:213], v176 offset:1024
	ds_read_b128 v[214:217], v176 offset:2048
	ds_read_b128 v[218:221], v176 offset:3072
	ds_read_b128 v[222:225], v176 offset:4096
	ds_read_b128 v[226:229], v176 offset:5120
	ds_read_b128 v[230:233], v176 offset:6144
	ds_read_b128 v[234:237], v176 offset:7168
	global_load_lds_dwordx4 v[238:239], off
	v_lshl_add_u64 v[238:239], s[52:53], 0, v[142:143]
	s_add_i32 m0, s59, 0xe000
	s_nop 0
	global_load_lds_dwordx4 v[238:239], off
	s_waitcnt vmcnt(8)
	s_waitcnt lgkmcnt(0)
	s_barrier
	s_setprio 1
	v_mfma_f32_16x16x32_bf16 v[124:127], v[128:131], v[206:209], v[124:127]
	v_mfma_f32_16x16x32_bf16 v[120:123], v[182:185], v[206:209], v[120:123]
	v_mfma_f32_16x16x32_bf16 v[108:111], v[128:131], v[214:217], v[108:111]
	v_mfma_f32_16x16x32_bf16 v[104:107], v[182:185], v[214:217], v[104:107]
	v_mfma_f32_16x16x32_bf16 v[92:95], v[128:131], v[222:225], v[92:95]
	v_mfma_f32_16x16x32_bf16 v[88:91], v[182:185], v[222:225], v[88:91]
	v_mfma_f32_16x16x32_bf16 v[76:79], v[128:131], v[230:233], v[76:79]
	v_mfma_f32_16x16x32_bf16 v[72:75], v[182:185], v[230:233], v[72:75]
	v_mfma_f32_16x16x32_bf16 v[124:127], v[178:181], v[210:213], v[124:127]
	v_mfma_f32_16x16x32_bf16 v[120:123], v[186:189], v[210:213], v[120:123]
	v_mfma_f32_16x16x32_bf16 v[108:111], v[178:181], v[218:221], v[108:111]
	v_mfma_f32_16x16x32_bf16 v[104:107], v[186:189], v[218:221], v[104:107]
	v_mfma_f32_16x16x32_bf16 v[92:95], v[178:181], v[226:229], v[92:95]
	v_mfma_f32_16x16x32_bf16 v[88:91], v[186:189], v[226:229], v[88:91]
	v_mfma_f32_16x16x32_bf16 v[76:79], v[178:181], v[234:237], v[76:79]
	v_mfma_f32_16x16x32_bf16 v[72:75], v[186:189], v[234:237], v[72:75]
	s_setprio 0
	s_setprio 1
	v_mfma_f32_16x16x32_bf16 v[116:119], v[190:193], v[206:209], v[116:119]
	v_mfma_f32_16x16x32_bf16 v[112:115], v[198:201], v[206:209], v[112:115]
	v_mfma_f32_16x16x32_bf16 v[100:103], v[190:193], v[214:217], v[100:103]
	v_mfma_f32_16x16x32_bf16 v[96:99], v[198:201], v[214:217], v[96:99]
	v_mfma_f32_16x16x32_bf16 v[84:87], v[190:193], v[222:225], v[84:87]
	v_mfma_f32_16x16x32_bf16 v[80:83], v[198:201], v[222:225], v[80:83]
	v_mfma_f32_16x16x32_bf16 v[68:71], v[190:193], v[230:233], v[68:71]
	v_mfma_f32_16x16x32_bf16 v[64:67], v[198:201], v[230:233], v[64:67]
	v_mfma_f32_16x16x32_bf16 v[116:119], v[194:197], v[210:213], v[116:119]
	v_mfma_f32_16x16x32_bf16 v[112:115], v[202:205], v[210:213], v[112:115]
	v_mfma_f32_16x16x32_bf16 v[100:103], v[194:197], v[218:221], v[100:103]
	v_mfma_f32_16x16x32_bf16 v[96:99], v[202:205], v[218:221], v[96:99]
	v_mfma_f32_16x16x32_bf16 v[84:87], v[194:197], v[226:229], v[84:87]
	v_mfma_f32_16x16x32_bf16 v[80:83], v[202:205], v[226:229], v[80:83]
	v_mfma_f32_16x16x32_bf16 v[68:71], v[194:197], v[234:237], v[68:71]
	v_mfma_f32_16x16x32_bf16 v[64:67], v[202:205], v[234:237], v[64:67]
	s_setprio 0
	s_barrier
	s_add_i32 s49, s70, s0
	v_lshl_add_u64 v[238:239], s[54:55], 0, v[136:137]
	s_mov_b32 m0, s49
	ds_read_b128 v[206:209], v176 offset:16384
	ds_read_b128 v[210:213], v176 offset:17408
	ds_read_b128 v[214:217], v176 offset:18432
	ds_read_b128 v[218:221], v176 offset:19456
	ds_read_b128 v[222:225], v176 offset:20480
	ds_read_b128 v[226:229], v176 offset:21504
	ds_read_b128 v[230:233], v176 offset:22528
	ds_read_b128 v[234:237], v176 offset:23552
	global_load_lds_dwordx4 v[238:239], off
	s_add_i32 m0, s49, 0x2000
	s_add_u32 s70, s54, 0x40000
	v_lshl_add_u64 v[240:241], s[54:55], 0, v[132:133]
	s_addc_u32 s71, s55, 0
	s_add_i32 s9, s9, s0
	global_load_lds_dwordx4 v[240:241], off
	v_lshl_add_u64 v[242:243], s[70:71], 0, v[136:137]
	s_mov_b32 m0, s9
	v_lshl_add_u64 v[244:245], s[56:57], 0, v[134:135]
	global_load_lds_dwordx4 v[242:243], off
	v_lshl_add_u64 v[242:243], s[70:71], 0, v[132:133]
	s_add_i32 m0, s9, 0x2000
	s_nop 0
	global_load_lds_dwordx4 v[242:243], off
	v_lshl_add_u64 v[242:243], s[56:57], 0, v[138:139]
	s_mov_b32 m0, s59
	s_nop 0
	global_load_lds_dwordx4 v[242:243], off
	s_mov_b32 m0, s60
	s_nop 0
	global_load_lds_dwordx4 v[244:245], off
	s_waitcnt vmcnt(8)
	s_waitcnt lgkmcnt(0)
	s_barrier
; #define PG8_STAGE(bufoff, gbase, voff) do { _Pragma("unroll") for (int _i = 0; _i < 2; ++_i) \
;         __builtin_amdgcn_global_load_lds((const unsigned*)((const char*)(gbase) + (voff)[_i]), (PG8_LAS unsigned*)(lds + (bufoff) + ldsw + _i * 8192), 16, 0, 0); } while (0)
; #define PG8_LDA(dst, b, h) do { _Pragma("unroll") for (int m = 0; m < 4; ++m) _Pragma("unroll") for (int k = 0; k < 2; ++k) dst[m][k] = *(const PG8_LAS bf16x8*)(lds + PG8_SA(b, h) + aoff + m * 2048 + k * 1024); } while (0)
; #define PG8_LDB(dst, b, h) do { _Pragma("unroll") for (int n = 0; n < 2; ++n) _Pragma("unroll") for (int k = 0; k < 2; ++k) dst[n][k] = *(const PG8_LAS bf16x8*)(lds + PG8_SB(b, h) + boff + n * 2048 + k * 1024); } while (0)
; #define PG8_MMA(ai, bj, At, Bt) do { __builtin_amdgcn_s_setprio(1); _Pragma("unroll") for (int m = 0; m < 4; ++m) _Pragma("unroll") for (int n = 0; n < 2; ++n) _Pragma("unroll") for (int k = 0; k < 2; ++k) \
;         acc[ai][bj][m][n] = __builtin_amdgcn_mfma_f32_16x16x32_bf16(Bt[n][k], At[m][k], acc[ai][bj][m][n], 0, 0, 0); __builtin_amdgcn_s_setprio(0); } while (0)
; #define PG8_WAIT_V(n) asm volatile("s_waitcnt vmcnt(" #n ")" ::: "memory")
; #define PG8_WAIT_L(n) asm volatile("s_waitcnt lgkmcnt(" #n ")" ::: "memory")
; #define PG8_BAR __builtin_amdgcn_s_barrier()
; #define PG8_SCHED __builtin_amdgcn_sched_barrier(0)
; template <class Epi, class Sched, bool ALIGN_EPI = false, bool SP2 = false>
; __device__ __forceinline__ void gemm_phase(PG8_LAS unsigned char* lds, const Gemm g, const Sched& S, const Epi& E, const int wid) {
;     ...
;             PG8_WAIT_V(8); PG8_WAIT_L(0); PG8_BAR; PG8_MMA(1, 0, At, B0); PG8_MMA(1, 1, At, B1); PG8_BAR; PG8_SCHED;
;             PG8_LDB(B0, 1, 0); PG8_LDB(B1, 1, 1); PG8_SCHED; PG8_LDA(At, 1, 0); PG8_STAGE(PG8_SA(0, 1), a2 + hstepA, voffA);
;             PG8_WAIT_V(8); PG8_WAIT_L(0); PG8_BAR; PG8_MMA(0, 0, At, B0); PG8_MMA(0, 1, At, B1); PG8_BAR; PG8_SCHED;
	s_setprio 1
	v_mfma_f32_16x16x32_bf16 v[60:63], v[128:131], v[206:209], v[60:63]
	v_mfma_f32_16x16x32_bf16 v[56:59], v[182:185], v[206:209], v[56:59]
	v_mfma_f32_16x16x32_bf16 v[44:47], v[128:131], v[214:217], v[44:47]
	v_mfma_f32_16x16x32_bf16 v[40:43], v[182:185], v[214:217], v[40:43]
	v_mfma_f32_16x16x32_bf16 v[28:31], v[128:131], v[222:225], v[28:31]
	v_mfma_f32_16x16x32_bf16 v[24:27], v[182:185], v[222:225], v[24:27]
	v_mfma_f32_16x16x32_bf16 v[12:15], v[128:131], v[230:233], v[12:15]
	v_mfma_f32_16x16x32_bf16 v[8:11], v[182:185], v[230:233], v[8:11]
	v_mfma_f32_16x16x32_bf16 v[60:63], v[178:181], v[210:213], v[60:63]
	v_mfma_f32_16x16x32_bf16 v[56:59], v[186:189], v[210:213], v[56:59]
	v_mfma_f32_16x16x32_bf16 v[44:47], v[178:181], v[218:221], v[44:47]
	v_mfma_f32_16x16x32_bf16 v[40:43], v[186:189], v[218:221], v[40:43]
	v_mfma_f32_16x16x32_bf16 v[28:31], v[178:181], v[226:229], v[28:31]
	v_mfma_f32_16x16x32_bf16 v[24:27], v[186:189], v[226:229], v[24:27]
	v_mfma_f32_16x16x32_bf16 v[12:15], v[178:181], v[234:237], v[12:15]
	v_mfma_f32_16x16x32_bf16 v[8:11], v[186:189], v[234:237], v[8:11]
	s_setprio 0
	s_setprio 1
	v_mfma_f32_16x16x32_bf16 v[52:55], v[190:193], v[206:209], v[52:55]
	v_mfma_f32_16x16x32_bf16 v[48:51], v[198:201], v[206:209], v[48:51]
	v_mfma_f32_16x16x32_bf16 v[36:39], v[190:193], v[214:217], v[36:39]
	v_mfma_f32_16x16x32_bf16 v[32:35], v[198:201], v[214:217], v[32:35]
	v_mfma_f32_16x16x32_bf16 v[20:23], v[190:193], v[222:225], v[20:23]
	v_mfma_f32_16x16x32_bf16 v[16:19], v[198:201], v[222:225], v[16:19]
	v_mfma_f32_16x16x32_bf16 v[4:7], v[190:193], v[230:233], v[4:7]
	v_mfma_f32_16x16x32_bf16 v[0:3], v[198:201], v[230:233], v[0:3]
	v_mfma_f32_16x16x32_bf16 v[52:55], v[194:197], v[210:213], v[52:55]
	v_mfma_f32_16x16x32_bf16 v[48:51], v[202:205], v[210:213], v[48:51]
	v_mfma_f32_16x16x32_bf16 v[36:39], v[194:197], v[218:221], v[36:39]
	v_mfma_f32_16x16x32_bf16 v[32:35], v[202:205], v[218:221], v[32:35]
	v_mfma_f32_16x16x32_bf16 v[20:23], v[194:197], v[226:229], v[20:23]
	v_mfma_f32_16x16x32_bf16 v[16:19], v[202:205], v[226:229], v[16:19]
	v_mfma_f32_16x16x32_bf16 v[4:7], v[194:197], v[234:237], v[4:7]
	v_mfma_f32_16x16x32_bf16 v[0:3], v[202:205], v[234:237], v[0:3]
	s_setprio 0
	s_barrier
	s_add_i32 s9, 0, 0x18000
	v_add_u32_e32 v146, s9, v162
	s_add_i32 s49, 0, 0x1c000
	ds_read_b128 v[128:131], v146
	ds_read_b128 v[178:181], v146 offset:1024
	ds_read_b128 v[182:185], v146 offset:2048
	ds_read_b128 v[186:189], v146 offset:3072
	v_add_u32_e32 v146, s49, v162
	ds_read_b128 v[190:193], v146
	ds_read_b128 v[194:197], v146 offset:1024
	ds_read_b128 v[198:201], v146 offset:2048
	ds_read_b128 v[202:205], v146 offset:3072
	s_add_u32 s56, s56, 0x40000
	s_addc_u32 s57, s57, 0
	s_mov_b32 m0, s61
	v_lshl_add_u64 v[246:247], s[56:57], 0, v[138:139]
	ds_read_b128 v[206:209], v176 offset:32768
	ds_read_b128 v[210:213], v176 offset:33792
	ds_read_b128 v[214:217], v176 offset:34816
	ds_read_b128 v[218:221], v176 offset:35840
	ds_read_b128 v[222:225], v176 offset:36864
	ds_read_b128 v[226:229], v176 offset:37888
	ds_read_b128 v[230:233], v176 offset:38912
	ds_read_b128 v[234:237], v176 offset:39936
	global_load_lds_dwordx4 v[246:247], off
	v_lshl_add_u64 v[246:247], s[56:57], 0, v[134:135]
	s_mov_b32 m0, s62
	s_nop 0
	global_load_lds_dwordx4 v[246:247], off
	s_waitcnt vmcnt(8)
	s_waitcnt lgkmcnt(0)
	s_barrier
	s_setprio 1
	v_mfma_f32_16x16x32_bf16 v[124:127], v[128:131], v[206:209], v[124:127]
	v_mfma_f32_16x16x32_bf16 v[120:123], v[182:185], v[206:209], v[120:123]
	v_mfma_f32_16x16x32_bf16 v[108:111], v[128:131], v[214:217], v[108:111]
	v_mfma_f32_16x16x32_bf16 v[104:107], v[182:185], v[214:217], v[104:107]
	v_mfma_f32_16x16x32_bf16 v[92:95], v[128:131], v[222:225], v[92:95]
	v_mfma_f32_16x16x32_bf16 v[88:91], v[182:185], v[222:225], v[88:91]
	v_mfma_f32_16x16x32_bf16 v[76:79], v[128:131], v[230:233], v[76:79]
	v_mfma_f32_16x16x32_bf16 v[72:75], v[182:185], v[230:233], v[72:75]
	v_mfma_f32_16x16x32_bf16 v[124:127], v[178:181], v[210:213], v[124:127]
	v_mfma_f32_16x16x32_bf16 v[120:123], v[186:189], v[210:213], v[120:123]
	v_mfma_f32_16x16x32_bf16 v[108:111], v[178:181], v[218:221], v[108:111]
	v_mfma_f32_16x16x32_bf16 v[104:107], v[186:189], v[218:221], v[104:107]
	v_mfma_f32_16x16x32_bf16 v[92:95], v[178:181], v[226:229], v[92:95]
	v_mfma_f32_16x16x32_bf16 v[88:91], v[186:189], v[226:229], v[88:91]
	v_mfma_f32_16x16x32_bf16 v[76:79], v[178:181], v[234:237], v[76:79]
	v_mfma_f32_16x16x32_bf16 v[72:75], v[186:189], v[234:237], v[72:75]
	s_setprio 0
	s_setprio 1
	v_mfma_f32_16x16x32_bf16 v[116:119], v[190:193], v[206:209], v[116:119]
	v_mfma_f32_16x16x32_bf16 v[112:115], v[198:201], v[206:209], v[112:115]
	v_mfma_f32_16x16x32_bf16 v[100:103], v[190:193], v[214:217], v[100:103]
	v_mfma_f32_16x16x32_bf16 v[96:99], v[198:201], v[214:217], v[96:99]
	v_mfma_f32_16x16x32_bf16 v[84:87], v[190:193], v[222:225], v[84:87]
	v_mfma_f32_16x16x32_bf16 v[80:83], v[198:201], v[222:225], v[80:83]
	v_mfma_f32_16x16x32_bf16 v[68:71], v[190:193], v[230:233], v[68:71]
	v_mfma_f32_16x16x32_bf16 v[64:67], v[198:201], v[230:233], v[64:67]
	v_mfma_f32_16x16x32_bf16 v[116:119], v[194:197], v[210:213], v[116:119]
	v_mfma_f32_16x16x32_bf16 v[112:115], v[202:205], v[210:213], v[112:115]
	v_mfma_f32_16x16x32_bf16 v[100:103], v[194:197], v[218:221], v[100:103]
	v_mfma_f32_16x16x32_bf16 v[96:99], v[202:205], v[218:221], v[96:99]
	v_mfma_f32_16x16x32_bf16 v[84:87], v[194:197], v[226:229], v[84:87]
	v_mfma_f32_16x16x32_bf16 v[80:83], v[202:205], v[226:229], v[80:83]
	v_mfma_f32_16x16x32_bf16 v[68:71], v[194:197], v[234:237], v[68:71]
	v_mfma_f32_16x16x32_bf16 v[64:67], v[202:205], v[234:237], v[64:67]
	s_setprio 0
	s_barrier
; #define PG8_STAGE(bufoff, gbase, voff) do { _Pragma("unroll") for (int _i = 0; _i < 2; ++_i) \
;         __builtin_amdgcn_global_load_lds((const unsigned*)((const char*)(gbase) + (voff)[_i]), (PG8_LAS unsigned*)(lds + (bufoff) + ldsw + _i * 8192), 16, 0, 0); } while (0)
; #define PG8_LDA(dst, b, h) do { _Pragma("unroll") for (int m = 0; m < 4; ++m) _Pragma("unroll") for (int k = 0; k < 2; ++k) dst[m][k] = *(const PG8_LAS bf16x8*)(lds + PG8_SA(b, h) + aoff + m * 2048 + k * 1024); } while (0)
; #define PG8_MMA(ai, bj, At, Bt) do { __builtin_amdgcn_s_setprio(1); _Pragma("unroll") for (int m = 0; m < 4; ++m) _Pragma("unroll") for (int n = 0; n < 2; ++n) _Pragma("unroll") for (int k = 0; k < 2; ++k) \
;         acc[ai][bj][m][n] = __builtin_amdgcn_mfma_f32_16x16x32_bf16(Bt[n][k], At[m][k], acc[ai][bj][m][n], 0, 0, 0); __builtin_amdgcn_s_setprio(0); } while (0)
; #define PG8_WAIT_V(n) asm volatile("s_waitcnt vmcnt(" #n ")" ::: "memory")
; #define PG8_WAIT_L(n) asm volatile("s_waitcnt lgkmcnt(" #n ")" ::: "memory")
; #define PG8_BAR __builtin_amdgcn_s_barrier()
; #define PG8_SCHED __builtin_amdgcn_sched_barrier(0)
; template <class Epi, class Sched, bool ALIGN_EPI = false, bool SP2 = false>
; __device__ __forceinline__ void gemm_phase(PG8_LAS unsigned char* lds, const Gemm g, const Sched& S, const Epi& E, const int wid) {
;     ...
;             PG8_LDA(At, 1, 1); PG8_STAGE(PG8_SB(1, 0), b3, voffB); PG8_STAGE(PG8_SB(1, 1), b3 + hstepB, voffB); PG8_STAGE(PG8_SA(1, 0), a3, voffA);
;             PG8_WAIT_V(8); PG8_WAIT_L(0); PG8_BAR; PG8_MMA(1, 0, At, B0); PG8_MMA(1, 1, At, B1); PG8_BAR; PG8_SCHED;
	s_add_i32 s9, s9, s0
	v_lshl_add_u64 v[238:239], v[238:239], 0, s[80:81]
	s_mov_b32 m0, s9
	ds_read_b128 v[206:209], v176 offset:49152
	ds_read_b128 v[210:213], v176 offset:50176
	ds_read_b128 v[214:217], v176 offset:51200
	ds_read_b128 v[218:221], v176 offset:52224
	ds_read_b128 v[222:225], v176 offset:53248
	ds_read_b128 v[226:229], v176 offset:54272
	ds_read_b128 v[230:233], v176 offset:55296
	ds_read_b128 v[234:237], v176 offset:56320
	global_load_lds_dwordx4 v[238:239], off
	s_add_i32 m0, s9, 0x2000
	s_add_u32 s54, s54, 0x40080
	v_lshl_add_u64 v[238:239], v[240:241], 0, s[80:81]
	s_addc_u32 s55, s55, 0
	s_add_i32 s9, s49, s0
	global_load_lds_dwordx4 v[238:239], off
	v_lshl_add_u64 v[238:239], s[54:55], 0, v[136:137]
	s_mov_b32 m0, s9
	s_nop 0
	global_load_lds_dwordx4 v[238:239], off
	v_lshl_add_u64 v[238:239], s[54:55], 0, v[132:133]
	s_add_i32 m0, s9, 0x2000
	s_nop 0
	global_load_lds_dwordx4 v[238:239], off
	v_lshl_add_u64 v[238:239], v[242:243], 0, s[80:81]
	s_mov_b32 m0, s63
	s_nop 0
	global_load_lds_dwordx4 v[238:239], off
	v_lshl_add_u64 v[238:239], v[244:245], 0, s[80:81]
	s_mov_b32 m0, s64
	s_nop 0
	global_load_lds_dwordx4 v[238:239], off
	s_waitcnt vmcnt(8)
	s_waitcnt lgkmcnt(0)
	s_barrier
	s_setprio 1
	v_mfma_f32_16x16x32_bf16 v[60:63], v[128:131], v[206:209], v[60:63]
	v_mfma_f32_16x16x32_bf16 v[56:59], v[182:185], v[206:209], v[56:59]
	v_mfma_f32_16x16x32_bf16 v[44:47], v[128:131], v[214:217], v[44:47]
	v_mfma_f32_16x16x32_bf16 v[40:43], v[182:185], v[214:217], v[40:43]
	v_mfma_f32_16x16x32_bf16 v[28:31], v[128:131], v[222:225], v[28:31]
	v_mfma_f32_16x16x32_bf16 v[24:27], v[182:185], v[222:225], v[24:27]
	v_mfma_f32_16x16x32_bf16 v[12:15], v[128:131], v[230:233], v[12:15]
	v_mfma_f32_16x16x32_bf16 v[8:11], v[182:185], v[230:233], v[8:11]
	v_mfma_f32_16x16x32_bf16 v[60:63], v[178:181], v[210:213], v[60:63]
	v_mfma_f32_16x16x32_bf16 v[56:59], v[186:189], v[210:213], v[56:59]
	v_mfma_f32_16x16x32_bf16 v[44:47], v[178:181], v[218:221], v[44:47]
	v_mfma_f32_16x16x32_bf16 v[40:43], v[186:189], v[218:221], v[40:43]
	v_mfma_f32_16x16x32_bf16 v[28:31], v[178:181], v[226:229], v[28:31]
	v_mfma_f32_16x16x32_bf16 v[24:27], v[186:189], v[226:229], v[24:27]
	v_mfma_f32_16x16x32_bf16 v[12:15], v[178:181], v[234:237], v[12:15]
	v_mfma_f32_16x16x32_bf16 v[8:11], v[186:189], v[234:237], v[8:11]
	s_setprio 0
	s_setprio 1
	v_mfma_f32_16x16x32_bf16 v[52:55], v[190:193], v[206:209], v[52:55]
	v_mfma_f32_16x16x32_bf16 v[48:51], v[198:201], v[206:209], v[48:51]
	v_mfma_f32_16x16x32_bf16 v[36:39], v[190:193], v[214:217], v[36:39]
	v_mfma_f32_16x16x32_bf16 v[32:35], v[198:201], v[214:217], v[32:35]
	v_mfma_f32_16x16x32_bf16 v[20:23], v[190:193], v[222:225], v[20:23]
	v_mfma_f32_16x16x32_bf16 v[16:19], v[198:201], v[222:225], v[16:19]
	v_mfma_f32_16x16x32_bf16 v[4:7], v[190:193], v[230:233], v[4:7]
	v_mfma_f32_16x16x32_bf16 v[0:3], v[198:201], v[230:233], v[0:3]
	v_mfma_f32_16x16x32_bf16 v[52:55], v[194:197], v[210:213], v[52:55]
	v_mfma_f32_16x16x32_bf16 v[48:51], v[202:205], v[210:213], v[48:51]
	v_mfma_f32_16x16x32_bf16 v[36:39], v[194:197], v[218:221], v[36:39]
	v_mfma_f32_16x16x32_bf16 v[32:35], v[202:205], v[218:221], v[32:35]
	v_mfma_f32_16x16x32_bf16 v[20:23], v[194:197], v[226:229], v[20:23]
	v_mfma_f32_16x16x32_bf16 v[16:19], v[202:205], v[226:229], v[16:19]
	v_mfma_f32_16x16x32_bf16 v[4:7], v[194:197], v[234:237], v[4:7]
	v_mfma_f32_16x16x32_bf16 v[0:3], v[202:205], v[234:237], v[0:3]
	s_setprio 0
	s_barrier
	s_add_u32 s52, s52, 0x100
	s_addc_u32 s53, s53, 0
	s_add_u32 s8, s8, 0x100
	s_addc_u32 s11, s11, 0
	s_cmp_ge_i32 s69, s58
	s_mov_b32 s49, s69
	s_cbranch_scc0 .LBB0_716
	s_mov_b32 s70, 0x1a000
	s_mov_b32 s71, 0xa000
	s_mov_b32 s56, 0x34000
	s_mov_b32 s57, 0x36000
	s_and_b64 vcc, exec, s[6:7]
	s_cbranch_vccz .LBB0_719

; #define PG8_STAGE(bufoff, gbase, voff) do { _Pragma("unroll") for (int _i = 0; _i < 2; ++_i) \
;         __builtin_amdgcn_global_load_lds((const unsigned*)((const char*)(gbase) + (voff)[_i]), (PG8_LAS unsigned*)(lds + (bufoff) + ldsw + _i * 8192), 16, 0, 0); } while (0)
; #define PG8_LDA(dst, b, h) do { _Pragma("unroll") for (int m = 0; m < 4; ++m) _Pragma("unroll") for (int k = 0; k < 2; ++k) dst[m][k] = *(const PG8_LAS bf16x8*)(lds + PG8_SA(b, h) + aoff + m * 2048 + k * 1024); } while (0)
; #define PG8_LDB(dst, b, h) do { _Pragma("unroll") for (int n = 0; n < 2; ++n) _Pragma("unroll") for (int k = 0; k < 2; ++k) dst[n][k] = *(const PG8_LAS bf16x8*)(lds + PG8_SB(b, h) + boff + n * 2048 + k * 1024); } while (0)
; #define PG8_MMA(ai, bj, At, Bt) do { __builtin_amdgcn_s_setprio(1); _Pragma("unroll") for (int m = 0; m < 4; ++m) _Pragma("unroll") for (int n = 0; n < 2; ++n) _Pragma("unroll") for (int k = 0; k < 2; ++k) \
;         acc[ai][bj][m][n] = __builtin_amdgcn_mfma_f32_16x16x32_bf16(Bt[n][k], At[m][k], acc[ai][bj][m][n], 0, 0, 0); __builtin_amdgcn_s_setprio(0); } while (0)
; #define PG8_WAIT_V(n) asm volatile("s_waitcnt vmcnt(" #n ")" ::: "memory")
; #define PG8_WAIT_L(n) asm volatile("s_waitcnt lgkmcnt(" #n ")" ::: "memory")
; template <class Epi, class Sched, bool ALIGN_EPI = false, bool SP2 = false>
; __device__ __forceinline__ void gemm_phase(PG8_LAS unsigned char* lds, const Gemm g, const Sched& S, const Epi& E, const int wid) {
;     ...
;             const bool last = (t == nt - 2);
;             const char* a1 = cA + (size_t)(t + 1) * kstep;
;             const char* a2 = last ? nA : cA + (size_t)(t + 2) * kstep; const char* b2 = last ? nB : cB + (size_t)(t + 2) * kstep;
;             const char* a3 = a2 + kstep; const char* b3 = b2 + kstep;
;             if (last && has_next) S.a_ready(nxt);
;             if constexpr (SP2) {
;             PG8_LDB(B0, 0, 0); PG8_LDB(B1, 0, 1); PG8_SCHED; PG8_LDA(At, 0, 0); PG8_STAGE(PG8_SA(1, 1), a1 + hstepA, voffA);
;             PG8_WAIT_V(8); PG8_WAIT_L(0); PG8_BAR; PG8_MMA(0, 0, At, B0); PG8_MMA(0, 1, At, B1); PG8_BAR; PG8_SCHED;
;             PG8_LDA(At, 0, 1); PG8_STAGE(PG8_SB(0, 0), b2, voffB); PG8_STAGE(PG8_SB(0, 1), b2 + hstepB, voffB); PG8_STAGE(PG8_SA(0, 0), a2, voffA);
;             PG8_WAIT_V(8); PG8_WAIT_L(0); PG8_BAR; PG8_MMA(1, 0, At, B0); PG8_MMA(1, 1, At, B1); PG8_BAR; PG8_SCHED;
.LBB0_830:
	s_add_i32 s73, s60, 2
	s_add_u32 s9, s58, 0xfffc0080
	s_addc_u32 s61, s59, -1
	s_add_i32 s74, 0, 0x10000
	s_cmp_eq_u32 s71, s60
	s_cselect_b32 s63, s55, s61
	s_cselect_b32 s62, s54, s9
	s_cselect_b32 s61, s57, s53
	s_cselect_b32 s60, s56, s51
	s_add_i32 s9, 0, 0x14000
	v_add_u32_e32 v178, s74, v142
	v_add_u32_e32 v194, s9, v142
	ds_read_b128 v[160:163], v178
	ds_read_b128 v[170:173], v178 offset:1024
	ds_read_b128 v[174:177], v178 offset:2048
	ds_read_b128 v[178:181], v178 offset:3072
	ds_read_b128 v[182:185], v194
	ds_read_b128 v[186:189], v194 offset:1024
	ds_read_b128 v[190:193], v194 offset:2048
	ds_read_b128 v[194:197], v194 offset:3072
	v_lshl_add_u64 v[230:231], s[58:59], 0, v[134:135]
	s_add_i32 m0, s64, 0xc000
	ds_read_b128 v[198:201], v143
	ds_read_b128 v[202:205], v143 offset:1024
	ds_read_b128 v[206:209], v143 offset:2048
	ds_read_b128 v[210:213], v143 offset:3072
	ds_read_b128 v[214:217], v143 offset:4096
	ds_read_b128 v[218:221], v143 offset:5120
	ds_read_b128 v[222:225], v143 offset:6144
	ds_read_b128 v[226:229], v143 offset:7168
	global_load_lds_dwordx4 v[230:231], off
	v_lshl_add_u64 v[230:231], s[58:59], 0, v[136:137]
	s_add_i32 m0, s64, 0xe000
	s_nop 0
	global_load_lds_dwordx4 v[230:231], off
	s_waitcnt vmcnt(8)
	s_waitcnt lgkmcnt(0)
	s_barrier
	s_setprio 1
	v_mfma_f32_16x16x32_bf16 v[124:127], v[160:163], v[198:201], v[124:127]
	v_mfma_f32_16x16x32_bf16 v[120:123], v[174:177], v[198:201], v[120:123]
	v_mfma_f32_16x16x32_bf16 v[108:111], v[160:163], v[206:209], v[108:111]
	v_mfma_f32_16x16x32_bf16 v[104:107], v[174:177], v[206:209], v[104:107]
	v_mfma_f32_16x16x32_bf16 v[100:103], v[160:163], v[214:217], v[100:103]
	v_mfma_f32_16x16x32_bf16 v[92:95], v[174:177], v[214:217], v[92:95]
	v_mfma_f32_16x16x32_bf16 v[84:87], v[160:163], v[222:225], v[84:87]
	v_mfma_f32_16x16x32_bf16 v[76:79], v[174:177], v[222:225], v[76:79]
	v_mfma_f32_16x16x32_bf16 v[124:127], v[170:173], v[202:205], v[124:127]
	v_mfma_f32_16x16x32_bf16 v[120:123], v[178:181], v[202:205], v[120:123]
	v_mfma_f32_16x16x32_bf16 v[108:111], v[170:173], v[210:213], v[108:111]
	v_mfma_f32_16x16x32_bf16 v[104:107], v[178:181], v[210:213], v[104:107]
	v_mfma_f32_16x16x32_bf16 v[100:103], v[170:173], v[218:221], v[100:103]
	v_mfma_f32_16x16x32_bf16 v[92:95], v[178:181], v[218:221], v[92:95]
	v_mfma_f32_16x16x32_bf16 v[84:87], v[170:173], v[226:229], v[84:87]
	v_mfma_f32_16x16x32_bf16 v[76:79], v[178:181], v[226:229], v[76:79]
	s_setprio 0
	s_setprio 1
	v_mfma_f32_16x16x32_bf16 v[116:119], v[182:185], v[198:201], v[116:119]
	v_mfma_f32_16x16x32_bf16 v[112:115], v[190:193], v[198:201], v[112:115]
	v_mfma_f32_16x16x32_bf16 v[96:99], v[182:185], v[206:209], v[96:99]
	v_mfma_f32_16x16x32_bf16 v[88:91], v[190:193], v[206:209], v[88:91]
	v_mfma_f32_16x16x32_bf16 v[80:83], v[182:185], v[214:217], v[80:83]
	v_mfma_f32_16x16x32_bf16 v[72:75], v[190:193], v[214:217], v[72:75]
	v_mfma_f32_16x16x32_bf16 v[68:71], v[182:185], v[222:225], v[68:71]
	v_mfma_f32_16x16x32_bf16 v[56:59], v[190:193], v[222:225], v[56:59]
	v_mfma_f32_16x16x32_bf16 v[116:119], v[186:189], v[202:205], v[116:119]
	v_mfma_f32_16x16x32_bf16 v[112:115], v[194:197], v[202:205], v[112:115]
	v_mfma_f32_16x16x32_bf16 v[96:99], v[186:189], v[210:213], v[96:99]
	v_mfma_f32_16x16x32_bf16 v[88:91], v[194:197], v[210:213], v[88:91]
	v_mfma_f32_16x16x32_bf16 v[80:83], v[186:189], v[218:221], v[80:83]
	v_mfma_f32_16x16x32_bf16 v[72:75], v[194:197], v[218:221], v[72:75]
	v_mfma_f32_16x16x32_bf16 v[68:71], v[186:189], v[226:229], v[68:71]
	v_mfma_f32_16x16x32_bf16 v[56:59], v[194:197], v[226:229], v[56:59]
	s_setprio 0
	s_barrier
	s_add_i32 s74, s74, s0
	v_lshl_add_u64 v[230:231], s[60:61], 0, v[146:147]
	s_mov_b32 m0, s74
	ds_read_b128 v[198:201], v143 offset:16384
	ds_read_b128 v[202:205], v143 offset:17408
	ds_read_b128 v[206:209], v143 offset:18432
	ds_read_b128 v[210:213], v143 offset:19456
	ds_read_b128 v[214:217], v143 offset:20480
	ds_read_b128 v[218:221], v143 offset:21504
	ds_read_b128 v[222:225], v143 offset:22528
	ds_read_b128 v[226:229], v143 offset:23552
	global_load_lds_dwordx4 v[230:231], off
	s_add_i32 m0, s74, 0x2000
	s_add_u32 s74, s60, 0x40000
	v_lshl_add_u64 v[232:233], s[60:61], 0, v[128:129]
	s_addc_u32 s75, s61, 0
	s_add_i32 s9, s9, s0
	global_load_lds_dwordx4 v[232:233], off
	v_lshl_add_u64 v[234:235], s[74:75], 0, v[146:147]
	s_mov_b32 m0, s9
	v_lshl_add_u64 v[236:237], s[62:63], 0, v[130:131]
	global_load_lds_dwordx4 v[234:235], off
	v_lshl_add_u64 v[234:235], s[74:75], 0, v[128:129]
	s_add_i32 m0, s9, 0x2000
	s_nop 0
	global_load_lds_dwordx4 v[234:235], off
	v_lshl_add_u64 v[234:235], s[62:63], 0, v[132:133]
	s_mov_b32 m0, s64
	s_nop 0
	global_load_lds_dwordx4 v[234:235], off
	s_mov_b32 m0, s65
	s_nop 0
	global_load_lds_dwordx4 v[236:237], off
	s_waitcnt vmcnt(8)
	s_waitcnt lgkmcnt(0)
	s_barrier
; #define PG8_STAGE(bufoff, gbase, voff) do { _Pragma("unroll") for (int _i = 0; _i < 2; ++_i) \
;         __builtin_amdgcn_global_load_lds((const unsigned*)((const char*)(gbase) + (voff)[_i]), (PG8_LAS unsigned*)(lds + (bufoff) + ldsw + _i * 8192), 16, 0, 0); } while (0)
; #define PG8_LDA(dst, b, h) do { _Pragma("unroll") for (int m = 0; m < 4; ++m) _Pragma("unroll") for (int k = 0; k < 2; ++k) dst[m][k] = *(const PG8_LAS bf16x8*)(lds + PG8_SA(b, h) + aoff + m * 2048 + k * 1024); } while (0)
; #define PG8_LDB(dst, b, h) do { _Pragma("unroll") for (int n = 0; n < 2; ++n) _Pragma("unroll") for (int k = 0; k < 2; ++k) dst[n][k] = *(const PG8_LAS bf16x8*)(lds + PG8_SB(b, h) + boff + n * 2048 + k * 1024); } while (0)
; #define PG8_MMA(ai, bj, At, Bt) do { __builtin_amdgcn_s_setprio(1); _Pragma("unroll") for (int m = 0; m < 4; ++m) _Pragma("unroll") for (int n = 0; n < 2; ++n) _Pragma("unroll") for (int k = 0; k < 2; ++k) \
;         acc[ai][bj][m][n] = __builtin_amdgcn_mfma_f32_16x16x32_bf16(Bt[n][k], At[m][k], acc[ai][bj][m][n], 0, 0, 0); __builtin_amdgcn_s_setprio(0); } while (0)
; #define PG8_WAIT_V(n) asm volatile("s_waitcnt vmcnt(" #n ")" ::: "memory")
; #define PG8_WAIT_L(n) asm volatile("s_waitcnt lgkmcnt(" #n ")" ::: "memory")
; #define PG8_BAR __builtin_amdgcn_s_barrier()
; #define PG8_SCHED __builtin_amdgcn_sched_barrier(0)
; template <class Epi, class Sched, bool ALIGN_EPI = false, bool SP2 = false>
; __device__ __forceinline__ void gemm_phase(PG8_LAS unsigned char* lds, const Gemm g, const Sched& S, const Epi& E, const int wid) {
;     ...
;             PG8_WAIT_V(8); PG8_WAIT_L(0); PG8_BAR; PG8_MMA(1, 0, At, B0); PG8_MMA(1, 1, At, B1); PG8_BAR; PG8_SCHED;
;             PG8_LDB(B0, 1, 0); PG8_LDB(B1, 1, 1); PG8_SCHED; PG8_LDA(At, 1, 0); PG8_STAGE(PG8_SA(0, 1), a2 + hstepA, voffA);
;             PG8_WAIT_V(8); PG8_WAIT_L(0); PG8_BAR; PG8_MMA(0, 0, At, B0); PG8_MMA(0, 1, At, B1); PG8_BAR; PG8_SCHED;
	s_setprio 1
	v_mfma_f32_16x16x32_bf16 v[44:47], v[160:163], v[198:201], v[44:47]
	v_mfma_f32_16x16x32_bf16 v[40:43], v[174:177], v[198:201], v[40:43]
	v_mfma_f32_16x16x32_bf16 v[20:23], v[160:163], v[206:209], v[20:23]
	v_mfma_f32_16x16x32_bf16 v[12:15], v[174:177], v[206:209], v[12:15]
	v_mfma_f32_16x16x32_bf16 v[64:67], v[160:163], v[214:217], v[64:67]
	v_mfma_f32_16x16x32_bf16 v[52:55], v[174:177], v[214:217], v[52:55]
	v_mfma_f32_16x16x32_bf16 v[36:39], v[160:163], v[222:225], v[36:39]
	v_mfma_f32_16x16x32_bf16 v[28:31], v[174:177], v[222:225], v[28:31]
	v_mfma_f32_16x16x32_bf16 v[44:47], v[170:173], v[202:205], v[44:47]
	v_mfma_f32_16x16x32_bf16 v[40:43], v[178:181], v[202:205], v[40:43]
	v_mfma_f32_16x16x32_bf16 v[20:23], v[170:173], v[210:213], v[20:23]
	v_mfma_f32_16x16x32_bf16 v[12:15], v[178:181], v[210:213], v[12:15]
	v_mfma_f32_16x16x32_bf16 v[64:67], v[170:173], v[218:221], v[64:67]
	v_mfma_f32_16x16x32_bf16 v[52:55], v[178:181], v[218:221], v[52:55]
	v_mfma_f32_16x16x32_bf16 v[36:39], v[170:173], v[226:229], v[36:39]
	v_mfma_f32_16x16x32_bf16 v[28:31], v[178:181], v[226:229], v[28:31]
	s_setprio 0
	s_setprio 1
	v_mfma_f32_16x16x32_bf16 v[16:19], v[182:185], v[198:201], v[16:19]
	v_mfma_f32_16x16x32_bf16 v[8:11], v[190:193], v[198:201], v[8:11]
	v_mfma_f32_16x16x32_bf16 v[60:63], v[182:185], v[206:209], v[60:63]
	v_mfma_f32_16x16x32_bf16 v[48:51], v[190:193], v[206:209], v[48:51]
	v_mfma_f32_16x16x32_bf16 v[32:35], v[182:185], v[214:217], v[32:35]
	v_mfma_f32_16x16x32_bf16 v[24:27], v[190:193], v[214:217], v[24:27]
	v_mfma_f32_16x16x32_bf16 v[4:7], v[182:185], v[222:225], v[4:7]
	v_mfma_f32_16x16x32_bf16 v[0:3], v[190:193], v[222:225], v[0:3]
	v_mfma_f32_16x16x32_bf16 v[16:19], v[186:189], v[202:205], v[16:19]
	v_mfma_f32_16x16x32_bf16 v[8:11], v[194:197], v[202:205], v[8:11]
	v_mfma_f32_16x16x32_bf16 v[60:63], v[186:189], v[210:213], v[60:63]
	v_mfma_f32_16x16x32_bf16 v[48:51], v[194:197], v[210:213], v[48:51]
	v_mfma_f32_16x16x32_bf16 v[32:35], v[186:189], v[218:221], v[32:35]
	v_mfma_f32_16x16x32_bf16 v[24:27], v[194:197], v[218:221], v[24:27]
	v_mfma_f32_16x16x32_bf16 v[4:7], v[186:189], v[226:229], v[4:7]
	v_mfma_f32_16x16x32_bf16 v[0:3], v[194:197], v[226:229], v[0:3]
	s_setprio 0
	s_barrier
	s_add_i32 s9, 0, 0x18000
	s_add_i32 s74, 0, 0x1c000
	v_add_u32_e32 v178, s9, v142
	v_add_u32_e32 v194, s74, v142
	ds_read_b128 v[160:163], v178
	ds_read_b128 v[170:173], v178 offset:1024
	ds_read_b128 v[174:177], v178 offset:2048
	ds_read_b128 v[178:181], v178 offset:3072
	ds_read_b128 v[182:185], v194
	ds_read_b128 v[186:189], v194 offset:1024
	ds_read_b128 v[190:193], v194 offset:2048
	ds_read_b128 v[194:197], v194 offset:3072
	s_add_u32 s62, s62, 0x40000
	s_addc_u32 s63, s63, 0
	s_mov_b32 m0, s66
	v_lshl_add_u64 v[238:239], s[62:63], 0, v[132:133]
	ds_read_b128 v[198:201], v143 offset:32768
	ds_read_b128 v[202:205], v143 offset:33792
	ds_read_b128 v[206:209], v143 offset:34816
	ds_read_b128 v[210:213], v143 offset:35840
	ds_read_b128 v[214:217], v143 offset:36864
	ds_read_b128 v[218:221], v143 offset:37888
	ds_read_b128 v[222:225], v143 offset:38912
	ds_read_b128 v[226:229], v143 offset:39936
	global_load_lds_dwordx4 v[238:239], off
	v_lshl_add_u64 v[238:239], s[62:63], 0, v[130:131]
	s_mov_b32 m0, s67
	s_nop 0
	global_load_lds_dwordx4 v[238:239], off
	s_waitcnt vmcnt(8)
	s_waitcnt lgkmcnt(0)
	s_barrier
	s_setprio 1
	v_mfma_f32_16x16x32_bf16 v[124:127], v[160:163], v[198:201], v[124:127]
	v_mfma_f32_16x16x32_bf16 v[120:123], v[174:177], v[198:201], v[120:123]
	v_mfma_f32_16x16x32_bf16 v[108:111], v[160:163], v[206:209], v[108:111]
	v_mfma_f32_16x16x32_bf16 v[104:107], v[174:177], v[206:209], v[104:107]
	v_mfma_f32_16x16x32_bf16 v[100:103], v[160:163], v[214:217], v[100:103]
	v_mfma_f32_16x16x32_bf16 v[92:95], v[174:177], v[214:217], v[92:95]
	v_mfma_f32_16x16x32_bf16 v[84:87], v[160:163], v[222:225], v[84:87]
	v_mfma_f32_16x16x32_bf16 v[76:79], v[174:177], v[222:225], v[76:79]
	v_mfma_f32_16x16x32_bf16 v[124:127], v[170:173], v[202:205], v[124:127]
	v_mfma_f32_16x16x32_bf16 v[120:123], v[178:181], v[202:205], v[120:123]
	v_mfma_f32_16x16x32_bf16 v[108:111], v[170:173], v[210:213], v[108:111]
	v_mfma_f32_16x16x32_bf16 v[104:107], v[178:181], v[210:213], v[104:107]
	v_mfma_f32_16x16x32_bf16 v[100:103], v[170:173], v[218:221], v[100:103]
	v_mfma_f32_16x16x32_bf16 v[92:95], v[178:181], v[218:221], v[92:95]
	v_mfma_f32_16x16x32_bf16 v[84:87], v[170:173], v[226:229], v[84:87]
	v_mfma_f32_16x16x32_bf16 v[76:79], v[178:181], v[226:229], v[76:79]
	s_setprio 0
	s_setprio 1
	v_mfma_f32_16x16x32_bf16 v[116:119], v[182:185], v[198:201], v[116:119]
	v_mfma_f32_16x16x32_bf16 v[112:115], v[190:193], v[198:201], v[112:115]
	v_mfma_f32_16x16x32_bf16 v[96:99], v[182:185], v[206:209], v[96:99]
	v_mfma_f32_16x16x32_bf16 v[88:91], v[190:193], v[206:209], v[88:91]
	v_mfma_f32_16x16x32_bf16 v[80:83], v[182:185], v[214:217], v[80:83]
	v_mfma_f32_16x16x32_bf16 v[72:75], v[190:193], v[214:217], v[72:75]
	v_mfma_f32_16x16x32_bf16 v[68:71], v[182:185], v[222:225], v[68:71]
	v_mfma_f32_16x16x32_bf16 v[56:59], v[190:193], v[222:225], v[56:59]
	v_mfma_f32_16x16x32_bf16 v[116:119], v[186:189], v[202:205], v[116:119]
	v_mfma_f32_16x16x32_bf16 v[112:115], v[194:197], v[202:205], v[112:115]
	v_mfma_f32_16x16x32_bf16 v[96:99], v[186:189], v[210:213], v[96:99]
	v_mfma_f32_16x16x32_bf16 v[88:91], v[194:197], v[210:213], v[88:91]
	v_mfma_f32_16x16x32_bf16 v[80:83], v[186:189], v[218:221], v[80:83]
	v_mfma_f32_16x16x32_bf16 v[72:75], v[194:197], v[218:221], v[72:75]
	v_mfma_f32_16x16x32_bf16 v[68:71], v[186:189], v[226:229], v[68:71]
	v_mfma_f32_16x16x32_bf16 v[56:59], v[194:197], v[226:229], v[56:59]
	s_setprio 0
	s_barrier
; #define PG8_STAGE(bufoff, gbase, voff) do { _Pragma("unroll") for (int _i = 0; _i < 2; ++_i) \
;         __builtin_amdgcn_global_load_lds((const unsigned*)((const char*)(gbase) + (voff)[_i]), (PG8_LAS unsigned*)(lds + (bufoff) + ldsw + _i * 8192), 16, 0, 0); } while (0)
; #define PG8_LDA(dst, b, h) do { _Pragma("unroll") for (int m = 0; m < 4; ++m) _Pragma("unroll") for (int k = 0; k < 2; ++k) dst[m][k] = *(const PG8_LAS bf16x8*)(lds + PG8_SA(b, h) + aoff + m * 2048 + k * 1024); } while (0)
; #define PG8_MMA(ai, bj, At, Bt) do { __builtin_amdgcn_s_setprio(1); _Pragma("unroll") for (int m = 0; m < 4; ++m) _Pragma("unroll") for (int n = 0; n < 2; ++n) _Pragma("unroll") for (int k = 0; k < 2; ++k) \
;         acc[ai][bj][m][n] = __builtin_amdgcn_mfma_f32_16x16x32_bf16(Bt[n][k], At[m][k], acc[ai][bj][m][n], 0, 0, 0); __builtin_amdgcn_s_setprio(0); } while (0)
; #define PG8_WAIT_V(n) asm volatile("s_waitcnt vmcnt(" #n ")" ::: "memory")
; #define PG8_WAIT_L(n) asm volatile("s_waitcnt lgkmcnt(" #n ")" ::: "memory")
; #define PG8_BAR __builtin_amdgcn_s_barrier()
; #define PG8_SCHED __builtin_amdgcn_sched_barrier(0)
; template <class Epi, class Sched, bool ALIGN_EPI = false, bool SP2 = false>
; __device__ __forceinline__ void gemm_phase(PG8_LAS unsigned char* lds, const Gemm g, const Sched& S, const Epi& E, const int wid) {
;     ...
;             PG8_LDA(At, 1, 1); PG8_STAGE(PG8_SB(1, 0), b3, voffB); PG8_STAGE(PG8_SB(1, 1), b3 + hstepB, voffB); PG8_STAGE(PG8_SA(1, 0), a3, voffA);
;             PG8_WAIT_V(8); PG8_WAIT_L(0); PG8_BAR; PG8_MMA(1, 0, At, B0); PG8_MMA(1, 1, At, B1); PG8_BAR; PG8_SCHED;
	s_add_i32 s9, s9, s0
	v_lshl_add_u64 v[230:231], v[230:231], 0, s[80:81]
	s_mov_b32 m0, s9
	ds_read_b128 v[198:201], v143 offset:49152
	ds_read_b128 v[202:205], v143 offset:50176
	ds_read_b128 v[206:209], v143 offset:51200
	ds_read_b128 v[210:213], v143 offset:52224
	ds_read_b128 v[214:217], v143 offset:53248
	ds_read_b128 v[218:221], v143 offset:54272
	ds_read_b128 v[222:225], v143 offset:55296
	ds_read_b128 v[226:229], v143 offset:56320
	global_load_lds_dwordx4 v[230:231], off
	s_add_i32 m0, s9, 0x2000
	s_add_u32 s60, s60, 0x40080
	v_lshl_add_u64 v[230:231], v[232:233], 0, s[80:81]
	s_addc_u32 s61, s61, 0
	s_add_i32 s9, s74, s0
	global_load_lds_dwordx4 v[230:231], off
	v_lshl_add_u64 v[230:231], s[60:61], 0, v[146:147]
	s_mov_b32 m0, s9
	s_nop 0
	global_load_lds_dwordx4 v[230:231], off
	v_lshl_add_u64 v[230:231], s[60:61], 0, v[128:129]
	s_add_i32 m0, s9, 0x2000
	s_nop 0
	global_load_lds_dwordx4 v[230:231], off
	v_lshl_add_u64 v[230:231], v[234:235], 0, s[80:81]
	s_mov_b32 m0, s69
	s_nop 0
	global_load_lds_dwordx4 v[230:231], off
	v_lshl_add_u64 v[230:231], v[236:237], 0, s[80:81]
	s_mov_b32 m0, s70
	s_nop 0
	global_load_lds_dwordx4 v[230:231], off
	s_waitcnt vmcnt(8)
	s_waitcnt lgkmcnt(0)
	s_barrier
	s_setprio 1
	v_mfma_f32_16x16x32_bf16 v[44:47], v[160:163], v[198:201], v[44:47]
	v_mfma_f32_16x16x32_bf16 v[40:43], v[174:177], v[198:201], v[40:43]
	v_mfma_f32_16x16x32_bf16 v[20:23], v[160:163], v[206:209], v[20:23]
	v_mfma_f32_16x16x32_bf16 v[12:15], v[174:177], v[206:209], v[12:15]
	v_mfma_f32_16x16x32_bf16 v[64:67], v[160:163], v[214:217], v[64:67]
	v_mfma_f32_16x16x32_bf16 v[52:55], v[174:177], v[214:217], v[52:55]
	v_mfma_f32_16x16x32_bf16 v[36:39], v[160:163], v[222:225], v[36:39]
	v_mfma_f32_16x16x32_bf16 v[28:31], v[174:177], v[222:225], v[28:31]
	v_mfma_f32_16x16x32_bf16 v[44:47], v[170:173], v[202:205], v[44:47]
	v_mfma_f32_16x16x32_bf16 v[40:43], v[178:181], v[202:205], v[40:43]
	v_mfma_f32_16x16x32_bf16 v[20:23], v[170:173], v[210:213], v[20:23]
	v_mfma_f32_16x16x32_bf16 v[12:15], v[178:181], v[210:213], v[12:15]
	v_mfma_f32_16x16x32_bf16 v[64:67], v[170:173], v[218:221], v[64:67]
	v_mfma_f32_16x16x32_bf16 v[52:55], v[178:181], v[218:221], v[52:55]
	v_mfma_f32_16x16x32_bf16 v[36:39], v[170:173], v[226:229], v[36:39]
	v_mfma_f32_16x16x32_bf16 v[28:31], v[178:181], v[226:229], v[28:31]
	s_setprio 0
	s_setprio 1
	v_mfma_f32_16x16x32_bf16 v[16:19], v[182:185], v[198:201], v[16:19]
	v_mfma_f32_16x16x32_bf16 v[8:11], v[190:193], v[198:201], v[8:11]
	v_mfma_f32_16x16x32_bf16 v[60:63], v[182:185], v[206:209], v[60:63]
	v_mfma_f32_16x16x32_bf16 v[48:51], v[190:193], v[206:209], v[48:51]
	v_mfma_f32_16x16x32_bf16 v[32:35], v[182:185], v[214:217], v[32:35]
	v_mfma_f32_16x16x32_bf16 v[24:27], v[190:193], v[214:217], v[24:27]
	v_mfma_f32_16x16x32_bf16 v[4:7], v[182:185], v[222:225], v[4:7]
	v_mfma_f32_16x16x32_bf16 v[0:3], v[190:193], v[222:225], v[0:3]
	v_mfma_f32_16x16x32_bf16 v[16:19], v[186:189], v[202:205], v[16:19]
	v_mfma_f32_16x16x32_bf16 v[8:11], v[194:197], v[202:205], v[8:11]
	v_mfma_f32_16x16x32_bf16 v[60:63], v[186:189], v[210:213], v[60:63]
	v_mfma_f32_16x16x32_bf16 v[48:51], v[194:197], v[210:213], v[48:51]
	v_mfma_f32_16x16x32_bf16 v[32:35], v[186:189], v[218:221], v[32:35]
	v_mfma_f32_16x16x32_bf16 v[24:27], v[194:197], v[218:221], v[24:27]
	v_mfma_f32_16x16x32_bf16 v[4:7], v[186:189], v[226:229], v[4:7]
	v_mfma_f32_16x16x32_bf16 v[0:3], v[194:197], v[226:229], v[0:3]
	s_setprio 0
	s_barrier
	s_add_u32 s58, s58, 0x100
	s_addc_u32 s59, s59, 0
	s_add_u32 s51, s51, 0x100
	s_addc_u32 s53, s53, 0
	s_cmp_ge_i32 s73, s5
	s_mov_b32 s60, s73
	s_cbranch_scc0 .LBB0_830
	s_mov_b32 s73, 0x18000
	s_mov_b32 s74, 0x1e000
	s_mov_b32 s75, 0xc000
	s_mov_b32 s63, 0xe000
	s_mov_b32 s59, 0x28000
	s_mov_b32 s58, 0x2a000
	s_mov_b32 s61, 0x2c000
	s_mov_b32 s60, 0x32000
